# v17 plus two-accumulator FMA chains in the triangular solve and kernarg s_load wait moved past the row-stat loads in the compact and up epilogues
# baseline (speedup 1.0000x reference)
; __device__ __forceinline__ bf16_t f2bf(float f) { return (bf16_t)(cvt_pk_bf16(f, 0.f) & 0xffffu); }
; __device__ __forceinline__ float bf2f(bf16_t b) { return __uint_as_float(((unsigned)b) << 16); }
; template <int I>
; __device__ __forceinline__ void solve_rows(float (&x)[64], const f32x4* A4, const bf16_t* src, const float* sBeta, const float* sGam, int part, bf16_t* dst, int nvalid) {
;     ...
;         for (int q = 0; q < (I + 3) / 4; ++q) a4[q] = A4[I * 16 + q];
;         float a = bf2f(src[I * 136]) * sBeta[I];
;         if (part == 1) a *= __expf(sGam[I]);
; #pragma unroll
;         for (int j = 0; j < I; ++j) a -= a4[j >> 2][j & 3] * x[j];
;         x[I] = a;
;         if (I < nvalid) *dst = f2bf(a);
.LBB0_463:
	s_waitcnt lgkmcnt(3)
	v_fma_f32 v12, -v64, v12, v18
	v_mul_f32_e64 v246, -v65, v13
	v_fma_f32 v12, -v67, v14, v12
	v_fma_f32 v246, -v69, v15, v246
	s_waitcnt lgkmcnt(2)
	v_fma_f32 v8, -v71, v8, v12
	v_fma_f32 v246, -v73, v9, v246
	v_fma_f32 v8, -v75, v10, v8
	v_fma_f32 v246, -v77, v11, v246
	s_waitcnt lgkmcnt(1)
	v_fma_f32 v4, -v79, v4, v8
	v_fma_f32 v246, -v81, v5, v246
	v_fma_f32 v4, -v83, v6, v4
	v_fma_f32 v246, -v85, v7, v246
	s_waitcnt lgkmcnt(0)
	v_fma_f32 v0, -v87, v0, v4
	v_fma_f32 v246, -v89, v1, v246
	v_fma_f32 v0, -v91, v2, v0
	v_add_f32_e32 v0, v0, v246
	v_cndmask_b32_e64 v1, 0, 1, s[62:63]
	v_cmp_ne_u32_e64 s[52:53], 1, v1
	s_andn2_b64 vcc, exec, s[62:63]
	v_fma_f32 v68, -v3, v66, v0
	s_cbranch_vccnz .LBB0_465
	v_cvt_pk_bf16_f32 v0, v68, s0
	global_store_short v[16:17], v0, off

; __device__ __forceinline__ bf16_t f2bf(float f) { return (bf16_t)(cvt_pk_bf16(f, 0.f) & 0xffffu); }
; __device__ __forceinline__ float bf2f(bf16_t b) { return __uint_as_float(((unsigned)b) << 16); }
; template <int I>
; __device__ __forceinline__ void solve_rows(float (&x)[64], const f32x4* A4, const bf16_t* src, const float* sBeta, const float* sGam, int part, bf16_t* dst, int nvalid) {
;     ...
;         for (int q = 0; q < (I + 3) / 4; ++q) a4[q] = A4[I * 16 + q];
;         float a = bf2f(src[I * 136]) * sBeta[I];
;         if (part == 1) a *= __expf(sGam[I]);
; #pragma unroll
;         for (int j = 0; j < I; ++j) a -= a4[j >> 2][j & 3] * x[j];
;         x[I] = a;
;         if (I < nvalid) *dst = f2bf(a);
.LBB0_467:
	s_waitcnt lgkmcnt(0)
	v_fma_f32 v1, -v64, v12, v235
	v_mul_f32_e64 v246, -v65, v13
	v_fma_f32 v1, -v67, v14, v1
	v_fma_f32 v246, -v69, v15, v246
	v_fma_f32 v1, -v71, v16, v1
	v_fma_f32 v246, -v73, v17, v246
	v_fma_f32 v1, -v75, v18, v1
	v_fma_f32 v246, -v77, v19, v246
	v_fma_f32 v1, -v79, v8, v1
	v_fma_f32 v246, -v81, v9, v246
	v_fma_f32 v1, -v83, v10, v1
	v_fma_f32 v246, -v85, v11, v246
	v_fma_f32 v1, -v87, v4, v1
	v_fma_f32 v246, -v89, v5, v246
	v_fma_f32 v1, -v91, v6, v1
	v_fma_f32 v246, -v66, v7, v246
	s_and_b64 vcc, exec, s[52:53]
	v_fma_f32 v70, -v68, v0, v1
	v_add_f32_e32 v70, v70, v246
	s_cbranch_vccnz .LBB0_469
	v_cvt_pk_bf16_f32 v0, v70, s0
	global_store_short v[20:21], v0, off

; __device__ __forceinline__ bf16_t f2bf(float f) { return (bf16_t)(cvt_pk_bf16(f, 0.f) & 0xffffu); }
; __device__ __forceinline__ float bf2f(bf16_t b) { return __uint_as_float(((unsigned)b) << 16); }
; template <int I>
; __device__ __forceinline__ void solve_rows(float (&x)[64], const f32x4* A4, const bf16_t* src, const float* sBeta, const float* sGam, int part, bf16_t* dst, int nvalid) {
;     ...
;         for (int q = 0; q < (I + 3) / 4; ++q) a4[q] = A4[I * 16 + q];
;         float a = bf2f(src[I * 136]) * sBeta[I];
;         if (part == 1) a *= __expf(sGam[I]);
; #pragma unroll
;         for (int j = 0; j < I; ++j) a -= a4[j >> 2][j & 3] * x[j];
;         x[I] = a;
;         if (I < nvalid) *dst = f2bf(a);
.LBB0_471:
	s_waitcnt lgkmcnt(0)
	v_fma_f32 v2, -v64, v12, v235
	v_mul_f32_e64 v246, -v65, v13
	v_fma_f32 v2, -v67, v14, v2
	v_fma_f32 v246, -v69, v15, v246
	v_fma_f32 v2, -v71, v16, v2
	v_fma_f32 v246, -v73, v17, v246
	v_fma_f32 v2, -v75, v18, v2
	v_fma_f32 v246, -v77, v19, v246
	v_fma_f32 v2, -v79, v8, v2
	v_fma_f32 v246, -v81, v9, v246
	v_fma_f32 v2, -v83, v10, v2
	v_fma_f32 v246, -v85, v11, v246
	v_fma_f32 v2, -v87, v4, v2
	v_fma_f32 v246, -v89, v5, v246
	v_fma_f32 v2, -v91, v6, v2
	v_fma_f32 v246, -v66, v7, v246
	v_fma_f32 v0, -v68, v0, v2
	s_and_b64 vcc, exec, s[52:53]
	v_fma_f32 v246, -v70, v1, v246
	v_add_f32_e32 v72, v0, v246
	s_cbranch_vccnz .LBB0_473
	v_cvt_pk_bf16_f32 v0, v72, s0
	global_store_short v[20:21], v0, off

; __device__ __forceinline__ bf16_t f2bf(float f) { return (bf16_t)(cvt_pk_bf16(f, 0.f) & 0xffffu); }
; __device__ __forceinline__ float bf2f(bf16_t b) { return __uint_as_float(((unsigned)b) << 16); }
; template <int I>
; __device__ __forceinline__ void solve_rows(float (&x)[64], const f32x4* A4, const bf16_t* src, const float* sBeta, const float* sGam, int part, bf16_t* dst, int nvalid) {
;     ...
;         for (int q = 0; q < (I + 3) / 4; ++q) a4[q] = A4[I * 16 + q];
;         float a = bf2f(src[I * 136]) * sBeta[I];
;         if (part == 1) a *= __expf(sGam[I]);
; #pragma unroll
;         for (int j = 0; j < I; ++j) a -= a4[j >> 2][j & 3] * x[j];
;         x[I] = a;
;         if (I < nvalid) *dst = f2bf(a);
.LBB0_475:
	s_waitcnt lgkmcnt(0)
	v_fma_f32 v3, -v64, v16, v235
	v_mul_f32_e64 v246, -v65, v17
	v_fma_f32 v3, -v67, v18, v3
	v_fma_f32 v246, -v69, v19, v246
	v_fma_f32 v3, -v71, v8, v3
	v_fma_f32 v246, -v73, v9, v246
	v_fma_f32 v3, -v75, v10, v3
	v_fma_f32 v246, -v77, v11, v246
	v_fma_f32 v3, -v79, v4, v3
	v_fma_f32 v246, -v81, v5, v246
	v_fma_f32 v3, -v83, v6, v3
	v_fma_f32 v246, -v85, v7, v246
	v_fma_f32 v3, -v87, v12, v3
	v_fma_f32 v246, -v89, v13, v246
	v_fma_f32 v3, -v91, v14, v3
	v_fma_f32 v246, -v66, v15, v246
	v_fma_f32 v0, -v68, v0, v3
	v_fma_f32 v246, -v70, v1, v246
	s_and_b64 vcc, exec, s[52:53]
	v_fma_f32 v74, -v72, v2, v0
	v_add_f32_e32 v74, v74, v246
	s_cbranch_vccnz .LBB0_477
	v_cvt_pk_bf16_f32 v0, v74, s0
	global_store_short v[20:21], v0, off

; __device__ __forceinline__ bf16_t f2bf(float f) { return (bf16_t)(cvt_pk_bf16(f, 0.f) & 0xffffu); }
; __device__ __forceinline__ float bf2f(bf16_t b) { return __uint_as_float(((unsigned)b) << 16); }
; template <int I>
; __device__ __forceinline__ void solve_rows(float (&x)[64], const f32x4* A4, const bf16_t* src, const float* sBeta, const float* sGam, int part, bf16_t* dst, int nvalid) {
;     ...
;         for (int q = 0; q < (I + 3) / 4; ++q) a4[q] = A4[I * 16 + q];
;         float a = bf2f(src[I * 136]) * sBeta[I];
;         if (part == 1) a *= __expf(sGam[I]);
; #pragma unroll
;         for (int j = 0; j < I; ++j) a -= a4[j >> 2][j & 3] * x[j];
;         x[I] = a;
;         if (I < nvalid) *dst = f2bf(a);
.LBB0_479:
	s_waitcnt lgkmcnt(4)
	v_fma_f32 v16, -v64, v16, v22
	v_mul_f32_e64 v246, -v65, v17
	v_fma_f32 v16, -v67, v18, v16
	v_fma_f32 v246, -v69, v19, v246
	s_waitcnt lgkmcnt(3)
	v_fma_f32 v8, -v71, v8, v16
	v_fma_f32 v246, -v73, v9, v246
	v_fma_f32 v8, -v75, v10, v8
	v_fma_f32 v246, -v77, v11, v246
	s_waitcnt lgkmcnt(2)
	v_fma_f32 v4, -v79, v4, v8
	v_fma_f32 v246, -v81, v5, v246
	v_fma_f32 v4, -v83, v6, v4
	v_fma_f32 v246, -v85, v7, v246
	s_waitcnt lgkmcnt(1)
	v_fma_f32 v4, -v87, v12, v4
	v_fma_f32 v246, -v89, v13, v246
	v_fma_f32 v4, -v91, v14, v4
	v_fma_f32 v246, -v66, v15, v246
	s_waitcnt lgkmcnt(0)
	v_fma_f32 v0, -v68, v0, v4
	v_fma_f32 v246, -v70, v1, v246
	v_fma_f32 v0, -v72, v2, v0
	s_and_b64 vcc, exec, s[52:53]
	v_fma_f32 v246, -v74, v3, v246
	v_add_f32_e32 v76, v0, v246
	s_cbranch_vccnz .LBB0_481
	v_cvt_pk_bf16_f32 v0, v76, s0
	global_store_short v[20:21], v0, off

; __device__ __forceinline__ bf16_t f2bf(float f) { return (bf16_t)(cvt_pk_bf16(f, 0.f) & 0xffffu); }
; __device__ __forceinline__ float bf2f(bf16_t b) { return __uint_as_float(((unsigned)b) << 16); }
; template <int I>
; __device__ __forceinline__ void solve_rows(float (&x)[64], const f32x4* A4, const bf16_t* src, const float* sBeta, const float* sGam, int part, bf16_t* dst, int nvalid) {
;     ...
;         for (int q = 0; q < (I + 3) / 4; ++q) a4[q] = A4[I * 16 + q];
;         float a = bf2f(src[I * 136]) * sBeta[I];
;         if (part == 1) a *= __expf(sGam[I]);
; #pragma unroll
;         for (int j = 0; j < I; ++j) a -= a4[j >> 2][j & 3] * x[j];
;         x[I] = a;
;         if (I < nvalid) *dst = f2bf(a);
.LBB0_483:
	s_waitcnt lgkmcnt(0)
	v_fma_f32 v1, -v64, v16, v235
	v_mul_f32_e64 v246, -v65, v17
	v_fma_f32 v1, -v67, v18, v1
	v_fma_f32 v246, -v69, v19, v246
	v_fma_f32 v1, -v71, v20, v1
	v_fma_f32 v246, -v73, v21, v246
	v_fma_f32 v1, -v75, v22, v1
	v_fma_f32 v246, -v77, v23, v246
	v_fma_f32 v1, -v79, v12, v1
	v_fma_f32 v246, -v81, v13, v246
	v_fma_f32 v1, -v83, v14, v1
	v_fma_f32 v246, -v85, v15, v246
	v_fma_f32 v1, -v87, v8, v1
	v_fma_f32 v246, -v89, v9, v246
	v_fma_f32 v1, -v91, v10, v1
	v_fma_f32 v246, -v66, v11, v246
	v_fma_f32 v1, -v68, v4, v1
	v_fma_f32 v246, -v70, v5, v246
	v_fma_f32 v1, -v72, v6, v1
	v_fma_f32 v246, -v74, v7, v246
	s_and_b64 vcc, exec, s[52:53]
	v_fma_f32 v78, -v76, v0, v1
	v_add_f32_e32 v78, v78, v246
	s_cbranch_vccnz .LBB0_485
	v_cvt_pk_bf16_f32 v0, v78, s0
	global_store_short v[24:25], v0, off

; __device__ __forceinline__ bf16_t f2bf(float f) { return (bf16_t)(cvt_pk_bf16(f, 0.f) & 0xffffu); }
; __device__ __forceinline__ float bf2f(bf16_t b) { return __uint_as_float(((unsigned)b) << 16); }
; template <int I>
; __device__ __forceinline__ void solve_rows(float (&x)[64], const f32x4* A4, const bf16_t* src, const float* sBeta, const float* sGam, int part, bf16_t* dst, int nvalid) {
;     ...
;         for (int q = 0; q < (I + 3) / 4; ++q) a4[q] = A4[I * 16 + q];
;         float a = bf2f(src[I * 136]) * sBeta[I];
;         if (part == 1) a *= __expf(sGam[I]);
; #pragma unroll
;         for (int j = 0; j < I; ++j) a -= a4[j >> 2][j & 3] * x[j];
;         x[I] = a;
;         if (I < nvalid) *dst = f2bf(a);
.LBB0_487:
	s_waitcnt lgkmcnt(0)
	v_fma_f32 v2, -v64, v16, v235
	v_mul_f32_e64 v246, -v65, v17
	v_fma_f32 v2, -v67, v18, v2
	v_fma_f32 v246, -v69, v19, v246
	v_fma_f32 v2, -v71, v20, v2
	v_fma_f32 v246, -v73, v21, v246
	v_fma_f32 v2, -v75, v22, v2
	v_fma_f32 v246, -v77, v23, v246
	v_fma_f32 v2, -v79, v12, v2
	v_fma_f32 v246, -v81, v13, v246
	v_fma_f32 v2, -v83, v14, v2
	v_fma_f32 v246, -v85, v15, v246
	v_fma_f32 v2, -v87, v8, v2
	v_fma_f32 v246, -v89, v9, v246
	v_fma_f32 v2, -v91, v10, v2
	v_fma_f32 v246, -v66, v11, v246
	v_fma_f32 v2, -v68, v4, v2
	v_fma_f32 v246, -v70, v5, v246
	v_fma_f32 v2, -v72, v6, v2
	v_fma_f32 v246, -v74, v7, v246
	v_fma_f32 v0, -v76, v0, v2
	s_and_b64 vcc, exec, s[52:53]
	v_fma_f32 v246, -v78, v1, v246
	v_add_f32_e32 v80, v0, v246
	s_cbranch_vccnz .LBB0_489
	v_cvt_pk_bf16_f32 v0, v80, s0
	global_store_short v[24:25], v0, off

; __device__ __forceinline__ bf16_t f2bf(float f) { return (bf16_t)(cvt_pk_bf16(f, 0.f) & 0xffffu); }
; __device__ __forceinline__ float bf2f(bf16_t b) { return __uint_as_float(((unsigned)b) << 16); }
; template <int I>
; __device__ __forceinline__ void solve_rows(float (&x)[64], const f32x4* A4, const bf16_t* src, const float* sBeta, const float* sGam, int part, bf16_t* dst, int nvalid) {
;     ...
;         for (int q = 0; q < (I + 3) / 4; ++q) a4[q] = A4[I * 16 + q];
;         float a = bf2f(src[I * 136]) * sBeta[I];
;         if (part == 1) a *= __expf(sGam[I]);
; #pragma unroll
;         for (int j = 0; j < I; ++j) a -= a4[j >> 2][j & 3] * x[j];
;         x[I] = a;
;         if (I < nvalid) *dst = f2bf(a);
.LBB0_491:
	s_waitcnt lgkmcnt(0)
	v_fma_f32 v7, -v64, v20, v235
	v_mul_f32_e64 v246, -v65, v21
	v_fma_f32 v7, -v67, v22, v7
	v_fma_f32 v246, -v69, v23, v246
	v_fma_f32 v7, -v71, v16, v7
	v_fma_f32 v246, -v73, v17, v246
	v_fma_f32 v7, -v75, v18, v7
	v_fma_f32 v246, -v77, v19, v246
	v_fma_f32 v7, -v79, v12, v7
	v_fma_f32 v246, -v81, v13, v246
	v_fma_f32 v7, -v83, v14, v7
	v_fma_f32 v246, -v85, v15, v246
	v_fma_f32 v7, -v87, v8, v7
	v_fma_f32 v246, -v89, v9, v246
	v_fma_f32 v7, -v91, v10, v7
	v_fma_f32 v246, -v66, v11, v246
	v_fma_f32 v0, -v68, v0, v7
	v_fma_f32 v246, -v70, v1, v246
	v_fma_f32 v0, -v72, v2, v0
	v_fma_f32 v246, -v74, v3, v246
	v_fma_f32 v0, -v76, v4, v0
	v_fma_f32 v246, -v78, v5, v246
	s_and_b64 vcc, exec, s[52:53]
	v_fma_f32 v82, -v80, v6, v0
	v_add_f32_e32 v82, v82, v246
	s_cbranch_vccnz .LBB0_493
	v_cvt_pk_bf16_f32 v0, v82, s0
	global_store_short v[24:25], v0, off

; __device__ __forceinline__ bf16_t f2bf(float f) { return (bf16_t)(cvt_pk_bf16(f, 0.f) & 0xffffu); }
; __device__ __forceinline__ float bf2f(bf16_t b) { return __uint_as_float(((unsigned)b) << 16); }
; template <int I>
; __device__ __forceinline__ void solve_rows(float (&x)[64], const f32x4* A4, const bf16_t* src, const float* sBeta, const float* sGam, int part, bf16_t* dst, int nvalid) {
;     ...
;         for (int q = 0; q < (I + 3) / 4; ++q) a4[q] = A4[I * 16 + q];
;         float a = bf2f(src[I * 136]) * sBeta[I];
;         if (part == 1) a *= __expf(sGam[I]);
; #pragma unroll
;         for (int j = 0; j < I; ++j) a -= a4[j >> 2][j & 3] * x[j];
;         x[I] = a;
;         if (I < nvalid) *dst = f2bf(a);
.LBB0_495:
	s_waitcnt lgkmcnt(5)
	v_fma_f32 v20, -v64, v20, v26
	v_mul_f32_e64 v246, -v65, v21
	v_fma_f32 v20, -v67, v22, v20
	v_fma_f32 v246, -v69, v23, v246
	s_waitcnt lgkmcnt(4)
	v_fma_f32 v16, -v71, v16, v20
	v_fma_f32 v246, -v73, v17, v246
	v_fma_f32 v16, -v75, v18, v16
	v_fma_f32 v246, -v77, v19, v246
	s_waitcnt lgkmcnt(3)
	v_fma_f32 v12, -v79, v12, v16
	v_fma_f32 v246, -v81, v13, v246
	v_fma_f32 v12, -v83, v14, v12
	v_fma_f32 v246, -v85, v15, v246
	s_waitcnt lgkmcnt(2)
	v_fma_f32 v8, -v87, v8, v12
	v_fma_f32 v246, -v89, v9, v246
	v_fma_f32 v8, -v91, v10, v8
	v_fma_f32 v246, -v66, v11, v246
	s_waitcnt lgkmcnt(1)
	v_fma_f32 v0, -v68, v0, v8
	v_fma_f32 v246, -v70, v1, v246
	v_fma_f32 v0, -v72, v2, v0
	v_fma_f32 v246, -v74, v3, v246
	s_waitcnt lgkmcnt(0)
	v_fma_f32 v0, -v76, v4, v0
	v_fma_f32 v246, -v78, v5, v246
	v_fma_f32 v0, -v80, v6, v0
	s_and_b64 vcc, exec, s[52:53]
	v_fma_f32 v246, -v82, v7, v246
	v_add_f32_e32 v84, v0, v246
	s_cbranch_vccnz .LBB0_497
	v_cvt_pk_bf16_f32 v0, v84, s0
	global_store_short v[24:25], v0, off

; __device__ __forceinline__ bf16_t f2bf(float f) { return (bf16_t)(cvt_pk_bf16(f, 0.f) & 0xffffu); }
; __device__ __forceinline__ float bf2f(bf16_t b) { return __uint_as_float(((unsigned)b) << 16); }
; template <int I>
; __device__ __forceinline__ void solve_rows(float (&x)[64], const f32x4* A4, const bf16_t* src, const float* sBeta, const float* sGam, int part, bf16_t* dst, int nvalid) {
;     ...
;         for (int q = 0; q < (I + 3) / 4; ++q) a4[q] = A4[I * 16 + q];
;         float a = bf2f(src[I * 136]) * sBeta[I];
;         if (part == 1) a *= __expf(sGam[I]);
; #pragma unroll
;         for (int j = 0; j < I; ++j) a -= a4[j >> 2][j & 3] * x[j];
;         x[I] = a;
;         if (I < nvalid) *dst = f2bf(a);
.LBB0_499:
	s_waitcnt lgkmcnt(0)
	v_fma_f32 v1, -v64, v20, v235
	v_mul_f32_e64 v246, -v65, v21
	v_fma_f32 v1, -v67, v22, v1
	v_fma_f32 v246, -v69, v23, v246
	v_fma_f32 v1, -v71, v24, v1
	v_fma_f32 v246, -v73, v25, v246
	v_fma_f32 v1, -v75, v26, v1
	v_fma_f32 v246, -v77, v27, v246
	v_fma_f32 v1, -v79, v16, v1
	v_fma_f32 v246, -v81, v17, v246
	v_fma_f32 v1, -v83, v18, v1
	v_fma_f32 v246, -v85, v19, v246
	v_fma_f32 v1, -v87, v12, v1
	v_fma_f32 v246, -v89, v13, v246
	v_fma_f32 v1, -v91, v14, v1
	v_fma_f32 v246, -v66, v15, v246
	v_fma_f32 v1, -v68, v8, v1
	v_fma_f32 v246, -v70, v9, v246
	v_fma_f32 v1, -v72, v10, v1
	v_fma_f32 v246, -v74, v11, v246
	v_fma_f32 v1, -v76, v4, v1
	v_fma_f32 v246, -v78, v5, v246
	v_fma_f32 v1, -v80, v6, v1
	v_fma_f32 v246, -v82, v7, v246
	s_and_b64 vcc, exec, s[52:53]
	v_fma_f32 v86, -v84, v0, v1
	v_add_f32_e32 v86, v86, v246
	s_cbranch_vccnz .LBB0_501
	v_cvt_pk_bf16_f32 v0, v86, s0
	global_store_short v[28:29], v0, off

; __device__ __forceinline__ bf16_t f2bf(float f) { return (bf16_t)(cvt_pk_bf16(f, 0.f) & 0xffffu); }
; __device__ __forceinline__ float bf2f(bf16_t b) { return __uint_as_float(((unsigned)b) << 16); }
; template <int I>
; __device__ __forceinline__ void solve_rows(float (&x)[64], const f32x4* A4, const bf16_t* src, const float* sBeta, const float* sGam, int part, bf16_t* dst, int nvalid) {
;     ...
;         for (int q = 0; q < (I + 3) / 4; ++q) a4[q] = A4[I * 16 + q];
;         float a = bf2f(src[I * 136]) * sBeta[I];
;         if (part == 1) a *= __expf(sGam[I]);
; #pragma unroll
;         for (int j = 0; j < I; ++j) a -= a4[j >> 2][j & 3] * x[j];
;         x[I] = a;
;         if (I < nvalid) *dst = f2bf(a);
.LBB0_503:
	s_waitcnt lgkmcnt(0)
	v_fma_f32 v2, -v64, v20, v235
	v_mul_f32_e64 v246, -v65, v21
	v_fma_f32 v2, -v67, v22, v2
	v_fma_f32 v246, -v69, v23, v246
	v_fma_f32 v2, -v71, v24, v2
	v_fma_f32 v246, -v73, v25, v246
	v_fma_f32 v2, -v75, v26, v2
	v_fma_f32 v246, -v77, v27, v246
	v_fma_f32 v2, -v79, v16, v2
	v_fma_f32 v246, -v81, v17, v246
	v_fma_f32 v2, -v83, v18, v2
	v_fma_f32 v246, -v85, v19, v246
	v_fma_f32 v2, -v87, v12, v2
	v_fma_f32 v246, -v89, v13, v246
	v_fma_f32 v2, -v91, v14, v2
	v_fma_f32 v246, -v66, v15, v246
	v_fma_f32 v2, -v68, v8, v2
	v_fma_f32 v246, -v70, v9, v246
	v_fma_f32 v2, -v72, v10, v2
	v_fma_f32 v246, -v74, v11, v246
	v_fma_f32 v2, -v76, v4, v2
	v_fma_f32 v246, -v78, v5, v246
	v_fma_f32 v2, -v80, v6, v2
	v_fma_f32 v246, -v82, v7, v246
	v_fma_f32 v0, -v84, v0, v2
	s_and_b64 vcc, exec, s[52:53]
	v_fma_f32 v246, -v86, v1, v246
	v_add_f32_e32 v88, v0, v246
	s_cbranch_vccnz .LBB0_505
	v_cvt_pk_bf16_f32 v0, v88, s0
	global_store_short v[28:29], v0, off

; __device__ __forceinline__ bf16_t f2bf(float f) { return (bf16_t)(cvt_pk_bf16(f, 0.f) & 0xffffu); }
; __device__ __forceinline__ float bf2f(bf16_t b) { return __uint_as_float(((unsigned)b) << 16); }
; template <int I>
; __device__ __forceinline__ void solve_rows(float (&x)[64], const f32x4* A4, const bf16_t* src, const float* sBeta, const float* sGam, int part, bf16_t* dst, int nvalid) {
;     ...
;         for (int q = 0; q < (I + 3) / 4; ++q) a4[q] = A4[I * 16 + q];
;         float a = bf2f(src[I * 136]) * sBeta[I];
;         if (part == 1) a *= __expf(sGam[I]);
; #pragma unroll
;         for (int j = 0; j < I; ++j) a -= a4[j >> 2][j & 3] * x[j];
;         x[I] = a;
;         if (I < nvalid) *dst = f2bf(a);
.LBB0_507:
	s_waitcnt lgkmcnt(0)
	v_fma_f32 v3, -v64, v24, v235
	v_mul_f32_e64 v246, -v65, v25
	v_fma_f32 v3, -v67, v26, v3
	v_fma_f32 v246, -v69, v27, v246
	v_fma_f32 v3, -v71, v20, v3
	v_fma_f32 v246, -v73, v21, v246
	v_fma_f32 v3, -v75, v22, v3
	v_fma_f32 v246, -v77, v23, v246
	v_fma_f32 v3, -v79, v16, v3
	v_fma_f32 v246, -v81, v17, v246
	v_fma_f32 v3, -v83, v18, v3
	v_fma_f32 v246, -v85, v19, v246
	v_fma_f32 v3, -v87, v8, v3
	v_fma_f32 v246, -v89, v9, v246
	v_fma_f32 v3, -v91, v10, v3
	v_fma_f32 v246, -v66, v11, v246
	v_fma_f32 v3, -v68, v4, v3
	v_fma_f32 v246, -v70, v5, v246
	v_fma_f32 v3, -v72, v6, v3
	v_fma_f32 v246, -v74, v7, v246
	v_fma_f32 v3, -v76, v12, v3
	v_fma_f32 v246, -v78, v13, v246
	v_fma_f32 v3, -v80, v14, v3
	v_fma_f32 v246, -v82, v15, v246
	v_fma_f32 v0, -v84, v0, v3
	v_fma_f32 v246, -v86, v1, v246
	s_and_b64 vcc, exec, s[52:53]
	v_fma_f32 v90, -v88, v2, v0
	v_add_f32_e32 v90, v90, v246
	s_cbranch_vccnz .LBB0_509
	v_cvt_pk_bf16_f32 v0, v90, s0
	global_store_short v[28:29], v0, off

; __device__ __forceinline__ bf16_t f2bf(float f) { return (bf16_t)(cvt_pk_bf16(f, 0.f) & 0xffffu); }
; __device__ __forceinline__ float bf2f(bf16_t b) { return __uint_as_float(((unsigned)b) << 16); }
; template <int I>
; __device__ __forceinline__ void solve_rows(float (&x)[64], const f32x4* A4, const bf16_t* src, const float* sBeta, const float* sGam, int part, bf16_t* dst, int nvalid) {
;     ...
;         for (int q = 0; q < (I + 3) / 4; ++q) a4[q] = A4[I * 16 + q];
;         float a = bf2f(src[I * 136]) * sBeta[I];
;         if (part == 1) a *= __expf(sGam[I]);
; #pragma unroll
;         for (int j = 0; j < I; ++j) a -= a4[j >> 2][j & 3] * x[j];
;         x[I] = a;
;         if (I < nvalid) *dst = f2bf(a);
.LBB0_511:
	s_waitcnt lgkmcnt(6)
	v_fma_f32 v24, -v64, v24, v30
	v_mul_f32_e64 v246, -v65, v25
	v_fma_f32 v24, -v67, v26, v24
	v_fma_f32 v246, -v69, v27, v246
	s_waitcnt lgkmcnt(5)
	v_fma_f32 v20, -v71, v20, v24
	v_fma_f32 v246, -v73, v21, v246
	v_fma_f32 v20, -v75, v22, v20
	v_fma_f32 v246, -v77, v23, v246
	s_waitcnt lgkmcnt(4)
	v_fma_f32 v16, -v79, v16, v20
	v_fma_f32 v246, -v81, v17, v246
	v_fma_f32 v16, -v83, v18, v16
	v_fma_f32 v246, -v85, v19, v246
	s_waitcnt lgkmcnt(3)
	v_fma_f32 v8, -v87, v8, v16
	v_fma_f32 v246, -v89, v9, v246
	v_fma_f32 v8, -v91, v10, v8
	v_fma_f32 v246, -v66, v11, v246
	s_waitcnt lgkmcnt(2)
	v_fma_f32 v4, -v68, v4, v8
	v_fma_f32 v246, -v70, v5, v246
	v_fma_f32 v4, -v72, v6, v4
	v_fma_f32 v246, -v74, v7, v246
	s_waitcnt lgkmcnt(1)
	v_fma_f32 v4, -v76, v12, v4
	v_fma_f32 v246, -v78, v13, v246
	v_fma_f32 v4, -v80, v14, v4
	v_fma_f32 v246, -v82, v15, v246
	s_waitcnt lgkmcnt(0)
	v_fma_f32 v0, -v84, v0, v4
	v_fma_f32 v246, -v86, v1, v246
	v_fma_f32 v0, -v88, v2, v0
	s_and_b64 vcc, exec, s[52:53]
	v_fma_f32 v246, -v90, v3, v246
	v_add_f32_e32 v109, v0, v246
	s_cbranch_vccnz .LBB0_513
	v_cvt_pk_bf16_f32 v0, v109, s0
	global_store_short v[28:29], v0, off

; __device__ __forceinline__ bf16_t f2bf(float f) { return (bf16_t)(cvt_pk_bf16(f, 0.f) & 0xffffu); }
; __device__ __forceinline__ float bf2f(bf16_t b) { return __uint_as_float(((unsigned)b) << 16); }
; template <int I>
; __device__ __forceinline__ void solve_rows(float (&x)[64], const f32x4* A4, const bf16_t* src, const float* sBeta, const float* sGam, int part, bf16_t* dst, int nvalid) {
;     ...
;         for (int q = 0; q < (I + 3) / 4; ++q) a4[q] = A4[I * 16 + q];
;         float a = bf2f(src[I * 136]) * sBeta[I];
;         if (part == 1) a *= __expf(sGam[I]);
; #pragma unroll
;         for (int j = 0; j < I; ++j) a -= a4[j >> 2][j & 3] * x[j];
;         x[I] = a;
;         if (I < nvalid) *dst = f2bf(a);
.LBB0_515:
	s_waitcnt lgkmcnt(0)
	v_fma_f32 v1, -v64, v24, v235
	v_mul_f32_e64 v246, -v65, v25
	v_fma_f32 v1, -v67, v26, v1
	v_fma_f32 v246, -v69, v27, v246
	v_fma_f32 v1, -v71, v28, v1
	v_fma_f32 v246, -v73, v29, v246
	v_fma_f32 v1, -v75, v30, v1
	v_fma_f32 v246, -v77, v31, v246
	v_fma_f32 v1, -v79, v20, v1
	v_fma_f32 v246, -v81, v21, v246
	v_fma_f32 v1, -v83, v22, v1
	v_fma_f32 v246, -v85, v23, v246
	v_fma_f32 v1, -v87, v16, v1
	v_fma_f32 v246, -v89, v17, v246
	v_fma_f32 v1, -v91, v18, v1
	v_fma_f32 v246, -v66, v19, v246
	v_fma_f32 v1, -v68, v12, v1
	v_fma_f32 v246, -v70, v13, v246
	v_fma_f32 v1, -v72, v14, v1
	v_fma_f32 v246, -v74, v15, v246
	v_fma_f32 v1, -v76, v8, v1
	v_fma_f32 v246, -v78, v9, v246
	v_fma_f32 v1, -v80, v10, v1
	v_fma_f32 v246, -v82, v11, v246
	v_fma_f32 v1, -v84, v4, v1
	v_fma_f32 v246, -v86, v5, v246
	v_fma_f32 v1, -v88, v6, v1
	v_fma_f32 v246, -v90, v7, v246
	s_and_b64 vcc, exec, s[52:53]
	v_fma_f32 v110, -v109, v0, v1
	v_add_f32_e32 v110, v110, v246
	s_cbranch_vccnz .LBB0_517
	v_cvt_pk_bf16_f32 v0, v110, s0
	global_store_short v[32:33], v0, off

; __device__ __forceinline__ bf16_t f2bf(float f) { return (bf16_t)(cvt_pk_bf16(f, 0.f) & 0xffffu); }
; __device__ __forceinline__ float bf2f(bf16_t b) { return __uint_as_float(((unsigned)b) << 16); }
; template <int I>
; __device__ __forceinline__ void solve_rows(float (&x)[64], const f32x4* A4, const bf16_t* src, const float* sBeta, const float* sGam, int part, bf16_t* dst, int nvalid) {
;     ...
;         for (int q = 0; q < (I + 3) / 4; ++q) a4[q] = A4[I * 16 + q];
;         float a = bf2f(src[I * 136]) * sBeta[I];
;         if (part == 1) a *= __expf(sGam[I]);
; #pragma unroll
;         for (int j = 0; j < I; ++j) a -= a4[j >> 2][j & 3] * x[j];
;         x[I] = a;
;         if (I < nvalid) *dst = f2bf(a);
.LBB0_519:
	s_waitcnt lgkmcnt(0)
	v_fma_f32 v2, -v64, v24, v235
	v_mul_f32_e64 v246, -v65, v25
	v_fma_f32 v2, -v67, v26, v2
	v_fma_f32 v246, -v69, v27, v246
	v_fma_f32 v2, -v71, v28, v2
	v_fma_f32 v246, -v73, v29, v246
	v_fma_f32 v2, -v75, v30, v2
	v_fma_f32 v246, -v77, v31, v246
	v_fma_f32 v2, -v79, v20, v2
	v_fma_f32 v246, -v81, v21, v246
	v_fma_f32 v2, -v83, v22, v2
	v_fma_f32 v246, -v85, v23, v246
	v_fma_f32 v2, -v87, v16, v2
	v_fma_f32 v246, -v89, v17, v246
	v_fma_f32 v2, -v91, v18, v2
	v_fma_f32 v246, -v66, v19, v246
	v_fma_f32 v2, -v68, v12, v2
	v_fma_f32 v246, -v70, v13, v246
	v_fma_f32 v2, -v72, v14, v2
	v_fma_f32 v246, -v74, v15, v246
	v_fma_f32 v2, -v76, v8, v2
	v_fma_f32 v246, -v78, v9, v246
	v_fma_f32 v2, -v80, v10, v2
	v_fma_f32 v246, -v82, v11, v246
	v_fma_f32 v2, -v84, v4, v2
	v_fma_f32 v246, -v86, v5, v246
	v_fma_f32 v2, -v88, v6, v2
	v_fma_f32 v246, -v90, v7, v246
	v_fma_f32 v0, -v109, v0, v2
	s_and_b64 vcc, exec, s[52:53]
	v_fma_f32 v246, -v110, v1, v246
	v_add_f32_e32 v111, v0, v246
	s_cbranch_vccnz .LBB0_521
	v_cvt_pk_bf16_f32 v0, v111, s0
	global_store_short v[32:33], v0, off

; __device__ __forceinline__ bf16_t f2bf(float f) { return (bf16_t)(cvt_pk_bf16(f, 0.f) & 0xffffu); }
; __device__ __forceinline__ float bf2f(bf16_t b) { return __uint_as_float(((unsigned)b) << 16); }
; template <int I>
; __device__ __forceinline__ void solve_rows(float (&x)[64], const f32x4* A4, const bf16_t* src, const float* sBeta, const float* sGam, int part, bf16_t* dst, int nvalid) {
;     ...
;         for (int q = 0; q < (I + 3) / 4; ++q) a4[q] = A4[I * 16 + q];
;         float a = bf2f(src[I * 136]) * sBeta[I];
;         if (part == 1) a *= __expf(sGam[I]);
; #pragma unroll
;         for (int j = 0; j < I; ++j) a -= a4[j >> 2][j & 3] * x[j];
;         x[I] = a;
;         if (I < nvalid) *dst = f2bf(a);
.LBB0_523:
	s_waitcnt lgkmcnt(0)
	v_fma_f32 v7, -v64, v28, v235
	v_mul_f32_e64 v246, -v65, v29
	v_fma_f32 v7, -v67, v30, v7
	v_fma_f32 v246, -v69, v31, v246
	v_fma_f32 v7, -v71, v24, v7
	v_fma_f32 v246, -v73, v25, v246
	v_fma_f32 v7, -v75, v26, v7
	v_fma_f32 v246, -v77, v27, v246
	v_fma_f32 v7, -v79, v20, v7
	v_fma_f32 v246, -v81, v21, v246
	v_fma_f32 v7, -v83, v22, v7
	v_fma_f32 v246, -v85, v23, v246
	v_fma_f32 v7, -v87, v16, v7
	v_fma_f32 v246, -v89, v17, v246
	v_fma_f32 v7, -v91, v18, v7
	v_fma_f32 v246, -v66, v19, v246
	v_fma_f32 v7, -v68, v12, v7
	v_fma_f32 v246, -v70, v13, v246
	v_fma_f32 v7, -v72, v14, v7
	v_fma_f32 v246, -v74, v15, v246
	v_fma_f32 v7, -v76, v8, v7
	v_fma_f32 v246, -v78, v9, v246
	v_fma_f32 v7, -v80, v10, v7
	v_fma_f32 v246, -v82, v11, v246
	v_fma_f32 v0, -v84, v0, v7
	v_fma_f32 v246, -v86, v1, v246
	v_fma_f32 v0, -v88, v2, v0
	v_fma_f32 v246, -v90, v3, v246
	v_fma_f32 v0, -v109, v4, v0
	v_fma_f32 v246, -v110, v5, v246
	s_and_b64 vcc, exec, s[52:53]
	v_fma_f32 v112, -v111, v6, v0
	v_add_f32_e32 v112, v112, v246
	s_cbranch_vccnz .LBB0_525
	v_cvt_pk_bf16_f32 v0, v112, s0
	global_store_short v[32:33], v0, off

; __device__ __forceinline__ bf16_t f2bf(float f) { return (bf16_t)(cvt_pk_bf16(f, 0.f) & 0xffffu); }
; __device__ __forceinline__ float bf2f(bf16_t b) { return __uint_as_float(((unsigned)b) << 16); }
; template <int I>
; __device__ __forceinline__ void solve_rows(float (&x)[64], const f32x4* A4, const bf16_t* src, const float* sBeta, const float* sGam, int part, bf16_t* dst, int nvalid) {
;     ...
;         for (int q = 0; q < (I + 3) / 4; ++q) a4[q] = A4[I * 16 + q];
;         float a = bf2f(src[I * 136]) * sBeta[I];
;         if (part == 1) a *= __expf(sGam[I]);
; #pragma unroll
;         for (int j = 0; j < I; ++j) a -= a4[j >> 2][j & 3] * x[j];
;         x[I] = a;
;         if (I < nvalid) *dst = f2bf(a);
.LBB0_527:
	s_waitcnt lgkmcnt(7)
	v_fma_f32 v28, -v64, v28, v34
	v_mul_f32_e64 v246, -v65, v29
	v_fma_f32 v28, -v67, v30, v28
	v_fma_f32 v246, -v69, v31, v246
	s_waitcnt lgkmcnt(6)
	v_fma_f32 v24, -v71, v24, v28
	v_fma_f32 v246, -v73, v25, v246
	v_fma_f32 v24, -v75, v26, v24
	v_fma_f32 v246, -v77, v27, v246
	s_waitcnt lgkmcnt(5)
	v_fma_f32 v20, -v79, v20, v24
	v_fma_f32 v246, -v81, v21, v246
	v_fma_f32 v20, -v83, v22, v20
	v_fma_f32 v246, -v85, v23, v246
	s_waitcnt lgkmcnt(4)
	v_fma_f32 v16, -v87, v16, v20
	v_fma_f32 v246, -v89, v17, v246
	v_fma_f32 v16, -v91, v18, v16
	v_fma_f32 v246, -v66, v19, v246
	s_waitcnt lgkmcnt(3)
	v_fma_f32 v12, -v68, v12, v16
	v_fma_f32 v246, -v70, v13, v246
	v_fma_f32 v12, -v72, v14, v12
	v_fma_f32 v246, -v74, v15, v246
	s_waitcnt lgkmcnt(2)
	v_fma_f32 v8, -v76, v8, v12
	v_fma_f32 v246, -v78, v9, v246
	v_fma_f32 v8, -v80, v10, v8
	v_fma_f32 v246, -v82, v11, v246
	s_waitcnt lgkmcnt(1)
	v_fma_f32 v0, -v84, v0, v8
	v_fma_f32 v246, -v86, v1, v246
	v_fma_f32 v0, -v88, v2, v0
	v_fma_f32 v246, -v90, v3, v246
	s_waitcnt lgkmcnt(0)
	v_fma_f32 v0, -v109, v4, v0
	v_fma_f32 v246, -v110, v5, v246
	v_fma_f32 v0, -v111, v6, v0
	s_and_b64 vcc, exec, s[52:53]
	v_fma_f32 v246, -v112, v7, v246
	v_add_f32_e32 v113, v0, v246
	s_cbranch_vccnz .LBB0_529
	v_cvt_pk_bf16_f32 v0, v113, s0
	global_store_short v[32:33], v0, off

; __device__ __forceinline__ bf16_t f2bf(float f) { return (bf16_t)(cvt_pk_bf16(f, 0.f) & 0xffffu); }
; __device__ __forceinline__ float bf2f(bf16_t b) { return __uint_as_float(((unsigned)b) << 16); }
; template <int I>
; __device__ __forceinline__ void solve_rows(float (&x)[64], const f32x4* A4, const bf16_t* src, const float* sBeta, const float* sGam, int part, bf16_t* dst, int nvalid) {
;     ...
;         for (int q = 0; q < (I + 3) / 4; ++q) a4[q] = A4[I * 16 + q];
;         float a = bf2f(src[I * 136]) * sBeta[I];
;         if (part == 1) a *= __expf(sGam[I]);
; #pragma unroll
;         for (int j = 0; j < I; ++j) a -= a4[j >> 2][j & 3] * x[j];
;         x[I] = a;
;         if (I < nvalid) *dst = f2bf(a);
.LBB0_531:
	s_waitcnt lgkmcnt(0)
	v_fma_f32 v1, -v64, v28, v235
	v_mul_f32_e64 v246, -v65, v29
	v_fma_f32 v1, -v67, v30, v1
	v_fma_f32 v246, -v69, v31, v246
	v_fma_f32 v1, -v71, v32, v1
	v_fma_f32 v246, -v73, v33, v246
	v_fma_f32 v1, -v75, v34, v1
	v_fma_f32 v246, -v77, v35, v246
	v_fma_f32 v1, -v79, v24, v1
	v_fma_f32 v246, -v81, v25, v246
	v_fma_f32 v1, -v83, v26, v1
	v_fma_f32 v246, -v85, v27, v246
	v_fma_f32 v1, -v87, v20, v1
	v_fma_f32 v246, -v89, v21, v246
	v_fma_f32 v1, -v91, v22, v1
	v_fma_f32 v246, -v66, v23, v246
	v_fma_f32 v1, -v68, v16, v1
	v_fma_f32 v246, -v70, v17, v246
	v_fma_f32 v1, -v72, v18, v1
	v_fma_f32 v246, -v74, v19, v246
	v_fma_f32 v1, -v76, v12, v1
	v_fma_f32 v246, -v78, v13, v246
	v_fma_f32 v1, -v80, v14, v1
	v_fma_f32 v246, -v82, v15, v246
	v_fma_f32 v1, -v84, v8, v1
	v_fma_f32 v246, -v86, v9, v246
	v_fma_f32 v1, -v88, v10, v1
	v_fma_f32 v246, -v90, v11, v246
	v_fma_f32 v1, -v109, v4, v1
	v_fma_f32 v246, -v110, v5, v246
	v_fma_f32 v1, -v111, v6, v1
	v_fma_f32 v246, -v112, v7, v246
	s_and_b64 vcc, exec, s[52:53]
	v_fma_f32 v114, -v113, v0, v1
	v_add_f32_e32 v114, v114, v246
	s_cbranch_vccnz .LBB0_533
	v_cvt_pk_bf16_f32 v0, v114, s0
	global_store_short v[36:37], v0, off

; __device__ __forceinline__ bf16_t f2bf(float f) { return (bf16_t)(cvt_pk_bf16(f, 0.f) & 0xffffu); }
; __device__ __forceinline__ float bf2f(bf16_t b) { return __uint_as_float(((unsigned)b) << 16); }
; template <int I>
; __device__ __forceinline__ void solve_rows(float (&x)[64], const f32x4* A4, const bf16_t* src, const float* sBeta, const float* sGam, int part, bf16_t* dst, int nvalid) {
;     ...
;         for (int q = 0; q < (I + 3) / 4; ++q) a4[q] = A4[I * 16 + q];
;         float a = bf2f(src[I * 136]) * sBeta[I];
;         if (part == 1) a *= __expf(sGam[I]);
; #pragma unroll
;         for (int j = 0; j < I; ++j) a -= a4[j >> 2][j & 3] * x[j];
;         x[I] = a;
;         if (I < nvalid) *dst = f2bf(a);
.LBB0_535:
	s_waitcnt lgkmcnt(0)
	v_fma_f32 v2, -v64, v28, v235
	v_mul_f32_e64 v246, -v65, v29
	v_fma_f32 v2, -v67, v30, v2
	v_fma_f32 v246, -v69, v31, v246
	v_fma_f32 v2, -v71, v32, v2
	v_fma_f32 v246, -v73, v33, v246
	v_fma_f32 v2, -v75, v34, v2
	v_fma_f32 v246, -v77, v35, v246
	v_fma_f32 v2, -v79, v24, v2
	v_fma_f32 v246, -v81, v25, v246
	v_fma_f32 v2, -v83, v26, v2
	v_fma_f32 v246, -v85, v27, v246
	v_fma_f32 v2, -v87, v20, v2
	v_fma_f32 v246, -v89, v21, v246
	v_fma_f32 v2, -v91, v22, v2
	v_fma_f32 v246, -v66, v23, v246
	v_fma_f32 v2, -v68, v16, v2
	v_fma_f32 v246, -v70, v17, v246
	v_fma_f32 v2, -v72, v18, v2
	v_fma_f32 v246, -v74, v19, v246
	v_fma_f32 v2, -v76, v12, v2
	v_fma_f32 v246, -v78, v13, v246
	v_fma_f32 v2, -v80, v14, v2
	v_fma_f32 v246, -v82, v15, v246
	v_fma_f32 v2, -v84, v8, v2
	v_fma_f32 v246, -v86, v9, v246
	v_fma_f32 v2, -v88, v10, v2
	v_fma_f32 v246, -v90, v11, v246
	v_fma_f32 v2, -v109, v4, v2
	v_fma_f32 v246, -v110, v5, v246
	v_fma_f32 v2, -v111, v6, v2
	v_fma_f32 v246, -v112, v7, v246
	v_fma_f32 v0, -v113, v0, v2
	s_and_b64 vcc, exec, s[52:53]
	v_fma_f32 v246, -v114, v1, v246
	v_add_f32_e32 v115, v0, v246
	s_cbranch_vccnz .LBB0_537
	v_cvt_pk_bf16_f32 v0, v115, s0
	global_store_short v[36:37], v0, off

; __device__ __forceinline__ bf16_t f2bf(float f) { return (bf16_t)(cvt_pk_bf16(f, 0.f) & 0xffffu); }
; __device__ __forceinline__ float bf2f(bf16_t b) { return __uint_as_float(((unsigned)b) << 16); }
; template <int I>
; __device__ __forceinline__ void solve_rows(float (&x)[64], const f32x4* A4, const bf16_t* src, const float* sBeta, const float* sGam, int part, bf16_t* dst, int nvalid) {
;     ...
;         for (int q = 0; q < (I + 3) / 4; ++q) a4[q] = A4[I * 16 + q];
;         float a = bf2f(src[I * 136]) * sBeta[I];
;         if (part == 1) a *= __expf(sGam[I]);
; #pragma unroll
;         for (int j = 0; j < I; ++j) a -= a4[j >> 2][j & 3] * x[j];
;         x[I] = a;
;         if (I < nvalid) *dst = f2bf(a);
.LBB0_539:
	s_waitcnt lgkmcnt(0)
	v_fma_f32 v3, -v64, v32, v235
	v_mul_f32_e64 v246, -v65, v33
	v_fma_f32 v3, -v67, v34, v3
	v_fma_f32 v246, -v69, v35, v246
	v_fma_f32 v3, -v71, v28, v3
	v_fma_f32 v246, -v73, v29, v246
	v_fma_f32 v3, -v75, v30, v3
	v_fma_f32 v246, -v77, v31, v246
	v_fma_f32 v3, -v79, v24, v3
	v_fma_f32 v246, -v81, v25, v246
	v_fma_f32 v3, -v83, v26, v3
	v_fma_f32 v246, -v85, v27, v246
	v_fma_f32 v3, -v87, v20, v3
	v_fma_f32 v246, -v89, v21, v246
	v_fma_f32 v3, -v91, v22, v3
	v_fma_f32 v246, -v66, v23, v246
	v_fma_f32 v3, -v68, v16, v3
	v_fma_f32 v246, -v70, v17, v246
	v_fma_f32 v3, -v72, v18, v3
	v_fma_f32 v246, -v74, v19, v246
	v_fma_f32 v3, -v76, v8, v3
	v_fma_f32 v246, -v78, v9, v246
	v_fma_f32 v3, -v80, v10, v3
	v_fma_f32 v246, -v82, v11, v246
	v_fma_f32 v3, -v84, v4, v3
	v_fma_f32 v246, -v86, v5, v246
	v_fma_f32 v3, -v88, v6, v3
	v_fma_f32 v246, -v90, v7, v246
	v_fma_f32 v3, -v109, v12, v3
	v_fma_f32 v246, -v110, v13, v246
	v_fma_f32 v3, -v111, v14, v3
	v_fma_f32 v246, -v112, v15, v246
	v_fma_f32 v0, -v113, v0, v3
	v_fma_f32 v246, -v114, v1, v246
	s_and_b64 vcc, exec, s[52:53]
	v_fma_f32 v116, -v115, v2, v0
	v_add_f32_e32 v116, v116, v246
	s_cbranch_vccnz .LBB0_541
	v_cvt_pk_bf16_f32 v0, v116, s0
	global_store_short v[36:37], v0, off

; __device__ __forceinline__ bf16_t f2bf(float f) { return (bf16_t)(cvt_pk_bf16(f, 0.f) & 0xffffu); }
; __device__ __forceinline__ float bf2f(bf16_t b) { return __uint_as_float(((unsigned)b) << 16); }
; template <int I>
; __device__ __forceinline__ void solve_rows(float (&x)[64], const f32x4* A4, const bf16_t* src, const float* sBeta, const float* sGam, int part, bf16_t* dst, int nvalid) {
;     ...
;         for (int q = 0; q < (I + 3) / 4; ++q) a4[q] = A4[I * 16 + q];
;         float a = bf2f(src[I * 136]) * sBeta[I];
;         if (part == 1) a *= __expf(sGam[I]);
; #pragma unroll
;         for (int j = 0; j < I; ++j) a -= a4[j >> 2][j & 3] * x[j];
;         x[I] = a;
;         if (I < nvalid) *dst = f2bf(a);
.LBB0_543:
	s_waitcnt lgkmcnt(8)
	v_fma_f32 v32, -v64, v32, v38
	v_mul_f32_e64 v246, -v65, v33
	v_fma_f32 v32, -v67, v34, v32
	v_fma_f32 v246, -v69, v35, v246
	s_waitcnt lgkmcnt(7)
	v_fma_f32 v28, -v71, v28, v32
	v_fma_f32 v246, -v73, v29, v246
	v_fma_f32 v28, -v75, v30, v28
	v_fma_f32 v246, -v77, v31, v246
	s_waitcnt lgkmcnt(6)
	v_fma_f32 v24, -v79, v24, v28
	v_fma_f32 v246, -v81, v25, v246
	v_fma_f32 v24, -v83, v26, v24
	v_fma_f32 v246, -v85, v27, v246
	s_waitcnt lgkmcnt(5)
	v_fma_f32 v20, -v87, v20, v24
	v_fma_f32 v246, -v89, v21, v246
	v_fma_f32 v20, -v91, v22, v20
	v_fma_f32 v246, -v66, v23, v246
	s_waitcnt lgkmcnt(4)
	v_fma_f32 v16, -v68, v16, v20
	v_fma_f32 v246, -v70, v17, v246
	v_fma_f32 v16, -v72, v18, v16
	v_fma_f32 v246, -v74, v19, v246
	s_waitcnt lgkmcnt(3)
	v_fma_f32 v8, -v76, v8, v16
	v_fma_f32 v246, -v78, v9, v246
	v_fma_f32 v8, -v80, v10, v8
	v_fma_f32 v246, -v82, v11, v246
	s_waitcnt lgkmcnt(2)
	v_fma_f32 v4, -v84, v4, v8
	v_fma_f32 v246, -v86, v5, v246
	v_fma_f32 v4, -v88, v6, v4
	v_fma_f32 v246, -v90, v7, v246
	s_waitcnt lgkmcnt(1)
	v_fma_f32 v4, -v109, v12, v4
	v_fma_f32 v246, -v110, v13, v246
	v_fma_f32 v4, -v111, v14, v4
	v_fma_f32 v246, -v112, v15, v246
	s_waitcnt lgkmcnt(0)
	v_fma_f32 v0, -v113, v0, v4
	v_fma_f32 v246, -v114, v1, v246
	v_fma_f32 v0, -v115, v2, v0
	s_and_b64 vcc, exec, s[52:53]
	v_fma_f32 v246, -v116, v3, v246
	v_add_f32_e32 v117, v0, v246
	s_cbranch_vccnz .LBB0_545
	v_cvt_pk_bf16_f32 v0, v117, s0
	global_store_short v[36:37], v0, off

; __device__ __forceinline__ bf16_t f2bf(float f) { return (bf16_t)(cvt_pk_bf16(f, 0.f) & 0xffffu); }
; __device__ __forceinline__ float bf2f(bf16_t b) { return __uint_as_float(((unsigned)b) << 16); }
; template <int I>
; __device__ __forceinline__ void solve_rows(float (&x)[64], const f32x4* A4, const bf16_t* src, const float* sBeta, const float* sGam, int part, bf16_t* dst, int nvalid) {
;     ...
;         for (int q = 0; q < (I + 3) / 4; ++q) a4[q] = A4[I * 16 + q];
;         float a = bf2f(src[I * 136]) * sBeta[I];
;         if (part == 1) a *= __expf(sGam[I]);
; #pragma unroll
;         for (int j = 0; j < I; ++j) a -= a4[j >> 2][j & 3] * x[j];
;         x[I] = a;
;         if (I < nvalid) *dst = f2bf(a);
.LBB0_547:
	s_waitcnt lgkmcnt(0)
	v_fma_f32 v1, -v64, v32, v235
	v_mul_f32_e64 v246, -v65, v33
	v_fma_f32 v1, -v67, v34, v1
	v_fma_f32 v246, -v69, v35, v246
	v_fma_f32 v1, -v71, v36, v1
	v_fma_f32 v246, -v73, v37, v246
	v_fma_f32 v1, -v75, v38, v1
	v_fma_f32 v246, -v77, v39, v246
	v_fma_f32 v1, -v79, v28, v1
	v_fma_f32 v246, -v81, v29, v246
	v_fma_f32 v1, -v83, v30, v1
	v_fma_f32 v246, -v85, v31, v246
	v_fma_f32 v1, -v87, v24, v1
	v_fma_f32 v246, -v89, v25, v246
	v_fma_f32 v1, -v91, v26, v1
	v_fma_f32 v246, -v66, v27, v246
	v_fma_f32 v1, -v68, v20, v1
	v_fma_f32 v246, -v70, v21, v246
	v_fma_f32 v1, -v72, v22, v1
	v_fma_f32 v246, -v74, v23, v246
	v_fma_f32 v1, -v76, v16, v1
	v_fma_f32 v246, -v78, v17, v246
	v_fma_f32 v1, -v80, v18, v1
	v_fma_f32 v246, -v82, v19, v246
	v_fma_f32 v1, -v84, v12, v1
	v_fma_f32 v246, -v86, v13, v246
	v_fma_f32 v1, -v88, v14, v1
	v_fma_f32 v246, -v90, v15, v246
	v_fma_f32 v1, -v109, v8, v1
	v_fma_f32 v246, -v110, v9, v246
	v_fma_f32 v1, -v111, v10, v1
	v_fma_f32 v246, -v112, v11, v246
	v_fma_f32 v1, -v113, v4, v1
	v_fma_f32 v246, -v114, v5, v246
	v_fma_f32 v1, -v115, v6, v1
	v_fma_f32 v246, -v116, v7, v246
	s_and_b64 vcc, exec, s[52:53]
	v_fma_f32 v118, -v117, v0, v1
	v_add_f32_e32 v118, v118, v246
	s_cbranch_vccnz .LBB0_549
	v_cvt_pk_bf16_f32 v0, v118, s0
	global_store_short v[40:41], v0, off

; __device__ __forceinline__ bf16_t f2bf(float f) { return (bf16_t)(cvt_pk_bf16(f, 0.f) & 0xffffu); }
; __device__ __forceinline__ float bf2f(bf16_t b) { return __uint_as_float(((unsigned)b) << 16); }
; template <int I>
; __device__ __forceinline__ void solve_rows(float (&x)[64], const f32x4* A4, const bf16_t* src, const float* sBeta, const float* sGam, int part, bf16_t* dst, int nvalid) {
;     ...
;         for (int q = 0; q < (I + 3) / 4; ++q) a4[q] = A4[I * 16 + q];
;         float a = bf2f(src[I * 136]) * sBeta[I];
;         if (part == 1) a *= __expf(sGam[I]);
; #pragma unroll
;         for (int j = 0; j < I; ++j) a -= a4[j >> 2][j & 3] * x[j];
;         x[I] = a;
;         if (I < nvalid) *dst = f2bf(a);
.LBB0_551:
	s_waitcnt lgkmcnt(0)
	v_fma_f32 v2, -v64, v32, v235
	v_mul_f32_e64 v246, -v65, v33
	v_fma_f32 v2, -v67, v34, v2
	v_fma_f32 v246, -v69, v35, v246
	v_fma_f32 v2, -v71, v36, v2
	v_fma_f32 v246, -v73, v37, v246
	v_fma_f32 v2, -v75, v38, v2
	v_fma_f32 v246, -v77, v39, v246
	v_fma_f32 v2, -v79, v28, v2
	v_fma_f32 v246, -v81, v29, v246
	v_fma_f32 v2, -v83, v30, v2
	v_fma_f32 v246, -v85, v31, v246
	v_fma_f32 v2, -v87, v24, v2
	v_fma_f32 v246, -v89, v25, v246
	v_fma_f32 v2, -v91, v26, v2
	v_fma_f32 v246, -v66, v27, v246
	v_fma_f32 v2, -v68, v20, v2
	v_fma_f32 v246, -v70, v21, v246
	v_fma_f32 v2, -v72, v22, v2
	v_fma_f32 v246, -v74, v23, v246
	v_fma_f32 v2, -v76, v16, v2
	v_fma_f32 v246, -v78, v17, v246
	v_fma_f32 v2, -v80, v18, v2
	v_fma_f32 v246, -v82, v19, v246
	v_fma_f32 v2, -v84, v12, v2
	v_fma_f32 v246, -v86, v13, v246
	v_fma_f32 v2, -v88, v14, v2
	v_fma_f32 v246, -v90, v15, v246
	v_fma_f32 v2, -v109, v8, v2
	v_fma_f32 v246, -v110, v9, v246
	v_fma_f32 v2, -v111, v10, v2
	v_fma_f32 v246, -v112, v11, v246
	v_fma_f32 v2, -v113, v4, v2
	v_fma_f32 v246, -v114, v5, v246
	v_fma_f32 v2, -v115, v6, v2
	v_fma_f32 v246, -v116, v7, v246
	v_fma_f32 v0, -v117, v0, v2
	s_and_b64 vcc, exec, s[52:53]
	v_fma_f32 v246, -v118, v1, v246
	v_add_f32_e32 v119, v0, v246
	s_cbranch_vccnz .LBB0_553
	v_cvt_pk_bf16_f32 v0, v119, s0
	global_store_short v[40:41], v0, off

; __device__ __forceinline__ bf16_t f2bf(float f) { return (bf16_t)(cvt_pk_bf16(f, 0.f) & 0xffffu); }
; __device__ __forceinline__ float bf2f(bf16_t b) { return __uint_as_float(((unsigned)b) << 16); }
; template <int I>
; __device__ __forceinline__ void solve_rows(float (&x)[64], const f32x4* A4, const bf16_t* src, const float* sBeta, const float* sGam, int part, bf16_t* dst, int nvalid) {
;     ...
;         for (int q = 0; q < (I + 3) / 4; ++q) a4[q] = A4[I * 16 + q];
;         float a = bf2f(src[I * 136]) * sBeta[I];
;         if (part == 1) a *= __expf(sGam[I]);
; #pragma unroll
;         for (int j = 0; j < I; ++j) a -= a4[j >> 2][j & 3] * x[j];
;         x[I] = a;
;         if (I < nvalid) *dst = f2bf(a);
.LBB0_555:
	s_waitcnt lgkmcnt(0)
	v_fma_f32 v7, -v64, v36, v235
	v_mul_f32_e64 v246, -v65, v37
	v_fma_f32 v7, -v67, v38, v7
	v_fma_f32 v246, -v69, v39, v246
	v_fma_f32 v7, -v71, v32, v7
	v_fma_f32 v246, -v73, v33, v246
	v_fma_f32 v7, -v75, v34, v7
	v_fma_f32 v246, -v77, v35, v246
	v_fma_f32 v7, -v79, v28, v7
	v_fma_f32 v246, -v81, v29, v246
	v_fma_f32 v7, -v83, v30, v7
	v_fma_f32 v246, -v85, v31, v246
	v_fma_f32 v7, -v87, v24, v7
	v_fma_f32 v246, -v89, v25, v246
	v_fma_f32 v7, -v91, v26, v7
	v_fma_f32 v246, -v66, v27, v246
	v_fma_f32 v7, -v68, v20, v7
	v_fma_f32 v246, -v70, v21, v246
	v_fma_f32 v7, -v72, v22, v7
	v_fma_f32 v246, -v74, v23, v246
	v_fma_f32 v7, -v76, v16, v7
	v_fma_f32 v246, -v78, v17, v246
	v_fma_f32 v7, -v80, v18, v7
	v_fma_f32 v246, -v82, v19, v246
	v_fma_f32 v7, -v84, v12, v7
	v_fma_f32 v246, -v86, v13, v246
	v_fma_f32 v7, -v88, v14, v7
	v_fma_f32 v246, -v90, v15, v246
	v_fma_f32 v7, -v109, v8, v7
	v_fma_f32 v246, -v110, v9, v246
	v_fma_f32 v7, -v111, v10, v7
	v_fma_f32 v246, -v112, v11, v246
	v_fma_f32 v0, -v113, v0, v7
	v_fma_f32 v246, -v114, v1, v246
	v_fma_f32 v0, -v115, v2, v0
	v_fma_f32 v246, -v116, v3, v246
	v_fma_f32 v0, -v117, v4, v0
	v_fma_f32 v246, -v118, v5, v246
	s_and_b64 vcc, exec, s[52:53]
	v_fma_f32 v120, -v119, v6, v0
	v_add_f32_e32 v120, v120, v246
	s_cbranch_vccnz .LBB0_557
	v_cvt_pk_bf16_f32 v0, v120, s0
	global_store_short v[40:41], v0, off

; __device__ __forceinline__ bf16_t f2bf(float f) { return (bf16_t)(cvt_pk_bf16(f, 0.f) & 0xffffu); }
; __device__ __forceinline__ float bf2f(bf16_t b) { return __uint_as_float(((unsigned)b) << 16); }
; template <int I>
; __device__ __forceinline__ void solve_rows(float (&x)[64], const f32x4* A4, const bf16_t* src, const float* sBeta, const float* sGam, int part, bf16_t* dst, int nvalid) {
;     ...
;         for (int q = 0; q < (I + 3) / 4; ++q) a4[q] = A4[I * 16 + q];
;         float a = bf2f(src[I * 136]) * sBeta[I];
;         if (part == 1) a *= __expf(sGam[I]);
; #pragma unroll
;         for (int j = 0; j < I; ++j) a -= a4[j >> 2][j & 3] * x[j];
;         x[I] = a;
;         if (I < nvalid) *dst = f2bf(a);
.LBB0_559:
	s_waitcnt lgkmcnt(9)
	v_fma_f32 v36, -v64, v36, v42
	v_mul_f32_e64 v246, -v65, v37
	v_fma_f32 v36, -v67, v38, v36
	v_fma_f32 v246, -v69, v39, v246
	s_waitcnt lgkmcnt(8)
	v_fma_f32 v32, -v71, v32, v36
	v_fma_f32 v246, -v73, v33, v246
	v_fma_f32 v32, -v75, v34, v32
	v_fma_f32 v246, -v77, v35, v246
	s_waitcnt lgkmcnt(7)
	v_fma_f32 v28, -v79, v28, v32
	v_fma_f32 v246, -v81, v29, v246
	v_fma_f32 v28, -v83, v30, v28
	v_fma_f32 v246, -v85, v31, v246
	s_waitcnt lgkmcnt(6)
	v_fma_f32 v24, -v87, v24, v28
	v_fma_f32 v246, -v89, v25, v246
	v_fma_f32 v24, -v91, v26, v24
	v_fma_f32 v246, -v66, v27, v246
	s_waitcnt lgkmcnt(5)
	v_fma_f32 v20, -v68, v20, v24
	v_fma_f32 v246, -v70, v21, v246
	v_fma_f32 v20, -v72, v22, v20
	v_fma_f32 v246, -v74, v23, v246
	s_waitcnt lgkmcnt(4)
	v_fma_f32 v16, -v76, v16, v20
	v_fma_f32 v246, -v78, v17, v246
	v_fma_f32 v16, -v80, v18, v16
	v_fma_f32 v246, -v82, v19, v246
	s_waitcnt lgkmcnt(3)
	v_fma_f32 v12, -v84, v12, v16
	v_fma_f32 v246, -v86, v13, v246
	v_fma_f32 v12, -v88, v14, v12
	v_fma_f32 v246, -v90, v15, v246
	s_waitcnt lgkmcnt(2)
	v_fma_f32 v8, -v109, v8, v12
	v_fma_f32 v246, -v110, v9, v246
	v_fma_f32 v8, -v111, v10, v8
	v_fma_f32 v246, -v112, v11, v246
	s_waitcnt lgkmcnt(1)
	v_fma_f32 v0, -v113, v0, v8
	v_fma_f32 v246, -v114, v1, v246
	v_fma_f32 v0, -v115, v2, v0
	v_fma_f32 v246, -v116, v3, v246
	s_waitcnt lgkmcnt(0)
	v_fma_f32 v0, -v117, v4, v0
	v_fma_f32 v246, -v118, v5, v246
	v_fma_f32 v0, -v119, v6, v0
	s_and_b64 vcc, exec, s[52:53]
	v_fma_f32 v246, -v120, v7, v246
	v_add_f32_e32 v121, v0, v246
	s_cbranch_vccnz .LBB0_561
	v_cvt_pk_bf16_f32 v0, v121, s0
	global_store_short v[40:41], v0, off

; __device__ __forceinline__ bf16_t f2bf(float f) { return (bf16_t)(cvt_pk_bf16(f, 0.f) & 0xffffu); }
; __device__ __forceinline__ float bf2f(bf16_t b) { return __uint_as_float(((unsigned)b) << 16); }
; template <int I>
; __device__ __forceinline__ void solve_rows(float (&x)[64], const f32x4* A4, const bf16_t* src, const float* sBeta, const float* sGam, int part, bf16_t* dst, int nvalid) {
;     ...
;         for (int q = 0; q < (I + 3) / 4; ++q) a4[q] = A4[I * 16 + q];
;         float a = bf2f(src[I * 136]) * sBeta[I];
;         if (part == 1) a *= __expf(sGam[I]);
; #pragma unroll
;         for (int j = 0; j < I; ++j) a -= a4[j >> 2][j & 3] * x[j];
;         x[I] = a;
;         if (I < nvalid) *dst = f2bf(a);
.LBB0_563:
	s_waitcnt lgkmcnt(0)
	v_fma_f32 v1, -v64, v36, v235
	v_mul_f32_e64 v246, -v65, v37
	v_fma_f32 v1, -v67, v38, v1
	v_fma_f32 v246, -v69, v39, v246
	v_fma_f32 v1, -v71, v40, v1
	v_fma_f32 v246, -v73, v41, v246
	v_fma_f32 v1, -v75, v42, v1
	v_fma_f32 v246, -v77, v43, v246
	v_fma_f32 v1, -v79, v32, v1
	v_fma_f32 v246, -v81, v33, v246
	v_fma_f32 v1, -v83, v34, v1
	v_fma_f32 v246, -v85, v35, v246
	v_fma_f32 v1, -v87, v28, v1
	v_fma_f32 v246, -v89, v29, v246
	v_fma_f32 v1, -v91, v30, v1
	v_fma_f32 v246, -v66, v31, v246
	v_fma_f32 v1, -v68, v24, v1
	v_fma_f32 v246, -v70, v25, v246
	v_fma_f32 v1, -v72, v26, v1
	v_fma_f32 v246, -v74, v27, v246
	v_fma_f32 v1, -v76, v20, v1
	v_fma_f32 v246, -v78, v21, v246
	v_fma_f32 v1, -v80, v22, v1
	v_fma_f32 v246, -v82, v23, v246
	v_fma_f32 v1, -v84, v16, v1
	v_fma_f32 v246, -v86, v17, v246
	v_fma_f32 v1, -v88, v18, v1
	v_fma_f32 v246, -v90, v19, v246
	v_fma_f32 v1, -v109, v12, v1
	v_fma_f32 v246, -v110, v13, v246
	v_fma_f32 v1, -v111, v14, v1
	v_fma_f32 v246, -v112, v15, v246
	v_fma_f32 v1, -v113, v8, v1
	v_fma_f32 v246, -v114, v9, v246
	v_fma_f32 v1, -v115, v10, v1
	v_fma_f32 v246, -v116, v11, v246
	v_fma_f32 v1, -v117, v4, v1
	v_fma_f32 v246, -v118, v5, v246
	v_fma_f32 v1, -v119, v6, v1
	v_fma_f32 v246, -v120, v7, v246
	s_and_b64 vcc, exec, s[52:53]
	v_fma_f32 v122, -v121, v0, v1
	v_add_f32_e32 v122, v122, v246
	s_cbranch_vccnz .LBB0_565
	v_cvt_pk_bf16_f32 v0, v122, s0
	global_store_short v[44:45], v0, off

; __device__ __forceinline__ bf16_t f2bf(float f) { return (bf16_t)(cvt_pk_bf16(f, 0.f) & 0xffffu); }
; __device__ __forceinline__ float bf2f(bf16_t b) { return __uint_as_float(((unsigned)b) << 16); }
; template <int I>
; __device__ __forceinline__ void solve_rows(float (&x)[64], const f32x4* A4, const bf16_t* src, const float* sBeta, const float* sGam, int part, bf16_t* dst, int nvalid) {
;     ...
;         for (int q = 0; q < (I + 3) / 4; ++q) a4[q] = A4[I * 16 + q];
;         float a = bf2f(src[I * 136]) * sBeta[I];
;         if (part == 1) a *= __expf(sGam[I]);
; #pragma unroll
;         for (int j = 0; j < I; ++j) a -= a4[j >> 2][j & 3] * x[j];
;         x[I] = a;
;         if (I < nvalid) *dst = f2bf(a);
.LBB0_567:
	s_waitcnt lgkmcnt(0)
	v_fma_f32 v2, -v64, v36, v235
	v_mul_f32_e64 v246, -v65, v37
	v_fma_f32 v2, -v67, v38, v2
	v_fma_f32 v246, -v69, v39, v246
	v_fma_f32 v2, -v71, v40, v2
	v_fma_f32 v246, -v73, v41, v246
	v_fma_f32 v2, -v75, v42, v2
	v_fma_f32 v246, -v77, v43, v246
	v_fma_f32 v2, -v79, v32, v2
	v_fma_f32 v246, -v81, v33, v246
	v_fma_f32 v2, -v83, v34, v2
	v_fma_f32 v246, -v85, v35, v246
	v_fma_f32 v2, -v87, v28, v2
	v_fma_f32 v246, -v89, v29, v246
	v_fma_f32 v2, -v91, v30, v2
	v_fma_f32 v246, -v66, v31, v246
	v_fma_f32 v2, -v68, v24, v2
	v_fma_f32 v246, -v70, v25, v246
	v_fma_f32 v2, -v72, v26, v2
	v_fma_f32 v246, -v74, v27, v246
	v_fma_f32 v2, -v76, v20, v2
	v_fma_f32 v246, -v78, v21, v246
	v_fma_f32 v2, -v80, v22, v2
	v_fma_f32 v246, -v82, v23, v246
	v_fma_f32 v2, -v84, v16, v2
	v_fma_f32 v246, -v86, v17, v246
	v_fma_f32 v2, -v88, v18, v2
	v_fma_f32 v246, -v90, v19, v246
	v_fma_f32 v2, -v109, v12, v2
	v_fma_f32 v246, -v110, v13, v246
	v_fma_f32 v2, -v111, v14, v2
	v_fma_f32 v246, -v112, v15, v246
	v_fma_f32 v2, -v113, v8, v2
	v_fma_f32 v246, -v114, v9, v246
	v_fma_f32 v2, -v115, v10, v2
	v_fma_f32 v246, -v116, v11, v246
	v_fma_f32 v2, -v117, v4, v2
	v_fma_f32 v246, -v118, v5, v246
	v_fma_f32 v2, -v119, v6, v2
	v_fma_f32 v246, -v120, v7, v246
	v_fma_f32 v0, -v121, v0, v2
	s_and_b64 vcc, exec, s[52:53]
	v_fma_f32 v246, -v122, v1, v246
	v_add_f32_e32 v123, v0, v246
	s_cbranch_vccnz .LBB0_569
	v_cvt_pk_bf16_f32 v0, v123, s0
	global_store_short v[44:45], v0, off

; __device__ __forceinline__ bf16_t f2bf(float f) { return (bf16_t)(cvt_pk_bf16(f, 0.f) & 0xffffu); }
; __device__ __forceinline__ float bf2f(bf16_t b) { return __uint_as_float(((unsigned)b) << 16); }
; template <int I>
; __device__ __forceinline__ void solve_rows(float (&x)[64], const f32x4* A4, const bf16_t* src, const float* sBeta, const float* sGam, int part, bf16_t* dst, int nvalid) {
;     ...
;         for (int q = 0; q < (I + 3) / 4; ++q) a4[q] = A4[I * 16 + q];
;         float a = bf2f(src[I * 136]) * sBeta[I];
;         if (part == 1) a *= __expf(sGam[I]);
; #pragma unroll
;         for (int j = 0; j < I; ++j) a -= a4[j >> 2][j & 3] * x[j];
;         x[I] = a;
;         if (I < nvalid) *dst = f2bf(a);
.LBB0_571:
	s_waitcnt lgkmcnt(0)
	v_fma_f32 v3, -v64, v40, v235
	v_mul_f32_e64 v246, -v65, v41
	v_fma_f32 v3, -v67, v42, v3
	v_fma_f32 v246, -v69, v43, v246
	v_fma_f32 v3, -v71, v36, v3
	v_fma_f32 v246, -v73, v37, v246
	v_fma_f32 v3, -v75, v38, v3
	v_fma_f32 v246, -v77, v39, v246
	v_fma_f32 v3, -v79, v32, v3
	v_fma_f32 v246, -v81, v33, v246
	v_fma_f32 v3, -v83, v34, v3
	v_fma_f32 v246, -v85, v35, v246
	v_fma_f32 v3, -v87, v28, v3
	v_fma_f32 v246, -v89, v29, v246
	v_fma_f32 v3, -v91, v30, v3
	v_fma_f32 v246, -v66, v31, v246
	v_fma_f32 v3, -v68, v24, v3
	v_fma_f32 v246, -v70, v25, v246
	v_fma_f32 v3, -v72, v26, v3
	v_fma_f32 v246, -v74, v27, v246
	v_fma_f32 v3, -v76, v20, v3
	v_fma_f32 v246, -v78, v21, v246
	v_fma_f32 v3, -v80, v22, v3
	v_fma_f32 v246, -v82, v23, v246
	v_fma_f32 v3, -v84, v16, v3
	v_fma_f32 v246, -v86, v17, v246
	v_fma_f32 v3, -v88, v18, v3
	v_fma_f32 v246, -v90, v19, v246
	v_fma_f32 v3, -v109, v8, v3
	v_fma_f32 v246, -v110, v9, v246
	v_fma_f32 v3, -v111, v10, v3
	v_fma_f32 v246, -v112, v11, v246
	v_fma_f32 v3, -v113, v4, v3
	v_fma_f32 v246, -v114, v5, v246
	v_fma_f32 v3, -v115, v6, v3
	v_fma_f32 v246, -v116, v7, v246
	v_fma_f32 v3, -v117, v12, v3
	v_fma_f32 v246, -v118, v13, v246
	v_fma_f32 v3, -v119, v14, v3
	v_fma_f32 v246, -v120, v15, v246
	v_fma_f32 v0, -v121, v0, v3
	v_fma_f32 v246, -v122, v1, v246
	s_and_b64 vcc, exec, s[52:53]
	v_fma_f32 v124, -v123, v2, v0
	v_add_f32_e32 v124, v124, v246
	s_cbranch_vccnz .LBB0_573
	v_cvt_pk_bf16_f32 v0, v124, s0
	global_store_short v[44:45], v0, off

; __device__ __forceinline__ bf16_t f2bf(float f) { return (bf16_t)(cvt_pk_bf16(f, 0.f) & 0xffffu); }
; __device__ __forceinline__ float bf2f(bf16_t b) { return __uint_as_float(((unsigned)b) << 16); }
; template <int I>
; __device__ __forceinline__ void solve_rows(float (&x)[64], const f32x4* A4, const bf16_t* src, const float* sBeta, const float* sGam, int part, bf16_t* dst, int nvalid) {
;     ...
;         for (int q = 0; q < (I + 3) / 4; ++q) a4[q] = A4[I * 16 + q];
;         float a = bf2f(src[I * 136]) * sBeta[I];
;         if (part == 1) a *= __expf(sGam[I]);
; #pragma unroll
;         for (int j = 0; j < I; ++j) a -= a4[j >> 2][j & 3] * x[j];
;         x[I] = a;
;         if (I < nvalid) *dst = f2bf(a);
.LBB0_575:
	s_waitcnt lgkmcnt(10)
	v_fma_f32 v40, -v64, v40, v46
	v_mul_f32_e64 v246, -v65, v41
	v_fma_f32 v40, -v67, v42, v40
	v_fma_f32 v246, -v69, v43, v246
	s_waitcnt lgkmcnt(9)
	v_fma_f32 v36, -v71, v36, v40
	v_fma_f32 v246, -v73, v37, v246
	v_fma_f32 v36, -v75, v38, v36
	v_fma_f32 v246, -v77, v39, v246
	s_waitcnt lgkmcnt(8)
	v_fma_f32 v32, -v79, v32, v36
	v_fma_f32 v246, -v81, v33, v246
	v_fma_f32 v32, -v83, v34, v32
	v_fma_f32 v246, -v85, v35, v246
	s_waitcnt lgkmcnt(7)
	v_fma_f32 v28, -v87, v28, v32
	v_fma_f32 v246, -v89, v29, v246
	v_fma_f32 v28, -v91, v30, v28
	v_fma_f32 v246, -v66, v31, v246
	s_waitcnt lgkmcnt(6)
	v_fma_f32 v24, -v68, v24, v28
	v_fma_f32 v246, -v70, v25, v246
	v_fma_f32 v24, -v72, v26, v24
	v_fma_f32 v246, -v74, v27, v246
	s_waitcnt lgkmcnt(5)
	v_fma_f32 v20, -v76, v20, v24
	v_fma_f32 v246, -v78, v21, v246
	v_fma_f32 v20, -v80, v22, v20
	v_fma_f32 v246, -v82, v23, v246
	s_waitcnt lgkmcnt(4)
	v_fma_f32 v16, -v84, v16, v20
	v_fma_f32 v246, -v86, v17, v246
	v_fma_f32 v16, -v88, v18, v16
	v_fma_f32 v246, -v90, v19, v246
	s_waitcnt lgkmcnt(3)
	v_fma_f32 v8, -v109, v8, v16
	v_fma_f32 v246, -v110, v9, v246
	v_fma_f32 v8, -v111, v10, v8
	v_fma_f32 v246, -v112, v11, v246
	s_waitcnt lgkmcnt(2)
	v_fma_f32 v4, -v113, v4, v8
	v_fma_f32 v246, -v114, v5, v246
	v_fma_f32 v4, -v115, v6, v4
	v_fma_f32 v246, -v116, v7, v246
	s_waitcnt lgkmcnt(1)
	v_fma_f32 v4, -v117, v12, v4
	v_fma_f32 v246, -v118, v13, v246
	v_fma_f32 v4, -v119, v14, v4
	v_fma_f32 v246, -v120, v15, v246
	s_waitcnt lgkmcnt(0)
	v_fma_f32 v0, -v121, v0, v4
	v_fma_f32 v246, -v122, v1, v246
	v_fma_f32 v0, -v123, v2, v0
	s_and_b64 vcc, exec, s[52:53]
	v_fma_f32 v246, -v124, v3, v246
	v_add_f32_e32 v125, v0, v246
	s_cbranch_vccnz .LBB0_577
	v_cvt_pk_bf16_f32 v0, v125, s0
	global_store_short v[44:45], v0, off

; __device__ __forceinline__ bf16_t f2bf(float f) { return (bf16_t)(cvt_pk_bf16(f, 0.f) & 0xffffu); }
; __device__ __forceinline__ float bf2f(bf16_t b) { return __uint_as_float(((unsigned)b) << 16); }
; template <int I>
; __device__ __forceinline__ void solve_rows(float (&x)[64], const f32x4* A4, const bf16_t* src, const float* sBeta, const float* sGam, int part, bf16_t* dst, int nvalid) {
;     ...
;         for (int q = 0; q < (I + 3) / 4; ++q) a4[q] = A4[I * 16 + q];
;         float a = bf2f(src[I * 136]) * sBeta[I];
;         if (part == 1) a *= __expf(sGam[I]);
; #pragma unroll
;         for (int j = 0; j < I; ++j) a -= a4[j >> 2][j & 3] * x[j];
;         x[I] = a;
;         if (I < nvalid) *dst = f2bf(a);
.LBB0_579:
	s_waitcnt lgkmcnt(0)
	v_fma_f32 v1, -v64, v40, v235
	v_mul_f32_e64 v246, -v65, v41
	v_fma_f32 v1, -v67, v42, v1
	v_fma_f32 v246, -v69, v43, v246
	v_fma_f32 v1, -v71, v44, v1
	v_fma_f32 v246, -v73, v45, v246
	v_fma_f32 v1, -v75, v46, v1
	v_fma_f32 v246, -v77, v47, v246
	v_fma_f32 v1, -v79, v36, v1
	v_fma_f32 v246, -v81, v37, v246
	v_fma_f32 v1, -v83, v38, v1
	v_fma_f32 v246, -v85, v39, v246
	v_fma_f32 v1, -v87, v32, v1
	v_fma_f32 v246, -v89, v33, v246
	v_fma_f32 v1, -v91, v34, v1
	v_fma_f32 v246, -v66, v35, v246
	v_fma_f32 v1, -v68, v28, v1
	v_fma_f32 v246, -v70, v29, v246
	v_fma_f32 v1, -v72, v30, v1
	v_fma_f32 v246, -v74, v31, v246
	v_fma_f32 v1, -v76, v24, v1
	v_fma_f32 v246, -v78, v25, v246
	v_fma_f32 v1, -v80, v26, v1
	v_fma_f32 v246, -v82, v27, v246
	v_fma_f32 v1, -v84, v20, v1
	v_fma_f32 v246, -v86, v21, v246
	v_fma_f32 v1, -v88, v22, v1
	v_fma_f32 v246, -v90, v23, v246
	v_fma_f32 v1, -v109, v16, v1
	v_fma_f32 v246, -v110, v17, v246
	v_fma_f32 v1, -v111, v18, v1
	v_fma_f32 v246, -v112, v19, v246
	v_fma_f32 v1, -v113, v12, v1
	v_fma_f32 v246, -v114, v13, v246
	v_fma_f32 v1, -v115, v14, v1
	v_fma_f32 v246, -v116, v15, v246
	v_fma_f32 v1, -v117, v8, v1
	v_fma_f32 v246, -v118, v9, v246
	v_fma_f32 v1, -v119, v10, v1
	v_fma_f32 v246, -v120, v11, v246
	v_fma_f32 v1, -v121, v4, v1
	v_fma_f32 v246, -v122, v5, v246
	v_fma_f32 v1, -v123, v6, v1
	v_fma_f32 v246, -v124, v7, v246
	s_and_b64 vcc, exec, s[52:53]
	v_fma_f32 v126, -v125, v0, v1
	v_add_f32_e32 v126, v126, v246
	s_cbranch_vccnz .LBB0_581
	v_cvt_pk_bf16_f32 v0, v126, s0
	global_store_short v[48:49], v0, off

; __device__ __forceinline__ bf16_t f2bf(float f) { return (bf16_t)(cvt_pk_bf16(f, 0.f) & 0xffffu); }
; __device__ __forceinline__ float bf2f(bf16_t b) { return __uint_as_float(((unsigned)b) << 16); }
; template <int I>
; __device__ __forceinline__ void solve_rows(float (&x)[64], const f32x4* A4, const bf16_t* src, const float* sBeta, const float* sGam, int part, bf16_t* dst, int nvalid) {
;     ...
;         for (int q = 0; q < (I + 3) / 4; ++q) a4[q] = A4[I * 16 + q];
;         float a = bf2f(src[I * 136]) * sBeta[I];
;         if (part == 1) a *= __expf(sGam[I]);
; #pragma unroll
;         for (int j = 0; j < I; ++j) a -= a4[j >> 2][j & 3] * x[j];
;         x[I] = a;
;         if (I < nvalid) *dst = f2bf(a);
.LBB0_583:
	s_waitcnt lgkmcnt(0)
	v_fma_f32 v2, -v64, v40, v235
	v_mul_f32_e64 v246, -v65, v41
	v_fma_f32 v2, -v67, v42, v2
	v_fma_f32 v246, -v69, v43, v246
	v_fma_f32 v2, -v71, v44, v2
	v_fma_f32 v246, -v73, v45, v246
	v_fma_f32 v2, -v75, v46, v2
	v_fma_f32 v246, -v77, v47, v246
	v_fma_f32 v2, -v79, v36, v2
	v_fma_f32 v246, -v81, v37, v246
	v_fma_f32 v2, -v83, v38, v2
	v_fma_f32 v246, -v85, v39, v246
	v_fma_f32 v2, -v87, v32, v2
	v_fma_f32 v246, -v89, v33, v246
	v_fma_f32 v2, -v91, v34, v2
	v_fma_f32 v246, -v66, v35, v246
	v_fma_f32 v2, -v68, v28, v2
	v_fma_f32 v246, -v70, v29, v246
	v_fma_f32 v2, -v72, v30, v2
	v_fma_f32 v246, -v74, v31, v246
	v_fma_f32 v2, -v76, v24, v2
	v_fma_f32 v246, -v78, v25, v246
	v_fma_f32 v2, -v80, v26, v2
	v_fma_f32 v246, -v82, v27, v246
	v_fma_f32 v2, -v84, v20, v2
	v_fma_f32 v246, -v86, v21, v246
	v_fma_f32 v2, -v88, v22, v2
	v_fma_f32 v246, -v90, v23, v246
	v_fma_f32 v2, -v109, v16, v2
	v_fma_f32 v246, -v110, v17, v246
	v_fma_f32 v2, -v111, v18, v2
	v_fma_f32 v246, -v112, v19, v246
	v_fma_f32 v2, -v113, v12, v2
	v_fma_f32 v246, -v114, v13, v246
	v_fma_f32 v2, -v115, v14, v2
	v_fma_f32 v246, -v116, v15, v246
	v_fma_f32 v2, -v117, v8, v2
	v_fma_f32 v246, -v118, v9, v246
	v_fma_f32 v2, -v119, v10, v2
	v_fma_f32 v246, -v120, v11, v246
	v_fma_f32 v2, -v121, v4, v2
	v_fma_f32 v246, -v122, v5, v246
	v_fma_f32 v2, -v123, v6, v2
	v_fma_f32 v246, -v124, v7, v246
	v_fma_f32 v0, -v125, v0, v2
	s_and_b64 vcc, exec, s[52:53]
	v_fma_f32 v246, -v126, v1, v246
	v_add_f32_e32 v127, v0, v246
	s_cbranch_vccnz .LBB0_585
	v_cvt_pk_bf16_f32 v0, v127, s0
	global_store_short v[48:49], v0, off

; __device__ __forceinline__ bf16_t f2bf(float f) { return (bf16_t)(cvt_pk_bf16(f, 0.f) & 0xffffu); }
; __device__ __forceinline__ float bf2f(bf16_t b) { return __uint_as_float(((unsigned)b) << 16); }
; template <int I>
; __device__ __forceinline__ void solve_rows(float (&x)[64], const f32x4* A4, const bf16_t* src, const float* sBeta, const float* sGam, int part, bf16_t* dst, int nvalid) {
;     ...
;         for (int q = 0; q < (I + 3) / 4; ++q) a4[q] = A4[I * 16 + q];
;         float a = bf2f(src[I * 136]) * sBeta[I];
;         if (part == 1) a *= __expf(sGam[I]);
; #pragma unroll
;         for (int j = 0; j < I; ++j) a -= a4[j >> 2][j & 3] * x[j];
;         x[I] = a;
;         if (I < nvalid) *dst = f2bf(a);
.LBB0_587:
	s_waitcnt lgkmcnt(0)
	v_fma_f32 v7, -v64, v44, v235
	v_mul_f32_e64 v246, -v65, v45
	v_fma_f32 v7, -v67, v46, v7
	v_fma_f32 v246, -v69, v47, v246
	v_fma_f32 v7, -v71, v40, v7
	v_fma_f32 v246, -v73, v41, v246
	v_fma_f32 v7, -v75, v42, v7
	v_fma_f32 v246, -v77, v43, v246
	v_fma_f32 v7, -v79, v36, v7
	v_fma_f32 v246, -v81, v37, v246
	v_fma_f32 v7, -v83, v38, v7
	v_fma_f32 v246, -v85, v39, v246
	v_fma_f32 v7, -v87, v32, v7
	v_fma_f32 v246, -v89, v33, v246
	v_fma_f32 v7, -v91, v34, v7
	v_fma_f32 v246, -v66, v35, v246
	v_fma_f32 v7, -v68, v28, v7
	v_fma_f32 v246, -v70, v29, v246
	v_fma_f32 v7, -v72, v30, v7
	v_fma_f32 v246, -v74, v31, v246
	v_fma_f32 v7, -v76, v24, v7
	v_fma_f32 v246, -v78, v25, v246
	v_fma_f32 v7, -v80, v26, v7
	v_fma_f32 v246, -v82, v27, v246
	v_fma_f32 v7, -v84, v20, v7
	v_fma_f32 v246, -v86, v21, v246
	v_fma_f32 v7, -v88, v22, v7
	v_fma_f32 v246, -v90, v23, v246
	v_fma_f32 v7, -v109, v16, v7
	v_fma_f32 v246, -v110, v17, v246
	v_fma_f32 v7, -v111, v18, v7
	v_fma_f32 v246, -v112, v19, v246
	v_fma_f32 v7, -v113, v12, v7
	v_fma_f32 v246, -v114, v13, v246
	v_fma_f32 v7, -v115, v14, v7
	v_fma_f32 v246, -v116, v15, v246
	v_fma_f32 v7, -v117, v8, v7
	v_fma_f32 v246, -v118, v9, v246
	v_fma_f32 v7, -v119, v10, v7
	v_fma_f32 v246, -v120, v11, v246
	v_fma_f32 v0, -v121, v0, v7
	v_fma_f32 v246, -v122, v1, v246
	v_fma_f32 v0, -v123, v2, v0
	v_fma_f32 v246, -v124, v3, v246
	v_fma_f32 v0, -v125, v4, v0
	v_fma_f32 v246, -v126, v5, v246
	s_and_b64 vcc, exec, s[52:53]
	v_fma_f32 v137, -v127, v6, v0
	v_add_f32_e32 v137, v137, v246
	s_cbranch_vccnz .LBB0_589
	v_cvt_pk_bf16_f32 v0, v137, s0
	global_store_short v[48:49], v0, off

; __device__ __forceinline__ bf16_t f2bf(float f) { return (bf16_t)(cvt_pk_bf16(f, 0.f) & 0xffffu); }
; __device__ __forceinline__ float bf2f(bf16_t b) { return __uint_as_float(((unsigned)b) << 16); }
; template <int I>
; __device__ __forceinline__ void solve_rows(float (&x)[64], const f32x4* A4, const bf16_t* src, const float* sBeta, const float* sGam, int part, bf16_t* dst, int nvalid) {
;     ...
;         for (int q = 0; q < (I + 3) / 4; ++q) a4[q] = A4[I * 16 + q];
;         float a = bf2f(src[I * 136]) * sBeta[I];
;         if (part == 1) a *= __expf(sGam[I]);
; #pragma unroll
;         for (int j = 0; j < I; ++j) a -= a4[j >> 2][j & 3] * x[j];
;         x[I] = a;
;         if (I < nvalid) *dst = f2bf(a);
.LBB0_591:
	s_waitcnt lgkmcnt(11)
	v_fma_f32 v44, -v64, v44, v50
	v_mul_f32_e64 v246, -v65, v45
	v_fma_f32 v44, -v67, v46, v44
	v_fma_f32 v246, -v69, v47, v246
	s_waitcnt lgkmcnt(10)
	v_fma_f32 v40, -v71, v40, v44
	v_fma_f32 v246, -v73, v41, v246
	v_fma_f32 v40, -v75, v42, v40
	v_fma_f32 v246, -v77, v43, v246
	s_waitcnt lgkmcnt(9)
	v_fma_f32 v36, -v79, v36, v40
	v_fma_f32 v246, -v81, v37, v246
	v_fma_f32 v36, -v83, v38, v36
	v_fma_f32 v246, -v85, v39, v246
	s_waitcnt lgkmcnt(8)
	v_fma_f32 v32, -v87, v32, v36
	v_fma_f32 v246, -v89, v33, v246
	v_fma_f32 v32, -v91, v34, v32
	v_fma_f32 v246, -v66, v35, v246
	s_waitcnt lgkmcnt(7)
	v_fma_f32 v28, -v68, v28, v32
	v_fma_f32 v246, -v70, v29, v246
	v_fma_f32 v28, -v72, v30, v28
	v_fma_f32 v246, -v74, v31, v246
	s_waitcnt lgkmcnt(6)
	v_fma_f32 v24, -v76, v24, v28
	v_fma_f32 v246, -v78, v25, v246
	v_fma_f32 v24, -v80, v26, v24
	v_fma_f32 v246, -v82, v27, v246
	s_waitcnt lgkmcnt(5)
	v_fma_f32 v20, -v84, v20, v24
	v_fma_f32 v246, -v86, v21, v246
	v_fma_f32 v20, -v88, v22, v20
	v_fma_f32 v246, -v90, v23, v246
	s_waitcnt lgkmcnt(4)
	v_fma_f32 v16, -v109, v16, v20
	v_fma_f32 v246, -v110, v17, v246
	v_fma_f32 v16, -v111, v18, v16
	v_fma_f32 v246, -v112, v19, v246
	s_waitcnt lgkmcnt(3)
	v_fma_f32 v12, -v113, v12, v16
	v_fma_f32 v246, -v114, v13, v246
	v_fma_f32 v12, -v115, v14, v12
	v_fma_f32 v246, -v116, v15, v246
	s_waitcnt lgkmcnt(2)
	v_fma_f32 v8, -v117, v8, v12
	v_fma_f32 v246, -v118, v9, v246
	v_fma_f32 v8, -v119, v10, v8
	v_fma_f32 v246, -v120, v11, v246
	s_waitcnt lgkmcnt(1)
	v_fma_f32 v0, -v121, v0, v8
	v_fma_f32 v246, -v122, v1, v246
	v_fma_f32 v0, -v123, v2, v0
	v_fma_f32 v246, -v124, v3, v246
	s_waitcnt lgkmcnt(0)
	v_fma_f32 v0, -v125, v4, v0
	v_fma_f32 v246, -v126, v5, v246
	v_fma_f32 v0, -v127, v6, v0
	s_and_b64 vcc, exec, s[52:53]
	v_fma_f32 v246, -v137, v7, v246
	v_add_f32_e32 v139, v0, v246
	s_cbranch_vccnz .LBB0_593
	v_cvt_pk_bf16_f32 v0, v139, s0
	global_store_short v[48:49], v0, off

; __device__ __forceinline__ bf16_t f2bf(float f) { return (bf16_t)(cvt_pk_bf16(f, 0.f) & 0xffffu); }
; __device__ __forceinline__ float bf2f(bf16_t b) { return __uint_as_float(((unsigned)b) << 16); }
; template <int I>
; __device__ __forceinline__ void solve_rows(float (&x)[64], const f32x4* A4, const bf16_t* src, const float* sBeta, const float* sGam, int part, bf16_t* dst, int nvalid) {
;     ...
;         for (int q = 0; q < (I + 3) / 4; ++q) a4[q] = A4[I * 16 + q];
;         float a = bf2f(src[I * 136]) * sBeta[I];
;         if (part == 1) a *= __expf(sGam[I]);
; #pragma unroll
;         for (int j = 0; j < I; ++j) a -= a4[j >> 2][j & 3] * x[j];
;         x[I] = a;
;         if (I < nvalid) *dst = f2bf(a);
.LBB0_595:
	s_waitcnt lgkmcnt(0)
	v_fma_f32 v1, -v64, v44, v235
	v_mul_f32_e64 v246, -v65, v45
	v_fma_f32 v1, -v67, v46, v1
	v_fma_f32 v246, -v69, v47, v246
	v_fma_f32 v1, -v71, v48, v1
	v_fma_f32 v246, -v73, v49, v246
	v_fma_f32 v1, -v75, v50, v1
	v_fma_f32 v246, -v77, v51, v246
	v_fma_f32 v1, -v79, v40, v1
	v_fma_f32 v246, -v81, v41, v246
	v_fma_f32 v1, -v83, v42, v1
	v_fma_f32 v246, -v85, v43, v246
	v_fma_f32 v1, -v87, v36, v1
	v_fma_f32 v246, -v89, v37, v246
	v_fma_f32 v1, -v91, v38, v1
	v_fma_f32 v246, -v66, v39, v246
	v_fma_f32 v1, -v68, v32, v1
	v_fma_f32 v246, -v70, v33, v246
	v_fma_f32 v1, -v72, v34, v1
	v_fma_f32 v246, -v74, v35, v246
	v_fma_f32 v1, -v76, v28, v1
	v_fma_f32 v246, -v78, v29, v246
	v_fma_f32 v1, -v80, v30, v1
	v_fma_f32 v246, -v82, v31, v246
	v_fma_f32 v1, -v84, v24, v1
	v_fma_f32 v246, -v86, v25, v246
	v_fma_f32 v1, -v88, v26, v1
	v_fma_f32 v246, -v90, v27, v246
	v_fma_f32 v1, -v109, v20, v1
	v_fma_f32 v246, -v110, v21, v246
	v_fma_f32 v1, -v111, v22, v1
	v_fma_f32 v246, -v112, v23, v246
	v_fma_f32 v1, -v113, v16, v1
	v_fma_f32 v246, -v114, v17, v246
	v_fma_f32 v1, -v115, v18, v1
	v_fma_f32 v246, -v116, v19, v246
	v_fma_f32 v1, -v117, v12, v1
	v_fma_f32 v246, -v118, v13, v246
	v_fma_f32 v1, -v119, v14, v1
	v_fma_f32 v246, -v120, v15, v246
	v_fma_f32 v1, -v121, v8, v1
	v_fma_f32 v246, -v122, v9, v246
	v_fma_f32 v1, -v123, v10, v1
	v_fma_f32 v246, -v124, v11, v246
	v_fma_f32 v1, -v125, v4, v1
	v_fma_f32 v246, -v126, v5, v246
	v_fma_f32 v1, -v127, v6, v1
	v_fma_f32 v246, -v137, v7, v246
	s_and_b64 vcc, exec, s[52:53]
	v_fma_f32 v140, -v139, v0, v1
	v_add_f32_e32 v140, v140, v246
	s_cbranch_vccnz .LBB0_597
	v_cvt_pk_bf16_f32 v0, v140, s0
	global_store_short v[52:53], v0, off

; __device__ __forceinline__ bf16_t f2bf(float f) { return (bf16_t)(cvt_pk_bf16(f, 0.f) & 0xffffu); }
; __device__ __forceinline__ float bf2f(bf16_t b) { return __uint_as_float(((unsigned)b) << 16); }
; template <int I>
; __device__ __forceinline__ void solve_rows(float (&x)[64], const f32x4* A4, const bf16_t* src, const float* sBeta, const float* sGam, int part, bf16_t* dst, int nvalid) {
;     ...
;         for (int q = 0; q < (I + 3) / 4; ++q) a4[q] = A4[I * 16 + q];
;         float a = bf2f(src[I * 136]) * sBeta[I];
;         if (part == 1) a *= __expf(sGam[I]);
; #pragma unroll
;         for (int j = 0; j < I; ++j) a -= a4[j >> 2][j & 3] * x[j];
;         x[I] = a;
;         if (I < nvalid) *dst = f2bf(a);
.LBB0_599:
	s_waitcnt lgkmcnt(0)
	v_fma_f32 v2, -v64, v44, v235
	v_mul_f32_e64 v246, -v65, v45
	v_fma_f32 v2, -v67, v46, v2
	v_fma_f32 v246, -v69, v47, v246
	v_fma_f32 v2, -v71, v48, v2
	v_fma_f32 v246, -v73, v49, v246
	v_fma_f32 v2, -v75, v50, v2
	v_fma_f32 v246, -v77, v51, v246
	v_fma_f32 v2, -v79, v40, v2
	v_fma_f32 v246, -v81, v41, v246
	v_fma_f32 v2, -v83, v42, v2
	v_fma_f32 v246, -v85, v43, v246
	v_fma_f32 v2, -v87, v36, v2
	v_fma_f32 v246, -v89, v37, v246
	v_fma_f32 v2, -v91, v38, v2
	v_fma_f32 v246, -v66, v39, v246
	v_fma_f32 v2, -v68, v32, v2
	v_fma_f32 v246, -v70, v33, v246
	v_fma_f32 v2, -v72, v34, v2
	v_fma_f32 v246, -v74, v35, v246
	v_fma_f32 v2, -v76, v28, v2
	v_fma_f32 v246, -v78, v29, v246
	v_fma_f32 v2, -v80, v30, v2
	v_fma_f32 v246, -v82, v31, v246
	v_fma_f32 v2, -v84, v24, v2
	v_fma_f32 v246, -v86, v25, v246
	v_fma_f32 v2, -v88, v26, v2
	v_fma_f32 v246, -v90, v27, v246
	v_fma_f32 v2, -v109, v20, v2
	v_fma_f32 v246, -v110, v21, v246
	v_fma_f32 v2, -v111, v22, v2
	v_fma_f32 v246, -v112, v23, v246
	v_fma_f32 v2, -v113, v16, v2
	v_fma_f32 v246, -v114, v17, v246
	v_fma_f32 v2, -v115, v18, v2
	v_fma_f32 v246, -v116, v19, v246
	v_fma_f32 v2, -v117, v12, v2
	v_fma_f32 v246, -v118, v13, v246
	v_fma_f32 v2, -v119, v14, v2
	v_fma_f32 v246, -v120, v15, v246
	v_fma_f32 v2, -v121, v8, v2
	v_fma_f32 v246, -v122, v9, v246
	v_fma_f32 v2, -v123, v10, v2
	v_fma_f32 v246, -v124, v11, v246
	v_fma_f32 v2, -v125, v4, v2
	v_fma_f32 v246, -v126, v5, v246
	v_fma_f32 v2, -v127, v6, v2
	v_fma_f32 v246, -v137, v7, v246
	v_fma_f32 v0, -v139, v0, v2
	s_and_b64 vcc, exec, s[52:53]
	v_fma_f32 v246, -v140, v1, v246
	v_add_f32_e32 v142, v0, v246
	s_cbranch_vccnz .LBB0_601
	v_cvt_pk_bf16_f32 v0, v142, s0
	global_store_short v[52:53], v0, off

; __device__ __forceinline__ bf16_t f2bf(float f) { return (bf16_t)(cvt_pk_bf16(f, 0.f) & 0xffffu); }
; __device__ __forceinline__ float bf2f(bf16_t b) { return __uint_as_float(((unsigned)b) << 16); }
; template <int I>
; __device__ __forceinline__ void solve_rows(float (&x)[64], const f32x4* A4, const bf16_t* src, const float* sBeta, const float* sGam, int part, bf16_t* dst, int nvalid) {
;     ...
;         for (int q = 0; q < (I + 3) / 4; ++q) a4[q] = A4[I * 16 + q];
;         float a = bf2f(src[I * 136]) * sBeta[I];
;         if (part == 1) a *= __expf(sGam[I]);
; #pragma unroll
;         for (int j = 0; j < I; ++j) a -= a4[j >> 2][j & 3] * x[j];
;         x[I] = a;
;         if (I < nvalid) *dst = f2bf(a);
.LBB0_603:
	s_waitcnt lgkmcnt(0)
	v_fma_f32 v3, -v64, v48, v235
	v_mul_f32_e64 v246, -v65, v49
	v_fma_f32 v3, -v67, v50, v3
	v_fma_f32 v246, -v69, v51, v246
	v_fma_f32 v3, -v71, v44, v3
	v_fma_f32 v246, -v73, v45, v246
	v_fma_f32 v3, -v75, v46, v3
	v_fma_f32 v246, -v77, v47, v246
	v_fma_f32 v3, -v79, v40, v3
	v_fma_f32 v246, -v81, v41, v246
	v_fma_f32 v3, -v83, v42, v3
	v_fma_f32 v246, -v85, v43, v246
	v_fma_f32 v3, -v87, v36, v3
	v_fma_f32 v246, -v89, v37, v246
	v_fma_f32 v3, -v91, v38, v3
	v_fma_f32 v246, -v66, v39, v246
	v_fma_f32 v3, -v68, v32, v3
	v_fma_f32 v246, -v70, v33, v246
	v_fma_f32 v3, -v72, v34, v3
	v_fma_f32 v246, -v74, v35, v246
	v_fma_f32 v3, -v76, v28, v3
	v_fma_f32 v246, -v78, v29, v246
	v_fma_f32 v3, -v80, v30, v3
	v_fma_f32 v246, -v82, v31, v246
	v_fma_f32 v3, -v84, v24, v3
	v_fma_f32 v246, -v86, v25, v246
	v_fma_f32 v3, -v88, v26, v3
	v_fma_f32 v246, -v90, v27, v246
	v_fma_f32 v3, -v109, v20, v3
	v_fma_f32 v246, -v110, v21, v246
	v_fma_f32 v3, -v111, v22, v3
	v_fma_f32 v246, -v112, v23, v246
	v_fma_f32 v3, -v113, v16, v3
	v_fma_f32 v246, -v114, v17, v246
	v_fma_f32 v3, -v115, v18, v3
	v_fma_f32 v246, -v116, v19, v246
	v_fma_f32 v3, -v117, v8, v3
	v_fma_f32 v246, -v118, v9, v246
	v_fma_f32 v3, -v119, v10, v3
	v_fma_f32 v246, -v120, v11, v246
	v_fma_f32 v3, -v121, v4, v3
	v_fma_f32 v246, -v122, v5, v246
	v_fma_f32 v3, -v123, v6, v3
	v_fma_f32 v246, -v124, v7, v246
	v_fma_f32 v3, -v125, v12, v3
	v_fma_f32 v246, -v126, v13, v246
	v_fma_f32 v3, -v127, v14, v3
	v_fma_f32 v246, -v137, v15, v246
	v_fma_f32 v0, -v139, v0, v3
	v_fma_f32 v246, -v140, v1, v246
	s_and_b64 vcc, exec, s[52:53]
	v_fma_f32 v92, -v142, v2, v0
	v_add_f32_e32 v92, v92, v246
	s_cbranch_vccnz .LBB0_605
	v_cvt_pk_bf16_f32 v0, v92, s0
	global_store_short v[52:53], v0, off

; __device__ __forceinline__ bf16_t f2bf(float f) { return (bf16_t)(cvt_pk_bf16(f, 0.f) & 0xffffu); }
; __device__ __forceinline__ float bf2f(bf16_t b) { return __uint_as_float(((unsigned)b) << 16); }
; template <int I>
; __device__ __forceinline__ void solve_rows(float (&x)[64], const f32x4* A4, const bf16_t* src, const float* sBeta, const float* sGam, int part, bf16_t* dst, int nvalid) {
;     ...
;         for (int q = 0; q < (I + 3) / 4; ++q) a4[q] = A4[I * 16 + q];
;         float a = bf2f(src[I * 136]) * sBeta[I];
;         if (part == 1) a *= __expf(sGam[I]);
; #pragma unroll
;         for (int j = 0; j < I; ++j) a -= a4[j >> 2][j & 3] * x[j];
;         x[I] = a;
;         if (I < nvalid) *dst = f2bf(a);
.LBB0_607:
	v_fma_f32 v48, -v64, v48, v54
	v_mul_f32_e64 v246, -v65, v49
	v_fma_f32 v48, -v67, v50, v48
	v_fma_f32 v246, -v69, v51, v246
	v_fma_f32 v44, -v71, v44, v48
	v_fma_f32 v246, -v73, v45, v246
	v_fma_f32 v44, -v75, v46, v44
	v_fma_f32 v246, -v77, v47, v246
	v_fma_f32 v40, -v79, v40, v44
	v_fma_f32 v246, -v81, v41, v246
	v_fma_f32 v40, -v83, v42, v40
	v_fma_f32 v246, -v85, v43, v246
	v_fma_f32 v36, -v87, v36, v40
	v_fma_f32 v246, -v89, v37, v246
	v_fma_f32 v36, -v91, v38, v36
	v_fma_f32 v246, -v66, v39, v246
	v_fma_f32 v32, -v68, v32, v36
	v_fma_f32 v246, -v70, v33, v246
	v_fma_f32 v32, -v72, v34, v32
	v_fma_f32 v246, -v74, v35, v246
	v_fma_f32 v28, -v76, v28, v32
	v_fma_f32 v246, -v78, v29, v246
	v_fma_f32 v28, -v80, v30, v28
	v_fma_f32 v246, -v82, v31, v246
	v_fma_f32 v24, -v84, v24, v28
	v_fma_f32 v246, -v86, v25, v246
	v_fma_f32 v24, -v88, v26, v24
	v_fma_f32 v246, -v90, v27, v246
	v_fma_f32 v20, -v109, v20, v24
	v_fma_f32 v246, -v110, v21, v246
	v_fma_f32 v20, -v111, v22, v20
	v_fma_f32 v246, -v112, v23, v246
	v_fma_f32 v16, -v113, v16, v20
	v_fma_f32 v246, -v114, v17, v246
	v_fma_f32 v16, -v115, v18, v16
	v_fma_f32 v246, -v116, v19, v246
	v_fma_f32 v8, -v117, v8, v16
	v_fma_f32 v246, -v118, v9, v246
	v_fma_f32 v8, -v119, v10, v8
	v_fma_f32 v246, -v120, v11, v246
	v_fma_f32 v4, -v121, v4, v8
	v_fma_f32 v246, -v122, v5, v246
	v_fma_f32 v4, -v123, v6, v4
	v_fma_f32 v246, -v124, v7, v246
	v_fma_f32 v4, -v125, v12, v4
	v_fma_f32 v246, -v126, v13, v246
	v_fma_f32 v4, -v127, v14, v4
	v_fma_f32 v246, -v137, v15, v246
	v_fma_f32 v0, -v139, v0, v4
	v_fma_f32 v246, -v140, v1, v246
	v_fma_f32 v0, -v142, v2, v0
	s_and_b64 vcc, exec, s[52:53]
	v_fma_f32 v246, -v92, v3, v246
	v_add_f32_e32 v93, v0, v246
	s_cbranch_vccnz .LBB0_609
	v_cvt_pk_bf16_f32 v0, v93, s0
	global_store_short v[52:53], v0, off

; __device__ __forceinline__ bf16_t f2bf(float f) { return (bf16_t)(cvt_pk_bf16(f, 0.f) & 0xffffu); }
; __device__ __forceinline__ float bf2f(bf16_t b) { return __uint_as_float(((unsigned)b) << 16); }
; template <int I>
; __device__ __forceinline__ void solve_rows(float (&x)[64], const f32x4* A4, const bf16_t* src, const float* sBeta, const float* sGam, int part, bf16_t* dst, int nvalid) {
;     ...
;         for (int q = 0; q < (I + 3) / 4; ++q) a4[q] = A4[I * 16 + q];
;         float a = bf2f(src[I * 136]) * sBeta[I];
;         if (part == 1) a *= __expf(sGam[I]);
; #pragma unroll
;         for (int j = 0; j < I; ++j) a -= a4[j >> 2][j & 3] * x[j];
;         x[I] = a;
;         if (I < nvalid) *dst = f2bf(a);
.LBB0_611:
	v_fma_f32 v1, -v64, v48, v1
	v_mul_f32_e64 v246, -v65, v49
	v_fma_f32 v1, -v67, v50, v1
	v_fma_f32 v246, -v69, v51, v246
	v_fma_f32 v1, -v71, v52, v1
	v_fma_f32 v246, -v73, v53, v246
	v_fma_f32 v1, -v75, v54, v1
	v_fma_f32 v246, -v77, v55, v246
	v_fma_f32 v1, -v79, v44, v1
	v_fma_f32 v246, -v81, v45, v246
	v_fma_f32 v1, -v83, v46, v1
	v_fma_f32 v246, -v85, v47, v246
	v_fma_f32 v1, -v87, v40, v1
	v_fma_f32 v246, -v89, v41, v246
	v_fma_f32 v1, -v91, v42, v1
	v_fma_f32 v246, -v66, v43, v246
	v_fma_f32 v1, -v68, v36, v1
	v_fma_f32 v246, -v70, v37, v246
	v_fma_f32 v1, -v72, v38, v1
	v_fma_f32 v246, -v74, v39, v246
	v_fma_f32 v1, -v76, v32, v1
	v_fma_f32 v246, -v78, v33, v246
	v_fma_f32 v1, -v80, v34, v1
	v_fma_f32 v246, -v82, v35, v246
	v_fma_f32 v1, -v84, v28, v1
	v_fma_f32 v246, -v86, v29, v246
	v_fma_f32 v1, -v88, v30, v1
	v_fma_f32 v246, -v90, v31, v246
	v_fma_f32 v1, -v109, v24, v1
	v_fma_f32 v246, -v110, v25, v246
	v_fma_f32 v1, -v111, v26, v1
	v_fma_f32 v246, -v112, v27, v246
	v_fma_f32 v1, -v113, v20, v1
	v_fma_f32 v246, -v114, v21, v246
	v_fma_f32 v1, -v115, v22, v1
	v_fma_f32 v246, -v116, v23, v246
	v_fma_f32 v1, -v117, v16, v1
	v_fma_f32 v246, -v118, v17, v246
	v_fma_f32 v1, -v119, v18, v1
	v_fma_f32 v246, -v120, v19, v246
	v_fma_f32 v1, -v121, v12, v1
	v_fma_f32 v246, -v122, v13, v246
	v_fma_f32 v1, -v123, v14, v1
	v_fma_f32 v246, -v124, v15, v246
	v_fma_f32 v1, -v125, v8, v1
	v_fma_f32 v246, -v126, v9, v246
	v_fma_f32 v1, -v127, v10, v1
	v_fma_f32 v246, -v137, v11, v246
	v_fma_f32 v1, -v139, v4, v1
	v_fma_f32 v246, -v140, v5, v246
	v_fma_f32 v1, -v142, v6, v1
	v_fma_f32 v246, -v92, v7, v246
	s_and_b64 vcc, exec, s[52:53]
	v_fma_f32 v94, -v93, v0, v1
	v_add_f32_e32 v94, v94, v246
	s_cbranch_vccnz .LBB0_613
	v_cvt_pk_bf16_f32 v0, v94, s0
	global_store_short v[56:57], v0, off

; __device__ __forceinline__ bf16_t f2bf(float f) { return (bf16_t)(cvt_pk_bf16(f, 0.f) & 0xffffu); }
; __device__ __forceinline__ float bf2f(bf16_t b) { return __uint_as_float(((unsigned)b) << 16); }
; template <int I>
; __device__ __forceinline__ void solve_rows(float (&x)[64], const f32x4* A4, const bf16_t* src, const float* sBeta, const float* sGam, int part, bf16_t* dst, int nvalid) {
;     ...
;         for (int q = 0; q < (I + 3) / 4; ++q) a4[q] = A4[I * 16 + q];
;         float a = bf2f(src[I * 136]) * sBeta[I];
;         if (part == 1) a *= __expf(sGam[I]);
; #pragma unroll
;         for (int j = 0; j < I; ++j) a -= a4[j >> 2][j & 3] * x[j];
;         x[I] = a;
;         if (I < nvalid) *dst = f2bf(a);
.LBB0_615:
	v_fma_f32 v2, -v64, v48, v2
	v_mul_f32_e64 v246, -v65, v49
	v_fma_f32 v2, -v67, v50, v2
	v_fma_f32 v246, -v69, v51, v246
	v_fma_f32 v2, -v71, v52, v2
	v_fma_f32 v246, -v73, v53, v246
	v_fma_f32 v2, -v75, v54, v2
	v_fma_f32 v246, -v77, v55, v246
	v_fma_f32 v2, -v79, v44, v2
	v_fma_f32 v246, -v81, v45, v246
	v_fma_f32 v2, -v83, v46, v2
	v_fma_f32 v246, -v85, v47, v246
	v_fma_f32 v2, -v87, v40, v2
	v_fma_f32 v246, -v89, v41, v246
	v_fma_f32 v2, -v91, v42, v2
	v_fma_f32 v246, -v66, v43, v246
	v_fma_f32 v2, -v68, v36, v2
	v_fma_f32 v246, -v70, v37, v246
	v_fma_f32 v2, -v72, v38, v2
	v_fma_f32 v246, -v74, v39, v246
	v_fma_f32 v2, -v76, v32, v2
	v_fma_f32 v246, -v78, v33, v246
	v_fma_f32 v2, -v80, v34, v2
	v_fma_f32 v246, -v82, v35, v246
	v_fma_f32 v2, -v84, v28, v2
	v_fma_f32 v246, -v86, v29, v246
	v_fma_f32 v2, -v88, v30, v2
	v_fma_f32 v246, -v90, v31, v246
	v_fma_f32 v2, -v109, v24, v2
	v_fma_f32 v246, -v110, v25, v246
	v_fma_f32 v2, -v111, v26, v2
	v_fma_f32 v246, -v112, v27, v246
	v_fma_f32 v2, -v113, v20, v2
	v_fma_f32 v246, -v114, v21, v246
	v_fma_f32 v2, -v115, v22, v2
	v_fma_f32 v246, -v116, v23, v246
	v_fma_f32 v2, -v117, v16, v2
	v_fma_f32 v246, -v118, v17, v246
	v_fma_f32 v2, -v119, v18, v2
	v_fma_f32 v246, -v120, v19, v246
	v_fma_f32 v2, -v121, v12, v2
	v_fma_f32 v246, -v122, v13, v246
	v_fma_f32 v2, -v123, v14, v2
	v_fma_f32 v246, -v124, v15, v246
	v_fma_f32 v2, -v125, v8, v2
	v_fma_f32 v246, -v126, v9, v246
	v_fma_f32 v2, -v127, v10, v2
	v_fma_f32 v246, -v137, v11, v246
	v_fma_f32 v2, -v139, v4, v2
	v_fma_f32 v246, -v140, v5, v246
	v_fma_f32 v2, -v142, v6, v2
	v_fma_f32 v246, -v92, v7, v246
	v_fma_f32 v0, -v93, v0, v2
	s_and_b64 vcc, exec, s[52:53]
	v_fma_f32 v246, -v94, v1, v246
	v_add_f32_e32 v95, v0, v246
	s_cbranch_vccnz .LBB0_617
	v_cvt_pk_bf16_f32 v0, v95, s0
	global_store_short v[56:57], v0, off

; __device__ __forceinline__ bf16_t f2bf(float f) { return (bf16_t)(cvt_pk_bf16(f, 0.f) & 0xffffu); }
; __device__ __forceinline__ float bf2f(bf16_t b) { return __uint_as_float(((unsigned)b) << 16); }
; template <int I>
; __device__ __forceinline__ void solve_rows(float (&x)[64], const f32x4* A4, const bf16_t* src, const float* sBeta, const float* sGam, int part, bf16_t* dst, int nvalid) {
;     ...
;         for (int q = 0; q < (I + 3) / 4; ++q) a4[q] = A4[I * 16 + q];
;         float a = bf2f(src[I * 136]) * sBeta[I];
;         if (part == 1) a *= __expf(sGam[I]);
; #pragma unroll
;         for (int j = 0; j < I; ++j) a -= a4[j >> 2][j & 3] * x[j];
;         x[I] = a;
;         if (I < nvalid) *dst = f2bf(a);
.LBB0_619:
	v_fma_f32 v7, -v64, v52, v7
	v_mul_f32_e64 v246, -v65, v53
	v_fma_f32 v7, -v67, v54, v7
	v_fma_f32 v246, -v69, v55, v246
	v_fma_f32 v7, -v71, v48, v7
	v_fma_f32 v246, -v73, v49, v246
	v_fma_f32 v7, -v75, v50, v7
	v_fma_f32 v246, -v77, v51, v246
	v_fma_f32 v7, -v79, v44, v7
	v_fma_f32 v246, -v81, v45, v246
	v_fma_f32 v7, -v83, v46, v7
	v_fma_f32 v246, -v85, v47, v246
	v_fma_f32 v7, -v87, v40, v7
	v_fma_f32 v246, -v89, v41, v246
	v_fma_f32 v7, -v91, v42, v7
	v_fma_f32 v246, -v66, v43, v246
	v_fma_f32 v7, -v68, v36, v7
	v_fma_f32 v246, -v70, v37, v246
	v_fma_f32 v7, -v72, v38, v7
	v_fma_f32 v246, -v74, v39, v246
	v_fma_f32 v7, -v76, v32, v7
	v_fma_f32 v246, -v78, v33, v246
	v_fma_f32 v7, -v80, v34, v7
	v_fma_f32 v246, -v82, v35, v246
	v_fma_f32 v7, -v84, v28, v7
	v_fma_f32 v246, -v86, v29, v246
	v_fma_f32 v7, -v88, v30, v7
	v_fma_f32 v246, -v90, v31, v246
	v_fma_f32 v7, -v109, v24, v7
	v_fma_f32 v246, -v110, v25, v246
	v_fma_f32 v7, -v111, v26, v7
	v_fma_f32 v246, -v112, v27, v246
	v_fma_f32 v7, -v113, v20, v7
	v_fma_f32 v246, -v114, v21, v246
	v_fma_f32 v7, -v115, v22, v7
	v_fma_f32 v246, -v116, v23, v246
	v_fma_f32 v7, -v117, v16, v7
	v_fma_f32 v246, -v118, v17, v246
	v_fma_f32 v7, -v119, v18, v7
	v_fma_f32 v246, -v120, v19, v246
	v_fma_f32 v7, -v121, v12, v7
	v_fma_f32 v246, -v122, v13, v246
	v_fma_f32 v7, -v123, v14, v7
	v_fma_f32 v246, -v124, v15, v246
	v_fma_f32 v7, -v125, v8, v7
	v_fma_f32 v246, -v126, v9, v246
	v_fma_f32 v7, -v127, v10, v7
	v_fma_f32 v246, -v137, v11, v246
	v_fma_f32 v0, -v139, v0, v7
	v_fma_f32 v246, -v140, v1, v246
	v_fma_f32 v0, -v142, v2, v0
	v_fma_f32 v246, -v92, v3, v246
	v_fma_f32 v0, -v93, v4, v0
	v_fma_f32 v246, -v94, v5, v246
	s_and_b64 vcc, exec, s[52:53]
	v_fma_f32 v96, -v95, v6, v0
	v_add_f32_e32 v96, v96, v246
	s_cbranch_vccnz .LBB0_621
	v_cvt_pk_bf16_f32 v0, v96, s0
	global_store_short v[56:57], v0, off

; __device__ __forceinline__ bf16_t f2bf(float f) { return (bf16_t)(cvt_pk_bf16(f, 0.f) & 0xffffu); }
; __device__ __forceinline__ float bf2f(bf16_t b) { return __uint_as_float(((unsigned)b) << 16); }
; template <int I>
; __device__ __forceinline__ void solve_rows(float (&x)[64], const f32x4* A4, const bf16_t* src, const float* sBeta, const float* sGam, int part, bf16_t* dst, int nvalid) {
;     ...
;         for (int q = 0; q < (I + 3) / 4; ++q) a4[q] = A4[I * 16 + q];
;         float a = bf2f(src[I * 136]) * sBeta[I];
;         if (part == 1) a *= __expf(sGam[I]);
; #pragma unroll
;         for (int j = 0; j < I; ++j) a -= a4[j >> 2][j & 3] * x[j];
;         x[I] = a;
;         if (I < nvalid) *dst = f2bf(a);
.LBB0_623:
	v_fma_f32 v52, -v64, v52, v58
	v_mul_f32_e64 v246, -v65, v53
	v_fma_f32 v52, -v67, v54, v52
	v_fma_f32 v246, -v69, v55, v246
	v_fma_f32 v48, -v71, v48, v52
	v_fma_f32 v246, -v73, v49, v246
	v_fma_f32 v48, -v75, v50, v48
	v_fma_f32 v246, -v77, v51, v246
	v_fma_f32 v44, -v79, v44, v48
	v_fma_f32 v246, -v81, v45, v246
	v_fma_f32 v44, -v83, v46, v44
	v_fma_f32 v246, -v85, v47, v246
	v_fma_f32 v40, -v87, v40, v44
	v_fma_f32 v246, -v89, v41, v246
	v_fma_f32 v40, -v91, v42, v40
	v_fma_f32 v246, -v66, v43, v246
	v_fma_f32 v36, -v68, v36, v40
	v_fma_f32 v246, -v70, v37, v246
	v_fma_f32 v36, -v72, v38, v36
	v_fma_f32 v246, -v74, v39, v246
	v_fma_f32 v32, -v76, v32, v36
	v_fma_f32 v246, -v78, v33, v246
	v_fma_f32 v32, -v80, v34, v32
	v_fma_f32 v246, -v82, v35, v246
	v_fma_f32 v28, -v84, v28, v32
	v_fma_f32 v246, -v86, v29, v246
	v_fma_f32 v28, -v88, v30, v28
	v_fma_f32 v246, -v90, v31, v246
	v_fma_f32 v24, -v109, v24, v28
	v_fma_f32 v246, -v110, v25, v246
	v_fma_f32 v24, -v111, v26, v24
	v_fma_f32 v246, -v112, v27, v246
	v_fma_f32 v20, -v113, v20, v24
	v_fma_f32 v246, -v114, v21, v246
	v_fma_f32 v20, -v115, v22, v20
	v_fma_f32 v246, -v116, v23, v246
	v_fma_f32 v16, -v117, v16, v20
	v_fma_f32 v246, -v118, v17, v246
	v_fma_f32 v16, -v119, v18, v16
	v_fma_f32 v246, -v120, v19, v246
	v_fma_f32 v12, -v121, v12, v16
	v_fma_f32 v246, -v122, v13, v246
	v_fma_f32 v12, -v123, v14, v12
	v_fma_f32 v246, -v124, v15, v246
	v_fma_f32 v8, -v125, v8, v12
	v_fma_f32 v246, -v126, v9, v246
	v_fma_f32 v8, -v127, v10, v8
	v_fma_f32 v246, -v137, v11, v246
	v_fma_f32 v0, -v139, v0, v8
	v_fma_f32 v246, -v140, v1, v246
	v_fma_f32 v0, -v142, v2, v0
	v_fma_f32 v246, -v92, v3, v246
	v_fma_f32 v0, -v93, v4, v0
	v_fma_f32 v246, -v94, v5, v246
	v_fma_f32 v0, -v95, v6, v0
	s_and_b64 vcc, exec, s[52:53]
	v_fma_f32 v246, -v96, v7, v246
	v_add_f32_e32 v97, v0, v246
	s_cbranch_vccnz .LBB0_625
	v_cvt_pk_bf16_f32 v0, v97, s0
	global_store_short v[56:57], v0, off

; __device__ __forceinline__ bf16_t f2bf(float f) { return (bf16_t)(cvt_pk_bf16(f, 0.f) & 0xffffu); }
; __device__ __forceinline__ float bf2f(bf16_t b) { return __uint_as_float(((unsigned)b) << 16); }
; template <int I>
; __device__ __forceinline__ void solve_rows(float (&x)[64], const f32x4* A4, const bf16_t* src, const float* sBeta, const float* sGam, int part, bf16_t* dst, int nvalid) {
;     ...
;         for (int q = 0; q < (I + 3) / 4; ++q) a4[q] = A4[I * 16 + q];
;         float a = bf2f(src[I * 136]) * sBeta[I];
;         if (part == 1) a *= __expf(sGam[I]);
; #pragma unroll
;         for (int j = 0; j < I; ++j) a -= a4[j >> 2][j & 3] * x[j];
;         x[I] = a;
;         if (I < nvalid) *dst = f2bf(a);
.LBB0_627:
	v_fma_f32 v1, -v64, v52, v1
	v_mul_f32_e64 v246, -v65, v53
	v_fma_f32 v1, -v67, v54, v1
	v_fma_f32 v246, -v69, v55, v246
	v_fma_f32 v1, -v71, v56, v1
	v_fma_f32 v246, -v73, v57, v246
	v_fma_f32 v1, -v75, v58, v1
	v_fma_f32 v246, -v77, v59, v246
	v_fma_f32 v1, -v79, v48, v1
	v_fma_f32 v246, -v81, v49, v246
	v_fma_f32 v1, -v83, v50, v1
	v_fma_f32 v246, -v85, v51, v246
	v_fma_f32 v1, -v87, v44, v1
	v_fma_f32 v246, -v89, v45, v246
	v_fma_f32 v1, -v91, v46, v1
	v_fma_f32 v246, -v66, v47, v246
	v_fma_f32 v1, -v68, v40, v1
	v_fma_f32 v246, -v70, v41, v246
	v_fma_f32 v1, -v72, v42, v1
	v_fma_f32 v246, -v74, v43, v246
	v_fma_f32 v1, -v76, v36, v1
	v_fma_f32 v246, -v78, v37, v246
	v_fma_f32 v1, -v80, v38, v1
	v_fma_f32 v246, -v82, v39, v246
	v_fma_f32 v1, -v84, v32, v1
	v_fma_f32 v246, -v86, v33, v246
	v_fma_f32 v1, -v88, v34, v1
	v_fma_f32 v246, -v90, v35, v246
	v_fma_f32 v1, -v109, v28, v1
	v_fma_f32 v246, -v110, v29, v246
	v_fma_f32 v1, -v111, v30, v1
	v_fma_f32 v246, -v112, v31, v246
	v_fma_f32 v1, -v113, v24, v1
	v_fma_f32 v246, -v114, v25, v246
	v_fma_f32 v1, -v115, v26, v1
	v_fma_f32 v246, -v116, v27, v246
	v_fma_f32 v1, -v117, v20, v1
	v_fma_f32 v246, -v118, v21, v246
	v_fma_f32 v1, -v119, v22, v1
	v_fma_f32 v246, -v120, v23, v246
	v_fma_f32 v1, -v121, v16, v1
	v_fma_f32 v246, -v122, v17, v246
	v_fma_f32 v1, -v123, v18, v1
	v_fma_f32 v246, -v124, v19, v246
	v_fma_f32 v1, -v125, v12, v1
	v_fma_f32 v246, -v126, v13, v246
	v_fma_f32 v1, -v127, v14, v1
	v_fma_f32 v246, -v137, v15, v246
	v_fma_f32 v1, -v139, v8, v1
	v_fma_f32 v246, -v140, v9, v246
	v_fma_f32 v1, -v142, v10, v1
	v_fma_f32 v246, -v92, v11, v246
	v_fma_f32 v1, -v93, v4, v1
	v_fma_f32 v246, -v94, v5, v246
	v_fma_f32 v1, -v95, v6, v1
	v_fma_f32 v246, -v96, v7, v246
	s_and_b64 vcc, exec, s[52:53]
	v_fma_f32 v98, -v97, v0, v1
	v_add_f32_e32 v98, v98, v246
	s_cbranch_vccnz .LBB0_629
	v_cvt_pk_bf16_f32 v0, v98, s0
	global_store_short v[60:61], v0, off

; __device__ __forceinline__ bf16_t f2bf(float f) { return (bf16_t)(cvt_pk_bf16(f, 0.f) & 0xffffu); }
; __device__ __forceinline__ float bf2f(bf16_t b) { return __uint_as_float(((unsigned)b) << 16); }
; template <int I>
; __device__ __forceinline__ void solve_rows(float (&x)[64], const f32x4* A4, const bf16_t* src, const float* sBeta, const float* sGam, int part, bf16_t* dst, int nvalid) {
;     ...
;         for (int q = 0; q < (I + 3) / 4; ++q) a4[q] = A4[I * 16 + q];
;         float a = bf2f(src[I * 136]) * sBeta[I];
;         if (part == 1) a *= __expf(sGam[I]);
; #pragma unroll
;         for (int j = 0; j < I; ++j) a -= a4[j >> 2][j & 3] * x[j];
;         x[I] = a;
;         if (I < nvalid) *dst = f2bf(a);
.LBB0_631:
	v_fma_f32 v2, -v64, v52, v2
	v_mul_f32_e64 v246, -v65, v53
	v_fma_f32 v2, -v67, v54, v2
	v_fma_f32 v246, -v69, v55, v246
	v_fma_f32 v2, -v71, v56, v2
	v_fma_f32 v246, -v73, v57, v246
	v_fma_f32 v2, -v75, v58, v2
	v_fma_f32 v246, -v77, v59, v246
	v_fma_f32 v2, -v79, v48, v2
	v_fma_f32 v246, -v81, v49, v246
	v_fma_f32 v2, -v83, v50, v2
	v_fma_f32 v246, -v85, v51, v246
	v_fma_f32 v2, -v87, v44, v2
	v_fma_f32 v246, -v89, v45, v246
	v_fma_f32 v2, -v91, v46, v2
	v_fma_f32 v246, -v66, v47, v246
	v_fma_f32 v2, -v68, v40, v2
	v_fma_f32 v246, -v70, v41, v246
	v_fma_f32 v2, -v72, v42, v2
	v_fma_f32 v246, -v74, v43, v246
	v_fma_f32 v2, -v76, v36, v2
	v_fma_f32 v246, -v78, v37, v246
	v_fma_f32 v2, -v80, v38, v2
	v_fma_f32 v246, -v82, v39, v246
	v_fma_f32 v2, -v84, v32, v2
	v_fma_f32 v246, -v86, v33, v246
	v_fma_f32 v2, -v88, v34, v2
	v_fma_f32 v246, -v90, v35, v246
	v_fma_f32 v2, -v109, v28, v2
	v_fma_f32 v246, -v110, v29, v246
	v_fma_f32 v2, -v111, v30, v2
	v_fma_f32 v246, -v112, v31, v246
	v_fma_f32 v2, -v113, v24, v2
	v_fma_f32 v246, -v114, v25, v246
	v_fma_f32 v2, -v115, v26, v2
	v_fma_f32 v246, -v116, v27, v246
	v_fma_f32 v2, -v117, v20, v2
	v_fma_f32 v246, -v118, v21, v246
	v_fma_f32 v2, -v119, v22, v2
	v_fma_f32 v246, -v120, v23, v246
	v_fma_f32 v2, -v121, v16, v2
	v_fma_f32 v246, -v122, v17, v246
	v_fma_f32 v2, -v123, v18, v2
	v_fma_f32 v246, -v124, v19, v246
	v_fma_f32 v2, -v125, v12, v2
	v_fma_f32 v246, -v126, v13, v246
	v_fma_f32 v2, -v127, v14, v2
	v_fma_f32 v246, -v137, v15, v246
	v_fma_f32 v2, -v139, v8, v2
	v_fma_f32 v246, -v140, v9, v246
	v_fma_f32 v2, -v142, v10, v2
	v_fma_f32 v246, -v92, v11, v246
	v_fma_f32 v2, -v93, v4, v2
	v_fma_f32 v246, -v94, v5, v246
	v_fma_f32 v2, -v95, v6, v2
	v_fma_f32 v246, -v96, v7, v246
	v_fma_f32 v0, -v97, v0, v2
	s_and_b64 vcc, exec, s[52:53]
	v_fma_f32 v246, -v98, v1, v246
	v_add_f32_e32 v99, v0, v246
	s_cbranch_vccnz .LBB0_633
	v_cvt_pk_bf16_f32 v0, v99, s0
	global_store_short v[60:61], v0, off

; __device__ __forceinline__ bf16_t f2bf(float f) { return (bf16_t)(cvt_pk_bf16(f, 0.f) & 0xffffu); }
; __device__ __forceinline__ float bf2f(bf16_t b) { return __uint_as_float(((unsigned)b) << 16); }
; template <int I>
; __device__ __forceinline__ void solve_rows(float (&x)[64], const f32x4* A4, const bf16_t* src, const float* sBeta, const float* sGam, int part, bf16_t* dst, int nvalid) {
;     ...
;         for (int q = 0; q < (I + 3) / 4; ++q) a4[q] = A4[I * 16 + q];
;         float a = bf2f(src[I * 136]) * sBeta[I];
;         if (part == 1) a *= __expf(sGam[I]);
; #pragma unroll
;         for (int j = 0; j < I; ++j) a -= a4[j >> 2][j & 3] * x[j];
;         x[I] = a;
;         if (I < nvalid) *dst = f2bf(a);
.LBB0_635:
	v_fma_f32 v3, -v64, v56, v3
	v_mul_f32_e64 v246, -v65, v57
	v_fma_f32 v3, -v67, v58, v3
	v_fma_f32 v246, -v69, v59, v246
	v_fma_f32 v3, -v71, v52, v3
	v_fma_f32 v246, -v73, v53, v246
	v_fma_f32 v3, -v75, v54, v3
	v_fma_f32 v246, -v77, v55, v246
	v_fma_f32 v3, -v79, v48, v3
	v_fma_f32 v246, -v81, v49, v246
	v_fma_f32 v3, -v83, v50, v3
	v_fma_f32 v246, -v85, v51, v246
	v_fma_f32 v3, -v87, v44, v3
	v_fma_f32 v246, -v89, v45, v246
	v_fma_f32 v3, -v91, v46, v3
	v_fma_f32 v246, -v66, v47, v246
	v_fma_f32 v3, -v68, v40, v3
	v_fma_f32 v246, -v70, v41, v246
	v_fma_f32 v3, -v72, v42, v3
	v_fma_f32 v246, -v74, v43, v246
	v_fma_f32 v3, -v76, v36, v3
	v_fma_f32 v246, -v78, v37, v246
	v_fma_f32 v3, -v80, v38, v3
	v_fma_f32 v246, -v82, v39, v246
	v_fma_f32 v3, -v84, v32, v3
	v_fma_f32 v246, -v86, v33, v246
	v_fma_f32 v3, -v88, v34, v3
	v_fma_f32 v246, -v90, v35, v246
	v_fma_f32 v3, -v109, v28, v3
	v_fma_f32 v246, -v110, v29, v246
	v_fma_f32 v3, -v111, v30, v3
	v_fma_f32 v246, -v112, v31, v246
	v_fma_f32 v3, -v113, v24, v3
	v_fma_f32 v246, -v114, v25, v246
	v_fma_f32 v3, -v115, v26, v3
	v_fma_f32 v246, -v116, v27, v246
	v_fma_f32 v3, -v117, v20, v3
	v_fma_f32 v246, -v118, v21, v246
	v_fma_f32 v3, -v119, v22, v3
	v_fma_f32 v246, -v120, v23, v246
	v_fma_f32 v3, -v121, v16, v3
	v_fma_f32 v246, -v122, v17, v246
	v_fma_f32 v3, -v123, v18, v3
	v_fma_f32 v246, -v124, v19, v246
	v_fma_f32 v3, -v125, v8, v3
	v_fma_f32 v246, -v126, v9, v246
	v_fma_f32 v3, -v127, v10, v3
	v_fma_f32 v246, -v137, v11, v246
	v_fma_f32 v3, -v139, v4, v3
	v_fma_f32 v246, -v140, v5, v246
	v_fma_f32 v3, -v142, v6, v3
	v_fma_f32 v246, -v92, v7, v246
	v_fma_f32 v3, -v93, v12, v3
	v_fma_f32 v246, -v94, v13, v246
	v_fma_f32 v3, -v95, v14, v3
	v_fma_f32 v246, -v96, v15, v246
	v_fma_f32 v0, -v97, v0, v3
	v_fma_f32 v246, -v98, v1, v246
	s_and_b64 vcc, exec, s[52:53]
	v_fma_f32 v100, -v99, v2, v0
	v_add_f32_e32 v100, v100, v246
	s_cbranch_vccnz .LBB0_637
	v_cvt_pk_bf16_f32 v0, v100, s0
	global_store_short v[60:61], v0, off

; __device__ __forceinline__ bf16_t f2bf(float f) { return (bf16_t)(cvt_pk_bf16(f, 0.f) & 0xffffu); }
; __device__ __forceinline__ float bf2f(bf16_t b) { return __uint_as_float(((unsigned)b) << 16); }
; template <int I>
; __device__ __forceinline__ void solve_rows(float (&x)[64], const f32x4* A4, const bf16_t* src, const float* sBeta, const float* sGam, int part, bf16_t* dst, int nvalid) {
;     ...
;         for (int q = 0; q < (I + 3) / 4; ++q) a4[q] = A4[I * 16 + q];
;         float a = bf2f(src[I * 136]) * sBeta[I];
;         if (part == 1) a *= __expf(sGam[I]);
; #pragma unroll
;         for (int j = 0; j < I; ++j) a -= a4[j >> 2][j & 3] * x[j];
;         x[I] = a;
;         if (I < nvalid) *dst = f2bf(a);
.LBB0_639:
	v_fma_f32 v56, -v64, v56, v62
	v_mul_f32_e64 v246, -v65, v57
	v_fma_f32 v56, -v67, v58, v56
	v_fma_f32 v246, -v69, v59, v246
	v_fma_f32 v52, -v71, v52, v56
	v_fma_f32 v246, -v73, v53, v246
	v_fma_f32 v52, -v75, v54, v52
	v_fma_f32 v246, -v77, v55, v246
	v_fma_f32 v48, -v79, v48, v52
	v_fma_f32 v246, -v81, v49, v246
	v_fma_f32 v48, -v83, v50, v48
	v_fma_f32 v246, -v85, v51, v246
	v_fma_f32 v44, -v87, v44, v48
	v_fma_f32 v246, -v89, v45, v246
	v_fma_f32 v44, -v91, v46, v44
	v_fma_f32 v246, -v66, v47, v246
	v_fma_f32 v40, -v68, v40, v44
	v_fma_f32 v246, -v70, v41, v246
	v_fma_f32 v40, -v72, v42, v40
	v_fma_f32 v246, -v74, v43, v246
	v_fma_f32 v36, -v76, v36, v40
	v_fma_f32 v246, -v78, v37, v246
	v_fma_f32 v36, -v80, v38, v36
	v_fma_f32 v246, -v82, v39, v246
	v_fma_f32 v32, -v84, v32, v36
	v_fma_f32 v246, -v86, v33, v246
	v_fma_f32 v32, -v88, v34, v32
	v_fma_f32 v246, -v90, v35, v246
	v_fma_f32 v28, -v109, v28, v32
	v_fma_f32 v246, -v110, v29, v246
	v_fma_f32 v28, -v111, v30, v28
	v_fma_f32 v246, -v112, v31, v246
	v_fma_f32 v24, -v113, v24, v28
	v_fma_f32 v246, -v114, v25, v246
	v_fma_f32 v24, -v115, v26, v24
	v_fma_f32 v246, -v116, v27, v246
	v_fma_f32 v20, -v117, v20, v24
	v_fma_f32 v246, -v118, v21, v246
	v_fma_f32 v20, -v119, v22, v20
	v_fma_f32 v246, -v120, v23, v246
	v_fma_f32 v16, -v121, v16, v20
	v_fma_f32 v246, -v122, v17, v246
	v_fma_f32 v16, -v123, v18, v16
	v_fma_f32 v246, -v124, v19, v246
	v_fma_f32 v8, -v125, v8, v16
	v_fma_f32 v246, -v126, v9, v246
	v_fma_f32 v8, -v127, v10, v8
	v_fma_f32 v246, -v137, v11, v246
	v_fma_f32 v4, -v139, v4, v8
	v_fma_f32 v246, -v140, v5, v246
	v_fma_f32 v4, -v142, v6, v4
	v_fma_f32 v246, -v92, v7, v246
	v_fma_f32 v4, -v93, v12, v4
	v_fma_f32 v246, -v94, v13, v246
	v_fma_f32 v4, -v95, v14, v4
	v_fma_f32 v246, -v96, v15, v246
	v_fma_f32 v0, -v97, v0, v4
	v_fma_f32 v246, -v98, v1, v246
	v_fma_f32 v0, -v99, v2, v0
	s_and_b64 vcc, exec, s[52:53]
	v_fma_f32 v246, -v100, v3, v246
	v_add_f32_e32 v101, v0, v246
	s_cbranch_vccnz .LBB0_641
	v_cvt_pk_bf16_f32 v0, v101, s0
	global_store_short v[60:61], v0, off

; __device__ __forceinline__ bf16_t f2bf(float f) { return (bf16_t)(cvt_pk_bf16(f, 0.f) & 0xffffu); }
; __device__ __forceinline__ float bf2f(bf16_t b) { return __uint_as_float(((unsigned)b) << 16); }
; template <int I>
; __device__ __forceinline__ void solve_rows(float (&x)[64], const f32x4* A4, const bf16_t* src, const float* sBeta, const float* sGam, int part, bf16_t* dst, int nvalid) {
;     ...
;         for (int q = 0; q < (I + 3) / 4; ++q) a4[q] = A4[I * 16 + q];
;         float a = bf2f(src[I * 136]) * sBeta[I];
;         if (part == 1) a *= __expf(sGam[I]);
; #pragma unroll
;         for (int j = 0; j < I; ++j) a -= a4[j >> 2][j & 3] * x[j];
;         x[I] = a;
;         if (I < nvalid) *dst = f2bf(a);
.LBB0_643:
	v_fma_f32 v1, -v64, v56, v1
	v_mul_f32_e64 v246, -v65, v57
	v_fma_f32 v1, -v67, v58, v1
	v_fma_f32 v246, -v69, v59, v246
	v_fma_f32 v1, -v71, v60, v1
	v_fma_f32 v246, -v73, v61, v246
	v_fma_f32 v1, -v75, v62, v1
	v_fma_f32 v246, -v77, v63, v246
	v_fma_f32 v1, -v79, v52, v1
	v_fma_f32 v246, -v81, v53, v246
	v_fma_f32 v1, -v83, v54, v1
	v_fma_f32 v246, -v85, v55, v246
	v_fma_f32 v1, -v87, v48, v1
	v_fma_f32 v246, -v89, v49, v246
	v_fma_f32 v1, -v91, v50, v1
	v_fma_f32 v246, -v66, v51, v246
	v_fma_f32 v1, -v68, v44, v1
	v_fma_f32 v246, -v70, v45, v246
	v_fma_f32 v1, -v72, v46, v1
	v_fma_f32 v246, -v74, v47, v246
	v_fma_f32 v1, -v76, v40, v1
	v_fma_f32 v246, -v78, v41, v246
	v_fma_f32 v1, -v80, v42, v1
	v_fma_f32 v246, -v82, v43, v246
	v_fma_f32 v1, -v84, v36, v1
	v_fma_f32 v246, -v86, v37, v246
	v_fma_f32 v1, -v88, v38, v1
	v_fma_f32 v246, -v90, v39, v246
	v_fma_f32 v1, -v109, v32, v1
	v_fma_f32 v246, -v110, v33, v246
	v_fma_f32 v1, -v111, v34, v1
	v_fma_f32 v246, -v112, v35, v246
	v_fma_f32 v1, -v113, v28, v1
	v_fma_f32 v246, -v114, v29, v246
	v_fma_f32 v1, -v115, v30, v1
	v_fma_f32 v246, -v116, v31, v246
	v_fma_f32 v1, -v117, v24, v1
	v_fma_f32 v246, -v118, v25, v246
	v_fma_f32 v1, -v119, v26, v1
	v_fma_f32 v246, -v120, v27, v246
	v_fma_f32 v1, -v121, v20, v1
	v_fma_f32 v246, -v122, v21, v246
	v_fma_f32 v1, -v123, v22, v1
	v_fma_f32 v246, -v124, v23, v246
	v_fma_f32 v1, -v125, v16, v1
	v_fma_f32 v246, -v126, v17, v246
	v_fma_f32 v1, -v127, v18, v1
	v_fma_f32 v246, -v137, v19, v246
	v_fma_f32 v1, -v139, v12, v1
	v_fma_f32 v246, -v140, v13, v246
	v_fma_f32 v1, -v142, v14, v1
	v_fma_f32 v246, -v92, v15, v246
	v_fma_f32 v1, -v93, v8, v1
	v_fma_f32 v246, -v94, v9, v246
	v_fma_f32 v1, -v95, v10, v1
	v_fma_f32 v246, -v96, v11, v246
	v_fma_f32 v1, -v97, v4, v1
	v_fma_f32 v246, -v98, v5, v246
	v_fma_f32 v1, -v99, v6, v1
	v_fma_f32 v246, -v100, v7, v246
	s_and_b64 vcc, exec, s[52:53]
	v_fma_f32 v102, -v101, v0, v1
	v_add_f32_e32 v102, v102, v246
	s_cbranch_vccnz .LBB0_645
	v_cvt_pk_bf16_f32 v0, v102, s0
	global_store_short v[104:105], v0, off

; __device__ __forceinline__ bf16_t f2bf(float f) { return (bf16_t)(cvt_pk_bf16(f, 0.f) & 0xffffu); }
; __device__ __forceinline__ float bf2f(bf16_t b) { return __uint_as_float(((unsigned)b) << 16); }
; template <int I>
; __device__ __forceinline__ void solve_rows(float (&x)[64], const f32x4* A4, const bf16_t* src, const float* sBeta, const float* sGam, int part, bf16_t* dst, int nvalid) {
;     ...
;         for (int q = 0; q < (I + 3) / 4; ++q) a4[q] = A4[I * 16 + q];
;         float a = bf2f(src[I * 136]) * sBeta[I];
;         if (part == 1) a *= __expf(sGam[I]);
; #pragma unroll
;         for (int j = 0; j < I; ++j) a -= a4[j >> 2][j & 3] * x[j];
;         x[I] = a;
;         if (I < nvalid) *dst = f2bf(a);
.LBB0_647:
	v_fma_f32 v2, -v64, v56, v2
	v_mul_f32_e64 v246, -v65, v57
	v_fma_f32 v2, -v67, v58, v2
	v_fma_f32 v246, -v69, v59, v246
	v_fma_f32 v2, -v71, v60, v2
	v_fma_f32 v246, -v73, v61, v246
	v_fma_f32 v2, -v75, v62, v2
	v_fma_f32 v246, -v77, v63, v246
	v_fma_f32 v2, -v79, v52, v2
	v_fma_f32 v246, -v81, v53, v246
	v_fma_f32 v2, -v83, v54, v2
	v_fma_f32 v246, -v85, v55, v246
	v_fma_f32 v2, -v87, v48, v2
	v_fma_f32 v246, -v89, v49, v246
	v_fma_f32 v2, -v91, v50, v2
	v_fma_f32 v246, -v66, v51, v246
	v_fma_f32 v2, -v68, v44, v2
	v_fma_f32 v246, -v70, v45, v246
	v_fma_f32 v2, -v72, v46, v2
	v_fma_f32 v246, -v74, v47, v246
	v_fma_f32 v2, -v76, v40, v2
	v_fma_f32 v246, -v78, v41, v246
	v_fma_f32 v2, -v80, v42, v2
	v_fma_f32 v246, -v82, v43, v246
	v_fma_f32 v2, -v84, v36, v2
	v_fma_f32 v246, -v86, v37, v246
	v_fma_f32 v2, -v88, v38, v2
	v_fma_f32 v246, -v90, v39, v246
	v_fma_f32 v2, -v109, v32, v2
	v_fma_f32 v246, -v110, v33, v246
	v_fma_f32 v2, -v111, v34, v2
	v_fma_f32 v246, -v112, v35, v246
	v_fma_f32 v2, -v113, v28, v2
	v_fma_f32 v246, -v114, v29, v246
	v_fma_f32 v2, -v115, v30, v2
	v_fma_f32 v246, -v116, v31, v246
	v_fma_f32 v2, -v117, v24, v2
	v_fma_f32 v246, -v118, v25, v246
	v_fma_f32 v2, -v119, v26, v2
	v_fma_f32 v246, -v120, v27, v246
	v_fma_f32 v2, -v121, v20, v2
	v_fma_f32 v246, -v122, v21, v246
	v_fma_f32 v2, -v123, v22, v2
	v_fma_f32 v246, -v124, v23, v246
	v_fma_f32 v2, -v125, v16, v2
	v_fma_f32 v246, -v126, v17, v246
	v_fma_f32 v2, -v127, v18, v2
	v_fma_f32 v246, -v137, v19, v246
	v_fma_f32 v2, -v139, v12, v2
	v_fma_f32 v246, -v140, v13, v246
	v_fma_f32 v2, -v142, v14, v2
	v_fma_f32 v246, -v92, v15, v246
	v_fma_f32 v2, -v93, v8, v2
	v_fma_f32 v246, -v94, v9, v246
	v_fma_f32 v2, -v95, v10, v2
	v_fma_f32 v246, -v96, v11, v246
	v_fma_f32 v2, -v97, v4, v2
	v_fma_f32 v246, -v98, v5, v246
	v_fma_f32 v2, -v99, v6, v2
	v_fma_f32 v246, -v100, v7, v246
	v_fma_f32 v0, -v101, v0, v2
	s_and_b64 vcc, exec, s[52:53]
	v_fma_f32 v246, -v102, v1, v246
	v_add_f32_e32 v103, v0, v246
	s_cbranch_vccnz .LBB0_649
	v_cvt_pk_bf16_f32 v0, v103, s0
	global_store_short v[104:105], v0, off

; __device__ __forceinline__ bf16_t f2bf(float f) { return (bf16_t)(cvt_pk_bf16(f, 0.f) & 0xffffu); }
; __device__ __forceinline__ float bf2f(bf16_t b) { return __uint_as_float(((unsigned)b) << 16); }
; template <int I>
; __device__ __forceinline__ void solve_rows(float (&x)[64], const f32x4* A4, const bf16_t* src, const float* sBeta, const float* sGam, int part, bf16_t* dst, int nvalid) {
;     ...
;         for (int q = 0; q < (I + 3) / 4; ++q) a4[q] = A4[I * 16 + q];
;         float a = bf2f(src[I * 136]) * sBeta[I];
;         if (part == 1) a *= __expf(sGam[I]);
; #pragma unroll
;         for (int j = 0; j < I; ++j) a -= a4[j >> 2][j & 3] * x[j];
;         x[I] = a;
;         if (I < nvalid) *dst = f2bf(a);
.LBB0_651:
	s_and_b64 vcc, exec, s[52:53]
	s_cbranch_vccnz .LBB0_653
	v_fma_f32 v3, -v64, v60, v3
	v_mul_f32_e64 v246, -v65, v61
	v_fma_f32 v3, -v67, v62, v3
	v_fma_f32 v246, -v69, v63, v246
	v_fma_f32 v3, -v71, v56, v3
	v_fma_f32 v246, -v73, v57, v246
	v_fma_f32 v3, -v75, v58, v3
	v_fma_f32 v246, -v77, v59, v246
	v_fma_f32 v3, -v79, v52, v3
	v_fma_f32 v246, -v81, v53, v246
	v_fma_f32 v3, -v83, v54, v3
	v_fma_f32 v246, -v85, v55, v246
	v_fma_f32 v3, -v87, v48, v3
	v_fma_f32 v246, -v89, v49, v246
	v_fma_f32 v3, -v91, v50, v3
	v_fma_f32 v246, -v66, v51, v246
	v_fma_f32 v3, -v68, v44, v3
	v_fma_f32 v246, -v70, v45, v246
	v_fma_f32 v3, -v72, v46, v3
	v_fma_f32 v246, -v74, v47, v246
	v_fma_f32 v3, -v76, v40, v3
	v_fma_f32 v246, -v78, v41, v246
	v_fma_f32 v3, -v80, v42, v3
	v_fma_f32 v246, -v82, v43, v246
	v_fma_f32 v3, -v84, v36, v3
	v_fma_f32 v246, -v86, v37, v246
	v_fma_f32 v3, -v88, v38, v3
	v_fma_f32 v246, -v90, v39, v246
	v_fma_f32 v3, -v109, v32, v3
	v_fma_f32 v246, -v110, v33, v246
	v_fma_f32 v3, -v111, v34, v3
	v_fma_f32 v246, -v112, v35, v246
	v_fma_f32 v3, -v113, v28, v3
	v_fma_f32 v246, -v114, v29, v246
	v_fma_f32 v3, -v115, v30, v3
	v_fma_f32 v246, -v116, v31, v246
	v_fma_f32 v3, -v117, v24, v3
	v_fma_f32 v246, -v118, v25, v246
	v_fma_f32 v3, -v119, v26, v3
	v_fma_f32 v246, -v120, v27, v246
	v_fma_f32 v3, -v121, v20, v3
	v_fma_f32 v246, -v122, v21, v246
	v_fma_f32 v3, -v123, v22, v3
	v_fma_f32 v246, -v124, v23, v246
	v_fma_f32 v3, -v125, v16, v3
	v_fma_f32 v246, -v126, v17, v246
	v_fma_f32 v3, -v127, v18, v3
	v_fma_f32 v246, -v137, v19, v246
	v_fma_f32 v3, -v139, v12, v3
	v_fma_f32 v246, -v140, v13, v246
	v_add_f32_e32 v3, v3, v246
	v_pk_mov_b32 v[12:13], v[14:15], v[8:9] op_sel:[1,0]
	v_fma_f32 v3, -v142, v14, v3
	v_pk_mul_f32 v[12:13], v[92:93], v[12:13]
	v_mov_b32_e32 v8, v9
	v_sub_f32_e32 v3, v3, v12
	v_mov_b32_e32 v9, v10
	v_sub_f32_e32 v3, v3, v13
	v_pk_mul_f32 v[8:9], v[94:95], v[8:9]
	s_nop 0
	v_sub_f32_e32 v3, v3, v8
	v_sub_f32_e32 v3, v3, v9
	v_pk_mov_b32 v[8:9], v[10:11], v[4:5] op_sel:[1,0]
	v_mov_b32_e32 v4, v5
	v_pk_mul_f32 v[8:9], v[96:97], v[8:9]
	v_mov_b32_e32 v5, v6
	v_sub_f32_e32 v3, v3, v8
	v_sub_f32_e32 v3, v3, v9
	v_pk_mul_f32 v[4:5], v[98:99], v[4:5]
	s_nop 0
	v_sub_f32_e32 v3, v3, v4
	v_sub_f32_e32 v3, v3, v5
	v_pk_mov_b32 v[4:5], v[6:7], v[0:1] op_sel:[1,0]
	s_nop 0
	v_pk_mul_f32 v[4:5], v[100:101], v[4:5]
	s_nop 0
	v_sub_f32_e32 v0, v3, v4
	v_sub_f32_e32 v3, v0, v5
	v_mov_b32_e32 v0, v1
	v_mov_b32_e32 v1, v2
	v_pk_mul_f32 v[0:1], v[102:103], v[0:1]
	s_nop 0
	v_sub_f32_e32 v0, v3, v0
	v_sub_f32_e32 v0, v0, v1
	v_cvt_pk_bf16_f32 v0, v0, s0
	global_store_short v[104:105], v0, off

; #define INP(i) (*(const float* const __attribute__((address_space(4)))*)(ka_base() + 8 * (i)))
; #define OUTP() (*(float* const __attribute__((address_space(4)))*)(ka_base() + 8 * 21))
; #define WSP() (*(unsigned char* const __attribute__((address_space(4)))*)(ka_base() + 8 * 22))
; __device__ __forceinline__ unsigned cvt_pk_bf16(float lo, float hi) { const f32x2 v = {lo, hi}; const bf16v2_t b = __builtin_convertvector(v, bf16v2_t); return __builtin_bit_cast(unsigned, b); }
;     __device__ __forceinline__ void epi_up(const f32x4 (&acc)[2][2][4][2], const pg8::Unit& u, int wr, int wc, int fr, int fq) const {
;         bf16_t* act = (bf16_t*)(WSP() + WS_ACT); bf16_t* H = act; bf16_t* halo = (bf16_t*)(WSP() + WS_HALO); float* bg = (float*)(WSP() + WS_BG); float* out = OUTP();
;         const float* a_log = INP(11); const float* dt_bias = INP(12);
;         const int row0 = u.pm * 256 + wr * 64 + fr;
;         const int colt = u.pn * 256 + wc * 32 + 8 * fq;
;         float rstd8[2][4];
; #pragma unroll
;         for (int ai = 0; ai < 2; ++ai)
; #pragma unroll
;             for (int m = 0; m < 4; ++m) rstd8[ai][m] = rs[row0 + ai * 128 + m * 16];
; #pragma unroll
;         for (int ai = 0; ai < 2; ++ai)
; #pragma unroll
;             for (int m = 0; m < 4; ++m) rstd8[ai][m] = rsqrtf(rstd8[ai][m] * (1.0f / 1024.0f) + EPS);
; #pragma unroll
;         for (int ai = 0; ai < 2; ++ai)
; #pragma unroll
;             for (int m = 0; m < 4; ++m) {
;                 const int r = row0 + ai * 128 + m * 16;
;                     const float rstd = rstd8[ai][m];
;                     bf16_t* rowp = H + (size_t)r * 4096 + colt;
; #pragma unroll
;                     for (int bj = 0; bj < 2; ++bj) {
;                         f32x4 v0 = acc[ai][bj][m][0] * rstd, v1 = acc[ai][bj][m][1] * rstd;
; #pragma unroll
;                         for (int j = 0; j < 4; ++j) { v0[j] = fmaxf(v0[j], 0.f); v0[j] *= v0[j]; v1[j] = fmaxf(v1[j], 0.f); v1[j] *= v1[j]; }
;                         u32x4 w; w.x = cvt_pk_bf16(v0[0], v0[1]); w.y = cvt_pk_bf16(v0[2], v0[3]); w.z = cvt_pk_bf16(v1[0], v1[1]); w.w = cvt_pk_bf16(v1[2], v1[3]);
;                         *(u32x4*)(rowp + bj * 128) = w;
.LBB0_994:
	s_and_b64 vcc, exec, s[0:1]
	s_cbranch_vccz .LBB0_996
	v_readlane_b32 s6, v254, 34
	v_readlane_b32 s7, v254, 35
	s_mov_b64 s[0:1], s[6:7]
	s_load_dwordx2 s[4:5], s[0:1], 0xb0
	s_mov_b64 s[0:1], s[6:7]
	s_mov_b64 s[0:1], s[6:7]
	s_mov_b64 s[0:1], s[6:7]
	s_mov_b64 s[0:1], s[6:7]
	v_lshl_add_u32 v136, s13, 8, v239
	v_ashrrev_i32_e32 v137, 31, v136
	s_mov_b64 s[0:1], s[6:7]
	v_lshl_add_u64 v[128:129], v[136:137], 2, s[66:67]
	global_load_dword v130, v[128:129], off
	global_load_dword v131, v[128:129], off offset:64
	global_load_dword v132, v[128:129], off offset:128
	global_load_dword v133, v[128:129], off offset:192
	global_load_dword v134, v[128:129], off offset:512
	global_load_dword v135, v[128:129], off offset:576
	global_load_dword v139, v[128:129], off offset:640
	s_nop 0
	global_load_dword v128, v[128:129], off offset:704
	s_mov_b32 s0, 0x800000
	v_lshl_or_b32 v152, s88, 8, v245
	v_ashrrev_i32_e32 v153, 31, v152
	s_waitcnt lgkmcnt(0)
	v_lshl_add_u64 v[152:153], v[152:153], 1, s[4:5]
	v_or_b32_e32 v146, 16, v136
	v_or_b32_e32 v142, 32, v136
	v_or_b32_e32 v140, 48, v136
	v_lshlrev_b64 v[136:137], 13, v[136:137]
	v_ashrrev_i32_e32 v147, 31, v146
	v_lshlrev_b64 v[146:147], 13, v[146:147]
	v_ashrrev_i32_e32 v143, 31, v142
	v_lshlrev_b64 v[142:143], 13, v[142:143]
	v_ashrrev_i32_e32 v141, 31, v140
	v_lshlrev_b64 v[140:141], 13, v[140:141]
	s_waitcnt vmcnt(0)
	v_fmamk_f32 v129, v130, 0x3a800000, v237
	v_cmp_gt_f32_e32 vcc, s0, v129
	v_mul_f32_e32 v130, 0x4b800000, v129
	v_fmamk_f32 v128, v128, 0x3a800000, v237
	v_cndmask_b32_e32 v129, v129, v130, vcc
	v_rsq_f32_e32 v129, v129
	s_nop 0
	v_mul_f32_e32 v130, 0x45800000, v129
	v_cndmask_b32_e32 v150, v129, v130, vcc
	v_fmamk_f32 v129, v131, 0x3a800000, v237
	v_cmp_gt_f32_e32 vcc, s0, v129
	v_mul_f32_e32 v130, 0x4b800000, v129
	v_pk_mul_f32 v[154:155], v[118:119], v[150:151] op_sel_hi:[1,0]
	v_cndmask_b32_e32 v129, v129, v130, vcc
	v_rsq_f32_e32 v129, v129
	v_pk_mul_f32 v[156:157], v[116:117], v[150:151] op_sel_hi:[1,0]
	v_pk_mul_f32 v[158:159], v[114:115], v[150:151] op_sel_hi:[1,0]
	v_pk_mul_f32 v[160:161], v[112:113], v[150:151] op_sel_hi:[1,0]
	v_mul_f32_e32 v130, 0x45800000, v129
	v_cndmask_b32_e32 v148, v129, v130, vcc
	v_fmamk_f32 v129, v132, 0x3a800000, v237
	v_cmp_gt_f32_e32 vcc, s0, v129
	v_mul_f32_e32 v130, 0x4b800000, v129
	v_max_f32_e32 v156, 0, v156
	v_cndmask_b32_e32 v129, v129, v130, vcc
	v_rsq_f32_e32 v129, v129
	v_max_f32_e32 v160, 0, v160
	v_max_f32_e32 v157, 0, v157
	v_max_f32_e32 v161, 0, v161
	v_mul_f32_e32 v130, 0x45800000, v129
	v_cndmask_b32_e32 v144, v129, v130, vcc
	v_fmamk_f32 v129, v133, 0x3a800000, v237
	v_cmp_gt_f32_e32 vcc, s0, v129
	v_mul_f32_e32 v130, 0x4b800000, v129
	v_max_f32_e32 v154, 0, v154
	v_cndmask_b32_e32 v129, v129, v130, vcc
	v_rsq_f32_e32 v129, v129
	v_max_f32_e32 v158, 0, v158
	v_max_f32_e32 v155, 0, v155
	v_max_f32_e32 v159, 0, v159
	v_mul_f32_e32 v130, 0x45800000, v129
	v_cndmask_b32_e32 v138, v129, v130, vcc
	v_fmamk_f32 v129, v134, 0x3a800000, v237
	v_cmp_gt_f32_e32 vcc, s0, v129
	v_mul_f32_e32 v130, 0x4b800000, v129
	v_pk_mul_f32 v[156:157], v[156:157], v[156:157]
	v_cndmask_b32_e32 v129, v129, v130, vcc
	v_rsq_f32_e32 v129, v129
	v_pk_mul_f32 v[160:161], v[160:161], v[160:161]
	v_pk_mul_f32 v[162:163], v[154:155], v[154:155]
	v_pk_mul_f32 v[158:159], v[158:159], v[158:159]
	v_mul_f32_e32 v130, 0x45800000, v129
	v_cndmask_b32_e32 v134, v129, v130, vcc
	v_fmamk_f32 v129, v135, 0x3a800000, v237
	v_cmp_gt_f32_e32 vcc, s0, v129
	v_mul_f32_e32 v130, 0x4b800000, v129
	v_cvt_pk_bf16_f32 v154, v156, v157
	v_cndmask_b32_e32 v129, v129, v130, vcc
	v_rsq_f32_e32 v129, v129
	v_cvt_pk_bf16_f32 v155, v162, v163
	v_cvt_pk_bf16_f32 v156, v160, v161
	v_cvt_pk_bf16_f32 v157, v158, v159
	v_mul_f32_e32 v130, 0x45800000, v129
	v_cndmask_b32_e32 v132, v129, v130, vcc
	v_fmamk_f32 v129, v139, 0x3a800000, v237
	v_cmp_gt_f32_e32 vcc, s0, v129
	v_mul_f32_e32 v130, 0x4b800000, v129
	v_pk_mul_f32 v[158:159], v[122:123], v[150:151] op_sel_hi:[1,0]
	v_cndmask_b32_e32 v129, v129, v130, vcc
	v_rsq_f32_e32 v129, v129
	v_max_f32_e32 v158, 0, v158
	v_max_f32_e32 v159, 0, v159
	v_pk_mul_f32 v[158:159], v[158:159], v[158:159]
	v_mul_f32_e32 v130, 0x45800000, v129
	v_cndmask_b32_e32 v130, v129, v130, vcc
	v_cmp_gt_f32_e32 vcc, s0, v128
	s_mov_b64 s[0:1], 0x8d80000
	v_lshl_add_u64 v[152:153], v[152:153], 0, s[0:1]
	v_lshl_add_u64 v[136:137], v[152:153], 0, v[136:137]
	global_store_dwordx4 v[136:137], v[154:157], off
	v_mul_f32_e32 v129, 0x4b800000, v128
	v_cndmask_b32_e32 v128, v128, v129, vcc
	v_pk_mul_f32 v[154:155], v[126:127], v[150:151] op_sel_hi:[1,0]
	v_pk_mul_f32 v[156:157], v[124:125], v[150:151] op_sel_hi:[1,0]
	v_pk_mul_f32 v[150:151], v[120:121], v[150:151] op_sel_hi:[1,0]
	v_max_f32_e32 v156, 0, v156
	v_max_f32_e32 v150, 0, v150
	v_max_f32_e32 v157, 0, v157
	v_max_f32_e32 v151, 0, v151
	v_max_f32_e32 v154, 0, v154
	v_max_f32_e32 v155, 0, v155
	v_pk_mul_f32 v[156:157], v[156:157], v[156:157]
	v_pk_mul_f32 v[150:151], v[150:151], v[150:151]
	v_pk_mul_f32 v[160:161], v[154:155], v[154:155]
	v_cvt_pk_bf16_f32 v154, v156, v157
	v_cvt_pk_bf16_f32 v155, v160, v161
	v_cvt_pk_bf16_f32 v156, v150, v151
	v_cvt_pk_bf16_f32 v157, v158, v159
	global_store_dwordx4 v[136:137], v[154:157], off offset:256
	v_lshl_add_u64 v[150:151], v[152:153], 0, v[146:147]
	v_pk_mul_f32 v[146:147], v[102:103], v[148:149] op_sel_hi:[1,0]
	v_pk_mul_f32 v[154:155], v[100:101], v[148:149] op_sel_hi:[1,0]
	v_pk_mul_f32 v[156:157], v[98:99], v[148:149] op_sel_hi:[1,0]
	v_pk_mul_f32 v[158:159], v[96:97], v[148:149] op_sel_hi:[1,0]
	v_max_f32_e32 v154, 0, v154
	v_max_f32_e32 v158, 0, v158
; __device__ __forceinline__ unsigned cvt_pk_bf16(float lo, float hi) { const f32x2 v = {lo, hi}; const bf16v2_t b = __builtin_convertvector(v, bf16v2_t); return __builtin_bit_cast(unsigned, b); }
;     __device__ __forceinline__ void epi_up(const f32x4 (&acc)[2][2][4][2], const pg8::Unit& u, int wr, int wc, int fr, int fq) const {
;     ...
;         for (int ai = 0; ai < 2; ++ai)
; #pragma unroll
;             for (int m = 0; m < 4; ++m) {
;                 const int r = row0 + ai * 128 + m * 16;
;                     const float rstd = rstd8[ai][m];
;                     bf16_t* rowp = H + (size_t)r * 4096 + colt;
; #pragma unroll
;                     for (int bj = 0; bj < 2; ++bj) {
;                         f32x4 v0 = acc[ai][bj][m][0] * rstd, v1 = acc[ai][bj][m][1] * rstd;
; #pragma unroll
;                         for (int j = 0; j < 4; ++j) { v0[j] = fmaxf(v0[j], 0.f); v0[j] *= v0[j]; v1[j] = fmaxf(v1[j], 0.f); v1[j] *= v1[j]; }
;                         u32x4 w; w.x = cvt_pk_bf16(v0[0], v0[1]); w.y = cvt_pk_bf16(v0[2], v0[3]); w.z = cvt_pk_bf16(v1[0], v1[1]); w.w = cvt_pk_bf16(v1[2], v1[3]);
;                         *(u32x4*)(rowp + bj * 128) = w;
;                     }
;             }
	v_max_f32_e32 v155, 0, v155
	v_max_f32_e32 v159, 0, v159
	v_max_f32_e32 v146, 0, v146
	v_max_f32_e32 v156, 0, v156
	v_max_f32_e32 v147, 0, v147
	v_max_f32_e32 v157, 0, v157
	v_pk_mul_f32 v[154:155], v[154:155], v[154:155]
	v_pk_mul_f32 v[158:159], v[158:159], v[158:159]
	v_pk_mul_f32 v[146:147], v[146:147], v[146:147]
	v_pk_mul_f32 v[160:161], v[156:157], v[156:157]
	v_cvt_pk_bf16_f32 v154, v154, v155
	v_cvt_pk_bf16_f32 v155, v146, v147
	v_cvt_pk_bf16_f32 v156, v158, v159
	v_cvt_pk_bf16_f32 v157, v160, v161
	global_store_dwordx4 v[150:151], v[154:157], off
	v_pk_mul_f32 v[146:147], v[110:111], v[148:149] op_sel_hi:[1,0]
	v_rsq_f32_e32 v128, v128
	v_pk_mul_f32 v[154:155], v[108:109], v[148:149] op_sel_hi:[1,0]
	v_pk_mul_f32 v[156:157], v[106:107], v[148:149] op_sel_hi:[1,0]
	v_pk_mul_f32 v[148:149], v[104:105], v[148:149] op_sel_hi:[1,0]
	v_max_f32_e32 v154, 0, v154
	v_max_f32_e32 v148, 0, v148
	v_max_f32_e32 v155, 0, v155
	v_max_f32_e32 v149, 0, v149
	v_max_f32_e32 v146, 0, v146
	v_max_f32_e32 v156, 0, v156
	v_max_f32_e32 v147, 0, v147
	v_max_f32_e32 v157, 0, v157
	v_pk_mul_f32 v[154:155], v[154:155], v[154:155]
	v_pk_mul_f32 v[148:149], v[148:149], v[148:149]
	v_pk_mul_f32 v[158:159], v[146:147], v[146:147]
	v_pk_mul_f32 v[156:157], v[156:157], v[156:157]
	v_cvt_pk_bf16_f32 v146, v154, v155
	v_cvt_pk_bf16_f32 v147, v158, v159
	v_cvt_pk_bf16_f32 v148, v148, v149
	v_cvt_pk_bf16_f32 v149, v156, v157
	global_store_dwordx4 v[150:151], v[146:149], off offset:256
	v_lshl_add_u64 v[150:151], v[152:153], 0, v[142:143]
	v_pk_mul_f32 v[142:143], v[86:87], v[144:145] op_sel_hi:[1,0]
	v_pk_mul_f32 v[146:147], v[84:85], v[144:145] op_sel_hi:[1,0]
	v_pk_mul_f32 v[148:149], v[82:83], v[144:145] op_sel_hi:[1,0]
	v_pk_mul_f32 v[154:155], v[80:81], v[144:145] op_sel_hi:[1,0]
	v_max_f32_e32 v146, 0, v146
	v_max_f32_e32 v154, 0, v154
	v_max_f32_e32 v147, 0, v147
	v_max_f32_e32 v155, 0, v155
	v_max_f32_e32 v142, 0, v142
	v_max_f32_e32 v148, 0, v148
	v_max_f32_e32 v143, 0, v143
	v_max_f32_e32 v149, 0, v149
	v_pk_mul_f32 v[146:147], v[146:147], v[146:147]
	v_pk_mul_f32 v[154:155], v[154:155], v[154:155]
	v_pk_mul_f32 v[142:143], v[142:143], v[142:143]
	v_pk_mul_f32 v[156:157], v[148:149], v[148:149]
	v_cvt_pk_bf16_f32 v146, v146, v147
	v_cvt_pk_bf16_f32 v147, v142, v143
	v_cvt_pk_bf16_f32 v148, v154, v155
	v_cvt_pk_bf16_f32 v149, v156, v157
	global_store_dwordx4 v[150:151], v[146:149], off
	v_pk_mul_f32 v[142:143], v[94:95], v[144:145] op_sel_hi:[1,0]
	s_mov_b64 s[0:1], 0x100000
	v_pk_mul_f32 v[146:147], v[92:93], v[144:145] op_sel_hi:[1,0]
	v_pk_mul_f32 v[148:149], v[90:91], v[144:145] op_sel_hi:[1,0]
	v_pk_mul_f32 v[144:145], v[88:89], v[144:145] op_sel_hi:[1,0]
	v_max_f32_e32 v146, 0, v146
	v_max_f32_e32 v144, 0, v144
	v_max_f32_e32 v147, 0, v147
	v_max_f32_e32 v145, 0, v145
	v_max_f32_e32 v142, 0, v142
	v_max_f32_e32 v148, 0, v148
	v_max_f32_e32 v143, 0, v143
	v_max_f32_e32 v149, 0, v149
	v_pk_mul_f32 v[146:147], v[146:147], v[146:147]
	v_pk_mul_f32 v[144:145], v[144:145], v[144:145]
	v_pk_mul_f32 v[154:155], v[142:143], v[142:143]
	v_pk_mul_f32 v[148:149], v[148:149], v[148:149]
	v_cvt_pk_bf16_f32 v142, v146, v147
	v_cvt_pk_bf16_f32 v143, v154, v155
	v_cvt_pk_bf16_f32 v144, v144, v145
	v_cvt_pk_bf16_f32 v145, v148, v149
	global_store_dwordx4 v[150:151], v[142:145], off offset:256
	v_pk_mul_f32 v[146:147], v[66:67], v[138:139] op_sel_hi:[1,0]
	v_pk_mul_f32 v[148:149], v[64:65], v[138:139] op_sel_hi:[1,0]
	v_lshl_add_u64 v[144:145], v[152:153], 0, v[140:141]
	v_pk_mul_f32 v[140:141], v[70:71], v[138:139] op_sel_hi:[1,0]
	v_pk_mul_f32 v[142:143], v[68:69], v[138:139] op_sel_hi:[1,0]
	v_max_f32_e32 v148, 0, v148
	v_max_f32_e32 v142, 0, v142
	v_max_f32_e32 v143, 0, v143
	v_max_f32_e32 v149, 0, v149
	v_max_f32_e32 v140, 0, v140
	v_max_f32_e32 v146, 0, v146
	v_max_f32_e32 v141, 0, v141
	v_max_f32_e32 v147, 0, v147
	v_pk_mul_f32 v[142:143], v[142:143], v[142:143]
	v_pk_mul_f32 v[148:149], v[148:149], v[148:149]
	v_pk_mul_f32 v[150:151], v[140:141], v[140:141]
	v_pk_mul_f32 v[146:147], v[146:147], v[146:147]
	v_cvt_pk_bf16_f32 v140, v142, v143
	v_cvt_pk_bf16_f32 v141, v150, v151
	v_cvt_pk_bf16_f32 v142, v148, v149
	v_cvt_pk_bf16_f32 v143, v146, v147
	global_store_dwordx4 v[144:145], v[140:143], off
	v_pk_mul_f32 v[146:147], v[74:75], v[138:139] op_sel_hi:[1,0]
	v_mul_f32_e32 v129, 0x45800000, v128
	v_pk_mul_f32 v[140:141], v[78:79], v[138:139] op_sel_hi:[1,0]
	v_pk_mul_f32 v[142:143], v[76:77], v[138:139] op_sel_hi:[1,0]
	v_pk_mul_f32 v[138:139], v[72:73], v[138:139] op_sel_hi:[1,0]
	v_max_f32_e32 v142, 0, v142
	v_max_f32_e32 v138, 0, v138
	v_max_f32_e32 v139, 0, v139
	v_max_f32_e32 v143, 0, v143
	v_pk_mul_f32 v[148:149], v[138:139], v[138:139]
	v_max_f32_e32 v138, 0, v140
	v_max_f32_e32 v140, 0, v146
	v_max_f32_e32 v139, 0, v141
	v_max_f32_e32 v141, 0, v147
	v_pk_mul_f32 v[142:143], v[142:143], v[142:143]
	v_pk_mul_f32 v[150:151], v[138:139], v[138:139]
	v_pk_mul_f32 v[146:147], v[140:141], v[140:141]
	v_cvt_pk_bf16_f32 v138, v142, v143
	v_cvt_pk_bf16_f32 v139, v150, v151
	v_cvt_pk_bf16_f32 v140, v148, v149
	v_cvt_pk_bf16_f32 v141, v146, v147
	global_store_dwordx4 v[144:145], v[138:141], off offset:256
	v_pk_mul_f32 v[144:145], v[50:51], v[134:135] op_sel_hi:[1,0]
	v_pk_mul_f32 v[146:147], v[48:49], v[134:135] op_sel_hi:[1,0]
	v_pk_mul_f32 v[140:141], v[52:53], v[134:135] op_sel_hi:[1,0]
	v_pk_mul_f32 v[138:139], v[54:55], v[134:135] op_sel_hi:[1,0]
	v_max_f32_e32 v140, 0, v140
	v_max_f32_e32 v141, 0, v141
	v_max_f32_e32 v144, 0, v144
	v_max_f32_e32 v145, 0, v145
	v_lshl_add_u64 v[142:143], v[136:137], 0, s[0:1]
	v_max_f32_e32 v146, 0, v146
; __device__ __forceinline__ unsigned cvt_pk_bf16(float lo, float hi) { const f32x2 v = {lo, hi}; const bf16v2_t b = __builtin_convertvector(v, bf16v2_t); return __builtin_bit_cast(unsigned, b); }
;     __device__ __forceinline__ void epi_up(const f32x4 (&acc)[2][2][4][2], const pg8::Unit& u, int wr, int wc, int fr, int fq) const {
;     ...
;         for (int ai = 0; ai < 2; ++ai)
; #pragma unroll
;             for (int m = 0; m < 4; ++m) {
;                 const int r = row0 + ai * 128 + m * 16;
;                     const float rstd = rstd8[ai][m];
;                     bf16_t* rowp = H + (size_t)r * 4096 + colt;
; #pragma unroll
;                     for (int bj = 0; bj < 2; ++bj) {
;                         f32x4 v0 = acc[ai][bj][m][0] * rstd, v1 = acc[ai][bj][m][1] * rstd;
; #pragma unroll
;                         for (int j = 0; j < 4; ++j) { v0[j] = fmaxf(v0[j], 0.f); v0[j] *= v0[j]; v1[j] = fmaxf(v1[j], 0.f); v1[j] *= v1[j]; }
;                         u32x4 w; w.x = cvt_pk_bf16(v0[0], v0[1]); w.y = cvt_pk_bf16(v0[2], v0[3]); w.z = cvt_pk_bf16(v1[0], v1[1]); w.w = cvt_pk_bf16(v1[2], v1[3]);
;                         *(u32x4*)(rowp + bj * 128) = w;
;                     }
;             }
	v_pk_mul_f32 v[140:141], v[140:141], v[140:141]
	v_max_f32_e32 v147, 0, v147
	v_max_f32_e32 v138, 0, v138
	v_max_f32_e32 v139, 0, v139
	v_pk_mul_f32 v[144:145], v[144:145], v[144:145]
	s_mov_b32 s0, 0x100000
	v_cndmask_b32_e32 v128, v128, v129, vcc
	v_pk_mul_f32 v[146:147], v[146:147], v[146:147]
	v_pk_mul_f32 v[148:149], v[138:139], v[138:139]
	v_cvt_pk_bf16_f32 v138, v140, v141
	v_cvt_pk_bf16_f32 v141, v144, v145
	v_add_co_u32_e32 v144, vcc, s0, v136
	v_cvt_pk_bf16_f32 v139, v148, v149
	v_cvt_pk_bf16_f32 v140, v146, v147
	v_addc_co_u32_e32 v145, vcc, 0, v137, vcc
	global_store_dwordx4 v[144:145], v[138:141], off
	v_pk_mul_f32 v[144:145], v[58:59], v[134:135] op_sel_hi:[1,0]
	s_mov_b64 s[0:1], 0x120000
	v_pk_mul_f32 v[138:139], v[62:63], v[134:135] op_sel_hi:[1,0]
	v_pk_mul_f32 v[140:141], v[60:61], v[134:135] op_sel_hi:[1,0]
	v_pk_mul_f32 v[134:135], v[56:57], v[134:135] op_sel_hi:[1,0]
	v_max_f32_e32 v140, 0, v140
	v_max_f32_e32 v134, 0, v134
	v_max_f32_e32 v141, 0, v141
	v_max_f32_e32 v135, 0, v135
	v_max_f32_e32 v138, 0, v138
	v_max_f32_e32 v144, 0, v144
	v_max_f32_e32 v139, 0, v139
	v_max_f32_e32 v145, 0, v145
	v_pk_mul_f32 v[140:141], v[140:141], v[140:141]
	v_pk_mul_f32 v[134:135], v[134:135], v[134:135]
	v_pk_mul_f32 v[146:147], v[138:139], v[138:139]
	v_pk_mul_f32 v[144:145], v[144:145], v[144:145]
	v_cvt_pk_bf16_f32 v138, v140, v141
	v_cvt_pk_bf16_f32 v139, v146, v147
	v_cvt_pk_bf16_f32 v140, v134, v135
	v_cvt_pk_bf16_f32 v141, v144, v145
	global_store_dwordx4 v[142:143], v[138:141], off offset:256
	v_pk_mul_f32 v[134:135], v[38:39], v[132:133] op_sel_hi:[1,0]
	v_pk_mul_f32 v[144:145], v[32:33], v[132:133] op_sel_hi:[1,0]
	v_pk_mul_f32 v[138:139], v[36:37], v[132:133] op_sel_hi:[1,0]
	v_pk_mul_f32 v[140:141], v[34:35], v[132:133] op_sel_hi:[1,0]
	v_max_f32_e32 v138, 0, v138
	v_max_f32_e32 v139, 0, v139
	v_max_f32_e32 v134, 0, v134
	v_max_f32_e32 v135, 0, v135
	v_lshl_add_u64 v[142:143], v[136:137], 0, s[0:1]
	v_max_f32_e32 v144, 0, v144
	v_pk_mul_f32 v[138:139], v[138:139], v[138:139]
	v_max_f32_e32 v145, 0, v145
	v_max_f32_e32 v140, 0, v140
	v_pk_mul_f32 v[134:135], v[134:135], v[134:135]
	v_max_f32_e32 v141, 0, v141
	s_mov_b32 s0, 0x120000
	v_pk_mul_f32 v[144:145], v[144:145], v[144:145]
	v_pk_mul_f32 v[146:147], v[140:141], v[140:141]
	v_cvt_pk_bf16_f32 v138, v138, v139
	v_cvt_pk_bf16_f32 v139, v134, v135
	v_add_co_u32_e32 v134, vcc, s0, v136
	v_cvt_pk_bf16_f32 v140, v144, v145
	v_cvt_pk_bf16_f32 v141, v146, v147
	v_addc_co_u32_e32 v135, vcc, 0, v137, vcc
	global_store_dwordx4 v[134:135], v[138:141], off
	v_pk_mul_f32 v[134:135], v[46:47], v[132:133] op_sel_hi:[1,0]
	s_mov_b64 s[0:1], 0x140000
	v_pk_mul_f32 v[138:139], v[44:45], v[132:133] op_sel_hi:[1,0]
	v_pk_mul_f32 v[140:141], v[42:43], v[132:133] op_sel_hi:[1,0]
	v_pk_mul_f32 v[132:133], v[40:41], v[132:133] op_sel_hi:[1,0]
	v_max_f32_e32 v138, 0, v138
	v_max_f32_e32 v132, 0, v132
	v_max_f32_e32 v133, 0, v133
	v_max_f32_e32 v139, 0, v139
	v_pk_mul_f32 v[144:145], v[132:133], v[132:133]
	v_max_f32_e32 v132, 0, v134
	v_max_f32_e32 v134, 0, v140
	v_max_f32_e32 v133, 0, v135
	v_max_f32_e32 v135, 0, v141
	v_pk_mul_f32 v[138:139], v[138:139], v[138:139]
	v_pk_mul_f32 v[146:147], v[132:133], v[132:133]
	v_pk_mul_f32 v[140:141], v[134:135], v[134:135]
	v_cvt_pk_bf16_f32 v132, v138, v139
	v_cvt_pk_bf16_f32 v133, v146, v147
	v_cvt_pk_bf16_f32 v134, v144, v145
	v_cvt_pk_bf16_f32 v135, v140, v141
	global_store_dwordx4 v[142:143], v[132:135], off offset:256
	v_pk_mul_f32 v[140:141], v[18:19], v[130:131] op_sel_hi:[1,0]
	v_pk_mul_f32 v[142:143], v[16:17], v[130:131] op_sel_hi:[1,0]
	v_pk_mul_f32 v[134:135], v[20:21], v[130:131] op_sel_hi:[1,0]
; __device__ __forceinline__ unsigned cvt_pk_bf16(float lo, float hi) { const f32x2 v = {lo, hi}; const bf16v2_t b = __builtin_convertvector(v, bf16v2_t); return __builtin_bit_cast(unsigned, b); }
;     __device__ __forceinline__ void epi_up(const f32x4 (&acc)[2][2][4][2], const pg8::Unit& u, int wr, int wc, int fr, int fq) const {
;     ...
;         for (int ai = 0; ai < 2; ++ai)
; #pragma unroll
;             for (int m = 0; m < 4; ++m) {
;                 const int r = row0 + ai * 128 + m * 16;
;                     const float rstd = rstd8[ai][m];
;                     bf16_t* rowp = H + (size_t)r * 4096 + colt;
; #pragma unroll
;                     for (int bj = 0; bj < 2; ++bj) {
;                         f32x4 v0 = acc[ai][bj][m][0] * rstd, v1 = acc[ai][bj][m][1] * rstd;
; #pragma unroll
;                         for (int j = 0; j < 4; ++j) { v0[j] = fmaxf(v0[j], 0.f); v0[j] *= v0[j]; v1[j] = fmaxf(v1[j], 0.f); v1[j] *= v1[j]; }
;                         u32x4 w; w.x = cvt_pk_bf16(v0[0], v0[1]); w.y = cvt_pk_bf16(v0[2], v0[3]); w.z = cvt_pk_bf16(v1[0], v1[1]); w.w = cvt_pk_bf16(v1[2], v1[3]);
;                         *(u32x4*)(rowp + bj * 128) = w;
;                     }
;             }
	v_pk_mul_f32 v[132:133], v[22:23], v[130:131] op_sel_hi:[1,0]
	v_max_f32_e32 v134, 0, v134
	v_max_f32_e32 v135, 0, v135
	v_max_f32_e32 v140, 0, v140
	v_max_f32_e32 v141, 0, v141
	v_lshl_add_u64 v[138:139], v[136:137], 0, s[0:1]
	v_max_f32_e32 v142, 0, v142
	v_pk_mul_f32 v[134:135], v[134:135], v[134:135]
	v_max_f32_e32 v143, 0, v143
	v_max_f32_e32 v132, 0, v132
	v_max_f32_e32 v133, 0, v133
	v_pk_mul_f32 v[140:141], v[140:141], v[140:141]
	s_mov_b32 s0, 0x140000
	v_pk_mul_f32 v[142:143], v[142:143], v[142:143]
	v_pk_mul_f32 v[144:145], v[132:133], v[132:133]
	v_cvt_pk_bf16_f32 v132, v134, v135
	v_cvt_pk_bf16_f32 v135, v140, v141
	v_add_co_u32_e32 v140, vcc, s0, v136
	v_cvt_pk_bf16_f32 v133, v144, v145
	v_cvt_pk_bf16_f32 v134, v142, v143
	v_addc_co_u32_e32 v141, vcc, 0, v137, vcc
	global_store_dwordx4 v[140:141], v[132:135], off
	v_pk_mul_f32 v[140:141], v[26:27], v[130:131] op_sel_hi:[1,0]
	s_mov_b64 s[0:1], 0x160000
	v_pk_mul_f32 v[132:133], v[30:31], v[130:131] op_sel_hi:[1,0]
	v_pk_mul_f32 v[134:135], v[28:29], v[130:131] op_sel_hi:[1,0]
	v_pk_mul_f32 v[130:131], v[24:25], v[130:131] op_sel_hi:[1,0]
	v_max_f32_e32 v134, 0, v134
	v_max_f32_e32 v130, 0, v130
	v_max_f32_e32 v131, 0, v131
	v_max_f32_e32 v135, 0, v135
	v_pk_mul_f32 v[142:143], v[130:131], v[130:131]
	v_max_f32_e32 v130, 0, v132
	v_max_f32_e32 v132, 0, v140
	v_max_f32_e32 v131, 0, v133
	v_max_f32_e32 v133, 0, v141
	v_pk_mul_f32 v[134:135], v[134:135], v[134:135]
	v_pk_mul_f32 v[144:145], v[130:131], v[130:131]
	v_pk_mul_f32 v[140:141], v[132:133], v[132:133]
	v_cvt_pk_bf16_f32 v130, v134, v135
	v_cvt_pk_bf16_f32 v131, v144, v145
	v_cvt_pk_bf16_f32 v132, v142, v143
	v_cvt_pk_bf16_f32 v133, v140, v141
	global_store_dwordx4 v[138:139], v[130:133], off offset:256
	v_pk_mul_f32 v[138:139], v[2:3], v[128:129] op_sel_hi:[1,0]
	v_pk_mul_f32 v[140:141], v[0:1], v[128:129] op_sel_hi:[1,0]
	v_pk_mul_f32 v[130:131], v[6:7], v[128:129] op_sel_hi:[1,0]
	v_pk_mul_f32 v[132:133], v[4:5], v[128:129] op_sel_hi:[1,0]
	v_lshl_add_u64 v[134:135], v[136:137], 0, s[0:1]
	v_max_f32_e32 v132, 0, v132
	v_max_f32_e32 v140, 0, v140
	v_max_f32_e32 v133, 0, v133
	v_max_f32_e32 v141, 0, v141
	v_max_f32_e32 v130, 0, v130
	v_max_f32_e32 v138, 0, v138
	v_max_f32_e32 v131, 0, v131
	v_max_f32_e32 v139, 0, v139
	s_mov_b32 s0, 0x160000
	v_pk_mul_f32 v[132:133], v[132:133], v[132:133]
	v_pk_mul_f32 v[140:141], v[140:141], v[140:141]
	v_pk_mul_f32 v[142:143], v[130:131], v[130:131]
	v_pk_mul_f32 v[138:139], v[138:139], v[138:139]
	v_add_co_u32_e32 v136, vcc, s0, v136
	v_cvt_pk_bf16_f32 v130, v132, v133
	v_cvt_pk_bf16_f32 v131, v142, v143
	v_cvt_pk_bf16_f32 v132, v140, v141
	v_cvt_pk_bf16_f32 v133, v138, v139
	v_addc_co_u32_e32 v137, vcc, 0, v137, vcc
	global_store_dwordx4 v[136:137], v[130:133], off
	v_pk_mul_f32 v[136:137], v[10:11], v[128:129] op_sel_hi:[1,0]
	s_nop 0
	v_pk_mul_f32 v[130:131], v[14:15], v[128:129] op_sel_hi:[1,0]
	v_pk_mul_f32 v[132:133], v[12:13], v[128:129] op_sel_hi:[1,0]
	v_pk_mul_f32 v[128:129], v[8:9], v[128:129] op_sel_hi:[1,0]
	v_max_f32_e32 v132, 0, v132
	v_max_f32_e32 v128, 0, v128
	v_max_f32_e32 v129, 0, v129
	v_max_f32_e32 v133, 0, v133
	v_pk_mul_f32 v[138:139], v[128:129], v[128:129]
	v_max_f32_e32 v128, 0, v130
	v_max_f32_e32 v130, 0, v136
	v_max_f32_e32 v129, 0, v131
	v_max_f32_e32 v131, 0, v137
	v_pk_mul_f32 v[132:133], v[132:133], v[132:133]
	v_pk_mul_f32 v[140:141], v[128:129], v[128:129]
	v_pk_mul_f32 v[136:137], v[130:131], v[130:131]
	v_cvt_pk_bf16_f32 v128, v132, v133
	v_cvt_pk_bf16_f32 v129, v140, v141
	v_cvt_pk_bf16_f32 v130, v138, v139
	v_cvt_pk_bf16_f32 v131, v136, v137
	global_store_dwordx4 v[134:135], v[128:131], off offset:256

;     __device__ __forceinline__ void epi_proj(const f32x4 (&acc)[2][2][4][2], const pg8::Unit& u, int wr, int wc, int fr, int fq) const {
;     ...
;         float rstd8[2][4];
; #pragma unroll
;         for (int ai = 0; ai < 2; ++ai)
; #pragma unroll
;             for (int m = 0; m < 4; ++m) rstd8[ai][m] = rs[row0 + ai * 128 + m * 16];
; #pragma unroll
;         for (int ai = 0; ai < 2; ++ai)
; #pragma unroll
;             for (int m = 0; m < 4; ++m) rstd8[ai][m] = rsqrtf(rstd8[ai][m] * (1.0f / 1024.0f) + EPS);
; #pragma unroll
;         for (int ai = 0; ai < 2; ++ai)
; #pragma unroll
;             for (int m = 0; m < 4; ++m) {
;                 const int r = row0 + ai * 128 + m * 16;
;                     const float rstd = rstd8[ai][m];
;                     if (u.pn == 32) {
;                         if (wc == 0 && fq < 2) {
;                             const f32x4 v0 = acc[ai][0][m][0] * rstd, v1 = acc[ai][0][m][1] * rstd;
;                             float o8[8] = {v0[0], v0[1], v0[2], v0[3], v1[0], v1[1], v1[2], v1[3]};
; #pragma unroll
;                             for (int h = 0; h < 8; ++h) {
;                                 if (fq == 0) o8[h] = sigmoidf_(o8[h]);
;                                 else { const float xx = o8[h] + dt_bias[l * 8 + h]; const float sp = xx > 20.f ? xx : log1pf(__expf(xx)); o8[h] = -__expf(a_log[l * 8 + h]) * sp; }
;                             }
;                             float* dst = bg + (size_t)r * 16 + 8 * fq;
;                             *(f32x4*)dst = (f32x4){o8[0], o8[1], o8[2], o8[3]}; *(f32x4*)(dst + 4) = (f32x4){o8[4], o8[5], o8[6], o8[7]};
;                         }
;                     } else {
;                         const int slot = u.pn >> 2;
;                         bf16_t* rowp = act + (size_t)slot * SLOT_EL + (size_t)r * 1024 + (colt & 1023);
; #pragma unroll
;                         for (int bj = 0; bj < 2; ++bj) {
;                             f32x4 v0 = acc[ai][bj][m][0] * rstd, v1 = acc[ai][bj][m][1] * rstd;
;                             if (slot < 2) {
;                                 f32x2 a = gelu_pk((f32x2){v0[0], v0[1]}), b = gelu_pk((f32x2){v0[2], v0[3]}), c = gelu_pk((f32x2){v1[0], v1[1]}), d = gelu_pk((f32x2){v1[2], v1[3]});
;                                 v0 = (f32x4){a.x, a.y, b.x, b.y}; v1 = (f32x4){c.x, c.y, d.x, d.y};
;                             } else if (slot == 5) {
.Lepi_sig:
	v_readlane_b32 s6, v254, 34
	v_readlane_b32 s7, v254, 35
	s_mov_b64 s[0:1], s[6:7]
	s_load_dwordx2 s[4:5], s[0:1], 0xb0
	s_mov_b64 s[0:1], s[6:7]
	s_mov_b64 s[0:1], s[6:7]
	s_mov_b64 s[0:1], s[6:7]
	s_mov_b64 s[0:1], s[6:7]
	v_lshl_add_u32 v136, s13, 8, v239
	v_ashrrev_i32_e32 v137, 31, v136
	s_mov_b64 s[0:1], s[6:7]
	v_lshl_add_u64 v[128:129], v[136:137], 2, s[66:67]
	global_load_dword v130, v[128:129], off
	global_load_dword v131, v[128:129], off offset:64
	global_load_dword v132, v[128:129], off offset:128
	global_load_dword v133, v[128:129], off offset:192
	global_load_dword v134, v[128:129], off offset:512
	global_load_dword v135, v[128:129], off offset:576
	global_load_dword v139, v[128:129], off offset:640
	s_nop 0
	global_load_dword v128, v[128:129], off offset:704
	s_mov_b32 s0, 0x800000
	v_lshl_or_b32 v152, s88, 8, v245
	v_and_b32_e32 v152, 0x3ff, v152
	v_ashrrev_i32_e32 v153, 31, v152
	s_waitcnt lgkmcnt(0)
	v_lshl_add_u64 v[152:153], v[152:153], 1, s[4:5]
	v_or_b32_e32 v146, 16, v136
	v_or_b32_e32 v142, 32, v136
	v_or_b32_e32 v140, 48, v136
	v_lshlrev_b64 v[136:137], 11, v[136:137]
	v_ashrrev_i32_e32 v147, 31, v146
	v_lshlrev_b64 v[146:147], 11, v[146:147]
	v_ashrrev_i32_e32 v143, 31, v142
	v_lshlrev_b64 v[142:143], 11, v[142:143]
	v_ashrrev_i32_e32 v141, 31, v140
	v_lshlrev_b64 v[140:141], 11, v[140:141]
	s_waitcnt vmcnt(0)
	v_fmamk_f32 v129, v130, 0x3a800000, v237
	v_cmp_gt_f32_e32 vcc, s0, v129
	v_mul_f32_e32 v130, 0x4b800000, v129
	v_fmamk_f32 v128, v128, 0x3a800000, v237
	v_cndmask_b32_e32 v129, v129, v130, vcc
	v_rsq_f32_e32 v129, v129
	s_nop 0
	v_mul_f32_e32 v130, 0x45800000, v129
	v_cndmask_b32_e32 v150, v129, v130, vcc
	v_fmamk_f32 v129, v131, 0x3a800000, v237
	v_cmp_gt_f32_e32 vcc, s0, v129
	v_mul_f32_e32 v130, 0x4b800000, v129
	v_pk_mul_f32 v[154:155], v[118:119], v[150:151] op_sel_hi:[1,0]
	v_cndmask_b32_e32 v129, v129, v130, vcc
	v_rsq_f32_e32 v129, v129
	v_pk_mul_f32 v[156:157], v[116:117], v[150:151] op_sel_hi:[1,0]
	v_pk_mul_f32 v[158:159], v[114:115], v[150:151] op_sel_hi:[1,0]
	v_pk_mul_f32 v[160:161], v[112:113], v[150:151] op_sel_hi:[1,0]
	v_mul_f32_e32 v130, 0x45800000, v129
	v_cndmask_b32_e32 v148, v129, v130, vcc
	v_fmamk_f32 v129, v132, 0x3a800000, v237
	v_cmp_gt_f32_e32 vcc, s0, v129
	v_mul_f32_e32 v130, 0x4b800000, v129
	v_mul_f32_e32 v156, 0xbfb8aa3b, v156
	v_exp_f32_e32 v156, v156
	v_cndmask_b32_e32 v129, v129, v130, vcc
	v_rsq_f32_e32 v129, v129
	v_mul_f32_e32 v160, 0xbfb8aa3b, v160
	v_exp_f32_e32 v160, v160
	v_mul_f32_e32 v157, 0xbfb8aa3b, v157
	v_exp_f32_e32 v157, v157
	v_mul_f32_e32 v161, 0xbfb8aa3b, v161
	v_exp_f32_e32 v161, v161
	v_mul_f32_e32 v130, 0x45800000, v129
	v_cndmask_b32_e32 v144, v129, v130, vcc
	v_fmamk_f32 v129, v133, 0x3a800000, v237
	v_cmp_gt_f32_e32 vcc, s0, v129
	v_mul_f32_e32 v130, 0x4b800000, v129
	v_mul_f32_e32 v154, 0xbfb8aa3b, v154
	v_exp_f32_e32 v154, v154
	v_cndmask_b32_e32 v129, v129, v130, vcc
	v_rsq_f32_e32 v129, v129
	v_mul_f32_e32 v158, 0xbfb8aa3b, v158
	v_exp_f32_e32 v158, v158
	v_mul_f32_e32 v155, 0xbfb8aa3b, v155
	v_exp_f32_e32 v155, v155
	v_mul_f32_e32 v159, 0xbfb8aa3b, v159
	v_exp_f32_e32 v159, v159
	v_mul_f32_e32 v130, 0x45800000, v129
	v_cndmask_b32_e32 v138, v129, v130, vcc
	v_fmamk_f32 v129, v134, 0x3a800000, v237
	v_cmp_gt_f32_e32 vcc, s0, v129
	v_mul_f32_e32 v130, 0x4b800000, v129
	s_nop 0
	v_add_f32_e32 v156, 1.0, v156
	v_add_f32_e32 v157, 1.0, v157
	v_rcp_f32_e32 v156, v156
	v_rcp_f32_e32 v157, v157
	s_nop 0
	v_cndmask_b32_e32 v129, v129, v130, vcc
	v_rsq_f32_e32 v129, v129
	s_nop 0
	v_add_f32_e32 v160, 1.0, v160
	v_add_f32_e32 v161, 1.0, v161
	v_rcp_f32_e32 v160, v160
	v_rcp_f32_e32 v161, v161
	s_nop 0
	s_nop 0
	v_add_f32_e32 v162, 1.0, v154
	v_add_f32_e32 v163, 1.0, v155
	v_rcp_f32_e32 v162, v162
	v_rcp_f32_e32 v163, v163
	s_nop 0
	s_nop 0
	v_add_f32_e32 v158, 1.0, v158
	v_add_f32_e32 v159, 1.0, v159
	v_rcp_f32_e32 v158, v158
	v_rcp_f32_e32 v159, v159
	s_nop 0
	v_mul_f32_e32 v130, 0x45800000, v129
	v_cndmask_b32_e32 v134, v129, v130, vcc
	v_fmamk_f32 v129, v135, 0x3a800000, v237
	v_cmp_gt_f32_e32 vcc, s0, v129
	v_mul_f32_e32 v130, 0x4b800000, v129
	v_cvt_pk_bf16_f32 v154, v156, v157
	v_cndmask_b32_e32 v129, v129, v130, vcc
	v_rsq_f32_e32 v129, v129
	v_cvt_pk_bf16_f32 v155, v162, v163
	v_cvt_pk_bf16_f32 v156, v160, v161
	v_cvt_pk_bf16_f32 v157, v158, v159
	v_mul_f32_e32 v130, 0x45800000, v129
	v_cndmask_b32_e32 v132, v129, v130, vcc
	v_fmamk_f32 v129, v139, 0x3a800000, v237
	v_cmp_gt_f32_e32 vcc, s0, v129
	v_mul_f32_e32 v130, 0x4b800000, v129
	v_pk_mul_f32 v[158:159], v[122:123], v[150:151] op_sel_hi:[1,0]
	v_cndmask_b32_e32 v129, v129, v130, vcc
	v_rsq_f32_e32 v129, v129
	v_mul_f32_e32 v158, 0xbfb8aa3b, v158
	v_exp_f32_e32 v158, v158
	v_mul_f32_e32 v159, 0xbfb8aa3b, v159
	v_exp_f32_e32 v159, v159
	s_nop 0
	v_add_f32_e32 v158, 1.0, v158
	v_add_f32_e32 v159, 1.0, v159
	v_rcp_f32_e32 v158, v158
	v_rcp_f32_e32 v159, v159
	s_nop 0
	v_mul_f32_e32 v130, 0x45800000, v129
	v_cndmask_b32_e32 v130, v129, v130, vcc
	v_cmp_gt_f32_e32 vcc, s0, v128
	s_lshr_b32 s0, s88, 2
	s_mul_i32 s0, s0, 0x4080000
	s_add_u32 s0, s0, 0x8d80000
	s_mov_b32 s1, 0
	v_lshl_add_u64 v[152:153], v[152:153], 0, s[0:1]
	v_lshl_add_u64 v[136:137], v[152:153], 0, v[136:137]
	global_store_dwordx4 v[136:137], v[154:157], off
	v_mul_f32_e32 v129, 0x4b800000, v128
	v_cndmask_b32_e32 v128, v128, v129, vcc
	v_pk_mul_f32 v[154:155], v[126:127], v[150:151] op_sel_hi:[1,0]
	v_pk_mul_f32 v[156:157], v[124:125], v[150:151] op_sel_hi:[1,0]
	v_pk_mul_f32 v[150:151], v[120:121], v[150:151] op_sel_hi:[1,0]
	v_mul_f32_e32 v156, 0xbfb8aa3b, v156
	v_exp_f32_e32 v156, v156
	v_mul_f32_e32 v150, 0xbfb8aa3b, v150
; __device__ __forceinline__ unsigned cvt_pk_bf16(float lo, float hi) { const f32x2 v = {lo, hi}; const bf16v2_t b = __builtin_convertvector(v, bf16v2_t); return __builtin_bit_cast(unsigned, b); }
; __device__ __forceinline__ float siluf_(float x) { return x * __builtin_amdgcn_rcpf(1.0f + __builtin_amdgcn_exp2f(x * -1.44269504089f)); }
; __device__ __forceinline__ float sigmoidf_(float x) { return __builtin_amdgcn_rcpf(1.0f + __builtin_amdgcn_exp2f(x * -1.44269504089f)); }
;     __device__ __forceinline__ void epi_proj(const f32x4 (&acc)[2][2][4][2], const pg8::Unit& u, int wr, int wc, int fr, int fq) const {
;     ...
; #pragma unroll
;                         for (int bj = 0; bj < 2; ++bj) {
;                             f32x4 v0 = acc[ai][bj][m][0] * rstd, v1 = acc[ai][bj][m][1] * rstd;
;                             if (slot < 2) {
;                                 f32x2 a = gelu_pk((f32x2){v0[0], v0[1]}), b = gelu_pk((f32x2){v0[2], v0[3]}), c = gelu_pk((f32x2){v1[0], v1[1]}), d = gelu_pk((f32x2){v1[2], v1[3]});
;                                 v0 = (f32x4){a.x, a.y, b.x, b.y}; v1 = (f32x4){c.x, c.y, d.x, d.y};
;                             } else if (slot == 5) {
; #pragma unroll
;                                 for (int j = 0; j < 4; ++j) { v0[j] = siluf_(v0[j]); v1[j] = siluf_(v1[j]); }
;                             } else if (slot >= 6) {
; #pragma unroll
;                                 for (int j = 0; j < 4; ++j) { v0[j] = sigmoidf_(v0[j]); v1[j] = sigmoidf_(v1[j]); }
;                             }
;                             u32x4 w; w.x = cvt_pk_bf16(v0[0], v0[1]); w.y = cvt_pk_bf16(v0[2], v0[3]); w.z = cvt_pk_bf16(v1[0], v1[1]); w.w = cvt_pk_bf16(v1[2], v1[3]);
;                             *(u32x4*)(rowp + bj * 128) = w;
	v_exp_f32_e32 v150, v150
	v_mul_f32_e32 v157, 0xbfb8aa3b, v157
	v_exp_f32_e32 v157, v157
	v_mul_f32_e32 v151, 0xbfb8aa3b, v151
	v_exp_f32_e32 v151, v151
	v_mul_f32_e32 v154, 0xbfb8aa3b, v154
	v_exp_f32_e32 v154, v154
	v_mul_f32_e32 v155, 0xbfb8aa3b, v155
	v_exp_f32_e32 v155, v155
	s_nop 0
	v_add_f32_e32 v156, 1.0, v156
	v_add_f32_e32 v157, 1.0, v157
	v_rcp_f32_e32 v156, v156
	v_rcp_f32_e32 v157, v157
	s_nop 0
	s_nop 0
	v_add_f32_e32 v150, 1.0, v150
	v_add_f32_e32 v151, 1.0, v151
	v_rcp_f32_e32 v150, v150
	v_rcp_f32_e32 v151, v151
	s_nop 0
	s_nop 0
	v_add_f32_e32 v160, 1.0, v154
	v_add_f32_e32 v161, 1.0, v155
	v_rcp_f32_e32 v160, v160
	v_rcp_f32_e32 v161, v161
	s_nop 0
	v_cvt_pk_bf16_f32 v154, v156, v157
	v_cvt_pk_bf16_f32 v155, v160, v161
	v_cvt_pk_bf16_f32 v156, v150, v151
	v_cvt_pk_bf16_f32 v157, v158, v159
	global_store_dwordx4 v[136:137], v[154:157], off offset:256
	v_lshl_add_u64 v[150:151], v[152:153], 0, v[146:147]
	v_pk_mul_f32 v[146:147], v[102:103], v[148:149] op_sel_hi:[1,0]
	v_pk_mul_f32 v[154:155], v[100:101], v[148:149] op_sel_hi:[1,0]
	v_pk_mul_f32 v[156:157], v[98:99], v[148:149] op_sel_hi:[1,0]
	v_pk_mul_f32 v[158:159], v[96:97], v[148:149] op_sel_hi:[1,0]
	v_mul_f32_e32 v154, 0xbfb8aa3b, v154
	v_exp_f32_e32 v154, v154
	v_mul_f32_e32 v158, 0xbfb8aa3b, v158
	v_exp_f32_e32 v158, v158
	v_mul_f32_e32 v155, 0xbfb8aa3b, v155
	v_exp_f32_e32 v155, v155
	v_mul_f32_e32 v159, 0xbfb8aa3b, v159
	v_exp_f32_e32 v159, v159
	v_mul_f32_e32 v146, 0xbfb8aa3b, v146
	v_exp_f32_e32 v146, v146
	v_mul_f32_e32 v156, 0xbfb8aa3b, v156
	v_exp_f32_e32 v156, v156
	v_mul_f32_e32 v147, 0xbfb8aa3b, v147
	v_exp_f32_e32 v147, v147
	v_mul_f32_e32 v157, 0xbfb8aa3b, v157
	v_exp_f32_e32 v157, v157
	s_nop 0
	v_add_f32_e32 v154, 1.0, v154
	v_add_f32_e32 v155, 1.0, v155
	v_rcp_f32_e32 v154, v154
	v_rcp_f32_e32 v155, v155
	s_nop 0
	s_nop 0
	v_add_f32_e32 v158, 1.0, v158
	v_add_f32_e32 v159, 1.0, v159
	v_rcp_f32_e32 v158, v158
	v_rcp_f32_e32 v159, v159
	s_nop 0
	s_nop 0
	v_add_f32_e32 v146, 1.0, v146
	v_add_f32_e32 v147, 1.0, v147
	v_rcp_f32_e32 v146, v146
	v_rcp_f32_e32 v147, v147
	s_nop 0
	s_nop 0
	v_add_f32_e32 v160, 1.0, v156
	v_add_f32_e32 v161, 1.0, v157
	v_rcp_f32_e32 v160, v160
	v_rcp_f32_e32 v161, v161
	s_nop 0
	v_cvt_pk_bf16_f32 v154, v154, v155
	v_cvt_pk_bf16_f32 v155, v146, v147
	v_cvt_pk_bf16_f32 v156, v158, v159
	v_cvt_pk_bf16_f32 v157, v160, v161
	global_store_dwordx4 v[150:151], v[154:157], off
	v_pk_mul_f32 v[146:147], v[110:111], v[148:149] op_sel_hi:[1,0]
	v_rsq_f32_e32 v128, v128
	v_pk_mul_f32 v[154:155], v[108:109], v[148:149] op_sel_hi:[1,0]
	v_pk_mul_f32 v[156:157], v[106:107], v[148:149] op_sel_hi:[1,0]
	v_pk_mul_f32 v[148:149], v[104:105], v[148:149] op_sel_hi:[1,0]
	v_mul_f32_e32 v154, 0xbfb8aa3b, v154
	v_exp_f32_e32 v154, v154
	v_mul_f32_e32 v148, 0xbfb8aa3b, v148
	v_exp_f32_e32 v148, v148
	v_mul_f32_e32 v155, 0xbfb8aa3b, v155
	v_exp_f32_e32 v155, v155
	v_mul_f32_e32 v149, 0xbfb8aa3b, v149
	v_exp_f32_e32 v149, v149
	v_mul_f32_e32 v146, 0xbfb8aa3b, v146
	v_exp_f32_e32 v146, v146
	v_mul_f32_e32 v156, 0xbfb8aa3b, v156
	v_exp_f32_e32 v156, v156
	v_mul_f32_e32 v147, 0xbfb8aa3b, v147
	v_exp_f32_e32 v147, v147
	v_mul_f32_e32 v157, 0xbfb8aa3b, v157
	v_exp_f32_e32 v157, v157
	s_nop 0
	v_add_f32_e32 v154, 1.0, v154
	v_add_f32_e32 v155, 1.0, v155
	v_rcp_f32_e32 v154, v154
	v_rcp_f32_e32 v155, v155
	s_nop 0
	s_nop 0
	v_add_f32_e32 v148, 1.0, v148
	v_add_f32_e32 v149, 1.0, v149
	v_rcp_f32_e32 v148, v148
	v_rcp_f32_e32 v149, v149
	s_nop 0
	s_nop 0
	v_add_f32_e32 v158, 1.0, v146
	v_add_f32_e32 v159, 1.0, v147
	v_rcp_f32_e32 v158, v158
	v_rcp_f32_e32 v159, v159
	s_nop 0
	s_nop 0
	v_add_f32_e32 v156, 1.0, v156
	v_add_f32_e32 v157, 1.0, v157
	v_rcp_f32_e32 v156, v156
	v_rcp_f32_e32 v157, v157
	s_nop 0
	v_cvt_pk_bf16_f32 v146, v154, v155
	v_cvt_pk_bf16_f32 v147, v158, v159
	v_cvt_pk_bf16_f32 v148, v148, v149
	v_cvt_pk_bf16_f32 v149, v156, v157
	global_store_dwordx4 v[150:151], v[146:149], off offset:256
	v_lshl_add_u64 v[150:151], v[152:153], 0, v[142:143]
	v_pk_mul_f32 v[142:143], v[86:87], v[144:145] op_sel_hi:[1,0]
	v_pk_mul_f32 v[146:147], v[84:85], v[144:145] op_sel_hi:[1,0]
	v_pk_mul_f32 v[148:149], v[82:83], v[144:145] op_sel_hi:[1,0]
	v_pk_mul_f32 v[154:155], v[80:81], v[144:145] op_sel_hi:[1,0]
	v_mul_f32_e32 v146, 0xbfb8aa3b, v146
	v_exp_f32_e32 v146, v146
	v_mul_f32_e32 v154, 0xbfb8aa3b, v154
	v_exp_f32_e32 v154, v154
	v_mul_f32_e32 v147, 0xbfb8aa3b, v147
	v_exp_f32_e32 v147, v147
	v_mul_f32_e32 v155, 0xbfb8aa3b, v155
	v_exp_f32_e32 v155, v155
	v_mul_f32_e32 v142, 0xbfb8aa3b, v142
	v_exp_f32_e32 v142, v142
	v_mul_f32_e32 v148, 0xbfb8aa3b, v148
	v_exp_f32_e32 v148, v148
	v_mul_f32_e32 v143, 0xbfb8aa3b, v143
	v_exp_f32_e32 v143, v143
	v_mul_f32_e32 v149, 0xbfb8aa3b, v149
	v_exp_f32_e32 v149, v149
	s_nop 0
	v_add_f32_e32 v146, 1.0, v146
	v_add_f32_e32 v147, 1.0, v147
	v_rcp_f32_e32 v146, v146
	v_rcp_f32_e32 v147, v147
	s_nop 0
	s_nop 0
	v_add_f32_e32 v154, 1.0, v154
	v_add_f32_e32 v155, 1.0, v155
	v_rcp_f32_e32 v154, v154
	v_rcp_f32_e32 v155, v155
	s_nop 0
	s_nop 0
	v_add_f32_e32 v142, 1.0, v142
	v_add_f32_e32 v143, 1.0, v143
	v_rcp_f32_e32 v142, v142
	v_rcp_f32_e32 v143, v143
	s_nop 0
	s_nop 0
	v_add_f32_e32 v156, 1.0, v148
	v_add_f32_e32 v157, 1.0, v149
	v_rcp_f32_e32 v156, v156
	v_rcp_f32_e32 v157, v157
	s_nop 0
	v_cvt_pk_bf16_f32 v146, v146, v147
	v_cvt_pk_bf16_f32 v147, v142, v143
	v_cvt_pk_bf16_f32 v148, v154, v155
	v_cvt_pk_bf16_f32 v149, v156, v157
	global_store_dwordx4 v[150:151], v[146:149], off
	v_pk_mul_f32 v[142:143], v[94:95], v[144:145] op_sel_hi:[1,0]
	s_mov_b64 s[0:1], 0x40000
	v_pk_mul_f32 v[146:147], v[92:93], v[144:145] op_sel_hi:[1,0]
; __device__ __forceinline__ unsigned cvt_pk_bf16(float lo, float hi) { const f32x2 v = {lo, hi}; const bf16v2_t b = __builtin_convertvector(v, bf16v2_t); return __builtin_bit_cast(unsigned, b); }
; __device__ __forceinline__ float siluf_(float x) { return x * __builtin_amdgcn_rcpf(1.0f + __builtin_amdgcn_exp2f(x * -1.44269504089f)); }
; __device__ __forceinline__ float sigmoidf_(float x) { return __builtin_amdgcn_rcpf(1.0f + __builtin_amdgcn_exp2f(x * -1.44269504089f)); }
;     __device__ __forceinline__ void epi_proj(const f32x4 (&acc)[2][2][4][2], const pg8::Unit& u, int wr, int wc, int fr, int fq) const {
;     ...
; #pragma unroll
;                         for (int bj = 0; bj < 2; ++bj) {
;                             f32x4 v0 = acc[ai][bj][m][0] * rstd, v1 = acc[ai][bj][m][1] * rstd;
;                             if (slot < 2) {
;                                 f32x2 a = gelu_pk((f32x2){v0[0], v0[1]}), b = gelu_pk((f32x2){v0[2], v0[3]}), c = gelu_pk((f32x2){v1[0], v1[1]}), d = gelu_pk((f32x2){v1[2], v1[3]});
;                                 v0 = (f32x4){a.x, a.y, b.x, b.y}; v1 = (f32x4){c.x, c.y, d.x, d.y};
;                             } else if (slot == 5) {
; #pragma unroll
;                                 for (int j = 0; j < 4; ++j) { v0[j] = siluf_(v0[j]); v1[j] = siluf_(v1[j]); }
;                             } else if (slot >= 6) {
; #pragma unroll
;                                 for (int j = 0; j < 4; ++j) { v0[j] = sigmoidf_(v0[j]); v1[j] = sigmoidf_(v1[j]); }
;                             }
;                             u32x4 w; w.x = cvt_pk_bf16(v0[0], v0[1]); w.y = cvt_pk_bf16(v0[2], v0[3]); w.z = cvt_pk_bf16(v1[0], v1[1]); w.w = cvt_pk_bf16(v1[2], v1[3]);
;                             *(u32x4*)(rowp + bj * 128) = w;
	v_pk_mul_f32 v[148:149], v[90:91], v[144:145] op_sel_hi:[1,0]
	v_pk_mul_f32 v[144:145], v[88:89], v[144:145] op_sel_hi:[1,0]
	v_mul_f32_e32 v146, 0xbfb8aa3b, v146
	v_exp_f32_e32 v146, v146
	v_mul_f32_e32 v144, 0xbfb8aa3b, v144
	v_exp_f32_e32 v144, v144
	v_mul_f32_e32 v147, 0xbfb8aa3b, v147
	v_exp_f32_e32 v147, v147
	v_mul_f32_e32 v145, 0xbfb8aa3b, v145
	v_exp_f32_e32 v145, v145
	v_mul_f32_e32 v142, 0xbfb8aa3b, v142
	v_exp_f32_e32 v142, v142
	v_mul_f32_e32 v148, 0xbfb8aa3b, v148
	v_exp_f32_e32 v148, v148
	v_mul_f32_e32 v143, 0xbfb8aa3b, v143
	v_exp_f32_e32 v143, v143
	v_mul_f32_e32 v149, 0xbfb8aa3b, v149
	v_exp_f32_e32 v149, v149
	s_nop 0
	v_add_f32_e32 v146, 1.0, v146
	v_add_f32_e32 v147, 1.0, v147
	v_rcp_f32_e32 v146, v146
	v_rcp_f32_e32 v147, v147
	s_nop 0
	s_nop 0
	v_add_f32_e32 v144, 1.0, v144
	v_add_f32_e32 v145, 1.0, v145
	v_rcp_f32_e32 v144, v144
	v_rcp_f32_e32 v145, v145
	s_nop 0
	s_nop 0
	v_add_f32_e32 v154, 1.0, v142
	v_add_f32_e32 v155, 1.0, v143
	v_rcp_f32_e32 v154, v154
	v_rcp_f32_e32 v155, v155
	s_nop 0
	s_nop 0
	v_add_f32_e32 v148, 1.0, v148
	v_add_f32_e32 v149, 1.0, v149
	v_rcp_f32_e32 v148, v148
	v_rcp_f32_e32 v149, v149
	s_nop 0
	v_cvt_pk_bf16_f32 v142, v146, v147
	v_cvt_pk_bf16_f32 v143, v154, v155
	v_cvt_pk_bf16_f32 v144, v144, v145
	v_cvt_pk_bf16_f32 v145, v148, v149
	global_store_dwordx4 v[150:151], v[142:145], off offset:256
	v_pk_mul_f32 v[146:147], v[66:67], v[138:139] op_sel_hi:[1,0]
	v_pk_mul_f32 v[148:149], v[64:65], v[138:139] op_sel_hi:[1,0]
	v_lshl_add_u64 v[144:145], v[152:153], 0, v[140:141]
	v_pk_mul_f32 v[140:141], v[70:71], v[138:139] op_sel_hi:[1,0]
	v_pk_mul_f32 v[142:143], v[68:69], v[138:139] op_sel_hi:[1,0]
	v_mul_f32_e32 v148, 0xbfb8aa3b, v148
	v_exp_f32_e32 v148, v148
	v_mul_f32_e32 v142, 0xbfb8aa3b, v142
	v_exp_f32_e32 v142, v142
	v_mul_f32_e32 v143, 0xbfb8aa3b, v143
	v_exp_f32_e32 v143, v143
	v_mul_f32_e32 v149, 0xbfb8aa3b, v149
	v_exp_f32_e32 v149, v149
	v_mul_f32_e32 v140, 0xbfb8aa3b, v140
	v_exp_f32_e32 v140, v140
	v_mul_f32_e32 v146, 0xbfb8aa3b, v146
	v_exp_f32_e32 v146, v146
	v_mul_f32_e32 v141, 0xbfb8aa3b, v141
	v_exp_f32_e32 v141, v141
	v_mul_f32_e32 v147, 0xbfb8aa3b, v147
	v_exp_f32_e32 v147, v147
	s_nop 0
	v_add_f32_e32 v142, 1.0, v142
	v_add_f32_e32 v143, 1.0, v143
	v_rcp_f32_e32 v142, v142
	v_rcp_f32_e32 v143, v143
	s_nop 0
	s_nop 0
	v_add_f32_e32 v148, 1.0, v148
	v_add_f32_e32 v149, 1.0, v149
	v_rcp_f32_e32 v148, v148
	v_rcp_f32_e32 v149, v149
	s_nop 0
	s_nop 0
	v_add_f32_e32 v150, 1.0, v140
	v_add_f32_e32 v151, 1.0, v141
	v_rcp_f32_e32 v150, v150
	v_rcp_f32_e32 v151, v151
	s_nop 0
	s_nop 0
	v_add_f32_e32 v146, 1.0, v146
	v_add_f32_e32 v147, 1.0, v147
	v_rcp_f32_e32 v146, v146
	v_rcp_f32_e32 v147, v147
	s_nop 0
	v_cvt_pk_bf16_f32 v140, v142, v143
	v_cvt_pk_bf16_f32 v141, v150, v151
	v_cvt_pk_bf16_f32 v142, v148, v149
	v_cvt_pk_bf16_f32 v143, v146, v147
	global_store_dwordx4 v[144:145], v[140:143], off
	v_pk_mul_f32 v[146:147], v[74:75], v[138:139] op_sel_hi:[1,0]
	v_mul_f32_e32 v129, 0x45800000, v128
	v_pk_mul_f32 v[140:141], v[78:79], v[138:139] op_sel_hi:[1,0]
	v_pk_mul_f32 v[142:143], v[76:77], v[138:139] op_sel_hi:[1,0]
	v_pk_mul_f32 v[138:139], v[72:73], v[138:139] op_sel_hi:[1,0]
	v_mul_f32_e32 v142, 0xbfb8aa3b, v142
	v_exp_f32_e32 v142, v142
	v_mul_f32_e32 v138, 0xbfb8aa3b, v138
	v_exp_f32_e32 v138, v138
	v_mul_f32_e32 v139, 0xbfb8aa3b, v139
	v_exp_f32_e32 v139, v139
	v_mul_f32_e32 v143, 0xbfb8aa3b, v143
	v_exp_f32_e32 v143, v143
	s_nop 0
	v_add_f32_e32 v148, 1.0, v138
	v_add_f32_e32 v149, 1.0, v139
	v_rcp_f32_e32 v148, v148
	v_rcp_f32_e32 v149, v149
	s_nop 0
	v_mul_f32_e32 v138, 0xbfb8aa3b, v140
	v_exp_f32_e32 v138, v138
	v_mul_f32_e32 v140, 0xbfb8aa3b, v146
	v_exp_f32_e32 v140, v140
	v_mul_f32_e32 v139, 0xbfb8aa3b, v141
	v_exp_f32_e32 v139, v139
	v_mul_f32_e32 v141, 0xbfb8aa3b, v147
	v_exp_f32_e32 v141, v141
	s_nop 0
	v_add_f32_e32 v142, 1.0, v142
	v_add_f32_e32 v143, 1.0, v143
	v_rcp_f32_e32 v142, v142
	v_rcp_f32_e32 v143, v143
	s_nop 0
	s_nop 0
	v_add_f32_e32 v150, 1.0, v138
	v_add_f32_e32 v151, 1.0, v139
	v_rcp_f32_e32 v150, v150
	v_rcp_f32_e32 v151, v151
	s_nop 0
	s_nop 0
	v_add_f32_e32 v146, 1.0, v140
	v_add_f32_e32 v147, 1.0, v141
	v_rcp_f32_e32 v146, v146
	v_rcp_f32_e32 v147, v147
	s_nop 0
	v_cvt_pk_bf16_f32 v138, v142, v143
	v_cvt_pk_bf16_f32 v139, v150, v151
	v_cvt_pk_bf16_f32 v140, v148, v149
	v_cvt_pk_bf16_f32 v141, v146, v147
	global_store_dwordx4 v[144:145], v[138:141], off offset:256
	v_pk_mul_f32 v[144:145], v[50:51], v[134:135] op_sel_hi:[1,0]
	v_pk_mul_f32 v[146:147], v[48:49], v[134:135] op_sel_hi:[1,0]
	v_pk_mul_f32 v[140:141], v[52:53], v[134:135] op_sel_hi:[1,0]
	v_pk_mul_f32 v[138:139], v[54:55], v[134:135] op_sel_hi:[1,0]
	v_mul_f32_e32 v140, 0xbfb8aa3b, v140
	v_exp_f32_e32 v140, v140
	v_mul_f32_e32 v141, 0xbfb8aa3b, v141
	v_exp_f32_e32 v141, v141
	v_mul_f32_e32 v144, 0xbfb8aa3b, v144
	v_exp_f32_e32 v144, v144
	v_mul_f32_e32 v145, 0xbfb8aa3b, v145
	v_exp_f32_e32 v145, v145
	v_lshl_add_u64 v[142:143], v[136:137], 0, s[0:1]
	v_mul_f32_e32 v146, 0xbfb8aa3b, v146
	v_exp_f32_e32 v146, v146
	s_nop 0
	v_add_f32_e32 v140, 1.0, v140
	v_add_f32_e32 v141, 1.0, v141
	v_rcp_f32_e32 v140, v140
	v_rcp_f32_e32 v141, v141
	s_nop 0
	v_mul_f32_e32 v147, 0xbfb8aa3b, v147
	v_exp_f32_e32 v147, v147
	v_mul_f32_e32 v138, 0xbfb8aa3b, v138
	v_exp_f32_e32 v138, v138
	v_mul_f32_e32 v139, 0xbfb8aa3b, v139
	v_exp_f32_e32 v139, v139
	s_nop 0
	v_add_f32_e32 v144, 1.0, v144
	v_add_f32_e32 v145, 1.0, v145
	v_rcp_f32_e32 v144, v144
	v_rcp_f32_e32 v145, v145
	s_nop 0
	s_mov_b32 s0, 0x40000
	v_cndmask_b32_e32 v128, v128, v129, vcc
	s_nop 0
	v_add_f32_e32 v146, 1.0, v146
; __device__ __forceinline__ unsigned cvt_pk_bf16(float lo, float hi) { const f32x2 v = {lo, hi}; const bf16v2_t b = __builtin_convertvector(v, bf16v2_t); return __builtin_bit_cast(unsigned, b); }
; __device__ __forceinline__ float siluf_(float x) { return x * __builtin_amdgcn_rcpf(1.0f + __builtin_amdgcn_exp2f(x * -1.44269504089f)); }
; __device__ __forceinline__ float sigmoidf_(float x) { return __builtin_amdgcn_rcpf(1.0f + __builtin_amdgcn_exp2f(x * -1.44269504089f)); }
;     __device__ __forceinline__ void epi_proj(const f32x4 (&acc)[2][2][4][2], const pg8::Unit& u, int wr, int wc, int fr, int fq) const {
;     ...
; #pragma unroll
;                         for (int bj = 0; bj < 2; ++bj) {
;                             f32x4 v0 = acc[ai][bj][m][0] * rstd, v1 = acc[ai][bj][m][1] * rstd;
;                             if (slot < 2) {
;                                 f32x2 a = gelu_pk((f32x2){v0[0], v0[1]}), b = gelu_pk((f32x2){v0[2], v0[3]}), c = gelu_pk((f32x2){v1[0], v1[1]}), d = gelu_pk((f32x2){v1[2], v1[3]});
;                                 v0 = (f32x4){a.x, a.y, b.x, b.y}; v1 = (f32x4){c.x, c.y, d.x, d.y};
;                             } else if (slot == 5) {
; #pragma unroll
;                                 for (int j = 0; j < 4; ++j) { v0[j] = siluf_(v0[j]); v1[j] = siluf_(v1[j]); }
;                             } else if (slot >= 6) {
; #pragma unroll
;                                 for (int j = 0; j < 4; ++j) { v0[j] = sigmoidf_(v0[j]); v1[j] = sigmoidf_(v1[j]); }
;                             }
;                             u32x4 w; w.x = cvt_pk_bf16(v0[0], v0[1]); w.y = cvt_pk_bf16(v0[2], v0[3]); w.z = cvt_pk_bf16(v1[0], v1[1]); w.w = cvt_pk_bf16(v1[2], v1[3]);
;                             *(u32x4*)(rowp + bj * 128) = w;
	v_add_f32_e32 v147, 1.0, v147
	v_rcp_f32_e32 v146, v146
	v_rcp_f32_e32 v147, v147
	s_nop 0
	s_nop 0
	v_add_f32_e32 v148, 1.0, v138
	v_add_f32_e32 v149, 1.0, v139
	v_rcp_f32_e32 v148, v148
	v_rcp_f32_e32 v149, v149
	s_nop 0
	v_cvt_pk_bf16_f32 v138, v140, v141
	v_cvt_pk_bf16_f32 v141, v144, v145
	v_add_co_u32_e32 v144, vcc, s0, v136
	v_cvt_pk_bf16_f32 v139, v148, v149
	v_cvt_pk_bf16_f32 v140, v146, v147
	v_addc_co_u32_e32 v145, vcc, 0, v137, vcc
	global_store_dwordx4 v[144:145], v[138:141], off
	v_pk_mul_f32 v[144:145], v[58:59], v[134:135] op_sel_hi:[1,0]
	s_mov_b64 s[0:1], 0x48000
	v_pk_mul_f32 v[138:139], v[62:63], v[134:135] op_sel_hi:[1,0]
	v_pk_mul_f32 v[140:141], v[60:61], v[134:135] op_sel_hi:[1,0]
	v_pk_mul_f32 v[134:135], v[56:57], v[134:135] op_sel_hi:[1,0]
	v_mul_f32_e32 v140, 0xbfb8aa3b, v140
	v_exp_f32_e32 v140, v140
	v_mul_f32_e32 v134, 0xbfb8aa3b, v134
	v_exp_f32_e32 v134, v134
	v_mul_f32_e32 v141, 0xbfb8aa3b, v141
	v_exp_f32_e32 v141, v141
	v_mul_f32_e32 v135, 0xbfb8aa3b, v135
	v_exp_f32_e32 v135, v135
	v_mul_f32_e32 v138, 0xbfb8aa3b, v138
	v_exp_f32_e32 v138, v138
	v_mul_f32_e32 v144, 0xbfb8aa3b, v144
	v_exp_f32_e32 v144, v144
	v_mul_f32_e32 v139, 0xbfb8aa3b, v139
	v_exp_f32_e32 v139, v139
	v_mul_f32_e32 v145, 0xbfb8aa3b, v145
	v_exp_f32_e32 v145, v145
	s_nop 0
	v_add_f32_e32 v140, 1.0, v140
	v_add_f32_e32 v141, 1.0, v141
	v_rcp_f32_e32 v140, v140
	v_rcp_f32_e32 v141, v141
	s_nop 0
	s_nop 0
	v_add_f32_e32 v134, 1.0, v134
	v_add_f32_e32 v135, 1.0, v135
	v_rcp_f32_e32 v134, v134
	v_rcp_f32_e32 v135, v135
	s_nop 0
	s_nop 0
	v_add_f32_e32 v146, 1.0, v138
	v_add_f32_e32 v147, 1.0, v139
	v_rcp_f32_e32 v146, v146
	v_rcp_f32_e32 v147, v147
	s_nop 0
	s_nop 0
	v_add_f32_e32 v144, 1.0, v144
	v_add_f32_e32 v145, 1.0, v145
	v_rcp_f32_e32 v144, v144
	v_rcp_f32_e32 v145, v145
	s_nop 0
	v_cvt_pk_bf16_f32 v138, v140, v141
	v_cvt_pk_bf16_f32 v139, v146, v147
	v_cvt_pk_bf16_f32 v140, v134, v135
	v_cvt_pk_bf16_f32 v141, v144, v145
	global_store_dwordx4 v[142:143], v[138:141], off offset:256
	v_pk_mul_f32 v[134:135], v[38:39], v[132:133] op_sel_hi:[1,0]
	v_pk_mul_f32 v[144:145], v[32:33], v[132:133] op_sel_hi:[1,0]
	v_pk_mul_f32 v[138:139], v[36:37], v[132:133] op_sel_hi:[1,0]
	v_pk_mul_f32 v[140:141], v[34:35], v[132:133] op_sel_hi:[1,0]
	v_mul_f32_e32 v138, 0xbfb8aa3b, v138
	v_exp_f32_e32 v138, v138
	v_mul_f32_e32 v139, 0xbfb8aa3b, v139
	v_exp_f32_e32 v139, v139
	v_mul_f32_e32 v134, 0xbfb8aa3b, v134
	v_exp_f32_e32 v134, v134
	v_mul_f32_e32 v135, 0xbfb8aa3b, v135
	v_exp_f32_e32 v135, v135
	v_lshl_add_u64 v[142:143], v[136:137], 0, s[0:1]
	v_mul_f32_e32 v144, 0xbfb8aa3b, v144
	v_exp_f32_e32 v144, v144
	s_nop 0
	v_add_f32_e32 v138, 1.0, v138
	v_add_f32_e32 v139, 1.0, v139
	v_rcp_f32_e32 v138, v138
	v_rcp_f32_e32 v139, v139
	s_nop 0
	v_mul_f32_e32 v145, 0xbfb8aa3b, v145
	v_exp_f32_e32 v145, v145
	v_mul_f32_e32 v140, 0xbfb8aa3b, v140
	v_exp_f32_e32 v140, v140
	s_nop 0
	v_add_f32_e32 v134, 1.0, v134
	v_add_f32_e32 v135, 1.0, v135
	v_rcp_f32_e32 v134, v134
	v_rcp_f32_e32 v135, v135
	s_nop 0
	v_mul_f32_e32 v141, 0xbfb8aa3b, v141
	v_exp_f32_e32 v141, v141
	s_mov_b32 s0, 0x48000
	s_nop 0
	v_add_f32_e32 v144, 1.0, v144
	v_add_f32_e32 v145, 1.0, v145
	v_rcp_f32_e32 v144, v144
	v_rcp_f32_e32 v145, v145
	s_nop 0
	s_nop 0
	v_add_f32_e32 v146, 1.0, v140
	v_add_f32_e32 v147, 1.0, v141
	v_rcp_f32_e32 v146, v146
	v_rcp_f32_e32 v147, v147
	s_nop 0
	v_cvt_pk_bf16_f32 v138, v138, v139
	v_cvt_pk_bf16_f32 v139, v134, v135
	v_add_co_u32_e32 v134, vcc, s0, v136
	v_cvt_pk_bf16_f32 v140, v144, v145
	v_cvt_pk_bf16_f32 v141, v146, v147
	v_addc_co_u32_e32 v135, vcc, 0, v137, vcc
	global_store_dwordx4 v[134:135], v[138:141], off
	v_pk_mul_f32 v[134:135], v[46:47], v[132:133] op_sel_hi:[1,0]
	s_mov_b64 s[0:1], 0x50000
	v_pk_mul_f32 v[138:139], v[44:45], v[132:133] op_sel_hi:[1,0]
	v_pk_mul_f32 v[140:141], v[42:43], v[132:133] op_sel_hi:[1,0]
	v_pk_mul_f32 v[132:133], v[40:41], v[132:133] op_sel_hi:[1,0]
	v_mul_f32_e32 v138, 0xbfb8aa3b, v138
	v_exp_f32_e32 v138, v138
	v_mul_f32_e32 v132, 0xbfb8aa3b, v132
	v_exp_f32_e32 v132, v132
	v_mul_f32_e32 v133, 0xbfb8aa3b, v133
	v_exp_f32_e32 v133, v133
	v_mul_f32_e32 v139, 0xbfb8aa3b, v139
	v_exp_f32_e32 v139, v139
	s_nop 0
	v_add_f32_e32 v144, 1.0, v132
	v_add_f32_e32 v145, 1.0, v133
	v_rcp_f32_e32 v144, v144
	v_rcp_f32_e32 v145, v145
	s_nop 0
	v_mul_f32_e32 v132, 0xbfb8aa3b, v134
	v_exp_f32_e32 v132, v132
	v_mul_f32_e32 v134, 0xbfb8aa3b, v140
	v_exp_f32_e32 v134, v134
	v_mul_f32_e32 v133, 0xbfb8aa3b, v135
	v_exp_f32_e32 v133, v133
	v_mul_f32_e32 v135, 0xbfb8aa3b, v141
	v_exp_f32_e32 v135, v135
	s_nop 0
	v_add_f32_e32 v138, 1.0, v138
	v_add_f32_e32 v139, 1.0, v139
	v_rcp_f32_e32 v138, v138
	v_rcp_f32_e32 v139, v139
	s_nop 0
	s_nop 0
	v_add_f32_e32 v146, 1.0, v132
	v_add_f32_e32 v147, 1.0, v133
	v_rcp_f32_e32 v146, v146
	v_rcp_f32_e32 v147, v147
	s_nop 0
	s_nop 0
	v_add_f32_e32 v140, 1.0, v134
	v_add_f32_e32 v141, 1.0, v135
	v_rcp_f32_e32 v140, v140
	v_rcp_f32_e32 v141, v141
	s_nop 0
	v_cvt_pk_bf16_f32 v132, v138, v139
	v_cvt_pk_bf16_f32 v133, v146, v147
	v_cvt_pk_bf16_f32 v134, v144, v145
	v_cvt_pk_bf16_f32 v135, v140, v141
	global_store_dwordx4 v[142:143], v[132:135], off offset:256
	v_pk_mul_f32 v[140:141], v[18:19], v[130:131] op_sel_hi:[1,0]
	v_pk_mul_f32 v[142:143], v[16:17], v[130:131] op_sel_hi:[1,0]
	v_pk_mul_f32 v[134:135], v[20:21], v[130:131] op_sel_hi:[1,0]
	v_pk_mul_f32 v[132:133], v[22:23], v[130:131] op_sel_hi:[1,0]
	v_mul_f32_e32 v134, 0xbfb8aa3b, v134
	v_exp_f32_e32 v134, v134
	v_mul_f32_e32 v135, 0xbfb8aa3b, v135
	v_exp_f32_e32 v135, v135
	v_mul_f32_e32 v140, 0xbfb8aa3b, v140
	v_exp_f32_e32 v140, v140
; __device__ __forceinline__ unsigned cvt_pk_bf16(float lo, float hi) { const f32x2 v = {lo, hi}; const bf16v2_t b = __builtin_convertvector(v, bf16v2_t); return __builtin_bit_cast(unsigned, b); }
; __device__ __forceinline__ float siluf_(float x) { return x * __builtin_amdgcn_rcpf(1.0f + __builtin_amdgcn_exp2f(x * -1.44269504089f)); }
; __device__ __forceinline__ float sigmoidf_(float x) { return __builtin_amdgcn_rcpf(1.0f + __builtin_amdgcn_exp2f(x * -1.44269504089f)); }
;     __device__ __forceinline__ void epi_proj(const f32x4 (&acc)[2][2][4][2], const pg8::Unit& u, int wr, int wc, int fr, int fq) const {
;     ...
; #pragma unroll
;                         for (int bj = 0; bj < 2; ++bj) {
;                             f32x4 v0 = acc[ai][bj][m][0] * rstd, v1 = acc[ai][bj][m][1] * rstd;
;                             if (slot < 2) {
;                                 f32x2 a = gelu_pk((f32x2){v0[0], v0[1]}), b = gelu_pk((f32x2){v0[2], v0[3]}), c = gelu_pk((f32x2){v1[0], v1[1]}), d = gelu_pk((f32x2){v1[2], v1[3]});
;                                 v0 = (f32x4){a.x, a.y, b.x, b.y}; v1 = (f32x4){c.x, c.y, d.x, d.y};
;                             } else if (slot == 5) {
; #pragma unroll
;                                 for (int j = 0; j < 4; ++j) { v0[j] = siluf_(v0[j]); v1[j] = siluf_(v1[j]); }
;                             } else if (slot >= 6) {
; #pragma unroll
;                                 for (int j = 0; j < 4; ++j) { v0[j] = sigmoidf_(v0[j]); v1[j] = sigmoidf_(v1[j]); }
;                             }
;                             u32x4 w; w.x = cvt_pk_bf16(v0[0], v0[1]); w.y = cvt_pk_bf16(v0[2], v0[3]); w.z = cvt_pk_bf16(v1[0], v1[1]); w.w = cvt_pk_bf16(v1[2], v1[3]);
;                             *(u32x4*)(rowp + bj * 128) = w;
	v_mul_f32_e32 v141, 0xbfb8aa3b, v141
	v_exp_f32_e32 v141, v141
	v_lshl_add_u64 v[138:139], v[136:137], 0, s[0:1]
	v_mul_f32_e32 v142, 0xbfb8aa3b, v142
	v_exp_f32_e32 v142, v142
	s_nop 0
	v_add_f32_e32 v134, 1.0, v134
	v_add_f32_e32 v135, 1.0, v135
	v_rcp_f32_e32 v134, v134
	v_rcp_f32_e32 v135, v135
	s_nop 0
	v_mul_f32_e32 v143, 0xbfb8aa3b, v143
	v_exp_f32_e32 v143, v143
	v_mul_f32_e32 v132, 0xbfb8aa3b, v132
	v_exp_f32_e32 v132, v132
	v_mul_f32_e32 v133, 0xbfb8aa3b, v133
	v_exp_f32_e32 v133, v133
	s_nop 0
	v_add_f32_e32 v140, 1.0, v140
	v_add_f32_e32 v141, 1.0, v141
	v_rcp_f32_e32 v140, v140
	v_rcp_f32_e32 v141, v141
	s_nop 0
	s_mov_b32 s0, 0x50000
	s_nop 0
	v_add_f32_e32 v142, 1.0, v142
	v_add_f32_e32 v143, 1.0, v143
	v_rcp_f32_e32 v142, v142
	v_rcp_f32_e32 v143, v143
	s_nop 0
	s_nop 0
	v_add_f32_e32 v144, 1.0, v132
	v_add_f32_e32 v145, 1.0, v133
	v_rcp_f32_e32 v144, v144
	v_rcp_f32_e32 v145, v145
	s_nop 0
	v_cvt_pk_bf16_f32 v132, v134, v135
	v_cvt_pk_bf16_f32 v135, v140, v141
	v_add_co_u32_e32 v140, vcc, s0, v136
	v_cvt_pk_bf16_f32 v133, v144, v145
	v_cvt_pk_bf16_f32 v134, v142, v143
	v_addc_co_u32_e32 v141, vcc, 0, v137, vcc
	global_store_dwordx4 v[140:141], v[132:135], off
	v_pk_mul_f32 v[140:141], v[26:27], v[130:131] op_sel_hi:[1,0]
	s_mov_b64 s[0:1], 0x58000
	v_pk_mul_f32 v[132:133], v[30:31], v[130:131] op_sel_hi:[1,0]
	v_pk_mul_f32 v[134:135], v[28:29], v[130:131] op_sel_hi:[1,0]
	v_pk_mul_f32 v[130:131], v[24:25], v[130:131] op_sel_hi:[1,0]
	v_mul_f32_e32 v134, 0xbfb8aa3b, v134
	v_exp_f32_e32 v134, v134
	v_mul_f32_e32 v130, 0xbfb8aa3b, v130
	v_exp_f32_e32 v130, v130
	v_mul_f32_e32 v131, 0xbfb8aa3b, v131
	v_exp_f32_e32 v131, v131
	v_mul_f32_e32 v135, 0xbfb8aa3b, v135
	v_exp_f32_e32 v135, v135
	s_nop 0
	v_add_f32_e32 v142, 1.0, v130
	v_add_f32_e32 v143, 1.0, v131
	v_rcp_f32_e32 v142, v142
	v_rcp_f32_e32 v143, v143
	s_nop 0
	v_mul_f32_e32 v130, 0xbfb8aa3b, v132
	v_exp_f32_e32 v130, v130
	v_mul_f32_e32 v132, 0xbfb8aa3b, v140
	v_exp_f32_e32 v132, v132
	v_mul_f32_e32 v131, 0xbfb8aa3b, v133
	v_exp_f32_e32 v131, v131
	v_mul_f32_e32 v133, 0xbfb8aa3b, v141
	v_exp_f32_e32 v133, v133
	s_nop 0
	v_add_f32_e32 v134, 1.0, v134
	v_add_f32_e32 v135, 1.0, v135
	v_rcp_f32_e32 v134, v134
	v_rcp_f32_e32 v135, v135
	s_nop 0
	s_nop 0
	v_add_f32_e32 v144, 1.0, v130
	v_add_f32_e32 v145, 1.0, v131
	v_rcp_f32_e32 v144, v144
	v_rcp_f32_e32 v145, v145
	s_nop 0
	s_nop 0
	v_add_f32_e32 v140, 1.0, v132
	v_add_f32_e32 v141, 1.0, v133
	v_rcp_f32_e32 v140, v140
	v_rcp_f32_e32 v141, v141
	s_nop 0
	v_cvt_pk_bf16_f32 v130, v134, v135
	v_cvt_pk_bf16_f32 v131, v144, v145
	v_cvt_pk_bf16_f32 v132, v142, v143
	v_cvt_pk_bf16_f32 v133, v140, v141
	global_store_dwordx4 v[138:139], v[130:133], off offset:256
	v_pk_mul_f32 v[138:139], v[2:3], v[128:129] op_sel_hi:[1,0]
	v_pk_mul_f32 v[140:141], v[0:1], v[128:129] op_sel_hi:[1,0]
	v_pk_mul_f32 v[130:131], v[6:7], v[128:129] op_sel_hi:[1,0]
	v_pk_mul_f32 v[132:133], v[4:5], v[128:129] op_sel_hi:[1,0]
	v_lshl_add_u64 v[134:135], v[136:137], 0, s[0:1]
	v_mul_f32_e32 v132, 0xbfb8aa3b, v132
	v_exp_f32_e32 v132, v132
	v_mul_f32_e32 v140, 0xbfb8aa3b, v140
	v_exp_f32_e32 v140, v140
	v_mul_f32_e32 v133, 0xbfb8aa3b, v133
	v_exp_f32_e32 v133, v133
	v_mul_f32_e32 v141, 0xbfb8aa3b, v141
	v_exp_f32_e32 v141, v141
	v_mul_f32_e32 v130, 0xbfb8aa3b, v130
	v_exp_f32_e32 v130, v130
	v_mul_f32_e32 v138, 0xbfb8aa3b, v138
	v_exp_f32_e32 v138, v138
	v_mul_f32_e32 v131, 0xbfb8aa3b, v131
	v_exp_f32_e32 v131, v131
	v_mul_f32_e32 v139, 0xbfb8aa3b, v139
	v_exp_f32_e32 v139, v139
	s_mov_b32 s0, 0x58000
	s_nop 0
	v_add_f32_e32 v132, 1.0, v132
	v_add_f32_e32 v133, 1.0, v133
	v_rcp_f32_e32 v132, v132
	v_rcp_f32_e32 v133, v133
	s_nop 0
	s_nop 0
	v_add_f32_e32 v140, 1.0, v140
	v_add_f32_e32 v141, 1.0, v141
	v_rcp_f32_e32 v140, v140
	v_rcp_f32_e32 v141, v141
	s_nop 0
	s_nop 0
	v_add_f32_e32 v142, 1.0, v130
	v_add_f32_e32 v143, 1.0, v131
	v_rcp_f32_e32 v142, v142
	v_rcp_f32_e32 v143, v143
	s_nop 0
	s_nop 0
	v_add_f32_e32 v138, 1.0, v138
	v_add_f32_e32 v139, 1.0, v139
	v_rcp_f32_e32 v138, v138
	v_rcp_f32_e32 v139, v139
	s_nop 0
	v_add_co_u32_e32 v136, vcc, s0, v136
	v_cvt_pk_bf16_f32 v130, v132, v133
	v_cvt_pk_bf16_f32 v131, v142, v143
	v_cvt_pk_bf16_f32 v132, v140, v141
	v_cvt_pk_bf16_f32 v133, v138, v139
	v_addc_co_u32_e32 v137, vcc, 0, v137, vcc
	global_store_dwordx4 v[136:137], v[130:133], off
	v_pk_mul_f32 v[136:137], v[10:11], v[128:129] op_sel_hi:[1,0]
	s_nop 0
	v_pk_mul_f32 v[130:131], v[14:15], v[128:129] op_sel_hi:[1,0]
	v_pk_mul_f32 v[132:133], v[12:13], v[128:129] op_sel_hi:[1,0]
	v_pk_mul_f32 v[128:129], v[8:9], v[128:129] op_sel_hi:[1,0]
	v_mul_f32_e32 v132, 0xbfb8aa3b, v132
	v_exp_f32_e32 v132, v132
	v_mul_f32_e32 v128, 0xbfb8aa3b, v128
	v_exp_f32_e32 v128, v128
	v_mul_f32_e32 v129, 0xbfb8aa3b, v129
	v_exp_f32_e32 v129, v129
	v_mul_f32_e32 v133, 0xbfb8aa3b, v133
	v_exp_f32_e32 v133, v133
	s_nop 0
	v_add_f32_e32 v138, 1.0, v128
	v_add_f32_e32 v139, 1.0, v129
	v_rcp_f32_e32 v138, v138
	v_rcp_f32_e32 v139, v139
	s_nop 0
	v_mul_f32_e32 v128, 0xbfb8aa3b, v130
	v_exp_f32_e32 v128, v128
	v_mul_f32_e32 v130, 0xbfb8aa3b, v136
	v_exp_f32_e32 v130, v130
	v_mul_f32_e32 v129, 0xbfb8aa3b, v131
	v_exp_f32_e32 v129, v129
	v_mul_f32_e32 v131, 0xbfb8aa3b, v137
	v_exp_f32_e32 v131, v131
	s_nop 0
	v_add_f32_e32 v132, 1.0, v132
	v_add_f32_e32 v133, 1.0, v133
	v_rcp_f32_e32 v132, v132
	v_rcp_f32_e32 v133, v133
	s_nop 0
	s_nop 0
	v_add_f32_e32 v140, 1.0, v128
	v_add_f32_e32 v141, 1.0, v129
	v_rcp_f32_e32 v140, v140
	v_rcp_f32_e32 v141, v141
	s_nop 0
	s_nop 0
	v_add_f32_e32 v136, 1.0, v130
	v_add_f32_e32 v137, 1.0, v131
	v_rcp_f32_e32 v136, v136
	v_rcp_f32_e32 v137, v137
	s_nop 0
	v_cvt_pk_bf16_f32 v128, v132, v133
	v_cvt_pk_bf16_f32 v129, v140, v141
	v_cvt_pk_bf16_f32 v130, v138, v139
	v_cvt_pk_bf16_f32 v131, v136, v137
	global_store_dwordx4 v[134:135], v[128:131], off offset:256
	s_branch .LBB0_701
;     __device__ __forceinline__ void epi_proj(const f32x4 (&acc)[2][2][4][2], const pg8::Unit& u, int wr, int wc, int fr, int fq) const {
;     ...
;         float rstd8[2][4];
; #pragma unroll
;         for (int ai = 0; ai < 2; ++ai)
; #pragma unroll
;             for (int m = 0; m < 4; ++m) rstd8[ai][m] = rs[row0 + ai * 128 + m * 16];
; #pragma unroll
;         for (int ai = 0; ai < 2; ++ai)
; #pragma unroll
;             for (int m = 0; m < 4; ++m) rstd8[ai][m] = rsqrtf(rstd8[ai][m] * (1.0f / 1024.0f) + EPS);
; #pragma unroll
;         for (int ai = 0; ai < 2; ++ai)
; #pragma unroll
;             for (int m = 0; m < 4; ++m) {
;                 const int r = row0 + ai * 128 + m * 16;
;                     const float rstd = rstd8[ai][m];
;                     if (u.pn == 32) {
;                         if (wc == 0 && fq < 2) {
;                             const f32x4 v0 = acc[ai][0][m][0] * rstd, v1 = acc[ai][0][m][1] * rstd;
;                             float o8[8] = {v0[0], v0[1], v0[2], v0[3], v1[0], v1[1], v1[2], v1[3]};
; #pragma unroll
;                             for (int h = 0; h < 8; ++h) {
;                                 if (fq == 0) o8[h] = sigmoidf_(o8[h]);
;                                 else { const float xx = o8[h] + dt_bias[l * 8 + h]; const float sp = xx > 20.f ? xx : log1pf(__expf(xx)); o8[h] = -__expf(a_log[l * 8 + h]) * sp; }
;                             }
;                             float* dst = bg + (size_t)r * 16 + 8 * fq;
;                             *(f32x4*)dst = (f32x4){o8[0], o8[1], o8[2], o8[3]}; *(f32x4*)(dst + 4) = (f32x4){o8[4], o8[5], o8[6], o8[7]};
;                         }
;                     } else {
;                         const int slot = u.pn >> 2;
;                         bf16_t* rowp = act + (size_t)slot * SLOT_EL + (size_t)r * 1024 + (colt & 1023);
; #pragma unroll
;                         for (int bj = 0; bj < 2; ++bj) {
;                             f32x4 v0 = acc[ai][bj][m][0] * rstd, v1 = acc[ai][bj][m][1] * rstd;
;                             if (slot < 2) {
;                                 f32x2 a = gelu_pk((f32x2){v0[0], v0[1]}), b = gelu_pk((f32x2){v0[2], v0[3]}), c = gelu_pk((f32x2){v1[0], v1[1]}), d = gelu_pk((f32x2){v1[2], v1[3]});
;                                 v0 = (f32x4){a.x, a.y, b.x, b.y}; v1 = (f32x4){c.x, c.y, d.x, d.y};
;                             } else if (slot == 5) {
.Lepi_silu:
	v_readlane_b32 s6, v254, 34
	v_readlane_b32 s7, v254, 35
	s_mov_b64 s[0:1], s[6:7]
	s_load_dwordx2 s[4:5], s[0:1], 0xb0
	s_mov_b64 s[0:1], s[6:7]
	s_mov_b64 s[0:1], s[6:7]
	s_mov_b64 s[0:1], s[6:7]
	s_mov_b64 s[0:1], s[6:7]
	v_lshl_add_u32 v136, s13, 8, v239
	v_ashrrev_i32_e32 v137, 31, v136
	s_mov_b64 s[0:1], s[6:7]
	v_lshl_add_u64 v[128:129], v[136:137], 2, s[66:67]
	global_load_dword v130, v[128:129], off
	global_load_dword v131, v[128:129], off offset:64
	global_load_dword v132, v[128:129], off offset:128
	global_load_dword v133, v[128:129], off offset:192
	global_load_dword v134, v[128:129], off offset:512
	global_load_dword v135, v[128:129], off offset:576
	global_load_dword v139, v[128:129], off offset:640
	s_nop 0
	global_load_dword v128, v[128:129], off offset:704
	s_mov_b32 s0, 0x800000
	v_lshl_or_b32 v152, s88, 8, v245
	v_and_b32_e32 v152, 0x3ff, v152
	v_ashrrev_i32_e32 v153, 31, v152
	s_waitcnt lgkmcnt(0)
	v_lshl_add_u64 v[152:153], v[152:153], 1, s[4:5]
	v_or_b32_e32 v146, 16, v136
	v_or_b32_e32 v142, 32, v136
	v_or_b32_e32 v140, 48, v136
	v_lshlrev_b64 v[136:137], 11, v[136:137]
	v_ashrrev_i32_e32 v147, 31, v146
	v_lshlrev_b64 v[146:147], 11, v[146:147]
	v_ashrrev_i32_e32 v143, 31, v142
	v_lshlrev_b64 v[142:143], 11, v[142:143]
	v_ashrrev_i32_e32 v141, 31, v140
	v_lshlrev_b64 v[140:141], 11, v[140:141]
	s_waitcnt vmcnt(0)
	v_fmamk_f32 v129, v130, 0x3a800000, v237
	v_cmp_gt_f32_e32 vcc, s0, v129
	v_mul_f32_e32 v130, 0x4b800000, v129
	v_fmamk_f32 v128, v128, 0x3a800000, v237
	v_cndmask_b32_e32 v129, v129, v130, vcc
	v_rsq_f32_e32 v129, v129
	s_nop 0
	v_mul_f32_e32 v130, 0x45800000, v129
	v_cndmask_b32_e32 v150, v129, v130, vcc
	v_fmamk_f32 v129, v131, 0x3a800000, v237
	v_cmp_gt_f32_e32 vcc, s0, v129
	v_mul_f32_e32 v130, 0x4b800000, v129
	v_pk_mul_f32 v[154:155], v[118:119], v[150:151] op_sel_hi:[1,0]
	v_cndmask_b32_e32 v129, v129, v130, vcc
	v_rsq_f32_e32 v129, v129
	v_pk_mul_f32 v[156:157], v[116:117], v[150:151] op_sel_hi:[1,0]
	v_pk_mul_f32 v[158:159], v[114:115], v[150:151] op_sel_hi:[1,0]
	v_pk_mul_f32 v[160:161], v[112:113], v[150:151] op_sel_hi:[1,0]
	v_mul_f32_e32 v130, 0x45800000, v129
	v_cndmask_b32_e32 v148, v129, v130, vcc
	v_fmamk_f32 v129, v132, 0x3a800000, v237
	v_cmp_gt_f32_e32 vcc, s0, v129
	v_mul_f32_e32 v130, 0x4b800000, v129
	v_mul_f32_e32 v164, 0xbfb8aa3b, v156
	v_exp_f32_e32 v164, v164
	v_cndmask_b32_e32 v129, v129, v130, vcc
	v_rsq_f32_e32 v129, v129
	v_mul_f32_e32 v166, 0xbfb8aa3b, v160
	v_exp_f32_e32 v166, v166
	v_mul_f32_e32 v165, 0xbfb8aa3b, v157
	v_exp_f32_e32 v165, v165
	v_mul_f32_e32 v167, 0xbfb8aa3b, v161
	v_exp_f32_e32 v167, v167
	v_mul_f32_e32 v130, 0x45800000, v129
	v_cndmask_b32_e32 v144, v129, v130, vcc
	v_fmamk_f32 v129, v133, 0x3a800000, v237
	v_cmp_gt_f32_e32 vcc, s0, v129
	v_mul_f32_e32 v130, 0x4b800000, v129
	v_mul_f32_e32 v168, 0xbfb8aa3b, v154
	v_exp_f32_e32 v168, v168
	v_cndmask_b32_e32 v129, v129, v130, vcc
	v_rsq_f32_e32 v129, v129
	v_mul_f32_e32 v170, 0xbfb8aa3b, v158
	v_exp_f32_e32 v170, v170
	v_mul_f32_e32 v169, 0xbfb8aa3b, v155
	v_exp_f32_e32 v169, v169
	v_mul_f32_e32 v171, 0xbfb8aa3b, v159
	v_exp_f32_e32 v171, v171
	v_mul_f32_e32 v130, 0x45800000, v129
	v_cndmask_b32_e32 v138, v129, v130, vcc
	v_fmamk_f32 v129, v134, 0x3a800000, v237
	v_cmp_gt_f32_e32 vcc, s0, v129
	v_mul_f32_e32 v130, 0x4b800000, v129
	s_nop 0
	v_add_f32_e32 v164, 1.0, v164
	v_add_f32_e32 v165, 1.0, v165
	v_rcp_f32_e32 v164, v164
	v_rcp_f32_e32 v165, v165
	s_nop 0
	v_pk_mul_f32 v[156:157], v[156:157], v[164:165]
	v_cndmask_b32_e32 v129, v129, v130, vcc
	v_rsq_f32_e32 v129, v129
	s_nop 0
	v_add_f32_e32 v166, 1.0, v166
	v_add_f32_e32 v167, 1.0, v167
	v_rcp_f32_e32 v166, v166
	v_rcp_f32_e32 v167, v167
	s_nop 0
	v_pk_mul_f32 v[160:161], v[160:161], v[166:167]
	s_nop 0
	v_add_f32_e32 v168, 1.0, v168
	v_add_f32_e32 v169, 1.0, v169
	v_rcp_f32_e32 v168, v168
	v_rcp_f32_e32 v169, v169
	s_nop 0
	v_pk_mul_f32 v[162:163], v[154:155], v[168:169]
	s_nop 0
	v_add_f32_e32 v170, 1.0, v170
	v_add_f32_e32 v171, 1.0, v171
	v_rcp_f32_e32 v170, v170
	v_rcp_f32_e32 v171, v171
	s_nop 0
	v_pk_mul_f32 v[158:159], v[158:159], v[170:171]
	v_mul_f32_e32 v130, 0x45800000, v129
	v_cndmask_b32_e32 v134, v129, v130, vcc
	v_fmamk_f32 v129, v135, 0x3a800000, v237
	v_cmp_gt_f32_e32 vcc, s0, v129
	v_mul_f32_e32 v130, 0x4b800000, v129
	v_cvt_pk_bf16_f32 v154, v156, v157
	v_cndmask_b32_e32 v129, v129, v130, vcc
	v_rsq_f32_e32 v129, v129
	v_cvt_pk_bf16_f32 v155, v162, v163
	v_cvt_pk_bf16_f32 v156, v160, v161
	v_cvt_pk_bf16_f32 v157, v158, v159
	v_mul_f32_e32 v130, 0x45800000, v129
	v_cndmask_b32_e32 v132, v129, v130, vcc
	v_fmamk_f32 v129, v139, 0x3a800000, v237
	v_cmp_gt_f32_e32 vcc, s0, v129
	v_mul_f32_e32 v130, 0x4b800000, v129
	v_pk_mul_f32 v[158:159], v[122:123], v[150:151] op_sel_hi:[1,0]
	v_cndmask_b32_e32 v129, v129, v130, vcc
	v_rsq_f32_e32 v129, v129
	v_mul_f32_e32 v172, 0xbfb8aa3b, v158
	v_exp_f32_e32 v172, v172
	v_mul_f32_e32 v173, 0xbfb8aa3b, v159
	v_exp_f32_e32 v173, v173
	s_nop 0
	v_add_f32_e32 v172, 1.0, v172
	v_add_f32_e32 v173, 1.0, v173
	v_rcp_f32_e32 v172, v172
	v_rcp_f32_e32 v173, v173
	s_nop 0
	v_pk_mul_f32 v[158:159], v[158:159], v[172:173]
	v_mul_f32_e32 v130, 0x45800000, v129
	v_cndmask_b32_e32 v130, v129, v130, vcc
	v_cmp_gt_f32_e32 vcc, s0, v128
	s_lshr_b32 s0, s88, 2
	s_mul_i32 s0, s0, 0x4080000
	s_add_u32 s0, s0, 0x8d80000
	s_mov_b32 s1, 0
	v_lshl_add_u64 v[152:153], v[152:153], 0, s[0:1]
	v_lshl_add_u64 v[136:137], v[152:153], 0, v[136:137]
	global_store_dwordx4 v[136:137], v[154:157], off
	v_mul_f32_e32 v129, 0x4b800000, v128
	v_cndmask_b32_e32 v128, v128, v129, vcc
	v_pk_mul_f32 v[154:155], v[126:127], v[150:151] op_sel_hi:[1,0]
; __device__ __forceinline__ unsigned cvt_pk_bf16(float lo, float hi) { const f32x2 v = {lo, hi}; const bf16v2_t b = __builtin_convertvector(v, bf16v2_t); return __builtin_bit_cast(unsigned, b); }
; __device__ __forceinline__ float sigmoidf_(float x) { return __builtin_amdgcn_rcpf(1.0f + __builtin_amdgcn_exp2f(x * -1.44269504089f)); }
; __device__ __forceinline__ float siluf_(float x) { return x * __builtin_amdgcn_rcpf(1.0f + __builtin_amdgcn_exp2f(x * -1.44269504089f)); }
;     __device__ __forceinline__ void epi_proj(const f32x4 (&acc)[2][2][4][2], const pg8::Unit& u, int wr, int wc, int fr, int fq) const {
;     ...
; #pragma unroll
;                         for (int bj = 0; bj < 2; ++bj) {
;                             f32x4 v0 = acc[ai][bj][m][0] * rstd, v1 = acc[ai][bj][m][1] * rstd;
;                             if (slot < 2) {
;                                 f32x2 a = gelu_pk((f32x2){v0[0], v0[1]}), b = gelu_pk((f32x2){v0[2], v0[3]}), c = gelu_pk((f32x2){v1[0], v1[1]}), d = gelu_pk((f32x2){v1[2], v1[3]});
;                                 v0 = (f32x4){a.x, a.y, b.x, b.y}; v1 = (f32x4){c.x, c.y, d.x, d.y};
;                             } else if (slot == 5) {
; #pragma unroll
;                                 for (int j = 0; j < 4; ++j) { v0[j] = siluf_(v0[j]); v1[j] = siluf_(v1[j]); }
;                             } else if (slot >= 6) {
; #pragma unroll
;                                 for (int j = 0; j < 4; ++j) { v0[j] = sigmoidf_(v0[j]); v1[j] = sigmoidf_(v1[j]); }
;                             }
;                             u32x4 w; w.x = cvt_pk_bf16(v0[0], v0[1]); w.y = cvt_pk_bf16(v0[2], v0[3]); w.z = cvt_pk_bf16(v1[0], v1[1]); w.w = cvt_pk_bf16(v1[2], v1[3]);
;                             *(u32x4*)(rowp + bj * 128) = w;
	v_pk_mul_f32 v[156:157], v[124:125], v[150:151] op_sel_hi:[1,0]
	v_pk_mul_f32 v[150:151], v[120:121], v[150:151] op_sel_hi:[1,0]
	v_mul_f32_e32 v174, 0xbfb8aa3b, v156
	v_exp_f32_e32 v174, v174
	v_mul_f32_e32 v176, 0xbfb8aa3b, v150
	v_exp_f32_e32 v176, v176
	v_mul_f32_e32 v175, 0xbfb8aa3b, v157
	v_exp_f32_e32 v175, v175
	v_mul_f32_e32 v177, 0xbfb8aa3b, v151
	v_exp_f32_e32 v177, v177
	v_mul_f32_e32 v178, 0xbfb8aa3b, v154
	v_exp_f32_e32 v178, v178
	v_mul_f32_e32 v179, 0xbfb8aa3b, v155
	v_exp_f32_e32 v179, v179
	s_nop 0
	v_add_f32_e32 v174, 1.0, v174
	v_add_f32_e32 v175, 1.0, v175
	v_rcp_f32_e32 v174, v174
	v_rcp_f32_e32 v175, v175
	s_nop 0
	v_pk_mul_f32 v[156:157], v[156:157], v[174:175]
	s_nop 0
	v_add_f32_e32 v176, 1.0, v176
	v_add_f32_e32 v177, 1.0, v177
	v_rcp_f32_e32 v176, v176
	v_rcp_f32_e32 v177, v177
	s_nop 0
	v_pk_mul_f32 v[150:151], v[150:151], v[176:177]
	s_nop 0
	v_add_f32_e32 v178, 1.0, v178
	v_add_f32_e32 v179, 1.0, v179
	v_rcp_f32_e32 v178, v178
	v_rcp_f32_e32 v179, v179
	s_nop 0
	v_pk_mul_f32 v[160:161], v[154:155], v[178:179]
	v_cvt_pk_bf16_f32 v154, v156, v157
	v_cvt_pk_bf16_f32 v155, v160, v161
	v_cvt_pk_bf16_f32 v156, v150, v151
	v_cvt_pk_bf16_f32 v157, v158, v159
	global_store_dwordx4 v[136:137], v[154:157], off offset:256
	v_lshl_add_u64 v[150:151], v[152:153], 0, v[146:147]
	v_pk_mul_f32 v[146:147], v[102:103], v[148:149] op_sel_hi:[1,0]
	v_pk_mul_f32 v[154:155], v[100:101], v[148:149] op_sel_hi:[1,0]
	v_pk_mul_f32 v[156:157], v[98:99], v[148:149] op_sel_hi:[1,0]
	v_pk_mul_f32 v[158:159], v[96:97], v[148:149] op_sel_hi:[1,0]
	v_mul_f32_e32 v180, 0xbfb8aa3b, v154
	v_exp_f32_e32 v180, v180
	v_mul_f32_e32 v182, 0xbfb8aa3b, v158
	v_exp_f32_e32 v182, v182
	v_mul_f32_e32 v181, 0xbfb8aa3b, v155
	v_exp_f32_e32 v181, v181
	v_mul_f32_e32 v183, 0xbfb8aa3b, v159
	v_exp_f32_e32 v183, v183
	v_mul_f32_e32 v184, 0xbfb8aa3b, v146
	v_exp_f32_e32 v184, v184
	v_mul_f32_e32 v186, 0xbfb8aa3b, v156
	v_exp_f32_e32 v186, v186
	v_mul_f32_e32 v185, 0xbfb8aa3b, v147
	v_exp_f32_e32 v185, v185
	v_mul_f32_e32 v187, 0xbfb8aa3b, v157
	v_exp_f32_e32 v187, v187
	s_nop 0
	v_add_f32_e32 v180, 1.0, v180
	v_add_f32_e32 v181, 1.0, v181
	v_rcp_f32_e32 v180, v180
	v_rcp_f32_e32 v181, v181
	s_nop 0
	v_pk_mul_f32 v[154:155], v[154:155], v[180:181]
	s_nop 0
	v_add_f32_e32 v182, 1.0, v182
	v_add_f32_e32 v183, 1.0, v183
	v_rcp_f32_e32 v182, v182
	v_rcp_f32_e32 v183, v183
	s_nop 0
	v_pk_mul_f32 v[158:159], v[158:159], v[182:183]
	s_nop 0
	v_add_f32_e32 v184, 1.0, v184
	v_add_f32_e32 v185, 1.0, v185
	v_rcp_f32_e32 v184, v184
	v_rcp_f32_e32 v185, v185
	s_nop 0
	v_pk_mul_f32 v[146:147], v[146:147], v[184:185]
	s_nop 0
	v_add_f32_e32 v186, 1.0, v186
	v_add_f32_e32 v187, 1.0, v187
	v_rcp_f32_e32 v186, v186
	v_rcp_f32_e32 v187, v187
	s_nop 0
	v_pk_mul_f32 v[160:161], v[156:157], v[186:187]
	v_cvt_pk_bf16_f32 v154, v154, v155
	v_cvt_pk_bf16_f32 v155, v146, v147
	v_cvt_pk_bf16_f32 v156, v158, v159
	v_cvt_pk_bf16_f32 v157, v160, v161
	global_store_dwordx4 v[150:151], v[154:157], off
	v_pk_mul_f32 v[146:147], v[110:111], v[148:149] op_sel_hi:[1,0]
	v_rsq_f32_e32 v128, v128
	v_pk_mul_f32 v[154:155], v[108:109], v[148:149] op_sel_hi:[1,0]
	v_pk_mul_f32 v[156:157], v[106:107], v[148:149] op_sel_hi:[1,0]
	v_pk_mul_f32 v[148:149], v[104:105], v[148:149] op_sel_hi:[1,0]
	v_mul_f32_e32 v188, 0xbfb8aa3b, v154
	v_exp_f32_e32 v188, v188
	v_mul_f32_e32 v190, 0xbfb8aa3b, v148
	v_exp_f32_e32 v190, v190
	v_mul_f32_e32 v189, 0xbfb8aa3b, v155
	v_exp_f32_e32 v189, v189
	v_mul_f32_e32 v191, 0xbfb8aa3b, v149
	v_exp_f32_e32 v191, v191
	v_mul_f32_e32 v164, 0xbfb8aa3b, v146
	v_exp_f32_e32 v164, v164
	v_mul_f32_e32 v166, 0xbfb8aa3b, v156
	v_exp_f32_e32 v166, v166
	v_mul_f32_e32 v165, 0xbfb8aa3b, v147
	v_exp_f32_e32 v165, v165
	v_mul_f32_e32 v167, 0xbfb8aa3b, v157
	v_exp_f32_e32 v167, v167
	s_nop 0
	v_add_f32_e32 v188, 1.0, v188
	v_add_f32_e32 v189, 1.0, v189
	v_rcp_f32_e32 v188, v188
	v_rcp_f32_e32 v189, v189
	s_nop 0
	v_pk_mul_f32 v[154:155], v[154:155], v[188:189]
	s_nop 0
	v_add_f32_e32 v190, 1.0, v190
	v_add_f32_e32 v191, 1.0, v191
	v_rcp_f32_e32 v190, v190
	v_rcp_f32_e32 v191, v191
	s_nop 0
	v_pk_mul_f32 v[148:149], v[148:149], v[190:191]
	s_nop 0
	v_add_f32_e32 v164, 1.0, v164
	v_add_f32_e32 v165, 1.0, v165
	v_rcp_f32_e32 v164, v164
	v_rcp_f32_e32 v165, v165
	s_nop 0
	v_pk_mul_f32 v[158:159], v[146:147], v[164:165]
	s_nop 0
	v_add_f32_e32 v166, 1.0, v166
	v_add_f32_e32 v167, 1.0, v167
	v_rcp_f32_e32 v166, v166
	v_rcp_f32_e32 v167, v167
	s_nop 0
	v_pk_mul_f32 v[156:157], v[156:157], v[166:167]
	v_cvt_pk_bf16_f32 v146, v154, v155
	v_cvt_pk_bf16_f32 v147, v158, v159
	v_cvt_pk_bf16_f32 v148, v148, v149
	v_cvt_pk_bf16_f32 v149, v156, v157
	global_store_dwordx4 v[150:151], v[146:149], off offset:256
	v_lshl_add_u64 v[150:151], v[152:153], 0, v[142:143]
	v_pk_mul_f32 v[142:143], v[86:87], v[144:145] op_sel_hi:[1,0]
	v_pk_mul_f32 v[146:147], v[84:85], v[144:145] op_sel_hi:[1,0]
	v_pk_mul_f32 v[148:149], v[82:83], v[144:145] op_sel_hi:[1,0]
	v_pk_mul_f32 v[154:155], v[80:81], v[144:145] op_sel_hi:[1,0]
	v_mul_f32_e32 v168, 0xbfb8aa3b, v146
	v_exp_f32_e32 v168, v168
	v_mul_f32_e32 v170, 0xbfb8aa3b, v154
	v_exp_f32_e32 v170, v170
	v_mul_f32_e32 v169, 0xbfb8aa3b, v147
	v_exp_f32_e32 v169, v169
	v_mul_f32_e32 v171, 0xbfb8aa3b, v155
	v_exp_f32_e32 v171, v171
	v_mul_f32_e32 v172, 0xbfb8aa3b, v142
	v_exp_f32_e32 v172, v172
	v_mul_f32_e32 v174, 0xbfb8aa3b, v148
	v_exp_f32_e32 v174, v174
	v_mul_f32_e32 v173, 0xbfb8aa3b, v143
	v_exp_f32_e32 v173, v173
	v_mul_f32_e32 v175, 0xbfb8aa3b, v149
	v_exp_f32_e32 v175, v175
	s_nop 0
	v_add_f32_e32 v168, 1.0, v168
	v_add_f32_e32 v169, 1.0, v169
	v_rcp_f32_e32 v168, v168
; __device__ __forceinline__ unsigned cvt_pk_bf16(float lo, float hi) { const f32x2 v = {lo, hi}; const bf16v2_t b = __builtin_convertvector(v, bf16v2_t); return __builtin_bit_cast(unsigned, b); }
; __device__ __forceinline__ float sigmoidf_(float x) { return __builtin_amdgcn_rcpf(1.0f + __builtin_amdgcn_exp2f(x * -1.44269504089f)); }
; __device__ __forceinline__ float siluf_(float x) { return x * __builtin_amdgcn_rcpf(1.0f + __builtin_amdgcn_exp2f(x * -1.44269504089f)); }
;     __device__ __forceinline__ void epi_proj(const f32x4 (&acc)[2][2][4][2], const pg8::Unit& u, int wr, int wc, int fr, int fq) const {
;     ...
; #pragma unroll
;                         for (int bj = 0; bj < 2; ++bj) {
;                             f32x4 v0 = acc[ai][bj][m][0] * rstd, v1 = acc[ai][bj][m][1] * rstd;
;                             if (slot < 2) {
;                                 f32x2 a = gelu_pk((f32x2){v0[0], v0[1]}), b = gelu_pk((f32x2){v0[2], v0[3]}), c = gelu_pk((f32x2){v1[0], v1[1]}), d = gelu_pk((f32x2){v1[2], v1[3]});
;                                 v0 = (f32x4){a.x, a.y, b.x, b.y}; v1 = (f32x4){c.x, c.y, d.x, d.y};
;                             } else if (slot == 5) {
; #pragma unroll
;                                 for (int j = 0; j < 4; ++j) { v0[j] = siluf_(v0[j]); v1[j] = siluf_(v1[j]); }
;                             } else if (slot >= 6) {
; #pragma unroll
;                                 for (int j = 0; j < 4; ++j) { v0[j] = sigmoidf_(v0[j]); v1[j] = sigmoidf_(v1[j]); }
;                             }
;                             u32x4 w; w.x = cvt_pk_bf16(v0[0], v0[1]); w.y = cvt_pk_bf16(v0[2], v0[3]); w.z = cvt_pk_bf16(v1[0], v1[1]); w.w = cvt_pk_bf16(v1[2], v1[3]);
;                             *(u32x4*)(rowp + bj * 128) = w;
	v_rcp_f32_e32 v169, v169
	s_nop 0
	v_pk_mul_f32 v[146:147], v[146:147], v[168:169]
	s_nop 0
	v_add_f32_e32 v170, 1.0, v170
	v_add_f32_e32 v171, 1.0, v171
	v_rcp_f32_e32 v170, v170
	v_rcp_f32_e32 v171, v171
	s_nop 0
	v_pk_mul_f32 v[154:155], v[154:155], v[170:171]
	s_nop 0
	v_add_f32_e32 v172, 1.0, v172
	v_add_f32_e32 v173, 1.0, v173
	v_rcp_f32_e32 v172, v172
	v_rcp_f32_e32 v173, v173
	s_nop 0
	v_pk_mul_f32 v[142:143], v[142:143], v[172:173]
	s_nop 0
	v_add_f32_e32 v174, 1.0, v174
	v_add_f32_e32 v175, 1.0, v175
	v_rcp_f32_e32 v174, v174
	v_rcp_f32_e32 v175, v175
	s_nop 0
	v_pk_mul_f32 v[156:157], v[148:149], v[174:175]
	v_cvt_pk_bf16_f32 v146, v146, v147
	v_cvt_pk_bf16_f32 v147, v142, v143
	v_cvt_pk_bf16_f32 v148, v154, v155
	v_cvt_pk_bf16_f32 v149, v156, v157
	global_store_dwordx4 v[150:151], v[146:149], off
	v_pk_mul_f32 v[142:143], v[94:95], v[144:145] op_sel_hi:[1,0]
	s_mov_b64 s[0:1], 0x40000
	v_pk_mul_f32 v[146:147], v[92:93], v[144:145] op_sel_hi:[1,0]
	v_pk_mul_f32 v[148:149], v[90:91], v[144:145] op_sel_hi:[1,0]
	v_pk_mul_f32 v[144:145], v[88:89], v[144:145] op_sel_hi:[1,0]
	v_mul_f32_e32 v176, 0xbfb8aa3b, v146
	v_exp_f32_e32 v176, v176
	v_mul_f32_e32 v178, 0xbfb8aa3b, v144
	v_exp_f32_e32 v178, v178
	v_mul_f32_e32 v177, 0xbfb8aa3b, v147
	v_exp_f32_e32 v177, v177
	v_mul_f32_e32 v179, 0xbfb8aa3b, v145
	v_exp_f32_e32 v179, v179
	v_mul_f32_e32 v180, 0xbfb8aa3b, v142
	v_exp_f32_e32 v180, v180
	v_mul_f32_e32 v182, 0xbfb8aa3b, v148
	v_exp_f32_e32 v182, v182
	v_mul_f32_e32 v181, 0xbfb8aa3b, v143
	v_exp_f32_e32 v181, v181
	v_mul_f32_e32 v183, 0xbfb8aa3b, v149
	v_exp_f32_e32 v183, v183
	s_nop 0
	v_add_f32_e32 v176, 1.0, v176
	v_add_f32_e32 v177, 1.0, v177
	v_rcp_f32_e32 v176, v176
	v_rcp_f32_e32 v177, v177
	s_nop 0
	v_pk_mul_f32 v[146:147], v[146:147], v[176:177]
	s_nop 0
	v_add_f32_e32 v178, 1.0, v178
	v_add_f32_e32 v179, 1.0, v179
	v_rcp_f32_e32 v178, v178
	v_rcp_f32_e32 v179, v179
	s_nop 0
	v_pk_mul_f32 v[144:145], v[144:145], v[178:179]
	s_nop 0
	v_add_f32_e32 v180, 1.0, v180
	v_add_f32_e32 v181, 1.0, v181
	v_rcp_f32_e32 v180, v180
	v_rcp_f32_e32 v181, v181
	s_nop 0
	v_pk_mul_f32 v[154:155], v[142:143], v[180:181]
	s_nop 0
	v_add_f32_e32 v182, 1.0, v182
	v_add_f32_e32 v183, 1.0, v183
	v_rcp_f32_e32 v182, v182
	v_rcp_f32_e32 v183, v183
	s_nop 0
	v_pk_mul_f32 v[148:149], v[148:149], v[182:183]
	v_cvt_pk_bf16_f32 v142, v146, v147
	v_cvt_pk_bf16_f32 v143, v154, v155
	v_cvt_pk_bf16_f32 v144, v144, v145
	v_cvt_pk_bf16_f32 v145, v148, v149
	global_store_dwordx4 v[150:151], v[142:145], off offset:256
	v_pk_mul_f32 v[146:147], v[66:67], v[138:139] op_sel_hi:[1,0]
	v_pk_mul_f32 v[148:149], v[64:65], v[138:139] op_sel_hi:[1,0]
	v_lshl_add_u64 v[144:145], v[152:153], 0, v[140:141]
	v_pk_mul_f32 v[140:141], v[70:71], v[138:139] op_sel_hi:[1,0]
	v_pk_mul_f32 v[142:143], v[68:69], v[138:139] op_sel_hi:[1,0]
	v_mul_f32_e32 v184, 0xbfb8aa3b, v148
	v_exp_f32_e32 v184, v184
	v_mul_f32_e32 v186, 0xbfb8aa3b, v142
	v_exp_f32_e32 v186, v186
	v_mul_f32_e32 v187, 0xbfb8aa3b, v143
	v_exp_f32_e32 v187, v187
	v_mul_f32_e32 v185, 0xbfb8aa3b, v149
	v_exp_f32_e32 v185, v185
	v_mul_f32_e32 v188, 0xbfb8aa3b, v140
	v_exp_f32_e32 v188, v188
	v_mul_f32_e32 v190, 0xbfb8aa3b, v146
	v_exp_f32_e32 v190, v190
	v_mul_f32_e32 v189, 0xbfb8aa3b, v141
	v_exp_f32_e32 v189, v189
	v_mul_f32_e32 v191, 0xbfb8aa3b, v147
	v_exp_f32_e32 v191, v191
	s_nop 0
	v_add_f32_e32 v186, 1.0, v186
	v_add_f32_e32 v187, 1.0, v187
	v_rcp_f32_e32 v186, v186
	v_rcp_f32_e32 v187, v187
	s_nop 0
	v_pk_mul_f32 v[142:143], v[142:143], v[186:187]
	s_nop 0
	v_add_f32_e32 v184, 1.0, v184
	v_add_f32_e32 v185, 1.0, v185
	v_rcp_f32_e32 v184, v184
	v_rcp_f32_e32 v185, v185
	s_nop 0
	v_pk_mul_f32 v[148:149], v[148:149], v[184:185]
	s_nop 0
	v_add_f32_e32 v188, 1.0, v188
	v_add_f32_e32 v189, 1.0, v189
	v_rcp_f32_e32 v188, v188
	v_rcp_f32_e32 v189, v189
	s_nop 0
	v_pk_mul_f32 v[150:151], v[140:141], v[188:189]
	s_nop 0
	v_add_f32_e32 v190, 1.0, v190
	v_add_f32_e32 v191, 1.0, v191
	v_rcp_f32_e32 v190, v190
	v_rcp_f32_e32 v191, v191
	s_nop 0
	v_pk_mul_f32 v[146:147], v[146:147], v[190:191]
	v_cvt_pk_bf16_f32 v140, v142, v143
	v_cvt_pk_bf16_f32 v141, v150, v151
	v_cvt_pk_bf16_f32 v142, v148, v149
	v_cvt_pk_bf16_f32 v143, v146, v147
	global_store_dwordx4 v[144:145], v[140:143], off
	v_pk_mul_f32 v[146:147], v[74:75], v[138:139] op_sel_hi:[1,0]
	v_mul_f32_e32 v129, 0x45800000, v128
	v_pk_mul_f32 v[140:141], v[78:79], v[138:139] op_sel_hi:[1,0]
	v_pk_mul_f32 v[142:143], v[76:77], v[138:139] op_sel_hi:[1,0]
	v_pk_mul_f32 v[138:139], v[72:73], v[138:139] op_sel_hi:[1,0]
	v_mul_f32_e32 v164, 0xbfb8aa3b, v142
	v_exp_f32_e32 v164, v164
	v_mul_f32_e32 v166, 0xbfb8aa3b, v138
	v_exp_f32_e32 v166, v166
	v_mul_f32_e32 v167, 0xbfb8aa3b, v139
	v_exp_f32_e32 v167, v167
	v_mul_f32_e32 v165, 0xbfb8aa3b, v143
	v_exp_f32_e32 v165, v165
	s_nop 0
	v_add_f32_e32 v166, 1.0, v166
	v_add_f32_e32 v167, 1.0, v167
	v_rcp_f32_e32 v166, v166
	v_rcp_f32_e32 v167, v167
	s_nop 0
	v_pk_mul_f32 v[148:149], v[138:139], v[166:167]
	v_mul_f32_e32 v168, 0xbfb8aa3b, v140
	v_exp_f32_e32 v168, v168
	v_mov_b32_e32 v138, v140
	v_mul_f32_e32 v170, 0xbfb8aa3b, v146
	v_exp_f32_e32 v170, v170
	v_mov_b32_e32 v140, v146
	v_mul_f32_e32 v169, 0xbfb8aa3b, v141
	v_exp_f32_e32 v169, v169
	v_mov_b32_e32 v139, v141
	v_mul_f32_e32 v171, 0xbfb8aa3b, v147
	v_exp_f32_e32 v171, v171
	v_mov_b32_e32 v141, v147
	s_nop 0
	v_add_f32_e32 v164, 1.0, v164
	v_add_f32_e32 v165, 1.0, v165
	v_rcp_f32_e32 v164, v164
	v_rcp_f32_e32 v165, v165
	s_nop 0
	v_pk_mul_f32 v[142:143], v[142:143], v[164:165]
	s_nop 0
	v_add_f32_e32 v168, 1.0, v168
	v_add_f32_e32 v169, 1.0, v169
	v_rcp_f32_e32 v168, v168
; __device__ __forceinline__ unsigned cvt_pk_bf16(float lo, float hi) { const f32x2 v = {lo, hi}; const bf16v2_t b = __builtin_convertvector(v, bf16v2_t); return __builtin_bit_cast(unsigned, b); }
; __device__ __forceinline__ float sigmoidf_(float x) { return __builtin_amdgcn_rcpf(1.0f + __builtin_amdgcn_exp2f(x * -1.44269504089f)); }
; __device__ __forceinline__ float siluf_(float x) { return x * __builtin_amdgcn_rcpf(1.0f + __builtin_amdgcn_exp2f(x * -1.44269504089f)); }
;     __device__ __forceinline__ void epi_proj(const f32x4 (&acc)[2][2][4][2], const pg8::Unit& u, int wr, int wc, int fr, int fq) const {
;     ...
; #pragma unroll
;                         for (int bj = 0; bj < 2; ++bj) {
;                             f32x4 v0 = acc[ai][bj][m][0] * rstd, v1 = acc[ai][bj][m][1] * rstd;
;                             if (slot < 2) {
;                                 f32x2 a = gelu_pk((f32x2){v0[0], v0[1]}), b = gelu_pk((f32x2){v0[2], v0[3]}), c = gelu_pk((f32x2){v1[0], v1[1]}), d = gelu_pk((f32x2){v1[2], v1[3]});
;                                 v0 = (f32x4){a.x, a.y, b.x, b.y}; v1 = (f32x4){c.x, c.y, d.x, d.y};
;                             } else if (slot == 5) {
; #pragma unroll
;                                 for (int j = 0; j < 4; ++j) { v0[j] = siluf_(v0[j]); v1[j] = siluf_(v1[j]); }
;                             } else if (slot >= 6) {
; #pragma unroll
;                                 for (int j = 0; j < 4; ++j) { v0[j] = sigmoidf_(v0[j]); v1[j] = sigmoidf_(v1[j]); }
;                             }
;                             u32x4 w; w.x = cvt_pk_bf16(v0[0], v0[1]); w.y = cvt_pk_bf16(v0[2], v0[3]); w.z = cvt_pk_bf16(v1[0], v1[1]); w.w = cvt_pk_bf16(v1[2], v1[3]);
;                             *(u32x4*)(rowp + bj * 128) = w;
	v_rcp_f32_e32 v169, v169
	s_nop 0
	v_pk_mul_f32 v[150:151], v[138:139], v[168:169]
	s_nop 0
	v_add_f32_e32 v170, 1.0, v170
	v_add_f32_e32 v171, 1.0, v171
	v_rcp_f32_e32 v170, v170
	v_rcp_f32_e32 v171, v171
	s_nop 0
	v_pk_mul_f32 v[146:147], v[140:141], v[170:171]
	v_cvt_pk_bf16_f32 v138, v142, v143
	v_cvt_pk_bf16_f32 v139, v150, v151
	v_cvt_pk_bf16_f32 v140, v148, v149
	v_cvt_pk_bf16_f32 v141, v146, v147
	global_store_dwordx4 v[144:145], v[138:141], off offset:256
	v_pk_mul_f32 v[144:145], v[50:51], v[134:135] op_sel_hi:[1,0]
	v_pk_mul_f32 v[146:147], v[48:49], v[134:135] op_sel_hi:[1,0]
	v_pk_mul_f32 v[140:141], v[52:53], v[134:135] op_sel_hi:[1,0]
	v_pk_mul_f32 v[138:139], v[54:55], v[134:135] op_sel_hi:[1,0]
	v_mul_f32_e32 v172, 0xbfb8aa3b, v140
	v_exp_f32_e32 v172, v172
	v_mul_f32_e32 v173, 0xbfb8aa3b, v141
	v_exp_f32_e32 v173, v173
	v_mul_f32_e32 v174, 0xbfb8aa3b, v144
	v_exp_f32_e32 v174, v174
	v_mul_f32_e32 v175, 0xbfb8aa3b, v145
	v_exp_f32_e32 v175, v175
	v_lshl_add_u64 v[142:143], v[136:137], 0, s[0:1]
	v_mul_f32_e32 v176, 0xbfb8aa3b, v146
	v_exp_f32_e32 v176, v176
	s_nop 0
	v_add_f32_e32 v172, 1.0, v172
	v_add_f32_e32 v173, 1.0, v173
	v_rcp_f32_e32 v172, v172
	v_rcp_f32_e32 v173, v173
	s_nop 0
	v_pk_mul_f32 v[140:141], v[140:141], v[172:173]
	v_mul_f32_e32 v177, 0xbfb8aa3b, v147
	v_exp_f32_e32 v177, v177
	v_mul_f32_e32 v178, 0xbfb8aa3b, v138
	v_exp_f32_e32 v178, v178
	v_mul_f32_e32 v179, 0xbfb8aa3b, v139
	v_exp_f32_e32 v179, v179
	s_nop 0
	v_add_f32_e32 v174, 1.0, v174
	v_add_f32_e32 v175, 1.0, v175
	v_rcp_f32_e32 v174, v174
	v_rcp_f32_e32 v175, v175
	s_nop 0
	v_pk_mul_f32 v[144:145], v[144:145], v[174:175]
	s_mov_b32 s0, 0x40000
	v_cndmask_b32_e32 v128, v128, v129, vcc
	s_nop 0
	v_add_f32_e32 v176, 1.0, v176
	v_add_f32_e32 v177, 1.0, v177
	v_rcp_f32_e32 v176, v176
	v_rcp_f32_e32 v177, v177
	s_nop 0
	v_pk_mul_f32 v[146:147], v[146:147], v[176:177]
	s_nop 0
	v_add_f32_e32 v178, 1.0, v178
	v_add_f32_e32 v179, 1.0, v179
	v_rcp_f32_e32 v178, v178
	v_rcp_f32_e32 v179, v179
	s_nop 0
	v_pk_mul_f32 v[148:149], v[138:139], v[178:179]
	v_cvt_pk_bf16_f32 v138, v140, v141
	v_cvt_pk_bf16_f32 v141, v144, v145
	v_add_co_u32_e32 v144, vcc, s0, v136
	v_cvt_pk_bf16_f32 v139, v148, v149
	v_cvt_pk_bf16_f32 v140, v146, v147
	v_addc_co_u32_e32 v145, vcc, 0, v137, vcc
	global_store_dwordx4 v[144:145], v[138:141], off
	v_pk_mul_f32 v[144:145], v[58:59], v[134:135] op_sel_hi:[1,0]
	s_mov_b64 s[0:1], 0x48000
	v_pk_mul_f32 v[138:139], v[62:63], v[134:135] op_sel_hi:[1,0]
	v_pk_mul_f32 v[140:141], v[60:61], v[134:135] op_sel_hi:[1,0]
	v_pk_mul_f32 v[134:135], v[56:57], v[134:135] op_sel_hi:[1,0]
	v_mul_f32_e32 v180, 0xbfb8aa3b, v140
	v_exp_f32_e32 v180, v180
	v_mul_f32_e32 v182, 0xbfb8aa3b, v134
	v_exp_f32_e32 v182, v182
	v_mul_f32_e32 v181, 0xbfb8aa3b, v141
	v_exp_f32_e32 v181, v181
	v_mul_f32_e32 v183, 0xbfb8aa3b, v135
	v_exp_f32_e32 v183, v183
	v_mul_f32_e32 v186, 0xbfb8aa3b, v138
	v_exp_f32_e32 v186, v186
	v_mul_f32_e32 v184, 0xbfb8aa3b, v144
	v_exp_f32_e32 v184, v184
	v_mul_f32_e32 v187, 0xbfb8aa3b, v139
	v_exp_f32_e32 v187, v187
	v_mul_f32_e32 v185, 0xbfb8aa3b, v145
	v_exp_f32_e32 v185, v185
	s_nop 0
	v_add_f32_e32 v180, 1.0, v180
	v_add_f32_e32 v181, 1.0, v181
	v_rcp_f32_e32 v180, v180
	v_rcp_f32_e32 v181, v181
	s_nop 0
	v_pk_mul_f32 v[140:141], v[140:141], v[180:181]
	s_nop 0
	v_add_f32_e32 v182, 1.0, v182
	v_add_f32_e32 v183, 1.0, v183
	v_rcp_f32_e32 v182, v182
	v_rcp_f32_e32 v183, v183
	s_nop 0
	v_pk_mul_f32 v[134:135], v[134:135], v[182:183]
	s_nop 0
	v_add_f32_e32 v186, 1.0, v186
	v_add_f32_e32 v187, 1.0, v187
	v_rcp_f32_e32 v186, v186
	v_rcp_f32_e32 v187, v187
	s_nop 0
	v_pk_mul_f32 v[146:147], v[138:139], v[186:187]
	s_nop 0
	v_add_f32_e32 v184, 1.0, v184
	v_add_f32_e32 v185, 1.0, v185
	v_rcp_f32_e32 v184, v184
	v_rcp_f32_e32 v185, v185
	s_nop 0
	v_pk_mul_f32 v[144:145], v[144:145], v[184:185]
	v_cvt_pk_bf16_f32 v138, v140, v141
	v_cvt_pk_bf16_f32 v139, v146, v147
	v_cvt_pk_bf16_f32 v140, v134, v135
	v_cvt_pk_bf16_f32 v141, v144, v145
	global_store_dwordx4 v[142:143], v[138:141], off offset:256
	v_pk_mul_f32 v[134:135], v[38:39], v[132:133] op_sel_hi:[1,0]
	v_pk_mul_f32 v[144:145], v[32:33], v[132:133] op_sel_hi:[1,0]
	v_pk_mul_f32 v[138:139], v[36:37], v[132:133] op_sel_hi:[1,0]
	v_pk_mul_f32 v[140:141], v[34:35], v[132:133] op_sel_hi:[1,0]
	v_mul_f32_e32 v188, 0xbfb8aa3b, v138
	v_exp_f32_e32 v188, v188
	v_mul_f32_e32 v189, 0xbfb8aa3b, v139
	v_exp_f32_e32 v189, v189
	v_mul_f32_e32 v190, 0xbfb8aa3b, v134
	v_exp_f32_e32 v190, v190
	v_mul_f32_e32 v191, 0xbfb8aa3b, v135
	v_exp_f32_e32 v191, v191
	v_lshl_add_u64 v[142:143], v[136:137], 0, s[0:1]
	v_mul_f32_e32 v166, 0xbfb8aa3b, v144
	v_exp_f32_e32 v166, v166
	s_nop 0
	v_add_f32_e32 v188, 1.0, v188
	v_add_f32_e32 v189, 1.0, v189
	v_rcp_f32_e32 v188, v188
	v_rcp_f32_e32 v189, v189
	s_nop 0
	v_pk_mul_f32 v[138:139], v[138:139], v[188:189]
	v_mul_f32_e32 v167, 0xbfb8aa3b, v145
	v_exp_f32_e32 v167, v167
	v_mul_f32_e32 v164, 0xbfb8aa3b, v140
	v_exp_f32_e32 v164, v164
	s_nop 0
	v_add_f32_e32 v190, 1.0, v190
	v_add_f32_e32 v191, 1.0, v191
	v_rcp_f32_e32 v190, v190
	v_rcp_f32_e32 v191, v191
	s_nop 0
	v_pk_mul_f32 v[134:135], v[134:135], v[190:191]
	v_mul_f32_e32 v165, 0xbfb8aa3b, v141
	v_exp_f32_e32 v165, v165
	s_mov_b32 s0, 0x48000
	s_nop 0
	v_add_f32_e32 v166, 1.0, v166
	v_add_f32_e32 v167, 1.0, v167
	v_rcp_f32_e32 v166, v166
	v_rcp_f32_e32 v167, v167
	s_nop 0
	v_pk_mul_f32 v[144:145], v[144:145], v[166:167]
	s_nop 0
	v_add_f32_e32 v164, 1.0, v164
	v_add_f32_e32 v165, 1.0, v165
	v_rcp_f32_e32 v164, v164
	v_rcp_f32_e32 v165, v165
	s_nop 0
	v_pk_mul_f32 v[146:147], v[140:141], v[164:165]
; __device__ __forceinline__ unsigned cvt_pk_bf16(float lo, float hi) { const f32x2 v = {lo, hi}; const bf16v2_t b = __builtin_convertvector(v, bf16v2_t); return __builtin_bit_cast(unsigned, b); }
; __device__ __forceinline__ float sigmoidf_(float x) { return __builtin_amdgcn_rcpf(1.0f + __builtin_amdgcn_exp2f(x * -1.44269504089f)); }
; __device__ __forceinline__ float siluf_(float x) { return x * __builtin_amdgcn_rcpf(1.0f + __builtin_amdgcn_exp2f(x * -1.44269504089f)); }
;     __device__ __forceinline__ void epi_proj(const f32x4 (&acc)[2][2][4][2], const pg8::Unit& u, int wr, int wc, int fr, int fq) const {
;     ...
; #pragma unroll
;                         for (int bj = 0; bj < 2; ++bj) {
;                             f32x4 v0 = acc[ai][bj][m][0] * rstd, v1 = acc[ai][bj][m][1] * rstd;
;                             if (slot < 2) {
;                                 f32x2 a = gelu_pk((f32x2){v0[0], v0[1]}), b = gelu_pk((f32x2){v0[2], v0[3]}), c = gelu_pk((f32x2){v1[0], v1[1]}), d = gelu_pk((f32x2){v1[2], v1[3]});
;                                 v0 = (f32x4){a.x, a.y, b.x, b.y}; v1 = (f32x4){c.x, c.y, d.x, d.y};
;                             } else if (slot == 5) {
; #pragma unroll
;                                 for (int j = 0; j < 4; ++j) { v0[j] = siluf_(v0[j]); v1[j] = siluf_(v1[j]); }
;                             } else if (slot >= 6) {
; #pragma unroll
;                                 for (int j = 0; j < 4; ++j) { v0[j] = sigmoidf_(v0[j]); v1[j] = sigmoidf_(v1[j]); }
;                             }
;                             u32x4 w; w.x = cvt_pk_bf16(v0[0], v0[1]); w.y = cvt_pk_bf16(v0[2], v0[3]); w.z = cvt_pk_bf16(v1[0], v1[1]); w.w = cvt_pk_bf16(v1[2], v1[3]);
;                             *(u32x4*)(rowp + bj * 128) = w;
	v_cvt_pk_bf16_f32 v138, v138, v139
	v_cvt_pk_bf16_f32 v139, v134, v135
	v_add_co_u32_e32 v134, vcc, s0, v136
	v_cvt_pk_bf16_f32 v140, v144, v145
	v_cvt_pk_bf16_f32 v141, v146, v147
	v_addc_co_u32_e32 v135, vcc, 0, v137, vcc
	global_store_dwordx4 v[134:135], v[138:141], off
	v_pk_mul_f32 v[134:135], v[46:47], v[132:133] op_sel_hi:[1,0]
	s_mov_b64 s[0:1], 0x50000
	v_pk_mul_f32 v[138:139], v[44:45], v[132:133] op_sel_hi:[1,0]
	v_pk_mul_f32 v[140:141], v[42:43], v[132:133] op_sel_hi:[1,0]
	v_pk_mul_f32 v[132:133], v[40:41], v[132:133] op_sel_hi:[1,0]
	v_mul_f32_e32 v168, 0xbfb8aa3b, v138
	v_exp_f32_e32 v168, v168
	v_mul_f32_e32 v170, 0xbfb8aa3b, v132
	v_exp_f32_e32 v170, v170
	v_mul_f32_e32 v171, 0xbfb8aa3b, v133
	v_exp_f32_e32 v171, v171
	v_mul_f32_e32 v169, 0xbfb8aa3b, v139
	v_exp_f32_e32 v169, v169
	s_nop 0
	v_add_f32_e32 v170, 1.0, v170
	v_add_f32_e32 v171, 1.0, v171
	v_rcp_f32_e32 v170, v170
	v_rcp_f32_e32 v171, v171
	s_nop 0
	v_pk_mul_f32 v[144:145], v[132:133], v[170:171]
	v_mul_f32_e32 v172, 0xbfb8aa3b, v134
	v_exp_f32_e32 v172, v172
	v_mov_b32_e32 v132, v134
	v_mul_f32_e32 v174, 0xbfb8aa3b, v140
	v_exp_f32_e32 v174, v174
	v_mov_b32_e32 v134, v140
	v_mul_f32_e32 v173, 0xbfb8aa3b, v135
	v_exp_f32_e32 v173, v173
	v_mov_b32_e32 v133, v135
	v_mul_f32_e32 v175, 0xbfb8aa3b, v141
	v_exp_f32_e32 v175, v175
	v_mov_b32_e32 v135, v141
	s_nop 0
	v_add_f32_e32 v168, 1.0, v168
	v_add_f32_e32 v169, 1.0, v169
	v_rcp_f32_e32 v168, v168
	v_rcp_f32_e32 v169, v169
	s_nop 0
	v_pk_mul_f32 v[138:139], v[138:139], v[168:169]
	s_nop 0
	v_add_f32_e32 v172, 1.0, v172
	v_add_f32_e32 v173, 1.0, v173
	v_rcp_f32_e32 v172, v172
	v_rcp_f32_e32 v173, v173
	s_nop 0
	v_pk_mul_f32 v[146:147], v[132:133], v[172:173]
	s_nop 0
	v_add_f32_e32 v174, 1.0, v174
	v_add_f32_e32 v175, 1.0, v175
	v_rcp_f32_e32 v174, v174
	v_rcp_f32_e32 v175, v175
	s_nop 0
	v_pk_mul_f32 v[140:141], v[134:135], v[174:175]
	v_cvt_pk_bf16_f32 v132, v138, v139
	v_cvt_pk_bf16_f32 v133, v146, v147
	v_cvt_pk_bf16_f32 v134, v144, v145
	v_cvt_pk_bf16_f32 v135, v140, v141
	global_store_dwordx4 v[142:143], v[132:135], off offset:256
	v_pk_mul_f32 v[140:141], v[18:19], v[130:131] op_sel_hi:[1,0]
	v_pk_mul_f32 v[142:143], v[16:17], v[130:131] op_sel_hi:[1,0]
	v_pk_mul_f32 v[134:135], v[20:21], v[130:131] op_sel_hi:[1,0]
	v_pk_mul_f32 v[132:133], v[22:23], v[130:131] op_sel_hi:[1,0]
	v_mul_f32_e32 v176, 0xbfb8aa3b, v134
	v_exp_f32_e32 v176, v176
	v_mul_f32_e32 v177, 0xbfb8aa3b, v135
	v_exp_f32_e32 v177, v177
	v_mul_f32_e32 v178, 0xbfb8aa3b, v140
	v_exp_f32_e32 v178, v178
	v_mul_f32_e32 v179, 0xbfb8aa3b, v141
	v_exp_f32_e32 v179, v179
	v_lshl_add_u64 v[138:139], v[136:137], 0, s[0:1]
	v_mul_f32_e32 v180, 0xbfb8aa3b, v142
	v_exp_f32_e32 v180, v180
	s_nop 0
	v_add_f32_e32 v176, 1.0, v176
	v_add_f32_e32 v177, 1.0, v177
	v_rcp_f32_e32 v176, v176
	v_rcp_f32_e32 v177, v177
	s_nop 0
	v_pk_mul_f32 v[134:135], v[134:135], v[176:177]
	v_mul_f32_e32 v181, 0xbfb8aa3b, v143
	v_exp_f32_e32 v181, v181
	v_mul_f32_e32 v182, 0xbfb8aa3b, v132
	v_exp_f32_e32 v182, v182
	v_mul_f32_e32 v183, 0xbfb8aa3b, v133
	v_exp_f32_e32 v183, v183
	s_nop 0
	v_add_f32_e32 v178, 1.0, v178
	v_add_f32_e32 v179, 1.0, v179
	v_rcp_f32_e32 v178, v178
	v_rcp_f32_e32 v179, v179
	s_nop 0
	v_pk_mul_f32 v[140:141], v[140:141], v[178:179]
	s_mov_b32 s0, 0x50000
	s_nop 0
	v_add_f32_e32 v180, 1.0, v180
	v_add_f32_e32 v181, 1.0, v181
	v_rcp_f32_e32 v180, v180
	v_rcp_f32_e32 v181, v181
	s_nop 0
	v_pk_mul_f32 v[142:143], v[142:143], v[180:181]
	s_nop 0
	v_add_f32_e32 v182, 1.0, v182
	v_add_f32_e32 v183, 1.0, v183
	v_rcp_f32_e32 v182, v182
	v_rcp_f32_e32 v183, v183
	s_nop 0
	v_pk_mul_f32 v[144:145], v[132:133], v[182:183]
	v_cvt_pk_bf16_f32 v132, v134, v135
	v_cvt_pk_bf16_f32 v135, v140, v141
	v_add_co_u32_e32 v140, vcc, s0, v136
	v_cvt_pk_bf16_f32 v133, v144, v145
	v_cvt_pk_bf16_f32 v134, v142, v143
	v_addc_co_u32_e32 v141, vcc, 0, v137, vcc
	global_store_dwordx4 v[140:141], v[132:135], off
	v_pk_mul_f32 v[140:141], v[26:27], v[130:131] op_sel_hi:[1,0]
	s_mov_b64 s[0:1], 0x58000
	v_pk_mul_f32 v[132:133], v[30:31], v[130:131] op_sel_hi:[1,0]
	v_pk_mul_f32 v[134:135], v[28:29], v[130:131] op_sel_hi:[1,0]
	v_pk_mul_f32 v[130:131], v[24:25], v[130:131] op_sel_hi:[1,0]
	v_mul_f32_e32 v186, 0xbfb8aa3b, v134
	v_exp_f32_e32 v186, v186
	v_mul_f32_e32 v184, 0xbfb8aa3b, v130
	v_exp_f32_e32 v184, v184
	v_mul_f32_e32 v185, 0xbfb8aa3b, v131
	v_exp_f32_e32 v185, v185
	v_mul_f32_e32 v187, 0xbfb8aa3b, v135
	v_exp_f32_e32 v187, v187
	s_nop 0
	v_add_f32_e32 v184, 1.0, v184
	v_add_f32_e32 v185, 1.0, v185
	v_rcp_f32_e32 v184, v184
	v_rcp_f32_e32 v185, v185
	s_nop 0
	v_pk_mul_f32 v[142:143], v[130:131], v[184:185]
	v_mul_f32_e32 v188, 0xbfb8aa3b, v132
	v_exp_f32_e32 v188, v188
	v_mov_b32_e32 v130, v132
	v_mul_f32_e32 v190, 0xbfb8aa3b, v140
	v_exp_f32_e32 v190, v190
	v_mov_b32_e32 v132, v140
	v_mul_f32_e32 v189, 0xbfb8aa3b, v133
	v_exp_f32_e32 v189, v189
	v_mov_b32_e32 v131, v133
	v_mul_f32_e32 v191, 0xbfb8aa3b, v141
	v_exp_f32_e32 v191, v191
	v_mov_b32_e32 v133, v141
	s_nop 0
	v_add_f32_e32 v186, 1.0, v186
	v_add_f32_e32 v187, 1.0, v187
	v_rcp_f32_e32 v186, v186
	v_rcp_f32_e32 v187, v187
	s_nop 0
	v_pk_mul_f32 v[134:135], v[134:135], v[186:187]
	s_nop 0
	v_add_f32_e32 v188, 1.0, v188
	v_add_f32_e32 v189, 1.0, v189
	v_rcp_f32_e32 v188, v188
	v_rcp_f32_e32 v189, v189
	s_nop 0
	v_pk_mul_f32 v[144:145], v[130:131], v[188:189]
	s_nop 0
	v_add_f32_e32 v190, 1.0, v190
	v_add_f32_e32 v191, 1.0, v191
	v_rcp_f32_e32 v190, v190
	v_rcp_f32_e32 v191, v191
	s_nop 0
	v_pk_mul_f32 v[140:141], v[132:133], v[190:191]
	v_cvt_pk_bf16_f32 v130, v134, v135
	v_cvt_pk_bf16_f32 v131, v144, v145
;     __device__ __forceinline__ void epi_proj(const f32x4 (&acc)[2][2][4][2], const pg8::Unit& u, int wr, int wc, int fr, int fq) const {
;     ...
;         float rstd8[2][4];
; #pragma unroll
;         for (int ai = 0; ai < 2; ++ai)
; #pragma unroll
;             for (int m = 0; m < 4; ++m) rstd8[ai][m] = rs[row0 + ai * 128 + m * 16];
; #pragma unroll
;         for (int ai = 0; ai < 2; ++ai)
; #pragma unroll
;             for (int m = 0; m < 4; ++m) rstd8[ai][m] = rsqrtf(rstd8[ai][m] * (1.0f / 1024.0f) + EPS);
; #pragma unroll
;         for (int ai = 0; ai < 2; ++ai)
; #pragma unroll
;             for (int m = 0; m < 4; ++m) {
;                 const int r = row0 + ai * 128 + m * 16;
;                     const float rstd = rstd8[ai][m];
;                     if (u.pn == 32) {
;                         if (wc == 0 && fq < 2) {
;                             const f32x4 v0 = acc[ai][0][m][0] * rstd, v1 = acc[ai][0][m][1] * rstd;
;                             float o8[8] = {v0[0], v0[1], v0[2], v0[3], v1[0], v1[1], v1[2], v1[3]};
; #pragma unroll
;                             for (int h = 0; h < 8; ++h) {
;                                 if (fq == 0) o8[h] = sigmoidf_(o8[h]);
;     ...
; #pragma unroll
;                         for (int bj = 0; bj < 2; ++bj) {
;                             f32x4 v0 = acc[ai][bj][m][0] * rstd, v1 = acc[ai][bj][m][1] * rstd;
;                             if (slot < 2) {
;                                 f32x2 a = gelu_pk((f32x2){v0[0], v0[1]}), b = gelu_pk((f32x2){v0[2], v0[3]}), c = gelu_pk((f32x2){v1[0], v1[1]}), d = gelu_pk((f32x2){v1[2], v1[3]});
;                                 v0 = (f32x4){a.x, a.y, b.x, b.y}; v1 = (f32x4){c.x, c.y, d.x, d.y};
;                             } else if (slot == 5) {
; #pragma unroll
;                                 for (int j = 0; j < 4; ++j) { v0[j] = siluf_(v0[j]); v1[j] = siluf_(v1[j]); }
;                             } else if (slot >= 6) {
; #pragma unroll
;                                 for (int j = 0; j < 4; ++j) { v0[j] = sigmoidf_(v0[j]); v1[j] = sigmoidf_(v1[j]); }
;                             }
;                             u32x4 w; w.x = cvt_pk_bf16(v0[0], v0[1]); w.y = cvt_pk_bf16(v0[2], v0[3]); w.z = cvt_pk_bf16(v1[0], v1[1]); w.w = cvt_pk_bf16(v1[2], v1[3]);
;                             *(u32x4*)(rowp + bj * 128) = w;
	v_cvt_pk_bf16_f32 v132, v142, v143
	v_cvt_pk_bf16_f32 v133, v140, v141
	global_store_dwordx4 v[138:139], v[130:133], off offset:256
	v_pk_mul_f32 v[138:139], v[2:3], v[128:129] op_sel_hi:[1,0]
	v_pk_mul_f32 v[140:141], v[0:1], v[128:129] op_sel_hi:[1,0]
	v_pk_mul_f32 v[130:131], v[6:7], v[128:129] op_sel_hi:[1,0]
	v_pk_mul_f32 v[132:133], v[4:5], v[128:129] op_sel_hi:[1,0]
	v_lshl_add_u64 v[134:135], v[136:137], 0, s[0:1]
	v_mul_f32_e32 v166, 0xbfb8aa3b, v132
	v_exp_f32_e32 v166, v166
	v_mul_f32_e32 v164, 0xbfb8aa3b, v140
	v_exp_f32_e32 v164, v164
	v_mul_f32_e32 v167, 0xbfb8aa3b, v133
	v_exp_f32_e32 v167, v167
	v_mul_f32_e32 v165, 0xbfb8aa3b, v141
	v_exp_f32_e32 v165, v165
	v_mul_f32_e32 v170, 0xbfb8aa3b, v130
	v_exp_f32_e32 v170, v170
	v_mul_f32_e32 v168, 0xbfb8aa3b, v138
	v_exp_f32_e32 v168, v168
	v_mul_f32_e32 v171, 0xbfb8aa3b, v131
	v_exp_f32_e32 v171, v171
	v_mul_f32_e32 v169, 0xbfb8aa3b, v139
	v_exp_f32_e32 v169, v169
	s_mov_b32 s0, 0x58000
	s_nop 0
	v_add_f32_e32 v166, 1.0, v166
	v_add_f32_e32 v167, 1.0, v167
	v_rcp_f32_e32 v166, v166
	v_rcp_f32_e32 v167, v167
	s_nop 0
	v_pk_mul_f32 v[132:133], v[132:133], v[166:167]
	s_nop 0
	v_add_f32_e32 v164, 1.0, v164
	v_add_f32_e32 v165, 1.0, v165
	v_rcp_f32_e32 v164, v164
	v_rcp_f32_e32 v165, v165
	s_nop 0
	v_pk_mul_f32 v[140:141], v[140:141], v[164:165]
	s_nop 0
	v_add_f32_e32 v170, 1.0, v170
	v_add_f32_e32 v171, 1.0, v171
	v_rcp_f32_e32 v170, v170
	v_rcp_f32_e32 v171, v171
	s_nop 0
	v_pk_mul_f32 v[142:143], v[130:131], v[170:171]
	s_nop 0
	v_add_f32_e32 v168, 1.0, v168
	v_add_f32_e32 v169, 1.0, v169
	v_rcp_f32_e32 v168, v168
	v_rcp_f32_e32 v169, v169
	s_nop 0
	v_pk_mul_f32 v[138:139], v[138:139], v[168:169]
	v_add_co_u32_e32 v136, vcc, s0, v136
	v_cvt_pk_bf16_f32 v130, v132, v133
	v_cvt_pk_bf16_f32 v131, v142, v143
	v_cvt_pk_bf16_f32 v132, v140, v141
	v_cvt_pk_bf16_f32 v133, v138, v139
	v_addc_co_u32_e32 v137, vcc, 0, v137, vcc
	global_store_dwordx4 v[136:137], v[130:133], off
	v_pk_mul_f32 v[136:137], v[10:11], v[128:129] op_sel_hi:[1,0]
	s_nop 0
	v_pk_mul_f32 v[130:131], v[14:15], v[128:129] op_sel_hi:[1,0]
	v_pk_mul_f32 v[132:133], v[12:13], v[128:129] op_sel_hi:[1,0]
	v_pk_mul_f32 v[128:129], v[8:9], v[128:129] op_sel_hi:[1,0]
	v_mul_f32_e32 v172, 0xbfb8aa3b, v132
	v_exp_f32_e32 v172, v172
	v_mul_f32_e32 v174, 0xbfb8aa3b, v128
	v_exp_f32_e32 v174, v174
	v_mul_f32_e32 v175, 0xbfb8aa3b, v129
	v_exp_f32_e32 v175, v175
	v_mul_f32_e32 v173, 0xbfb8aa3b, v133
	v_exp_f32_e32 v173, v173
	s_nop 0
	v_add_f32_e32 v174, 1.0, v174
	v_add_f32_e32 v175, 1.0, v175
	v_rcp_f32_e32 v174, v174
	v_rcp_f32_e32 v175, v175
	s_nop 0
	v_pk_mul_f32 v[138:139], v[128:129], v[174:175]
	v_mul_f32_e32 v176, 0xbfb8aa3b, v130
	v_exp_f32_e32 v176, v176
	v_mov_b32_e32 v128, v130
	v_mul_f32_e32 v178, 0xbfb8aa3b, v136
	v_exp_f32_e32 v178, v178
	v_mov_b32_e32 v130, v136
	v_mul_f32_e32 v177, 0xbfb8aa3b, v131
	v_exp_f32_e32 v177, v177
	v_mov_b32_e32 v129, v131
	v_mul_f32_e32 v179, 0xbfb8aa3b, v137
	v_exp_f32_e32 v179, v179
	v_mov_b32_e32 v131, v137
	s_nop 0
	v_add_f32_e32 v172, 1.0, v172
	v_add_f32_e32 v173, 1.0, v173
	v_rcp_f32_e32 v172, v172
	v_rcp_f32_e32 v173, v173
	s_nop 0
	v_pk_mul_f32 v[132:133], v[132:133], v[172:173]
	s_nop 0
	v_add_f32_e32 v176, 1.0, v176
	v_add_f32_e32 v177, 1.0, v177
	v_rcp_f32_e32 v176, v176
	v_rcp_f32_e32 v177, v177
	s_nop 0
	v_pk_mul_f32 v[140:141], v[128:129], v[176:177]
	s_nop 0
	v_add_f32_e32 v178, 1.0, v178
	v_add_f32_e32 v179, 1.0, v179
	v_rcp_f32_e32 v178, v178
	v_rcp_f32_e32 v179, v179
	s_nop 0
	v_pk_mul_f32 v[136:137], v[130:131], v[178:179]
	v_cvt_pk_bf16_f32 v128, v132, v133
	v_cvt_pk_bf16_f32 v129, v140, v141
	v_cvt_pk_bf16_f32 v130, v138, v139
	v_cvt_pk_bf16_f32 v131, v136, v137
	global_store_dwordx4 v[134:135], v[128:131], off offset:256
	s_branch .LBB0_701
.Lepi_plain:
	v_readlane_b32 s6, v254, 34
	v_readlane_b32 s7, v254, 35
	s_mov_b64 s[0:1], s[6:7]
	s_load_dwordx2 s[4:5], s[0:1], 0xb0
	s_mov_b64 s[0:1], s[6:7]
	s_mov_b64 s[0:1], s[6:7]
	s_mov_b64 s[0:1], s[6:7]
	s_mov_b64 s[0:1], s[6:7]
	v_lshl_add_u32 v136, s13, 8, v239
	v_ashrrev_i32_e32 v137, 31, v136
	s_mov_b64 s[0:1], s[6:7]
	v_lshl_add_u64 v[128:129], v[136:137], 2, s[66:67]
	global_load_dword v130, v[128:129], off
	global_load_dword v131, v[128:129], off offset:64
	global_load_dword v132, v[128:129], off offset:128
	global_load_dword v133, v[128:129], off offset:192
	global_load_dword v134, v[128:129], off offset:512
	global_load_dword v135, v[128:129], off offset:576
	global_load_dword v139, v[128:129], off offset:640
	s_nop 0
	global_load_dword v128, v[128:129], off offset:704
	s_mov_b32 s0, 0x800000
	v_lshl_or_b32 v152, s88, 8, v245
	v_and_b32_e32 v152, 0x3ff, v152
	v_ashrrev_i32_e32 v153, 31, v152
	s_waitcnt lgkmcnt(0)
	v_lshl_add_u64 v[152:153], v[152:153], 1, s[4:5]
	v_or_b32_e32 v146, 16, v136
	v_or_b32_e32 v142, 32, v136
	v_or_b32_e32 v140, 48, v136
	v_lshlrev_b64 v[136:137], 11, v[136:137]
	v_ashrrev_i32_e32 v147, 31, v146
	v_lshlrev_b64 v[146:147], 11, v[146:147]
	v_ashrrev_i32_e32 v143, 31, v142
	v_lshlrev_b64 v[142:143], 11, v[142:143]
	v_ashrrev_i32_e32 v141, 31, v140
	v_lshlrev_b64 v[140:141], 11, v[140:141]
	s_waitcnt vmcnt(0)
;     __device__ __forceinline__ void epi_proj(const f32x4 (&acc)[2][2][4][2], const pg8::Unit& u, int wr, int wc, int fr, int fq) const {
;     ...
;         float rstd8[2][4];
; #pragma unroll
;         for (int ai = 0; ai < 2; ++ai)
; #pragma unroll
;             for (int m = 0; m < 4; ++m) rstd8[ai][m] = rs[row0 + ai * 128 + m * 16];
; #pragma unroll
;         for (int ai = 0; ai < 2; ++ai)
; #pragma unroll
;             for (int m = 0; m < 4; ++m) rstd8[ai][m] = rsqrtf(rstd8[ai][m] * (1.0f / 1024.0f) + EPS);
; #pragma unroll
;         for (int ai = 0; ai < 2; ++ai)
; #pragma unroll
;             for (int m = 0; m < 4; ++m) {
;                 const int r = row0 + ai * 128 + m * 16;
;                     const float rstd = rstd8[ai][m];
;                     if (u.pn == 32) {
;                         if (wc == 0 && fq < 2) {
;                             const f32x4 v0 = acc[ai][0][m][0] * rstd, v1 = acc[ai][0][m][1] * rstd;
;                             float o8[8] = {v0[0], v0[1], v0[2], v0[3], v1[0], v1[1], v1[2], v1[3]};
; #pragma unroll
;                             for (int h = 0; h < 8; ++h) {
;                                 if (fq == 0) o8[h] = sigmoidf_(o8[h]);
;                                 else { const float xx = o8[h] + dt_bias[l * 8 + h]; const float sp = xx > 20.f ? xx : log1pf(__expf(xx)); o8[h] = -__expf(a_log[l * 8 + h]) * sp; }
;                             }
;                             float* dst = bg + (size_t)r * 16 + 8 * fq;
;                             *(f32x4*)dst = (f32x4){o8[0], o8[1], o8[2], o8[3]}; *(f32x4*)(dst + 4) = (f32x4){o8[4], o8[5], o8[6], o8[7]};
;                         }
;                     } else {
;                         const int slot = u.pn >> 2;
;                         bf16_t* rowp = act + (size_t)slot * SLOT_EL + (size_t)r * 1024 + (colt & 1023);
; #pragma unroll
;                         for (int bj = 0; bj < 2; ++bj) {
;                             f32x4 v0 = acc[ai][bj][m][0] * rstd, v1 = acc[ai][bj][m][1] * rstd;
;                             if (slot < 2) {
;                                 f32x2 a = gelu_pk((f32x2){v0[0], v0[1]}), b = gelu_pk((f32x2){v0[2], v0[3]}), c = gelu_pk((f32x2){v1[0], v1[1]}), d = gelu_pk((f32x2){v1[2], v1[3]});
;                                 v0 = (f32x4){a.x, a.y, b.x, b.y}; v1 = (f32x4){c.x, c.y, d.x, d.y};
;                             } else if (slot == 5) {
	v_fmamk_f32 v129, v130, 0x3a800000, v237
	v_cmp_gt_f32_e32 vcc, s0, v129
	v_mul_f32_e32 v130, 0x4b800000, v129
	v_fmamk_f32 v128, v128, 0x3a800000, v237
	v_cndmask_b32_e32 v129, v129, v130, vcc
	v_rsq_f32_e32 v129, v129
	s_nop 0
	v_mul_f32_e32 v130, 0x45800000, v129
	v_cndmask_b32_e32 v150, v129, v130, vcc
	v_fmamk_f32 v129, v131, 0x3a800000, v237
	v_cmp_gt_f32_e32 vcc, s0, v129
	v_mul_f32_e32 v130, 0x4b800000, v129
	v_pk_mul_f32 v[154:155], v[118:119], v[150:151] op_sel_hi:[1,0]
	v_cndmask_b32_e32 v129, v129, v130, vcc
	v_rsq_f32_e32 v129, v129
	v_pk_mul_f32 v[156:157], v[116:117], v[150:151] op_sel_hi:[1,0]
	v_pk_mul_f32 v[158:159], v[114:115], v[150:151] op_sel_hi:[1,0]
	v_pk_mul_f32 v[160:161], v[112:113], v[150:151] op_sel_hi:[1,0]
	v_mul_f32_e32 v130, 0x45800000, v129
	v_cndmask_b32_e32 v148, v129, v130, vcc
	v_fmamk_f32 v129, v132, 0x3a800000, v237
	v_cmp_gt_f32_e32 vcc, s0, v129
	v_mul_f32_e32 v130, 0x4b800000, v129
	v_cndmask_b32_e32 v129, v129, v130, vcc
	v_rsq_f32_e32 v129, v129
	v_mul_f32_e32 v130, 0x45800000, v129
	v_cndmask_b32_e32 v144, v129, v130, vcc
	v_fmamk_f32 v129, v133, 0x3a800000, v237
	v_cmp_gt_f32_e32 vcc, s0, v129
	v_mul_f32_e32 v130, 0x4b800000, v129
	v_cndmask_b32_e32 v129, v129, v130, vcc
	v_rsq_f32_e32 v129, v129
	v_mul_f32_e32 v130, 0x45800000, v129
	v_cndmask_b32_e32 v138, v129, v130, vcc
	v_fmamk_f32 v129, v134, 0x3a800000, v237
	v_cmp_gt_f32_e32 vcc, s0, v129
	v_mul_f32_e32 v130, 0x4b800000, v129
	v_cndmask_b32_e32 v129, v129, v130, vcc
	v_rsq_f32_e32 v129, v129
	v_mov_b32_e32 v162, v154
	v_mov_b32_e32 v163, v155
	v_mul_f32_e32 v130, 0x45800000, v129
	v_cndmask_b32_e32 v134, v129, v130, vcc
	v_fmamk_f32 v129, v135, 0x3a800000, v237
	v_cmp_gt_f32_e32 vcc, s0, v129
	v_mul_f32_e32 v130, 0x4b800000, v129
	v_cvt_pk_bf16_f32 v154, v156, v157
	v_cndmask_b32_e32 v129, v129, v130, vcc
	v_rsq_f32_e32 v129, v129
	v_cvt_pk_bf16_f32 v155, v162, v163
	v_cvt_pk_bf16_f32 v156, v160, v161
	v_cvt_pk_bf16_f32 v157, v158, v159
	v_mul_f32_e32 v130, 0x45800000, v129
	v_cndmask_b32_e32 v132, v129, v130, vcc
	v_fmamk_f32 v129, v139, 0x3a800000, v237
	v_cmp_gt_f32_e32 vcc, s0, v129
	v_mul_f32_e32 v130, 0x4b800000, v129
	v_pk_mul_f32 v[158:159], v[122:123], v[150:151] op_sel_hi:[1,0]
	v_cndmask_b32_e32 v129, v129, v130, vcc
	v_rsq_f32_e32 v129, v129
	v_mul_f32_e32 v130, 0x45800000, v129
	v_cndmask_b32_e32 v130, v129, v130, vcc
	v_cmp_gt_f32_e32 vcc, s0, v128
	s_lshl_b32 s100, s13, 2
	s_lshr_b32 s101, s56, 6
	s_add_i32 s100, s100, s101
	s_mul_i32 s100, s100, 3
	v_add_u32_e32 v164, s100, v204
	s_movk_i32 s101, 0x1800
	v_mul_lo_u32 v164, v164, s101
	v_mov_b32_e32 v165, 0
	s_lshr_b32 s100, s88, 2
	s_sub_i32 s100, s100, 2
	s_lshl_b32 s100, s100, 11
	s_add_u32 s100, s100, 0x33400000
	s_mov_b32 s101, 0
	v_lshl_add_u64 v[166:167], v[152:153], 0, v[164:165]
	v_lshl_add_u64 v[166:167], v[166:167], 0, s[100:101]
	s_mov_b64 s[100:101], 0x9000
	v_lshl_add_u64 v[168:169], v[166:167], 0, s[100:101]
	s_lshr_b32 s0, s88, 2
	s_mul_i32 s0, s0, 0x4080000
	s_add_u32 s0, s0, 0x8d80000
	s_mov_b32 s1, 0
	v_lshl_add_u64 v[152:153], v[152:153], 0, s[0:1]
	v_lshl_add_u64 v[136:137], v[152:153], 0, v[136:137]
	global_store_dwordx4 v[136:137], v[154:157], off
	v_mul_f32_e32 v129, 0x4b800000, v128
	v_cndmask_b32_e32 v128, v128, v129, vcc
	v_pk_mul_f32 v[154:155], v[126:127], v[150:151] op_sel_hi:[1,0]
	v_pk_mul_f32 v[156:157], v[124:125], v[150:151] op_sel_hi:[1,0]
	v_pk_mul_f32 v[150:151], v[120:121], v[150:151] op_sel_hi:[1,0]
	v_mov_b32_e32 v160, v154
	v_mov_b32_e32 v161, v155
	v_cvt_pk_bf16_f32 v154, v156, v157
	v_cvt_pk_bf16_f32 v155, v160, v161
	v_cvt_pk_bf16_f32 v156, v150, v151
	v_cvt_pk_bf16_f32 v157, v158, v159
	global_store_dwordx4 v[136:137], v[154:157], off offset:256
	v_lshl_add_u64 v[150:151], v[152:153], 0, v[146:147]
	v_pk_mul_f32 v[146:147], v[102:103], v[148:149] op_sel_hi:[1,0]
	v_pk_mul_f32 v[154:155], v[100:101], v[148:149] op_sel_hi:[1,0]
	v_pk_mul_f32 v[156:157], v[98:99], v[148:149] op_sel_hi:[1,0]
	v_pk_mul_f32 v[158:159], v[96:97], v[148:149] op_sel_hi:[1,0]
	v_mov_b32_e32 v160, v156
	v_mov_b32_e32 v161, v157
	v_cvt_pk_bf16_f32 v154, v154, v155
	v_cvt_pk_bf16_f32 v155, v146, v147
	v_cvt_pk_bf16_f32 v156, v158, v159
	v_cvt_pk_bf16_f32 v157, v160, v161
	global_store_dwordx4 v[150:151], v[154:157], off
	v_pk_mul_f32 v[146:147], v[110:111], v[148:149] op_sel_hi:[1,0]
	v_rsq_f32_e32 v128, v128
	v_pk_mul_f32 v[154:155], v[108:109], v[148:149] op_sel_hi:[1,0]
	v_pk_mul_f32 v[156:157], v[106:107], v[148:149] op_sel_hi:[1,0]
	v_pk_mul_f32 v[148:149], v[104:105], v[148:149] op_sel_hi:[1,0]
	v_mov_b32_e32 v158, v146
	v_mov_b32_e32 v159, v147
	v_cvt_pk_bf16_f32 v146, v154, v155
	v_cvt_pk_bf16_f32 v147, v158, v159
	v_cvt_pk_bf16_f32 v148, v148, v149
	v_cvt_pk_bf16_f32 v149, v156, v157
	global_store_dwordx4 v[150:151], v[146:149], off offset:256
	v_lshl_add_u64 v[150:151], v[152:153], 0, v[142:143]
	v_pk_mul_f32 v[142:143], v[86:87], v[144:145] op_sel_hi:[1,0]
	v_pk_mul_f32 v[146:147], v[84:85], v[144:145] op_sel_hi:[1,0]
	v_pk_mul_f32 v[148:149], v[82:83], v[144:145] op_sel_hi:[1,0]
	v_pk_mul_f32 v[154:155], v[80:81], v[144:145] op_sel_hi:[1,0]
	v_mov_b32_e32 v156, v148
	v_mov_b32_e32 v157, v149
	v_cvt_pk_bf16_f32 v146, v146, v147
	v_cvt_pk_bf16_f32 v147, v142, v143
	v_cvt_pk_bf16_f32 v148, v154, v155
	v_cvt_pk_bf16_f32 v149, v156, v157
	global_store_dwordx4 v[150:151], v[146:149], off
	v_pk_mul_f32 v[142:143], v[94:95], v[144:145] op_sel_hi:[1,0]
	s_mov_b64 s[0:1], 0x40000
	v_pk_mul_f32 v[146:147], v[92:93], v[144:145] op_sel_hi:[1,0]
	v_pk_mul_f32 v[148:149], v[90:91], v[144:145] op_sel_hi:[1,0]
	v_pk_mul_f32 v[144:145], v[88:89], v[144:145] op_sel_hi:[1,0]
; __device__ __forceinline__ unsigned cvt_pk_bf16(float lo, float hi) { const f32x2 v = {lo, hi}; const bf16v2_t b = __builtin_convertvector(v, bf16v2_t); return __builtin_bit_cast(unsigned, b); }
;     __device__ __forceinline__ void epi_proj(const f32x4 (&acc)[2][2][4][2], const pg8::Unit& u, int wr, int wc, int fr, int fq) const {
;     ...
;                             u32x4 w; w.x = cvt_pk_bf16(v0[0], v0[1]); w.y = cvt_pk_bf16(v0[2], v0[3]); w.z = cvt_pk_bf16(v1[0], v1[1]); w.w = cvt_pk_bf16(v1[2], v1[3]);
;                             *(u32x4*)(rowp + bj * 128) = w;
;                             if (slot >= 2 && slot <= 4) {
;                                 const int ch = (slot - 2) * 1024 + (colt & 1023) + bj * 128;
;                                 if ((r & 63) >= 61) *(u32x4*)(halo + ((size_t)(r >> 6) * 3 + ((r & 63) - 61)) * 3072 + ch) = w;
	v_mov_b32_e32 v154, v142
	v_mov_b32_e32 v155, v143
	v_cvt_pk_bf16_f32 v142, v146, v147
	v_cvt_pk_bf16_f32 v143, v154, v155
	v_cvt_pk_bf16_f32 v144, v144, v145
	v_cvt_pk_bf16_f32 v145, v148, v149
	global_store_dwordx4 v[150:151], v[142:145], off offset:256
	v_pk_mul_f32 v[146:147], v[66:67], v[138:139] op_sel_hi:[1,0]
	v_pk_mul_f32 v[148:149], v[64:65], v[138:139] op_sel_hi:[1,0]
	v_lshl_add_u64 v[144:145], v[152:153], 0, v[140:141]
	v_pk_mul_f32 v[140:141], v[70:71], v[138:139] op_sel_hi:[1,0]
	v_pk_mul_f32 v[142:143], v[68:69], v[138:139] op_sel_hi:[1,0]
	v_mov_b32_e32 v150, v140
	v_mov_b32_e32 v151, v141
	v_cvt_pk_bf16_f32 v140, v142, v143
	v_cvt_pk_bf16_f32 v141, v150, v151
	v_cvt_pk_bf16_f32 v142, v148, v149
	v_cvt_pk_bf16_f32 v143, v146, v147
	global_store_dwordx4 v[144:145], v[140:143], off
	s_and_saveexec_b64 s[100:101], s[36:37]
	global_store_dwordx4 v[166:167], v[140:143], off
	s_mov_b64 exec, s[100:101]
	v_pk_mul_f32 v[146:147], v[74:75], v[138:139] op_sel_hi:[1,0]
	v_mul_f32_e32 v129, 0x45800000, v128
	v_pk_mul_f32 v[140:141], v[78:79], v[138:139] op_sel_hi:[1,0]
	v_pk_mul_f32 v[142:143], v[76:77], v[138:139] op_sel_hi:[1,0]
	v_pk_mul_f32 v[138:139], v[72:73], v[138:139] op_sel_hi:[1,0]
	v_mov_b32_e32 v148, v138
	v_mov_b32_e32 v149, v139
	v_mov_b32_e32 v138, v140
	v_mov_b32_e32 v140, v146
	v_mov_b32_e32 v139, v141
	v_mov_b32_e32 v141, v147
	v_mov_b32_e32 v150, v138
	v_mov_b32_e32 v151, v139
	v_mov_b32_e32 v146, v140
	v_mov_b32_e32 v147, v141
	v_cvt_pk_bf16_f32 v138, v142, v143
	v_cvt_pk_bf16_f32 v139, v150, v151
	v_cvt_pk_bf16_f32 v140, v148, v149
	v_cvt_pk_bf16_f32 v141, v146, v147
	global_store_dwordx4 v[144:145], v[138:141], off offset:256
	s_and_saveexec_b64 s[100:101], s[36:37]
	global_store_dwordx4 v[166:167], v[138:141], off offset:256
	s_mov_b64 exec, s[100:101]
	v_pk_mul_f32 v[144:145], v[50:51], v[134:135] op_sel_hi:[1,0]
	v_pk_mul_f32 v[146:147], v[48:49], v[134:135] op_sel_hi:[1,0]
	v_pk_mul_f32 v[140:141], v[52:53], v[134:135] op_sel_hi:[1,0]
	v_pk_mul_f32 v[138:139], v[54:55], v[134:135] op_sel_hi:[1,0]
	v_lshl_add_u64 v[142:143], v[136:137], 0, s[0:1]
	s_mov_b32 s0, 0x40000
	v_cndmask_b32_e32 v128, v128, v129, vcc
	v_mov_b32_e32 v148, v138
	v_mov_b32_e32 v149, v139
	v_cvt_pk_bf16_f32 v138, v140, v141
	v_cvt_pk_bf16_f32 v141, v144, v145
	v_add_co_u32_e32 v144, vcc, s0, v136
	v_cvt_pk_bf16_f32 v139, v148, v149
	v_cvt_pk_bf16_f32 v140, v146, v147
	v_addc_co_u32_e32 v145, vcc, 0, v137, vcc
	global_store_dwordx4 v[144:145], v[138:141], off
	v_pk_mul_f32 v[144:145], v[58:59], v[134:135] op_sel_hi:[1,0]
	s_mov_b64 s[0:1], 0x48000
	v_pk_mul_f32 v[138:139], v[62:63], v[134:135] op_sel_hi:[1,0]
	v_pk_mul_f32 v[140:141], v[60:61], v[134:135] op_sel_hi:[1,0]
	v_pk_mul_f32 v[134:135], v[56:57], v[134:135] op_sel_hi:[1,0]
	v_mov_b32_e32 v146, v138
	v_mov_b32_e32 v147, v139
	v_cvt_pk_bf16_f32 v138, v140, v141
	v_cvt_pk_bf16_f32 v139, v146, v147
	v_cvt_pk_bf16_f32 v140, v134, v135
	v_cvt_pk_bf16_f32 v141, v144, v145
	global_store_dwordx4 v[142:143], v[138:141], off offset:256
	v_pk_mul_f32 v[134:135], v[38:39], v[132:133] op_sel_hi:[1,0]
	v_pk_mul_f32 v[144:145], v[32:33], v[132:133] op_sel_hi:[1,0]
	v_pk_mul_f32 v[138:139], v[36:37], v[132:133] op_sel_hi:[1,0]
	v_pk_mul_f32 v[140:141], v[34:35], v[132:133] op_sel_hi:[1,0]
	v_lshl_add_u64 v[142:143], v[136:137], 0, s[0:1]
	s_mov_b32 s0, 0x48000
	v_mov_b32_e32 v146, v140
	v_mov_b32_e32 v147, v141
	v_cvt_pk_bf16_f32 v138, v138, v139
	v_cvt_pk_bf16_f32 v139, v134, v135
	v_add_co_u32_e32 v134, vcc, s0, v136
	v_cvt_pk_bf16_f32 v140, v144, v145
	v_cvt_pk_bf16_f32 v141, v146, v147
	v_addc_co_u32_e32 v135, vcc, 0, v137, vcc
	global_store_dwordx4 v[134:135], v[138:141], off
	v_pk_mul_f32 v[134:135], v[46:47], v[132:133] op_sel_hi:[1,0]
	s_mov_b64 s[0:1], 0x50000
	v_pk_mul_f32 v[138:139], v[44:45], v[132:133] op_sel_hi:[1,0]
	v_pk_mul_f32 v[140:141], v[42:43], v[132:133] op_sel_hi:[1,0]
	v_pk_mul_f32 v[132:133], v[40:41], v[132:133] op_sel_hi:[1,0]
	v_mov_b32_e32 v144, v132
	v_mov_b32_e32 v145, v133
	v_mov_b32_e32 v132, v134
	v_mov_b32_e32 v134, v140
	v_mov_b32_e32 v133, v135
	v_mov_b32_e32 v135, v141
	v_mov_b32_e32 v146, v132
	v_mov_b32_e32 v147, v133
	v_mov_b32_e32 v140, v134
	v_mov_b32_e32 v141, v135
	v_cvt_pk_bf16_f32 v132, v138, v139
	v_cvt_pk_bf16_f32 v133, v146, v147
	v_cvt_pk_bf16_f32 v134, v144, v145
	v_cvt_pk_bf16_f32 v135, v140, v141
	global_store_dwordx4 v[142:143], v[132:135], off offset:256
	v_pk_mul_f32 v[140:141], v[18:19], v[130:131] op_sel_hi:[1,0]
	v_pk_mul_f32 v[142:143], v[16:17], v[130:131] op_sel_hi:[1,0]
	v_pk_mul_f32 v[134:135], v[20:21], v[130:131] op_sel_hi:[1,0]
	v_pk_mul_f32 v[132:133], v[22:23], v[130:131] op_sel_hi:[1,0]
	v_lshl_add_u64 v[138:139], v[136:137], 0, s[0:1]
	s_mov_b32 s0, 0x50000
	v_mov_b32_e32 v144, v132
	v_mov_b32_e32 v145, v133
	v_cvt_pk_bf16_f32 v132, v134, v135
	v_cvt_pk_bf16_f32 v135, v140, v141
	v_add_co_u32_e32 v140, vcc, s0, v136
	v_cvt_pk_bf16_f32 v133, v144, v145
	v_cvt_pk_bf16_f32 v134, v142, v143
	v_addc_co_u32_e32 v141, vcc, 0, v137, vcc
	global_store_dwordx4 v[140:141], v[132:135], off
	v_pk_mul_f32 v[140:141], v[26:27], v[130:131] op_sel_hi:[1,0]
	s_mov_b64 s[0:1], 0x58000
	v_pk_mul_f32 v[132:133], v[30:31], v[130:131] op_sel_hi:[1,0]
	v_pk_mul_f32 v[134:135], v[28:29], v[130:131] op_sel_hi:[1,0]
	v_pk_mul_f32 v[130:131], v[24:25], v[130:131] op_sel_hi:[1,0]
	v_mov_b32_e32 v142, v130
	v_mov_b32_e32 v143, v131
	v_mov_b32_e32 v130, v132
	v_mov_b32_e32 v132, v140
	v_mov_b32_e32 v131, v133
	v_mov_b32_e32 v133, v141
	v_mov_b32_e32 v144, v130
	v_mov_b32_e32 v145, v131
	v_mov_b32_e32 v140, v132
	v_mov_b32_e32 v141, v133
;     __device__ __forceinline__ void epi_proj(const f32x4 (&acc)[2][2][4][2], const pg8::Unit& u, int wr, int wc, int fr, int fq) const {
;     ...
;         float rstd8[2][4];
; #pragma unroll
;         for (int ai = 0; ai < 2; ++ai)
; #pragma unroll
;             for (int m = 0; m < 4; ++m) rstd8[ai][m] = rs[row0 + ai * 128 + m * 16];
; #pragma unroll
;         for (int ai = 0; ai < 2; ++ai)
; #pragma unroll
;             for (int m = 0; m < 4; ++m) rstd8[ai][m] = rsqrtf(rstd8[ai][m] * (1.0f / 1024.0f) + EPS);
; #pragma unroll
;         for (int ai = 0; ai < 2; ++ai)
; #pragma unroll
;             for (int m = 0; m < 4; ++m) {
;                 const int r = row0 + ai * 128 + m * 16;
;                     const float rstd = rstd8[ai][m];
;                     if (u.pn == 32) {
;                         if (wc == 0 && fq < 2) {
;                             const f32x4 v0 = acc[ai][0][m][0] * rstd, v1 = acc[ai][0][m][1] * rstd;
;                             float o8[8] = {v0[0], v0[1], v0[2], v0[3], v1[0], v1[1], v1[2], v1[3]};
; #pragma unroll
;                             for (int h = 0; h < 8; ++h) {
;                                 if (fq == 0) o8[h] = sigmoidf_(o8[h]);
;                                 else { const float xx = o8[h] + dt_bias[l * 8 + h]; const float sp = xx > 20.f ? xx : log1pf(__expf(xx)); o8[h] = -__expf(a_log[l * 8 + h]) * sp; }
;                             }
;                             float* dst = bg + (size_t)r * 16 + 8 * fq;
;                             *(f32x4*)dst = (f32x4){o8[0], o8[1], o8[2], o8[3]}; *(f32x4*)(dst + 4) = (f32x4){o8[4], o8[5], o8[6], o8[7]};
;                         }
;                     } else {
;                         const int slot = u.pn >> 2;
;                         bf16_t* rowp = act + (size_t)slot * SLOT_EL + (size_t)r * 1024 + (colt & 1023);
;     ...
;                             u32x4 w; w.x = cvt_pk_bf16(v0[0], v0[1]); w.y = cvt_pk_bf16(v0[2], v0[3]); w.z = cvt_pk_bf16(v1[0], v1[1]); w.w = cvt_pk_bf16(v1[2], v1[3]);
;                             *(u32x4*)(rowp + bj * 128) = w;
;                             if (slot >= 2 && slot <= 4) {
;                                 const int ch = (slot - 2) * 1024 + (colt & 1023) + bj * 128;
;                                 if ((r & 63) >= 61) *(u32x4*)(halo + ((size_t)(r >> 6) * 3 + ((r & 63) - 61)) * 3072 + ch) = w;
	v_cvt_pk_bf16_f32 v130, v134, v135
	v_cvt_pk_bf16_f32 v131, v144, v145
	v_cvt_pk_bf16_f32 v132, v142, v143
	v_cvt_pk_bf16_f32 v133, v140, v141
	global_store_dwordx4 v[138:139], v[130:133], off offset:256
	v_pk_mul_f32 v[138:139], v[2:3], v[128:129] op_sel_hi:[1,0]
	v_pk_mul_f32 v[140:141], v[0:1], v[128:129] op_sel_hi:[1,0]
	v_pk_mul_f32 v[130:131], v[6:7], v[128:129] op_sel_hi:[1,0]
	v_pk_mul_f32 v[132:133], v[4:5], v[128:129] op_sel_hi:[1,0]
	v_lshl_add_u64 v[134:135], v[136:137], 0, s[0:1]
	s_mov_b32 s0, 0x58000
	v_mov_b32_e32 v142, v130
	v_mov_b32_e32 v143, v131
	v_add_co_u32_e32 v136, vcc, s0, v136
	v_cvt_pk_bf16_f32 v130, v132, v133
	v_cvt_pk_bf16_f32 v131, v142, v143
	v_cvt_pk_bf16_f32 v132, v140, v141
	v_cvt_pk_bf16_f32 v133, v138, v139
	v_addc_co_u32_e32 v137, vcc, 0, v137, vcc
	global_store_dwordx4 v[136:137], v[130:133], off
	s_and_saveexec_b64 s[100:101], s[36:37]
	global_store_dwordx4 v[168:169], v[130:133], off
	s_mov_b64 exec, s[100:101]
	v_pk_mul_f32 v[136:137], v[10:11], v[128:129] op_sel_hi:[1,0]
	s_nop 0
	v_pk_mul_f32 v[130:131], v[14:15], v[128:129] op_sel_hi:[1,0]
	v_pk_mul_f32 v[132:133], v[12:13], v[128:129] op_sel_hi:[1,0]
	v_pk_mul_f32 v[128:129], v[8:9], v[128:129] op_sel_hi:[1,0]
	v_mov_b32_e32 v138, v128
	v_mov_b32_e32 v139, v129
	v_mov_b32_e32 v128, v130
	v_mov_b32_e32 v130, v136
	v_mov_b32_e32 v129, v131
	v_mov_b32_e32 v131, v137
	v_mov_b32_e32 v140, v128
	v_mov_b32_e32 v141, v129
	v_mov_b32_e32 v136, v130
	v_mov_b32_e32 v137, v131
	v_cvt_pk_bf16_f32 v128, v132, v133
	v_cvt_pk_bf16_f32 v129, v140, v141
	v_cvt_pk_bf16_f32 v130, v138, v139
	v_cvt_pk_bf16_f32 v131, v136, v137
	global_store_dwordx4 v[134:135], v[128:131], off offset:256
	s_and_saveexec_b64 s[100:101], s[36:37]
	global_store_dwordx4 v[168:169], v[128:131], off offset:256
	s_mov_b64 exec, s[100:101]
	s_branch .LBB0_701
.Lepi_gelu:
	s_mov_b32 s14, 0x3e6d3388
	s_mov_b32 s15, 0x3f07dc22
	s_mov_b32 s20, 0xbf38aa3b
	v_mov_b32_e32 v188, 0xbf3a00e3
	v_mov_b32_e32 v189, 0x3f35f0e3
	v_mov_b32_e32 v190, 0xbe11a98e
	v_mov_b32_e32 v191, 0x3e027906
	v_readlane_b32 s6, v254, 34
	v_readlane_b32 s7, v254, 35
	s_mov_b64 s[0:1], s[6:7]
	s_load_dwordx2 s[4:5], s[0:1], 0xb0
	s_mov_b64 s[0:1], s[6:7]
	s_mov_b64 s[0:1], s[6:7]
	s_mov_b64 s[0:1], s[6:7]
	s_mov_b64 s[0:1], s[6:7]
	v_lshl_add_u32 v136, s13, 8, v239
	v_ashrrev_i32_e32 v137, 31, v136
	s_mov_b64 s[0:1], s[6:7]
	v_lshl_add_u64 v[128:129], v[136:137], 2, s[66:67]
	global_load_dword v130, v[128:129], off
	global_load_dword v131, v[128:129], off offset:64
	global_load_dword v132, v[128:129], off offset:128
	global_load_dword v133, v[128:129], off offset:192
	global_load_dword v134, v[128:129], off offset:512
	global_load_dword v135, v[128:129], off offset:576
	global_load_dword v139, v[128:129], off offset:640
	s_nop 0
	global_load_dword v128, v[128:129], off offset:704
	s_mov_b32 s0, 0x800000
	v_lshl_or_b32 v152, s88, 8, v245
	v_and_b32_e32 v152, 0x3ff, v152
	v_ashrrev_i32_e32 v153, 31, v152
	s_waitcnt lgkmcnt(0)
	v_lshl_add_u64 v[152:153], v[152:153], 1, s[4:5]
	v_or_b32_e32 v146, 16, v136
	v_or_b32_e32 v142, 32, v136
	v_or_b32_e32 v140, 48, v136
	v_lshlrev_b64 v[136:137], 11, v[136:137]
	v_ashrrev_i32_e32 v147, 31, v146
	v_lshlrev_b64 v[146:147], 11, v[146:147]
	v_ashrrev_i32_e32 v143, 31, v142
	v_lshlrev_b64 v[142:143], 11, v[142:143]
	v_ashrrev_i32_e32 v141, 31, v140
	v_lshlrev_b64 v[140:141], 11, v[140:141]
	s_waitcnt vmcnt(0)
	v_fmamk_f32 v129, v130, 0x3a800000, v237
	v_cmp_gt_f32_e32 vcc, s0, v129
	v_mul_f32_e32 v130, 0x4b800000, v129
	v_fmamk_f32 v128, v128, 0x3a800000, v237
	v_cndmask_b32_e32 v129, v129, v130, vcc
	v_rsq_f32_e32 v129, v129
	s_nop 0
	v_mul_f32_e32 v130, 0x45800000, v129
	v_cndmask_b32_e32 v150, v129, v130, vcc
	v_fmamk_f32 v129, v131, 0x3a800000, v237
	v_cmp_gt_f32_e32 vcc, s0, v129
	v_mul_f32_e32 v130, 0x4b800000, v129
	v_pk_mul_f32 v[154:155], v[118:119], v[150:151] op_sel_hi:[1,0]
	v_cndmask_b32_e32 v129, v129, v130, vcc
	v_rsq_f32_e32 v129, v129
	v_pk_mul_f32 v[156:157], v[116:117], v[150:151] op_sel_hi:[1,0]
	v_pk_mul_f32 v[158:159], v[114:115], v[150:151] op_sel_hi:[1,0]
	v_pk_mul_f32 v[160:161], v[112:113], v[150:151] op_sel_hi:[1,0]
	v_mul_f32_e32 v130, 0x45800000, v129
	v_cndmask_b32_e32 v148, v129, v130, vcc
	v_fmamk_f32 v129, v132, 0x3a800000, v237
	v_cmp_gt_f32_e32 vcc, s0, v129
	v_mul_f32_e32 v130, 0x4b800000, v129
	v_cndmask_b32_e32 v129, v129, v130, vcc
	v_rsq_f32_e32 v129, v129
	v_mul_f32_e32 v130, 0x45800000, v129
	v_cndmask_b32_e32 v144, v129, v130, vcc
	v_fmamk_f32 v129, v133, 0x3a800000, v237
	v_cmp_gt_f32_e32 vcc, s0, v129
	v_mul_f32_e32 v130, 0x4b800000, v129
	v_cndmask_b32_e32 v129, v129, v130, vcc
	v_rsq_f32_e32 v129, v129
	v_mul_f32_e32 v130, 0x45800000, v129
	v_cndmask_b32_e32 v138, v129, v130, vcc
	v_fmamk_f32 v129, v134, 0x3a800000, v237
	v_cmp_gt_f32_e32 vcc, s0, v129
	v_mul_f32_e32 v130, 0x4b800000, v129
	v_and_b32_e32 v164, 0x7fffffff, v156
	v_and_b32_e32 v167, 0x7fffffff, v160
	v_and_b32_e32 v170, 0x7fffffff, v157
	v_and_b32_e32 v173, 0x7fffffff, v161
	v_and_b32_e32 v176, 0x7fffffff, v154
	v_and_b32_e32 v179, 0x7fffffff, v158
	v_and_b32_e32 v182, 0x7fffffff, v155
	v_and_b32_e32 v185, 0x7fffffff, v159
	v_mul_f32_e32 v165, v156, v156
	v_mul_f32_e32 v168, v160, v160
	v_mul_f32_e32 v171, v157, v157
	v_mul_f32_e32 v174, v161, v161
	v_mul_f32_e32 v177, v154, v154
	v_mul_f32_e32 v180, v158, v158
	v_mul_f32_e32 v183, v155, v155
	v_mul_f32_e32 v186, v159, v159
	v_fma_f32 v164, v164, s14, 1.0
	v_fma_f32 v167, v167, s14, 1.0
	v_fma_f32 v170, v170, s14, 1.0
	v_fma_f32 v173, v173, s14, 1.0
	v_fma_f32 v176, v176, s14, 1.0
	v_fma_f32 v179, v179, s14, 1.0
; __device__ __forceinline__ f32x2 gelu_pk(f32x2 v) {
;     const f32x2 av = __builtin_elementwise_abs(v), d = av * 0.2316418882f + 1.0f;
;     f32x2 t; t.x = __builtin_amdgcn_rcpf(d.x); t.y = __builtin_amdgcn_rcpf(d.y);
;     f32x2 q = t * 0.5307027145f + (-0.7265760135f); q = q * t + 0.7107068705f; q = q * t + (-0.142248368f); q = q * t + 0.127414796f; q = q * t;
;     const f32x2 s = (v * v) * (-0.72134752044f);
;     f32x2 e; e.x = __builtin_amdgcn_exp2f(s.x); e.y = __builtin_amdgcn_exp2f(s.y);
;     const f32x2 m = v * (q * e), r = v - m;
;     f32x2 o; o.x = v.x < 0.f ? m.x : r.x; o.y = v.y < 0.f ? m.y : r.y; return o;
; }
;     __device__ __forceinline__ void epi_proj(const f32x4 (&acc)[2][2][4][2], const pg8::Unit& u, int wr, int wc, int fr, int fq) const {
;     ...
; #pragma unroll
;                         for (int bj = 0; bj < 2; ++bj) {
;                             f32x4 v0 = acc[ai][bj][m][0] * rstd, v1 = acc[ai][bj][m][1] * rstd;
;                             if (slot < 2) {
;                                 f32x2 a = gelu_pk((f32x2){v0[0], v0[1]}), b = gelu_pk((f32x2){v0[2], v0[3]}), c = gelu_pk((f32x2){v1[0], v1[1]}), d = gelu_pk((f32x2){v1[2], v1[3]});
;                                 v0 = (f32x4){a.x, a.y, b.x, b.y}; v1 = (f32x4){c.x, c.y, d.x, d.y};
	v_fma_f32 v182, v182, s14, 1.0
	v_fma_f32 v185, v185, s14, 1.0
	v_mul_f32_e32 v165, s20, v165
	v_mul_f32_e32 v168, s20, v168
	v_mul_f32_e32 v171, s20, v171
	v_mul_f32_e32 v174, s20, v174
	v_mul_f32_e32 v177, s20, v177
	v_mul_f32_e32 v180, s20, v180
	v_mul_f32_e32 v183, s20, v183
	v_mul_f32_e32 v186, s20, v186
	v_rcp_f32_e32 v164, v164
	v_rcp_f32_e32 v167, v167
	v_rcp_f32_e32 v170, v170
	v_rcp_f32_e32 v173, v173
	v_rcp_f32_e32 v176, v176
	v_rcp_f32_e32 v179, v179
	v_rcp_f32_e32 v182, v182
	v_rcp_f32_e32 v185, v185
	s_nop 0
	v_exp_f32_e32 v165, v165
	v_exp_f32_e32 v168, v168
	v_exp_f32_e32 v171, v171
	v_exp_f32_e32 v174, v174
	v_exp_f32_e32 v177, v177
	v_exp_f32_e32 v180, v180
	v_exp_f32_e32 v183, v183
	v_exp_f32_e32 v186, v186
	s_nop 0
	v_fma_f32 v166, v164, s15, v188
	v_fma_f32 v169, v167, s15, v188
	v_fma_f32 v172, v170, s15, v188
	v_fma_f32 v175, v173, s15, v188
	v_fma_f32 v178, v176, s15, v188
	v_fma_f32 v181, v179, s15, v188
	v_fma_f32 v184, v182, s15, v188
	v_fma_f32 v187, v185, s15, v188
	v_fma_f32 v166, v166, v164, v189
	v_fma_f32 v169, v169, v167, v189
	v_fma_f32 v172, v172, v170, v189
	v_fma_f32 v175, v175, v173, v189
	v_fma_f32 v178, v178, v176, v189
	v_fma_f32 v181, v181, v179, v189
	v_fma_f32 v184, v184, v182, v189
	v_fma_f32 v187, v187, v185, v189
	v_fma_f32 v166, v166, v164, v190
	v_fma_f32 v169, v169, v167, v190
	v_fma_f32 v172, v172, v170, v190
	v_fma_f32 v175, v175, v173, v190
	v_fma_f32 v178, v178, v176, v190
	v_fma_f32 v181, v181, v179, v190
	v_fma_f32 v184, v184, v182, v190
	v_fma_f32 v187, v187, v185, v190
	v_fma_f32 v166, v166, v164, v191
	v_fma_f32 v169, v169, v167, v191
	v_fma_f32 v172, v172, v170, v191
	v_fma_f32 v175, v175, v173, v191
	v_fma_f32 v178, v178, v176, v191
	v_fma_f32 v181, v181, v179, v191
	v_fma_f32 v184, v184, v182, v191
	v_fma_f32 v187, v187, v185, v191
	v_mul_f32_e32 v166, v166, v164
	v_mul_f32_e32 v169, v169, v167
	v_mul_f32_e32 v172, v172, v170
	v_mul_f32_e32 v175, v175, v173
	v_mul_f32_e32 v178, v178, v176
	v_mul_f32_e32 v181, v181, v179
	v_mul_f32_e32 v184, v184, v182
	v_mul_f32_e32 v187, v187, v185
	v_mul_f32_e32 v166, v166, v165
	v_mul_f32_e32 v169, v169, v168
	v_mul_f32_e32 v172, v172, v171
	v_mul_f32_e32 v175, v175, v174
	v_mul_f32_e32 v178, v178, v177
	v_mul_f32_e32 v181, v181, v180
	v_mul_f32_e32 v184, v184, v183
	v_mul_f32_e32 v187, v187, v186
	v_mul_f32_e32 v166, v156, v166
	v_mul_f32_e32 v169, v160, v169
	v_mul_f32_e32 v172, v157, v172
	v_mul_f32_e32 v175, v161, v175
	v_mul_f32_e32 v178, v154, v178
	v_mul_f32_e32 v181, v158, v181
	v_mul_f32_e32 v184, v155, v184
	v_mul_f32_e32 v187, v159, v187
	v_sub_f32_e32 v165, v156, v166
	v_sub_f32_e32 v168, v160, v169
	v_sub_f32_e32 v171, v157, v172
	v_sub_f32_e32 v174, v161, v175
	v_sub_f32_e32 v177, v154, v178
	v_sub_f32_e32 v180, v158, v181
	v_sub_f32_e32 v183, v155, v184
	v_sub_f32_e32 v186, v159, v187
	v_cmp_gt_f32_e64 s[100:101], 0, v156
	s_nop 1
	v_cndmask_b32_e64 v156, v165, v166, s[100:101]
	v_cmp_gt_f32_e64 s[100:101], 0, v160
	s_nop 1
	v_cndmask_b32_e64 v160, v168, v169, s[100:101]
	v_cmp_gt_f32_e64 s[100:101], 0, v157
	s_nop 1
	v_cndmask_b32_e64 v157, v171, v172, s[100:101]
	v_cmp_gt_f32_e64 s[100:101], 0, v161
	s_nop 1
	v_cndmask_b32_e64 v161, v174, v175, s[100:101]
	v_cmp_gt_f32_e64 s[100:101], 0, v154
	s_nop 1
	v_cndmask_b32_e64 v154, v177, v178, s[100:101]
	v_cmp_gt_f32_e64 s[100:101], 0, v158
	s_nop 1
	v_cndmask_b32_e64 v158, v180, v181, s[100:101]
	v_cmp_gt_f32_e64 s[100:101], 0, v155
	s_nop 1
	v_cndmask_b32_e64 v155, v183, v184, s[100:101]
	v_cmp_gt_f32_e64 s[100:101], 0, v159
	s_nop 1
	v_cndmask_b32_e64 v159, v186, v187, s[100:101]
	v_cndmask_b32_e32 v129, v129, v130, vcc
	v_rsq_f32_e32 v129, v129
	v_mov_b32_e32 v162, v154
	v_mov_b32_e32 v163, v155
	v_mul_f32_e32 v130, 0x45800000, v129
	v_cndmask_b32_e32 v134, v129, v130, vcc
	v_fmamk_f32 v129, v135, 0x3a800000, v237
	v_cmp_gt_f32_e32 vcc, s0, v129
	v_mul_f32_e32 v130, 0x4b800000, v129
	v_cvt_pk_bf16_f32 v154, v156, v157
	v_cndmask_b32_e32 v129, v129, v130, vcc
	v_rsq_f32_e32 v129, v129
	v_cvt_pk_bf16_f32 v155, v162, v163
	v_cvt_pk_bf16_f32 v156, v160, v161
	v_cvt_pk_bf16_f32 v157, v158, v159
	v_mul_f32_e32 v130, 0x45800000, v129
	v_cndmask_b32_e32 v132, v129, v130, vcc
	v_fmamk_f32 v129, v139, 0x3a800000, v237
	v_cmp_gt_f32_e32 vcc, s0, v129
	v_mul_f32_e32 v130, 0x4b800000, v129
	v_pk_mul_f32 v[158:159], v[122:123], v[150:151] op_sel_hi:[1,0]
	v_cndmask_b32_e32 v129, v129, v130, vcc
	v_rsq_f32_e32 v129, v129
	v_and_b32_e32 v164, 0x7fffffff, v158
	v_and_b32_e32 v167, 0x7fffffff, v159
	v_mul_f32_e32 v165, v158, v158
	v_mul_f32_e32 v168, v159, v159
	v_fma_f32 v164, v164, s14, 1.0
	v_fma_f32 v167, v167, s14, 1.0
	v_mul_f32_e32 v165, s20, v165
	v_mul_f32_e32 v168, s20, v168
	v_rcp_f32_e32 v164, v164
	v_rcp_f32_e32 v167, v167
	s_nop 0
	v_exp_f32_e32 v165, v165
	v_exp_f32_e32 v168, v168
	s_nop 0
	v_fma_f32 v166, v164, s15, v188
	v_fma_f32 v169, v167, s15, v188
	v_fma_f32 v166, v166, v164, v189
	v_fma_f32 v169, v169, v167, v189
	v_fma_f32 v166, v166, v164, v190
	v_fma_f32 v169, v169, v167, v190
	v_fma_f32 v166, v166, v164, v191
	v_fma_f32 v169, v169, v167, v191
	v_mul_f32_e32 v166, v166, v164
	v_mul_f32_e32 v169, v169, v167
	v_mul_f32_e32 v166, v166, v165
	v_mul_f32_e32 v169, v169, v168
	v_mul_f32_e32 v166, v158, v166
	v_mul_f32_e32 v169, v159, v169
	v_sub_f32_e32 v165, v158, v166
	v_sub_f32_e32 v168, v159, v169
	v_cmp_gt_f32_e64 s[100:101], 0, v158
	s_nop 1
	v_cndmask_b32_e64 v158, v165, v166, s[100:101]
	v_cmp_gt_f32_e64 s[100:101], 0, v159
	s_nop 1
	v_cndmask_b32_e64 v159, v168, v169, s[100:101]
	v_mul_f32_e32 v130, 0x45800000, v129
	v_cndmask_b32_e32 v130, v129, v130, vcc
; __device__ __forceinline__ f32x2 gelu_pk(f32x2 v) {
;     const f32x2 av = __builtin_elementwise_abs(v), d = av * 0.2316418882f + 1.0f;
;     f32x2 t; t.x = __builtin_amdgcn_rcpf(d.x); t.y = __builtin_amdgcn_rcpf(d.y);
;     f32x2 q = t * 0.5307027145f + (-0.7265760135f); q = q * t + 0.7107068705f; q = q * t + (-0.142248368f); q = q * t + 0.127414796f; q = q * t;
;     const f32x2 s = (v * v) * (-0.72134752044f);
;     f32x2 e; e.x = __builtin_amdgcn_exp2f(s.x); e.y = __builtin_amdgcn_exp2f(s.y);
;     const f32x2 m = v * (q * e), r = v - m;
;     f32x2 o; o.x = v.x < 0.f ? m.x : r.x; o.y = v.y < 0.f ? m.y : r.y; return o;
; }
;     __device__ __forceinline__ void epi_proj(const f32x4 (&acc)[2][2][4][2], const pg8::Unit& u, int wr, int wc, int fr, int fq) const {
;     ...
; #pragma unroll
;                         for (int bj = 0; bj < 2; ++bj) {
;                             f32x4 v0 = acc[ai][bj][m][0] * rstd, v1 = acc[ai][bj][m][1] * rstd;
;                             if (slot < 2) {
;                                 f32x2 a = gelu_pk((f32x2){v0[0], v0[1]}), b = gelu_pk((f32x2){v0[2], v0[3]}), c = gelu_pk((f32x2){v1[0], v1[1]}), d = gelu_pk((f32x2){v1[2], v1[3]});
;                                 v0 = (f32x4){a.x, a.y, b.x, b.y}; v1 = (f32x4){c.x, c.y, d.x, d.y};
	v_cmp_gt_f32_e32 vcc, s0, v128
	s_lshr_b32 s0, s88, 2
	s_mul_i32 s0, s0, 0x4080000
	s_add_u32 s0, s0, 0x8d80000
	s_mov_b32 s1, 0
	v_lshl_add_u64 v[152:153], v[152:153], 0, s[0:1]
	v_lshl_add_u64 v[136:137], v[152:153], 0, v[136:137]
	global_store_dwordx4 v[136:137], v[154:157], off
	v_mul_f32_e32 v129, 0x4b800000, v128
	v_cndmask_b32_e32 v128, v128, v129, vcc
	v_pk_mul_f32 v[154:155], v[126:127], v[150:151] op_sel_hi:[1,0]
	v_pk_mul_f32 v[156:157], v[124:125], v[150:151] op_sel_hi:[1,0]
	v_pk_mul_f32 v[150:151], v[120:121], v[150:151] op_sel_hi:[1,0]
	v_and_b32_e32 v164, 0x7fffffff, v156
	v_and_b32_e32 v167, 0x7fffffff, v150
	v_and_b32_e32 v170, 0x7fffffff, v157
	v_and_b32_e32 v173, 0x7fffffff, v151
	v_and_b32_e32 v176, 0x7fffffff, v154
	v_and_b32_e32 v179, 0x7fffffff, v155
	v_mul_f32_e32 v165, v156, v156
	v_mul_f32_e32 v168, v150, v150
	v_mul_f32_e32 v171, v157, v157
	v_mul_f32_e32 v174, v151, v151
	v_mul_f32_e32 v177, v154, v154
	v_mul_f32_e32 v180, v155, v155
	v_fma_f32 v164, v164, s14, 1.0
	v_fma_f32 v167, v167, s14, 1.0
	v_fma_f32 v170, v170, s14, 1.0
	v_fma_f32 v173, v173, s14, 1.0
	v_fma_f32 v176, v176, s14, 1.0
	v_fma_f32 v179, v179, s14, 1.0
	v_mul_f32_e32 v165, s20, v165
	v_mul_f32_e32 v168, s20, v168
	v_mul_f32_e32 v171, s20, v171
	v_mul_f32_e32 v174, s20, v174
	v_mul_f32_e32 v177, s20, v177
	v_mul_f32_e32 v180, s20, v180
	v_rcp_f32_e32 v164, v164
	v_rcp_f32_e32 v167, v167
	v_rcp_f32_e32 v170, v170
	v_rcp_f32_e32 v173, v173
	v_rcp_f32_e32 v176, v176
	v_rcp_f32_e32 v179, v179
	s_nop 0
	v_exp_f32_e32 v165, v165
	v_exp_f32_e32 v168, v168
	v_exp_f32_e32 v171, v171
	v_exp_f32_e32 v174, v174
	v_exp_f32_e32 v177, v177
	v_exp_f32_e32 v180, v180
	s_nop 0
	v_fma_f32 v166, v164, s15, v188
	v_fma_f32 v169, v167, s15, v188
	v_fma_f32 v172, v170, s15, v188
	v_fma_f32 v175, v173, s15, v188
	v_fma_f32 v178, v176, s15, v188
	v_fma_f32 v181, v179, s15, v188
	v_fma_f32 v166, v166, v164, v189
	v_fma_f32 v169, v169, v167, v189
	v_fma_f32 v172, v172, v170, v189
	v_fma_f32 v175, v175, v173, v189
	v_fma_f32 v178, v178, v176, v189
	v_fma_f32 v181, v181, v179, v189
	v_fma_f32 v166, v166, v164, v190
	v_fma_f32 v169, v169, v167, v190
	v_fma_f32 v172, v172, v170, v190
	v_fma_f32 v175, v175, v173, v190
	v_fma_f32 v178, v178, v176, v190
	v_fma_f32 v181, v181, v179, v190
	v_fma_f32 v166, v166, v164, v191
	v_fma_f32 v169, v169, v167, v191
	v_fma_f32 v172, v172, v170, v191
	v_fma_f32 v175, v175, v173, v191
	v_fma_f32 v178, v178, v176, v191
	v_fma_f32 v181, v181, v179, v191
	v_mul_f32_e32 v166, v166, v164
	v_mul_f32_e32 v169, v169, v167
	v_mul_f32_e32 v172, v172, v170
	v_mul_f32_e32 v175, v175, v173
	v_mul_f32_e32 v178, v178, v176
	v_mul_f32_e32 v181, v181, v179
	v_mul_f32_e32 v166, v166, v165
	v_mul_f32_e32 v169, v169, v168
	v_mul_f32_e32 v172, v172, v171
	v_mul_f32_e32 v175, v175, v174
	v_mul_f32_e32 v178, v178, v177
	v_mul_f32_e32 v181, v181, v180
	v_mul_f32_e32 v166, v156, v166
	v_mul_f32_e32 v169, v150, v169
	v_mul_f32_e32 v172, v157, v172
	v_mul_f32_e32 v175, v151, v175
	v_mul_f32_e32 v178, v154, v178
	v_mul_f32_e32 v181, v155, v181
	v_sub_f32_e32 v165, v156, v166
	v_sub_f32_e32 v168, v150, v169
	v_sub_f32_e32 v171, v157, v172
	v_sub_f32_e32 v174, v151, v175
	v_sub_f32_e32 v177, v154, v178
	v_sub_f32_e32 v180, v155, v181
	v_cmp_gt_f32_e64 s[100:101], 0, v156
	s_nop 1
	v_cndmask_b32_e64 v156, v165, v166, s[100:101]
	v_cmp_gt_f32_e64 s[100:101], 0, v150
	s_nop 1
	v_cndmask_b32_e64 v150, v168, v169, s[100:101]
	v_cmp_gt_f32_e64 s[100:101], 0, v157
	s_nop 1
	v_cndmask_b32_e64 v157, v171, v172, s[100:101]
	v_cmp_gt_f32_e64 s[100:101], 0, v151
	s_nop 1
	v_cndmask_b32_e64 v151, v174, v175, s[100:101]
	v_cmp_gt_f32_e64 s[100:101], 0, v154
	s_nop 1
	v_cndmask_b32_e64 v154, v177, v178, s[100:101]
	v_cmp_gt_f32_e64 s[100:101], 0, v155
	s_nop 1
	v_cndmask_b32_e64 v155, v180, v181, s[100:101]
	v_mov_b32_e32 v160, v154
	v_mov_b32_e32 v161, v155
	v_cvt_pk_bf16_f32 v154, v156, v157
	v_cvt_pk_bf16_f32 v155, v160, v161
	v_cvt_pk_bf16_f32 v156, v150, v151
	v_cvt_pk_bf16_f32 v157, v158, v159
	global_store_dwordx4 v[136:137], v[154:157], off offset:256
	v_lshl_add_u64 v[150:151], v[152:153], 0, v[146:147]
	v_pk_mul_f32 v[146:147], v[102:103], v[148:149] op_sel_hi:[1,0]
	v_pk_mul_f32 v[154:155], v[100:101], v[148:149] op_sel_hi:[1,0]
	v_pk_mul_f32 v[156:157], v[98:99], v[148:149] op_sel_hi:[1,0]
	v_pk_mul_f32 v[158:159], v[96:97], v[148:149] op_sel_hi:[1,0]
	v_and_b32_e32 v164, 0x7fffffff, v154
	v_and_b32_e32 v167, 0x7fffffff, v158
	v_and_b32_e32 v170, 0x7fffffff, v155
	v_and_b32_e32 v173, 0x7fffffff, v159
	v_and_b32_e32 v176, 0x7fffffff, v146
	v_and_b32_e32 v179, 0x7fffffff, v156
	v_and_b32_e32 v182, 0x7fffffff, v147
	v_and_b32_e32 v185, 0x7fffffff, v157
	v_mul_f32_e32 v165, v154, v154
	v_mul_f32_e32 v168, v158, v158
	v_mul_f32_e32 v171, v155, v155
	v_mul_f32_e32 v174, v159, v159
	v_mul_f32_e32 v177, v146, v146
	v_mul_f32_e32 v180, v156, v156
	v_mul_f32_e32 v183, v147, v147
	v_mul_f32_e32 v186, v157, v157
	v_fma_f32 v164, v164, s14, 1.0
	v_fma_f32 v167, v167, s14, 1.0
	v_fma_f32 v170, v170, s14, 1.0
	v_fma_f32 v173, v173, s14, 1.0
	v_fma_f32 v176, v176, s14, 1.0
	v_fma_f32 v179, v179, s14, 1.0
	v_fma_f32 v182, v182, s14, 1.0
	v_fma_f32 v185, v185, s14, 1.0
	v_mul_f32_e32 v165, s20, v165
	v_mul_f32_e32 v168, s20, v168
	v_mul_f32_e32 v171, s20, v171
	v_mul_f32_e32 v174, s20, v174
	v_mul_f32_e32 v177, s20, v177
	v_mul_f32_e32 v180, s20, v180
	v_mul_f32_e32 v183, s20, v183
	v_mul_f32_e32 v186, s20, v186
	v_rcp_f32_e32 v164, v164
	v_rcp_f32_e32 v167, v167
	v_rcp_f32_e32 v170, v170
	v_rcp_f32_e32 v173, v173
	v_rcp_f32_e32 v176, v176
	v_rcp_f32_e32 v179, v179
	v_rcp_f32_e32 v182, v182
; __device__ __forceinline__ f32x2 gelu_pk(f32x2 v) {
;     const f32x2 av = __builtin_elementwise_abs(v), d = av * 0.2316418882f + 1.0f;
;     f32x2 t; t.x = __builtin_amdgcn_rcpf(d.x); t.y = __builtin_amdgcn_rcpf(d.y);
;     f32x2 q = t * 0.5307027145f + (-0.7265760135f); q = q * t + 0.7107068705f; q = q * t + (-0.142248368f); q = q * t + 0.127414796f; q = q * t;
;     const f32x2 s = (v * v) * (-0.72134752044f);
;     f32x2 e; e.x = __builtin_amdgcn_exp2f(s.x); e.y = __builtin_amdgcn_exp2f(s.y);
;     const f32x2 m = v * (q * e), r = v - m;
;     f32x2 o; o.x = v.x < 0.f ? m.x : r.x; o.y = v.y < 0.f ? m.y : r.y; return o;
; }
;     __device__ __forceinline__ void epi_proj(const f32x4 (&acc)[2][2][4][2], const pg8::Unit& u, int wr, int wc, int fr, int fq) const {
;     ...
; #pragma unroll
;                         for (int bj = 0; bj < 2; ++bj) {
;                             f32x4 v0 = acc[ai][bj][m][0] * rstd, v1 = acc[ai][bj][m][1] * rstd;
;                             if (slot < 2) {
;                                 f32x2 a = gelu_pk((f32x2){v0[0], v0[1]}), b = gelu_pk((f32x2){v0[2], v0[3]}), c = gelu_pk((f32x2){v1[0], v1[1]}), d = gelu_pk((f32x2){v1[2], v1[3]});
;                                 v0 = (f32x4){a.x, a.y, b.x, b.y}; v1 = (f32x4){c.x, c.y, d.x, d.y};
	v_rcp_f32_e32 v185, v185
	s_nop 0
	v_exp_f32_e32 v165, v165
	v_exp_f32_e32 v168, v168
	v_exp_f32_e32 v171, v171
	v_exp_f32_e32 v174, v174
	v_exp_f32_e32 v177, v177
	v_exp_f32_e32 v180, v180
	v_exp_f32_e32 v183, v183
	v_exp_f32_e32 v186, v186
	s_nop 0
	v_fma_f32 v166, v164, s15, v188
	v_fma_f32 v169, v167, s15, v188
	v_fma_f32 v172, v170, s15, v188
	v_fma_f32 v175, v173, s15, v188
	v_fma_f32 v178, v176, s15, v188
	v_fma_f32 v181, v179, s15, v188
	v_fma_f32 v184, v182, s15, v188
	v_fma_f32 v187, v185, s15, v188
	v_fma_f32 v166, v166, v164, v189
	v_fma_f32 v169, v169, v167, v189
	v_fma_f32 v172, v172, v170, v189
	v_fma_f32 v175, v175, v173, v189
	v_fma_f32 v178, v178, v176, v189
	v_fma_f32 v181, v181, v179, v189
	v_fma_f32 v184, v184, v182, v189
	v_fma_f32 v187, v187, v185, v189
	v_fma_f32 v166, v166, v164, v190
	v_fma_f32 v169, v169, v167, v190
	v_fma_f32 v172, v172, v170, v190
	v_fma_f32 v175, v175, v173, v190
	v_fma_f32 v178, v178, v176, v190
	v_fma_f32 v181, v181, v179, v190
	v_fma_f32 v184, v184, v182, v190
	v_fma_f32 v187, v187, v185, v190
	v_fma_f32 v166, v166, v164, v191
	v_fma_f32 v169, v169, v167, v191
	v_fma_f32 v172, v172, v170, v191
	v_fma_f32 v175, v175, v173, v191
	v_fma_f32 v178, v178, v176, v191
	v_fma_f32 v181, v181, v179, v191
	v_fma_f32 v184, v184, v182, v191
	v_fma_f32 v187, v187, v185, v191
	v_mul_f32_e32 v166, v166, v164
	v_mul_f32_e32 v169, v169, v167
	v_mul_f32_e32 v172, v172, v170
	v_mul_f32_e32 v175, v175, v173
	v_mul_f32_e32 v178, v178, v176
	v_mul_f32_e32 v181, v181, v179
	v_mul_f32_e32 v184, v184, v182
	v_mul_f32_e32 v187, v187, v185
	v_mul_f32_e32 v166, v166, v165
	v_mul_f32_e32 v169, v169, v168
	v_mul_f32_e32 v172, v172, v171
	v_mul_f32_e32 v175, v175, v174
	v_mul_f32_e32 v178, v178, v177
	v_mul_f32_e32 v181, v181, v180
	v_mul_f32_e32 v184, v184, v183
	v_mul_f32_e32 v187, v187, v186
	v_mul_f32_e32 v166, v154, v166
	v_mul_f32_e32 v169, v158, v169
	v_mul_f32_e32 v172, v155, v172
	v_mul_f32_e32 v175, v159, v175
	v_mul_f32_e32 v178, v146, v178
	v_mul_f32_e32 v181, v156, v181
	v_mul_f32_e32 v184, v147, v184
	v_mul_f32_e32 v187, v157, v187
	v_sub_f32_e32 v165, v154, v166
	v_sub_f32_e32 v168, v158, v169
	v_sub_f32_e32 v171, v155, v172
	v_sub_f32_e32 v174, v159, v175
	v_sub_f32_e32 v177, v146, v178
	v_sub_f32_e32 v180, v156, v181
	v_sub_f32_e32 v183, v147, v184
	v_sub_f32_e32 v186, v157, v187
	v_cmp_gt_f32_e64 s[100:101], 0, v154
	s_nop 1
	v_cndmask_b32_e64 v154, v165, v166, s[100:101]
	v_cmp_gt_f32_e64 s[100:101], 0, v158
	s_nop 1
	v_cndmask_b32_e64 v158, v168, v169, s[100:101]
	v_cmp_gt_f32_e64 s[100:101], 0, v155
	s_nop 1
	v_cndmask_b32_e64 v155, v171, v172, s[100:101]
	v_cmp_gt_f32_e64 s[100:101], 0, v159
	s_nop 1
	v_cndmask_b32_e64 v159, v174, v175, s[100:101]
	v_cmp_gt_f32_e64 s[100:101], 0, v146
	s_nop 1
	v_cndmask_b32_e64 v146, v177, v178, s[100:101]
	v_cmp_gt_f32_e64 s[100:101], 0, v156
	s_nop 1
	v_cndmask_b32_e64 v156, v180, v181, s[100:101]
	v_cmp_gt_f32_e64 s[100:101], 0, v147
	s_nop 1
	v_cndmask_b32_e64 v147, v183, v184, s[100:101]
	v_cmp_gt_f32_e64 s[100:101], 0, v157
	s_nop 1
	v_cndmask_b32_e64 v157, v186, v187, s[100:101]
	v_mov_b32_e32 v160, v156
	v_mov_b32_e32 v161, v157
	v_cvt_pk_bf16_f32 v154, v154, v155
	v_cvt_pk_bf16_f32 v155, v146, v147
	v_cvt_pk_bf16_f32 v156, v158, v159
	v_cvt_pk_bf16_f32 v157, v160, v161
	global_store_dwordx4 v[150:151], v[154:157], off
	v_pk_mul_f32 v[146:147], v[110:111], v[148:149] op_sel_hi:[1,0]
	v_rsq_f32_e32 v128, v128
	v_pk_mul_f32 v[154:155], v[108:109], v[148:149] op_sel_hi:[1,0]
	v_pk_mul_f32 v[156:157], v[106:107], v[148:149] op_sel_hi:[1,0]
	v_pk_mul_f32 v[148:149], v[104:105], v[148:149] op_sel_hi:[1,0]
	v_and_b32_e32 v164, 0x7fffffff, v154
	v_and_b32_e32 v167, 0x7fffffff, v148
	v_and_b32_e32 v170, 0x7fffffff, v155
	v_and_b32_e32 v173, 0x7fffffff, v149
	v_and_b32_e32 v176, 0x7fffffff, v146
	v_and_b32_e32 v179, 0x7fffffff, v156
	v_and_b32_e32 v182, 0x7fffffff, v147
	v_and_b32_e32 v185, 0x7fffffff, v157
	v_mul_f32_e32 v165, v154, v154
	v_mul_f32_e32 v168, v148, v148
	v_mul_f32_e32 v171, v155, v155
	v_mul_f32_e32 v174, v149, v149
	v_mul_f32_e32 v177, v146, v146
	v_mul_f32_e32 v180, v156, v156
	v_mul_f32_e32 v183, v147, v147
	v_mul_f32_e32 v186, v157, v157
	v_fma_f32 v164, v164, s14, 1.0
	v_fma_f32 v167, v167, s14, 1.0
	v_fma_f32 v170, v170, s14, 1.0
	v_fma_f32 v173, v173, s14, 1.0
	v_fma_f32 v176, v176, s14, 1.0
	v_fma_f32 v179, v179, s14, 1.0
	v_fma_f32 v182, v182, s14, 1.0
	v_fma_f32 v185, v185, s14, 1.0
	v_mul_f32_e32 v165, s20, v165
	v_mul_f32_e32 v168, s20, v168
	v_mul_f32_e32 v171, s20, v171
	v_mul_f32_e32 v174, s20, v174
	v_mul_f32_e32 v177, s20, v177
	v_mul_f32_e32 v180, s20, v180
	v_mul_f32_e32 v183, s20, v183
	v_mul_f32_e32 v186, s20, v186
	v_rcp_f32_e32 v164, v164
	v_rcp_f32_e32 v167, v167
	v_rcp_f32_e32 v170, v170
	v_rcp_f32_e32 v173, v173
	v_rcp_f32_e32 v176, v176
	v_rcp_f32_e32 v179, v179
	v_rcp_f32_e32 v182, v182
	v_rcp_f32_e32 v185, v185
	s_nop 0
	v_exp_f32_e32 v165, v165
	v_exp_f32_e32 v168, v168
	v_exp_f32_e32 v171, v171
	v_exp_f32_e32 v174, v174
	v_exp_f32_e32 v177, v177
	v_exp_f32_e32 v180, v180
	v_exp_f32_e32 v183, v183
	v_exp_f32_e32 v186, v186
	s_nop 0
	v_fma_f32 v166, v164, s15, v188
	v_fma_f32 v169, v167, s15, v188
	v_fma_f32 v172, v170, s15, v188
	v_fma_f32 v175, v173, s15, v188
	v_fma_f32 v178, v176, s15, v188
	v_fma_f32 v181, v179, s15, v188
	v_fma_f32 v184, v182, s15, v188
	v_fma_f32 v187, v185, s15, v188
	v_fma_f32 v166, v166, v164, v189
	v_fma_f32 v169, v169, v167, v189
	v_fma_f32 v172, v172, v170, v189
	v_fma_f32 v175, v175, v173, v189
	v_fma_f32 v178, v178, v176, v189
	v_fma_f32 v181, v181, v179, v189
	v_fma_f32 v184, v184, v182, v189
; __device__ __forceinline__ f32x2 gelu_pk(f32x2 v) {
;     const f32x2 av = __builtin_elementwise_abs(v), d = av * 0.2316418882f + 1.0f;
;     f32x2 t; t.x = __builtin_amdgcn_rcpf(d.x); t.y = __builtin_amdgcn_rcpf(d.y);
;     f32x2 q = t * 0.5307027145f + (-0.7265760135f); q = q * t + 0.7107068705f; q = q * t + (-0.142248368f); q = q * t + 0.127414796f; q = q * t;
;     const f32x2 s = (v * v) * (-0.72134752044f);
;     f32x2 e; e.x = __builtin_amdgcn_exp2f(s.x); e.y = __builtin_amdgcn_exp2f(s.y);
;     const f32x2 m = v * (q * e), r = v - m;
;     f32x2 o; o.x = v.x < 0.f ? m.x : r.x; o.y = v.y < 0.f ? m.y : r.y; return o;
; }
;     __device__ __forceinline__ void epi_proj(const f32x4 (&acc)[2][2][4][2], const pg8::Unit& u, int wr, int wc, int fr, int fq) const {
;     ...
; #pragma unroll
;                         for (int bj = 0; bj < 2; ++bj) {
;                             f32x4 v0 = acc[ai][bj][m][0] * rstd, v1 = acc[ai][bj][m][1] * rstd;
;                             if (slot < 2) {
;                                 f32x2 a = gelu_pk((f32x2){v0[0], v0[1]}), b = gelu_pk((f32x2){v0[2], v0[3]}), c = gelu_pk((f32x2){v1[0], v1[1]}), d = gelu_pk((f32x2){v1[2], v1[3]});
;                                 v0 = (f32x4){a.x, a.y, b.x, b.y}; v1 = (f32x4){c.x, c.y, d.x, d.y};
	v_fma_f32 v187, v187, v185, v189
	v_fma_f32 v166, v166, v164, v190
	v_fma_f32 v169, v169, v167, v190
	v_fma_f32 v172, v172, v170, v190
	v_fma_f32 v175, v175, v173, v190
	v_fma_f32 v178, v178, v176, v190
	v_fma_f32 v181, v181, v179, v190
	v_fma_f32 v184, v184, v182, v190
	v_fma_f32 v187, v187, v185, v190
	v_fma_f32 v166, v166, v164, v191
	v_fma_f32 v169, v169, v167, v191
	v_fma_f32 v172, v172, v170, v191
	v_fma_f32 v175, v175, v173, v191
	v_fma_f32 v178, v178, v176, v191
	v_fma_f32 v181, v181, v179, v191
	v_fma_f32 v184, v184, v182, v191
	v_fma_f32 v187, v187, v185, v191
	v_mul_f32_e32 v166, v166, v164
	v_mul_f32_e32 v169, v169, v167
	v_mul_f32_e32 v172, v172, v170
	v_mul_f32_e32 v175, v175, v173
	v_mul_f32_e32 v178, v178, v176
	v_mul_f32_e32 v181, v181, v179
	v_mul_f32_e32 v184, v184, v182
	v_mul_f32_e32 v187, v187, v185
	v_mul_f32_e32 v166, v166, v165
	v_mul_f32_e32 v169, v169, v168
	v_mul_f32_e32 v172, v172, v171
	v_mul_f32_e32 v175, v175, v174
	v_mul_f32_e32 v178, v178, v177
	v_mul_f32_e32 v181, v181, v180
	v_mul_f32_e32 v184, v184, v183
	v_mul_f32_e32 v187, v187, v186
	v_mul_f32_e32 v166, v154, v166
	v_mul_f32_e32 v169, v148, v169
	v_mul_f32_e32 v172, v155, v172
	v_mul_f32_e32 v175, v149, v175
	v_mul_f32_e32 v178, v146, v178
	v_mul_f32_e32 v181, v156, v181
	v_mul_f32_e32 v184, v147, v184
	v_mul_f32_e32 v187, v157, v187
	v_sub_f32_e32 v165, v154, v166
	v_sub_f32_e32 v168, v148, v169
	v_sub_f32_e32 v171, v155, v172
	v_sub_f32_e32 v174, v149, v175
	v_sub_f32_e32 v177, v146, v178
	v_sub_f32_e32 v180, v156, v181
	v_sub_f32_e32 v183, v147, v184
	v_sub_f32_e32 v186, v157, v187
	v_cmp_gt_f32_e64 s[100:101], 0, v154
	s_nop 1
	v_cndmask_b32_e64 v154, v165, v166, s[100:101]
	v_cmp_gt_f32_e64 s[100:101], 0, v148
	s_nop 1
	v_cndmask_b32_e64 v148, v168, v169, s[100:101]
	v_cmp_gt_f32_e64 s[100:101], 0, v155
	s_nop 1
	v_cndmask_b32_e64 v155, v171, v172, s[100:101]
	v_cmp_gt_f32_e64 s[100:101], 0, v149
	s_nop 1
	v_cndmask_b32_e64 v149, v174, v175, s[100:101]
	v_cmp_gt_f32_e64 s[100:101], 0, v146
	s_nop 1
	v_cndmask_b32_e64 v146, v177, v178, s[100:101]
	v_cmp_gt_f32_e64 s[100:101], 0, v156
	s_nop 1
	v_cndmask_b32_e64 v156, v180, v181, s[100:101]
	v_cmp_gt_f32_e64 s[100:101], 0, v147
	s_nop 1
	v_cndmask_b32_e64 v147, v183, v184, s[100:101]
	v_cmp_gt_f32_e64 s[100:101], 0, v157
	s_nop 1
	v_cndmask_b32_e64 v157, v186, v187, s[100:101]
	v_mov_b32_e32 v158, v146
	v_mov_b32_e32 v159, v147
	v_cvt_pk_bf16_f32 v146, v154, v155
	v_cvt_pk_bf16_f32 v147, v158, v159
	v_cvt_pk_bf16_f32 v148, v148, v149
	v_cvt_pk_bf16_f32 v149, v156, v157
	global_store_dwordx4 v[150:151], v[146:149], off offset:256
	v_lshl_add_u64 v[150:151], v[152:153], 0, v[142:143]
	v_pk_mul_f32 v[142:143], v[86:87], v[144:145] op_sel_hi:[1,0]
	v_pk_mul_f32 v[146:147], v[84:85], v[144:145] op_sel_hi:[1,0]
	v_pk_mul_f32 v[148:149], v[82:83], v[144:145] op_sel_hi:[1,0]
	v_pk_mul_f32 v[154:155], v[80:81], v[144:145] op_sel_hi:[1,0]
	v_and_b32_e32 v164, 0x7fffffff, v146
	v_and_b32_e32 v167, 0x7fffffff, v154
	v_and_b32_e32 v170, 0x7fffffff, v147
	v_and_b32_e32 v173, 0x7fffffff, v155
	v_and_b32_e32 v176, 0x7fffffff, v142
	v_and_b32_e32 v179, 0x7fffffff, v148
	v_and_b32_e32 v182, 0x7fffffff, v143
	v_and_b32_e32 v185, 0x7fffffff, v149
	v_mul_f32_e32 v165, v146, v146
	v_mul_f32_e32 v168, v154, v154
	v_mul_f32_e32 v171, v147, v147
	v_mul_f32_e32 v174, v155, v155
	v_mul_f32_e32 v177, v142, v142
	v_mul_f32_e32 v180, v148, v148
	v_mul_f32_e32 v183, v143, v143
	v_mul_f32_e32 v186, v149, v149
	v_fma_f32 v164, v164, s14, 1.0
	v_fma_f32 v167, v167, s14, 1.0
	v_fma_f32 v170, v170, s14, 1.0
	v_fma_f32 v173, v173, s14, 1.0
	v_fma_f32 v176, v176, s14, 1.0
	v_fma_f32 v179, v179, s14, 1.0
	v_fma_f32 v182, v182, s14, 1.0
	v_fma_f32 v185, v185, s14, 1.0
	v_mul_f32_e32 v165, s20, v165
	v_mul_f32_e32 v168, s20, v168
	v_mul_f32_e32 v171, s20, v171
	v_mul_f32_e32 v174, s20, v174
	v_mul_f32_e32 v177, s20, v177
	v_mul_f32_e32 v180, s20, v180
	v_mul_f32_e32 v183, s20, v183
	v_mul_f32_e32 v186, s20, v186
	v_rcp_f32_e32 v164, v164
	v_rcp_f32_e32 v167, v167
	v_rcp_f32_e32 v170, v170
	v_rcp_f32_e32 v173, v173
	v_rcp_f32_e32 v176, v176
	v_rcp_f32_e32 v179, v179
	v_rcp_f32_e32 v182, v182
	v_rcp_f32_e32 v185, v185
	s_nop 0
	v_exp_f32_e32 v165, v165
	v_exp_f32_e32 v168, v168
	v_exp_f32_e32 v171, v171
	v_exp_f32_e32 v174, v174
	v_exp_f32_e32 v177, v177
	v_exp_f32_e32 v180, v180
	v_exp_f32_e32 v183, v183
	v_exp_f32_e32 v186, v186
	s_nop 0
	v_fma_f32 v166, v164, s15, v188
	v_fma_f32 v169, v167, s15, v188
	v_fma_f32 v172, v170, s15, v188
	v_fma_f32 v175, v173, s15, v188
	v_fma_f32 v178, v176, s15, v188
	v_fma_f32 v181, v179, s15, v188
	v_fma_f32 v184, v182, s15, v188
	v_fma_f32 v187, v185, s15, v188
	v_fma_f32 v166, v166, v164, v189
	v_fma_f32 v169, v169, v167, v189
	v_fma_f32 v172, v172, v170, v189
	v_fma_f32 v175, v175, v173, v189
	v_fma_f32 v178, v178, v176, v189
	v_fma_f32 v181, v181, v179, v189
	v_fma_f32 v184, v184, v182, v189
	v_fma_f32 v187, v187, v185, v189
	v_fma_f32 v166, v166, v164, v190
	v_fma_f32 v169, v169, v167, v190
	v_fma_f32 v172, v172, v170, v190
	v_fma_f32 v175, v175, v173, v190
	v_fma_f32 v178, v178, v176, v190
	v_fma_f32 v181, v181, v179, v190
	v_fma_f32 v184, v184, v182, v190
	v_fma_f32 v187, v187, v185, v190
	v_fma_f32 v166, v166, v164, v191
	v_fma_f32 v169, v169, v167, v191
	v_fma_f32 v172, v172, v170, v191
	v_fma_f32 v175, v175, v173, v191
	v_fma_f32 v178, v178, v176, v191
	v_fma_f32 v181, v181, v179, v191
	v_fma_f32 v184, v184, v182, v191
	v_fma_f32 v187, v187, v185, v191
	v_mul_f32_e32 v166, v166, v164
	v_mul_f32_e32 v169, v169, v167
	v_mul_f32_e32 v172, v172, v170
	v_mul_f32_e32 v175, v175, v173
; __device__ __forceinline__ f32x2 gelu_pk(f32x2 v) {
;     const f32x2 av = __builtin_elementwise_abs(v), d = av * 0.2316418882f + 1.0f;
;     f32x2 t; t.x = __builtin_amdgcn_rcpf(d.x); t.y = __builtin_amdgcn_rcpf(d.y);
;     f32x2 q = t * 0.5307027145f + (-0.7265760135f); q = q * t + 0.7107068705f; q = q * t + (-0.142248368f); q = q * t + 0.127414796f; q = q * t;
;     const f32x2 s = (v * v) * (-0.72134752044f);
;     f32x2 e; e.x = __builtin_amdgcn_exp2f(s.x); e.y = __builtin_amdgcn_exp2f(s.y);
;     const f32x2 m = v * (q * e), r = v - m;
;     f32x2 o; o.x = v.x < 0.f ? m.x : r.x; o.y = v.y < 0.f ? m.y : r.y; return o;
; }
;     __device__ __forceinline__ void epi_proj(const f32x4 (&acc)[2][2][4][2], const pg8::Unit& u, int wr, int wc, int fr, int fq) const {
;     ...
; #pragma unroll
;                         for (int bj = 0; bj < 2; ++bj) {
;                             f32x4 v0 = acc[ai][bj][m][0] * rstd, v1 = acc[ai][bj][m][1] * rstd;
;                             if (slot < 2) {
;                                 f32x2 a = gelu_pk((f32x2){v0[0], v0[1]}), b = gelu_pk((f32x2){v0[2], v0[3]}), c = gelu_pk((f32x2){v1[0], v1[1]}), d = gelu_pk((f32x2){v1[2], v1[3]});
;                                 v0 = (f32x4){a.x, a.y, b.x, b.y}; v1 = (f32x4){c.x, c.y, d.x, d.y};
	v_mul_f32_e32 v178, v178, v176
	v_mul_f32_e32 v181, v181, v179
	v_mul_f32_e32 v184, v184, v182
	v_mul_f32_e32 v187, v187, v185
	v_mul_f32_e32 v166, v166, v165
	v_mul_f32_e32 v169, v169, v168
	v_mul_f32_e32 v172, v172, v171
	v_mul_f32_e32 v175, v175, v174
	v_mul_f32_e32 v178, v178, v177
	v_mul_f32_e32 v181, v181, v180
	v_mul_f32_e32 v184, v184, v183
	v_mul_f32_e32 v187, v187, v186
	v_mul_f32_e32 v166, v146, v166
	v_mul_f32_e32 v169, v154, v169
	v_mul_f32_e32 v172, v147, v172
	v_mul_f32_e32 v175, v155, v175
	v_mul_f32_e32 v178, v142, v178
	v_mul_f32_e32 v181, v148, v181
	v_mul_f32_e32 v184, v143, v184
	v_mul_f32_e32 v187, v149, v187
	v_sub_f32_e32 v165, v146, v166
	v_sub_f32_e32 v168, v154, v169
	v_sub_f32_e32 v171, v147, v172
	v_sub_f32_e32 v174, v155, v175
	v_sub_f32_e32 v177, v142, v178
	v_sub_f32_e32 v180, v148, v181
	v_sub_f32_e32 v183, v143, v184
	v_sub_f32_e32 v186, v149, v187
	v_cmp_gt_f32_e64 s[100:101], 0, v146
	s_nop 1
	v_cndmask_b32_e64 v146, v165, v166, s[100:101]
	v_cmp_gt_f32_e64 s[100:101], 0, v154
	s_nop 1
	v_cndmask_b32_e64 v154, v168, v169, s[100:101]
	v_cmp_gt_f32_e64 s[100:101], 0, v147
	s_nop 1
	v_cndmask_b32_e64 v147, v171, v172, s[100:101]
	v_cmp_gt_f32_e64 s[100:101], 0, v155
	s_nop 1
	v_cndmask_b32_e64 v155, v174, v175, s[100:101]
	v_cmp_gt_f32_e64 s[100:101], 0, v142
	s_nop 1
	v_cndmask_b32_e64 v142, v177, v178, s[100:101]
	v_cmp_gt_f32_e64 s[100:101], 0, v148
	s_nop 1
	v_cndmask_b32_e64 v148, v180, v181, s[100:101]
	v_cmp_gt_f32_e64 s[100:101], 0, v143
	s_nop 1
	v_cndmask_b32_e64 v143, v183, v184, s[100:101]
	v_cmp_gt_f32_e64 s[100:101], 0, v149
	s_nop 1
	v_cndmask_b32_e64 v149, v186, v187, s[100:101]
	v_mov_b32_e32 v156, v148
	v_mov_b32_e32 v157, v149
	v_cvt_pk_bf16_f32 v146, v146, v147
	v_cvt_pk_bf16_f32 v147, v142, v143
	v_cvt_pk_bf16_f32 v148, v154, v155
	v_cvt_pk_bf16_f32 v149, v156, v157
	global_store_dwordx4 v[150:151], v[146:149], off
	v_pk_mul_f32 v[142:143], v[94:95], v[144:145] op_sel_hi:[1,0]
	s_mov_b64 s[0:1], 0x40000
	v_pk_mul_f32 v[146:147], v[92:93], v[144:145] op_sel_hi:[1,0]
	v_pk_mul_f32 v[148:149], v[90:91], v[144:145] op_sel_hi:[1,0]
	v_pk_mul_f32 v[144:145], v[88:89], v[144:145] op_sel_hi:[1,0]
	v_and_b32_e32 v164, 0x7fffffff, v146
	v_and_b32_e32 v167, 0x7fffffff, v144
	v_and_b32_e32 v170, 0x7fffffff, v147
	v_and_b32_e32 v173, 0x7fffffff, v145
	v_and_b32_e32 v176, 0x7fffffff, v142
	v_and_b32_e32 v179, 0x7fffffff, v148
	v_and_b32_e32 v182, 0x7fffffff, v143
	v_and_b32_e32 v185, 0x7fffffff, v149
	v_mul_f32_e32 v165, v146, v146
	v_mul_f32_e32 v168, v144, v144
	v_mul_f32_e32 v171, v147, v147
	v_mul_f32_e32 v174, v145, v145
	v_mul_f32_e32 v177, v142, v142
	v_mul_f32_e32 v180, v148, v148
	v_mul_f32_e32 v183, v143, v143
	v_mul_f32_e32 v186, v149, v149
	v_fma_f32 v164, v164, s14, 1.0
	v_fma_f32 v167, v167, s14, 1.0
	v_fma_f32 v170, v170, s14, 1.0
	v_fma_f32 v173, v173, s14, 1.0
	v_fma_f32 v176, v176, s14, 1.0
	v_fma_f32 v179, v179, s14, 1.0
	v_fma_f32 v182, v182, s14, 1.0
	v_fma_f32 v185, v185, s14, 1.0
	v_mul_f32_e32 v165, s20, v165
	v_mul_f32_e32 v168, s20, v168
	v_mul_f32_e32 v171, s20, v171
	v_mul_f32_e32 v174, s20, v174
	v_mul_f32_e32 v177, s20, v177
	v_mul_f32_e32 v180, s20, v180
	v_mul_f32_e32 v183, s20, v183
	v_mul_f32_e32 v186, s20, v186
	v_rcp_f32_e32 v164, v164
	v_rcp_f32_e32 v167, v167
	v_rcp_f32_e32 v170, v170
	v_rcp_f32_e32 v173, v173
	v_rcp_f32_e32 v176, v176
	v_rcp_f32_e32 v179, v179
	v_rcp_f32_e32 v182, v182
	v_rcp_f32_e32 v185, v185
	s_nop 0
	v_exp_f32_e32 v165, v165
	v_exp_f32_e32 v168, v168
	v_exp_f32_e32 v171, v171
	v_exp_f32_e32 v174, v174
	v_exp_f32_e32 v177, v177
	v_exp_f32_e32 v180, v180
	v_exp_f32_e32 v183, v183
	v_exp_f32_e32 v186, v186
	s_nop 0
	v_fma_f32 v166, v164, s15, v188
	v_fma_f32 v169, v167, s15, v188
	v_fma_f32 v172, v170, s15, v188
	v_fma_f32 v175, v173, s15, v188
	v_fma_f32 v178, v176, s15, v188
	v_fma_f32 v181, v179, s15, v188
	v_fma_f32 v184, v182, s15, v188
	v_fma_f32 v187, v185, s15, v188
	v_fma_f32 v166, v166, v164, v189
	v_fma_f32 v169, v169, v167, v189
	v_fma_f32 v172, v172, v170, v189
	v_fma_f32 v175, v175, v173, v189
	v_fma_f32 v178, v178, v176, v189
	v_fma_f32 v181, v181, v179, v189
	v_fma_f32 v184, v184, v182, v189
	v_fma_f32 v187, v187, v185, v189
	v_fma_f32 v166, v166, v164, v190
	v_fma_f32 v169, v169, v167, v190
	v_fma_f32 v172, v172, v170, v190
	v_fma_f32 v175, v175, v173, v190
	v_fma_f32 v178, v178, v176, v190
	v_fma_f32 v181, v181, v179, v190
	v_fma_f32 v184, v184, v182, v190
	v_fma_f32 v187, v187, v185, v190
	v_fma_f32 v166, v166, v164, v191
	v_fma_f32 v169, v169, v167, v191
	v_fma_f32 v172, v172, v170, v191
	v_fma_f32 v175, v175, v173, v191
	v_fma_f32 v178, v178, v176, v191
	v_fma_f32 v181, v181, v179, v191
	v_fma_f32 v184, v184, v182, v191
	v_fma_f32 v187, v187, v185, v191
	v_mul_f32_e32 v166, v166, v164
	v_mul_f32_e32 v169, v169, v167
	v_mul_f32_e32 v172, v172, v170
	v_mul_f32_e32 v175, v175, v173
	v_mul_f32_e32 v178, v178, v176
	v_mul_f32_e32 v181, v181, v179
	v_mul_f32_e32 v184, v184, v182
	v_mul_f32_e32 v187, v187, v185
	v_mul_f32_e32 v166, v166, v165
	v_mul_f32_e32 v169, v169, v168
	v_mul_f32_e32 v172, v172, v171
	v_mul_f32_e32 v175, v175, v174
	v_mul_f32_e32 v178, v178, v177
	v_mul_f32_e32 v181, v181, v180
	v_mul_f32_e32 v184, v184, v183
	v_mul_f32_e32 v187, v187, v186
	v_mul_f32_e32 v166, v146, v166
	v_mul_f32_e32 v169, v144, v169
	v_mul_f32_e32 v172, v147, v172
	v_mul_f32_e32 v175, v145, v175
	v_mul_f32_e32 v178, v142, v178
	v_mul_f32_e32 v181, v148, v181
	v_mul_f32_e32 v184, v143, v184
	v_mul_f32_e32 v187, v149, v187
	v_sub_f32_e32 v165, v146, v166
	v_sub_f32_e32 v168, v144, v169
	v_sub_f32_e32 v171, v147, v172
	v_sub_f32_e32 v174, v145, v175
; __device__ __forceinline__ unsigned cvt_pk_bf16(float lo, float hi) { const f32x2 v = {lo, hi}; const bf16v2_t b = __builtin_convertvector(v, bf16v2_t); return __builtin_bit_cast(unsigned, b); }
; __device__ __forceinline__ float sigmoidf_(float x) { return __builtin_amdgcn_rcpf(1.0f + __builtin_amdgcn_exp2f(x * -1.44269504089f)); }
; __device__ __forceinline__ float siluf_(float x) { return x * __builtin_amdgcn_rcpf(1.0f + __builtin_amdgcn_exp2f(x * -1.44269504089f)); }
; __device__ __forceinline__ f32x2 gelu_pk(f32x2 v) {
;     const f32x2 av = __builtin_elementwise_abs(v), d = av * 0.2316418882f + 1.0f;
;     f32x2 t; t.x = __builtin_amdgcn_rcpf(d.x); t.y = __builtin_amdgcn_rcpf(d.y);
;     f32x2 q = t * 0.5307027145f + (-0.7265760135f); q = q * t + 0.7107068705f; q = q * t + (-0.142248368f); q = q * t + 0.127414796f; q = q * t;
;     const f32x2 s = (v * v) * (-0.72134752044f);
;     f32x2 e; e.x = __builtin_amdgcn_exp2f(s.x); e.y = __builtin_amdgcn_exp2f(s.y);
;     const f32x2 m = v * (q * e), r = v - m;
;     f32x2 o; o.x = v.x < 0.f ? m.x : r.x; o.y = v.y < 0.f ? m.y : r.y; return o;
; }
;     __device__ __forceinline__ void epi_proj(const f32x4 (&acc)[2][2][4][2], const pg8::Unit& u, int wr, int wc, int fr, int fq) const {
;     ...
;                         for (int bj = 0; bj < 2; ++bj) {
;                             f32x4 v0 = acc[ai][bj][m][0] * rstd, v1 = acc[ai][bj][m][1] * rstd;
;                             if (slot < 2) {
;                                 f32x2 a = gelu_pk((f32x2){v0[0], v0[1]}), b = gelu_pk((f32x2){v0[2], v0[3]}), c = gelu_pk((f32x2){v1[0], v1[1]}), d = gelu_pk((f32x2){v1[2], v1[3]});
;                                 v0 = (f32x4){a.x, a.y, b.x, b.y}; v1 = (f32x4){c.x, c.y, d.x, d.y};
;                             } else if (slot == 5) {
; #pragma unroll
;                                 for (int j = 0; j < 4; ++j) { v0[j] = siluf_(v0[j]); v1[j] = siluf_(v1[j]); }
;                             } else if (slot >= 6) {
; #pragma unroll
;                                 for (int j = 0; j < 4; ++j) { v0[j] = sigmoidf_(v0[j]); v1[j] = sigmoidf_(v1[j]); }
;                             }
;                             u32x4 w; w.x = cvt_pk_bf16(v0[0], v0[1]); w.y = cvt_pk_bf16(v0[2], v0[3]); w.z = cvt_pk_bf16(v1[0], v1[1]); w.w = cvt_pk_bf16(v1[2], v1[3]);
;                             *(u32x4*)(rowp + bj * 128) = w;
	v_sub_f32_e32 v177, v142, v178
	v_sub_f32_e32 v180, v148, v181
	v_sub_f32_e32 v183, v143, v184
	v_sub_f32_e32 v186, v149, v187
	v_cmp_gt_f32_e64 s[100:101], 0, v146
	s_nop 1
	v_cndmask_b32_e64 v146, v165, v166, s[100:101]
	v_cmp_gt_f32_e64 s[100:101], 0, v144
	s_nop 1
	v_cndmask_b32_e64 v144, v168, v169, s[100:101]
	v_cmp_gt_f32_e64 s[100:101], 0, v147
	s_nop 1
	v_cndmask_b32_e64 v147, v171, v172, s[100:101]
	v_cmp_gt_f32_e64 s[100:101], 0, v145
	s_nop 1
	v_cndmask_b32_e64 v145, v174, v175, s[100:101]
	v_cmp_gt_f32_e64 s[100:101], 0, v142
	s_nop 1
	v_cndmask_b32_e64 v142, v177, v178, s[100:101]
	v_cmp_gt_f32_e64 s[100:101], 0, v148
	s_nop 1
	v_cndmask_b32_e64 v148, v180, v181, s[100:101]
	v_cmp_gt_f32_e64 s[100:101], 0, v143
	s_nop 1
	v_cndmask_b32_e64 v143, v183, v184, s[100:101]
	v_cmp_gt_f32_e64 s[100:101], 0, v149
	s_nop 1
	v_cndmask_b32_e64 v149, v186, v187, s[100:101]
	v_mov_b32_e32 v154, v142
	v_mov_b32_e32 v155, v143
	v_cvt_pk_bf16_f32 v142, v146, v147
	v_cvt_pk_bf16_f32 v143, v154, v155
	v_cvt_pk_bf16_f32 v144, v144, v145
	v_cvt_pk_bf16_f32 v145, v148, v149
	global_store_dwordx4 v[150:151], v[142:145], off offset:256
	v_pk_mul_f32 v[146:147], v[66:67], v[138:139] op_sel_hi:[1,0]
	v_pk_mul_f32 v[148:149], v[64:65], v[138:139] op_sel_hi:[1,0]
	v_lshl_add_u64 v[144:145], v[152:153], 0, v[140:141]
	v_pk_mul_f32 v[140:141], v[70:71], v[138:139] op_sel_hi:[1,0]
	v_pk_mul_f32 v[142:143], v[68:69], v[138:139] op_sel_hi:[1,0]
	v_and_b32_e32 v164, 0x7fffffff, v148
	v_and_b32_e32 v167, 0x7fffffff, v142
	v_and_b32_e32 v170, 0x7fffffff, v143
	v_and_b32_e32 v173, 0x7fffffff, v149
	v_and_b32_e32 v176, 0x7fffffff, v140
	v_and_b32_e32 v179, 0x7fffffff, v146
	v_and_b32_e32 v182, 0x7fffffff, v141
	v_and_b32_e32 v185, 0x7fffffff, v147
	v_mul_f32_e32 v165, v148, v148
	v_mul_f32_e32 v168, v142, v142
	v_mul_f32_e32 v171, v143, v143
	v_mul_f32_e32 v174, v149, v149
	v_mul_f32_e32 v177, v140, v140
	v_mul_f32_e32 v180, v146, v146
	v_mul_f32_e32 v183, v141, v141
	v_mul_f32_e32 v186, v147, v147
	v_fma_f32 v164, v164, s14, 1.0
	v_fma_f32 v167, v167, s14, 1.0
	v_fma_f32 v170, v170, s14, 1.0
	v_fma_f32 v173, v173, s14, 1.0
	v_fma_f32 v176, v176, s14, 1.0
	v_fma_f32 v179, v179, s14, 1.0
	v_fma_f32 v182, v182, s14, 1.0
	v_fma_f32 v185, v185, s14, 1.0
	v_mul_f32_e32 v165, s20, v165
	v_mul_f32_e32 v168, s20, v168
	v_mul_f32_e32 v171, s20, v171
	v_mul_f32_e32 v174, s20, v174
	v_mul_f32_e32 v177, s20, v177
	v_mul_f32_e32 v180, s20, v180
	v_mul_f32_e32 v183, s20, v183
	v_mul_f32_e32 v186, s20, v186
	v_rcp_f32_e32 v164, v164
	v_rcp_f32_e32 v167, v167
	v_rcp_f32_e32 v170, v170
	v_rcp_f32_e32 v173, v173
	v_rcp_f32_e32 v176, v176
	v_rcp_f32_e32 v179, v179
	v_rcp_f32_e32 v182, v182
	v_rcp_f32_e32 v185, v185
	s_nop 0
	v_exp_f32_e32 v165, v165
	v_exp_f32_e32 v168, v168
	v_exp_f32_e32 v171, v171
	v_exp_f32_e32 v174, v174
	v_exp_f32_e32 v177, v177
	v_exp_f32_e32 v180, v180
	v_exp_f32_e32 v183, v183
	v_exp_f32_e32 v186, v186
	s_nop 0
	v_fma_f32 v166, v164, s15, v188
	v_fma_f32 v169, v167, s15, v188
	v_fma_f32 v172, v170, s15, v188
	v_fma_f32 v175, v173, s15, v188
	v_fma_f32 v178, v176, s15, v188
	v_fma_f32 v181, v179, s15, v188
	v_fma_f32 v184, v182, s15, v188
	v_fma_f32 v187, v185, s15, v188
	v_fma_f32 v166, v166, v164, v189
	v_fma_f32 v169, v169, v167, v189
	v_fma_f32 v172, v172, v170, v189
	v_fma_f32 v175, v175, v173, v189
	v_fma_f32 v178, v178, v176, v189
	v_fma_f32 v181, v181, v179, v189
	v_fma_f32 v184, v184, v182, v189
	v_fma_f32 v187, v187, v185, v189
	v_fma_f32 v166, v166, v164, v190
	v_fma_f32 v169, v169, v167, v190
	v_fma_f32 v172, v172, v170, v190
	v_fma_f32 v175, v175, v173, v190
	v_fma_f32 v178, v178, v176, v190
	v_fma_f32 v181, v181, v179, v190
	v_fma_f32 v184, v184, v182, v190
	v_fma_f32 v187, v187, v185, v190
	v_fma_f32 v166, v166, v164, v191
	v_fma_f32 v169, v169, v167, v191
	v_fma_f32 v172, v172, v170, v191
	v_fma_f32 v175, v175, v173, v191
	v_fma_f32 v178, v178, v176, v191
	v_fma_f32 v181, v181, v179, v191
	v_fma_f32 v184, v184, v182, v191
	v_fma_f32 v187, v187, v185, v191
	v_mul_f32_e32 v166, v166, v164
	v_mul_f32_e32 v169, v169, v167
	v_mul_f32_e32 v172, v172, v170
	v_mul_f32_e32 v175, v175, v173
	v_mul_f32_e32 v178, v178, v176
	v_mul_f32_e32 v181, v181, v179
	v_mul_f32_e32 v184, v184, v182
	v_mul_f32_e32 v187, v187, v185
	v_mul_f32_e32 v166, v166, v165
	v_mul_f32_e32 v169, v169, v168
	v_mul_f32_e32 v172, v172, v171
	v_mul_f32_e32 v175, v175, v174
	v_mul_f32_e32 v178, v178, v177
	v_mul_f32_e32 v181, v181, v180
	v_mul_f32_e32 v184, v184, v183
	v_mul_f32_e32 v187, v187, v186
	v_mul_f32_e32 v166, v148, v166
	v_mul_f32_e32 v169, v142, v169
	v_mul_f32_e32 v172, v143, v172
	v_mul_f32_e32 v175, v149, v175
	v_mul_f32_e32 v178, v140, v178
	v_mul_f32_e32 v181, v146, v181
	v_mul_f32_e32 v184, v141, v184
	v_mul_f32_e32 v187, v147, v187
	v_sub_f32_e32 v165, v148, v166
	v_sub_f32_e32 v168, v142, v169
	v_sub_f32_e32 v171, v143, v172
	v_sub_f32_e32 v174, v149, v175
	v_sub_f32_e32 v177, v140, v178
	v_sub_f32_e32 v180, v146, v181
	v_sub_f32_e32 v183, v141, v184
	v_sub_f32_e32 v186, v147, v187
	v_cmp_gt_f32_e64 s[100:101], 0, v148
	s_nop 1
	v_cndmask_b32_e64 v148, v165, v166, s[100:101]
	v_cmp_gt_f32_e64 s[100:101], 0, v142
	s_nop 1
	v_cndmask_b32_e64 v142, v168, v169, s[100:101]
	v_cmp_gt_f32_e64 s[100:101], 0, v143
	s_nop 1
	v_cndmask_b32_e64 v143, v171, v172, s[100:101]
	v_cmp_gt_f32_e64 s[100:101], 0, v149
	s_nop 1
	v_cndmask_b32_e64 v149, v174, v175, s[100:101]
	v_cmp_gt_f32_e64 s[100:101], 0, v140
	s_nop 1
	v_cndmask_b32_e64 v140, v177, v178, s[100:101]
	v_cmp_gt_f32_e64 s[100:101], 0, v146
	s_nop 1
	v_cndmask_b32_e64 v146, v180, v181, s[100:101]
; __device__ __forceinline__ unsigned cvt_pk_bf16(float lo, float hi) { const f32x2 v = {lo, hi}; const bf16v2_t b = __builtin_convertvector(v, bf16v2_t); return __builtin_bit_cast(unsigned, b); }
; __device__ __forceinline__ float sigmoidf_(float x) { return __builtin_amdgcn_rcpf(1.0f + __builtin_amdgcn_exp2f(x * -1.44269504089f)); }
; __device__ __forceinline__ float siluf_(float x) { return x * __builtin_amdgcn_rcpf(1.0f + __builtin_amdgcn_exp2f(x * -1.44269504089f)); }
; __device__ __forceinline__ f32x2 gelu_pk(f32x2 v) {
;     const f32x2 av = __builtin_elementwise_abs(v), d = av * 0.2316418882f + 1.0f;
;     f32x2 t; t.x = __builtin_amdgcn_rcpf(d.x); t.y = __builtin_amdgcn_rcpf(d.y);
;     f32x2 q = t * 0.5307027145f + (-0.7265760135f); q = q * t + 0.7107068705f; q = q * t + (-0.142248368f); q = q * t + 0.127414796f; q = q * t;
;     const f32x2 s = (v * v) * (-0.72134752044f);
;     f32x2 e; e.x = __builtin_amdgcn_exp2f(s.x); e.y = __builtin_amdgcn_exp2f(s.y);
;     const f32x2 m = v * (q * e), r = v - m;
;     f32x2 o; o.x = v.x < 0.f ? m.x : r.x; o.y = v.y < 0.f ? m.y : r.y; return o;
; }
;     __device__ __forceinline__ void epi_proj(const f32x4 (&acc)[2][2][4][2], const pg8::Unit& u, int wr, int wc, int fr, int fq) const {
;     ...
;                         for (int bj = 0; bj < 2; ++bj) {
;                             f32x4 v0 = acc[ai][bj][m][0] * rstd, v1 = acc[ai][bj][m][1] * rstd;
;                             if (slot < 2) {
;                                 f32x2 a = gelu_pk((f32x2){v0[0], v0[1]}), b = gelu_pk((f32x2){v0[2], v0[3]}), c = gelu_pk((f32x2){v1[0], v1[1]}), d = gelu_pk((f32x2){v1[2], v1[3]});
;                                 v0 = (f32x4){a.x, a.y, b.x, b.y}; v1 = (f32x4){c.x, c.y, d.x, d.y};
;                             } else if (slot == 5) {
; #pragma unroll
;                                 for (int j = 0; j < 4; ++j) { v0[j] = siluf_(v0[j]); v1[j] = siluf_(v1[j]); }
;                             } else if (slot >= 6) {
; #pragma unroll
;                                 for (int j = 0; j < 4; ++j) { v0[j] = sigmoidf_(v0[j]); v1[j] = sigmoidf_(v1[j]); }
;                             }
;                             u32x4 w; w.x = cvt_pk_bf16(v0[0], v0[1]); w.y = cvt_pk_bf16(v0[2], v0[3]); w.z = cvt_pk_bf16(v1[0], v1[1]); w.w = cvt_pk_bf16(v1[2], v1[3]);
;                             *(u32x4*)(rowp + bj * 128) = w;
	v_cmp_gt_f32_e64 s[100:101], 0, v141
	s_nop 1
	v_cndmask_b32_e64 v141, v183, v184, s[100:101]
	v_cmp_gt_f32_e64 s[100:101], 0, v147
	s_nop 1
	v_cndmask_b32_e64 v147, v186, v187, s[100:101]
	v_mov_b32_e32 v150, v140
	v_mov_b32_e32 v151, v141
	v_cvt_pk_bf16_f32 v140, v142, v143
	v_cvt_pk_bf16_f32 v141, v150, v151
	v_cvt_pk_bf16_f32 v142, v148, v149
	v_cvt_pk_bf16_f32 v143, v146, v147
	global_store_dwordx4 v[144:145], v[140:143], off
	v_pk_mul_f32 v[146:147], v[74:75], v[138:139] op_sel_hi:[1,0]
	v_mul_f32_e32 v129, 0x45800000, v128
	v_pk_mul_f32 v[140:141], v[78:79], v[138:139] op_sel_hi:[1,0]
	v_pk_mul_f32 v[142:143], v[76:77], v[138:139] op_sel_hi:[1,0]
	v_pk_mul_f32 v[138:139], v[72:73], v[138:139] op_sel_hi:[1,0]
	v_and_b32_e32 v164, 0x7fffffff, v142
	v_and_b32_e32 v167, 0x7fffffff, v138
	v_and_b32_e32 v170, 0x7fffffff, v139
	v_and_b32_e32 v173, 0x7fffffff, v143
	v_mul_f32_e32 v165, v142, v142
	v_mul_f32_e32 v168, v138, v138
	v_mul_f32_e32 v171, v139, v139
	v_mul_f32_e32 v174, v143, v143
	v_fma_f32 v164, v164, s14, 1.0
	v_fma_f32 v167, v167, s14, 1.0
	v_fma_f32 v170, v170, s14, 1.0
	v_fma_f32 v173, v173, s14, 1.0
	v_mul_f32_e32 v165, s20, v165
	v_mul_f32_e32 v168, s20, v168
	v_mul_f32_e32 v171, s20, v171
	v_mul_f32_e32 v174, s20, v174
	v_rcp_f32_e32 v164, v164
	v_rcp_f32_e32 v167, v167
	v_rcp_f32_e32 v170, v170
	v_rcp_f32_e32 v173, v173
	s_nop 0
	v_exp_f32_e32 v165, v165
	v_exp_f32_e32 v168, v168
	v_exp_f32_e32 v171, v171
	v_exp_f32_e32 v174, v174
	s_nop 0
	v_fma_f32 v166, v164, s15, v188
	v_fma_f32 v169, v167, s15, v188
	v_fma_f32 v172, v170, s15, v188
	v_fma_f32 v175, v173, s15, v188
	v_fma_f32 v166, v166, v164, v189
	v_fma_f32 v169, v169, v167, v189
	v_fma_f32 v172, v172, v170, v189
	v_fma_f32 v175, v175, v173, v189
	v_fma_f32 v166, v166, v164, v190
	v_fma_f32 v169, v169, v167, v190
	v_fma_f32 v172, v172, v170, v190
	v_fma_f32 v175, v175, v173, v190
	v_fma_f32 v166, v166, v164, v191
	v_fma_f32 v169, v169, v167, v191
	v_fma_f32 v172, v172, v170, v191
	v_fma_f32 v175, v175, v173, v191
	v_mul_f32_e32 v166, v166, v164
	v_mul_f32_e32 v169, v169, v167
	v_mul_f32_e32 v172, v172, v170
	v_mul_f32_e32 v175, v175, v173
	v_mul_f32_e32 v166, v166, v165
	v_mul_f32_e32 v169, v169, v168
	v_mul_f32_e32 v172, v172, v171
	v_mul_f32_e32 v175, v175, v174
	v_mul_f32_e32 v166, v142, v166
	v_mul_f32_e32 v169, v138, v169
	v_mul_f32_e32 v172, v139, v172
	v_mul_f32_e32 v175, v143, v175
	v_sub_f32_e32 v165, v142, v166
	v_sub_f32_e32 v168, v138, v169
	v_sub_f32_e32 v171, v139, v172
	v_sub_f32_e32 v174, v143, v175
	v_cmp_gt_f32_e64 s[100:101], 0, v142
	s_nop 1
	v_cndmask_b32_e64 v142, v165, v166, s[100:101]
	v_cmp_gt_f32_e64 s[100:101], 0, v138
	s_nop 1
	v_cndmask_b32_e64 v138, v168, v169, s[100:101]
	v_cmp_gt_f32_e64 s[100:101], 0, v139
	s_nop 1
	v_cndmask_b32_e64 v139, v171, v172, s[100:101]
	v_cmp_gt_f32_e64 s[100:101], 0, v143
	s_nop 1
	v_cndmask_b32_e64 v143, v174, v175, s[100:101]
	v_mov_b32_e32 v148, v138
	v_mov_b32_e32 v149, v139
	v_and_b32_e32 v164, 0x7fffffff, v140
	v_mul_f32_e32 v165, v140, v140
	v_fma_f32 v164, v164, s14, 1.0
	v_mul_f32_e32 v165, s20, v165
	v_rcp_f32_e32 v164, v164
	s_nop 0
	v_exp_f32_e32 v165, v165
	s_nop 0
	v_fma_f32 v166, v164, s15, v188
	v_fma_f32 v166, v166, v164, v189
	v_fma_f32 v166, v166, v164, v190
	v_fma_f32 v166, v166, v164, v191
	v_mul_f32_e32 v166, v166, v164
	v_mul_f32_e32 v166, v166, v165
	v_mul_f32_e32 v166, v140, v166
	v_sub_f32_e32 v165, v140, v166
	v_cmp_gt_f32_e64 s[100:101], 0, v140
	s_nop 1
	v_cndmask_b32_e64 v138, v165, v166, s[100:101]
	v_and_b32_e32 v164, 0x7fffffff, v146
	v_and_b32_e32 v167, 0x7fffffff, v141
	v_mul_f32_e32 v165, v146, v146
	v_mul_f32_e32 v168, v141, v141
	v_fma_f32 v164, v164, s14, 1.0
	v_fma_f32 v167, v167, s14, 1.0
	v_mul_f32_e32 v165, s20, v165
	v_mul_f32_e32 v168, s20, v168
	v_rcp_f32_e32 v164, v164
	v_rcp_f32_e32 v167, v167
	s_nop 0
	v_exp_f32_e32 v165, v165
	v_exp_f32_e32 v168, v168
	s_nop 0
	v_fma_f32 v166, v164, s15, v188
	v_fma_f32 v169, v167, s15, v188
	v_fma_f32 v166, v166, v164, v189
	v_fma_f32 v169, v169, v167, v189
	v_fma_f32 v166, v166, v164, v190
	v_fma_f32 v169, v169, v167, v190
	v_fma_f32 v166, v166, v164, v191
	v_fma_f32 v169, v169, v167, v191
	v_mul_f32_e32 v166, v166, v164
	v_mul_f32_e32 v169, v169, v167
	v_mul_f32_e32 v166, v166, v165
	v_mul_f32_e32 v169, v169, v168
	v_mul_f32_e32 v166, v146, v166
	v_mul_f32_e32 v169, v141, v169
	v_sub_f32_e32 v165, v146, v166
	v_sub_f32_e32 v168, v141, v169
	v_cmp_gt_f32_e64 s[100:101], 0, v146
	s_nop 1
	v_cndmask_b32_e64 v140, v165, v166, s[100:101]
	v_cmp_gt_f32_e64 s[100:101], 0, v141
	s_nop 1
	v_cndmask_b32_e64 v139, v168, v169, s[100:101]
	v_mov_b32_e32 v150, v138
	v_mov_b32_e32 v151, v139
	v_and_b32_e32 v164, 0x7fffffff, v147
	v_mul_f32_e32 v165, v147, v147
	v_fma_f32 v164, v164, s14, 1.0
	v_mul_f32_e32 v165, s20, v165
	v_rcp_f32_e32 v164, v164
	s_nop 0
	v_exp_f32_e32 v165, v165
	s_nop 0
	v_fma_f32 v166, v164, s15, v188
	v_fma_f32 v166, v166, v164, v189
	v_fma_f32 v166, v166, v164, v190
	v_fma_f32 v166, v166, v164, v191
	v_mul_f32_e32 v166, v166, v164
	v_mul_f32_e32 v166, v166, v165
	v_mul_f32_e32 v166, v147, v166
	v_sub_f32_e32 v165, v147, v166
	v_cmp_gt_f32_e64 s[100:101], 0, v147
	s_nop 1
	v_cndmask_b32_e64 v141, v165, v166, s[100:101]
	v_mov_b32_e32 v146, v140
	v_mov_b32_e32 v147, v141
	v_cvt_pk_bf16_f32 v138, v142, v143
	v_cvt_pk_bf16_f32 v139, v150, v151
	v_cvt_pk_bf16_f32 v140, v148, v149
	v_cvt_pk_bf16_f32 v141, v146, v147
	global_store_dwordx4 v[144:145], v[138:141], off offset:256
	v_pk_mul_f32 v[144:145], v[50:51], v[134:135] op_sel_hi:[1,0]
	v_pk_mul_f32 v[146:147], v[48:49], v[134:135] op_sel_hi:[1,0]
; __device__ __forceinline__ unsigned cvt_pk_bf16(float lo, float hi) { const f32x2 v = {lo, hi}; const bf16v2_t b = __builtin_convertvector(v, bf16v2_t); return __builtin_bit_cast(unsigned, b); }
; __device__ __forceinline__ float sigmoidf_(float x) { return __builtin_amdgcn_rcpf(1.0f + __builtin_amdgcn_exp2f(x * -1.44269504089f)); }
; __device__ __forceinline__ float siluf_(float x) { return x * __builtin_amdgcn_rcpf(1.0f + __builtin_amdgcn_exp2f(x * -1.44269504089f)); }
; __device__ __forceinline__ f32x2 gelu_pk(f32x2 v) {
;     const f32x2 av = __builtin_elementwise_abs(v), d = av * 0.2316418882f + 1.0f;
;     f32x2 t; t.x = __builtin_amdgcn_rcpf(d.x); t.y = __builtin_amdgcn_rcpf(d.y);
;     f32x2 q = t * 0.5307027145f + (-0.7265760135f); q = q * t + 0.7107068705f; q = q * t + (-0.142248368f); q = q * t + 0.127414796f; q = q * t;
;     const f32x2 s = (v * v) * (-0.72134752044f);
;     f32x2 e; e.x = __builtin_amdgcn_exp2f(s.x); e.y = __builtin_amdgcn_exp2f(s.y);
;     const f32x2 m = v * (q * e), r = v - m;
;     f32x2 o; o.x = v.x < 0.f ? m.x : r.x; o.y = v.y < 0.f ? m.y : r.y; return o;
; }
;     __device__ __forceinline__ void epi_proj(const f32x4 (&acc)[2][2][4][2], const pg8::Unit& u, int wr, int wc, int fr, int fq) const {
;     ...
;                         for (int bj = 0; bj < 2; ++bj) {
;                             f32x4 v0 = acc[ai][bj][m][0] * rstd, v1 = acc[ai][bj][m][1] * rstd;
;                             if (slot < 2) {
;                                 f32x2 a = gelu_pk((f32x2){v0[0], v0[1]}), b = gelu_pk((f32x2){v0[2], v0[3]}), c = gelu_pk((f32x2){v1[0], v1[1]}), d = gelu_pk((f32x2){v1[2], v1[3]});
;                                 v0 = (f32x4){a.x, a.y, b.x, b.y}; v1 = (f32x4){c.x, c.y, d.x, d.y};
;                             } else if (slot == 5) {
; #pragma unroll
;                                 for (int j = 0; j < 4; ++j) { v0[j] = siluf_(v0[j]); v1[j] = siluf_(v1[j]); }
;                             } else if (slot >= 6) {
; #pragma unroll
;                                 for (int j = 0; j < 4; ++j) { v0[j] = sigmoidf_(v0[j]); v1[j] = sigmoidf_(v1[j]); }
;                             }
;                             u32x4 w; w.x = cvt_pk_bf16(v0[0], v0[1]); w.y = cvt_pk_bf16(v0[2], v0[3]); w.z = cvt_pk_bf16(v1[0], v1[1]); w.w = cvt_pk_bf16(v1[2], v1[3]);
;                             *(u32x4*)(rowp + bj * 128) = w;
	v_pk_mul_f32 v[140:141], v[52:53], v[134:135] op_sel_hi:[1,0]
	v_pk_mul_f32 v[138:139], v[54:55], v[134:135] op_sel_hi:[1,0]
	v_lshl_add_u64 v[142:143], v[136:137], 0, s[0:1]
	v_and_b32_e32 v164, 0x7fffffff, v140
	v_and_b32_e32 v167, 0x7fffffff, v141
	v_and_b32_e32 v170, 0x7fffffff, v144
	v_and_b32_e32 v173, 0x7fffffff, v145
	v_and_b32_e32 v176, 0x7fffffff, v146
	v_mul_f32_e32 v165, v140, v140
	v_mul_f32_e32 v168, v141, v141
	v_mul_f32_e32 v171, v144, v144
	v_mul_f32_e32 v174, v145, v145
	v_mul_f32_e32 v177, v146, v146
	v_fma_f32 v164, v164, s14, 1.0
	v_fma_f32 v167, v167, s14, 1.0
	v_fma_f32 v170, v170, s14, 1.0
	v_fma_f32 v173, v173, s14, 1.0
	v_fma_f32 v176, v176, s14, 1.0
	v_mul_f32_e32 v165, s20, v165
	v_mul_f32_e32 v168, s20, v168
	v_mul_f32_e32 v171, s20, v171
	v_mul_f32_e32 v174, s20, v174
	v_mul_f32_e32 v177, s20, v177
	v_rcp_f32_e32 v164, v164
	v_rcp_f32_e32 v167, v167
	v_rcp_f32_e32 v170, v170
	v_rcp_f32_e32 v173, v173
	v_rcp_f32_e32 v176, v176
	s_nop 0
	v_exp_f32_e32 v165, v165
	v_exp_f32_e32 v168, v168
	v_exp_f32_e32 v171, v171
	v_exp_f32_e32 v174, v174
	v_exp_f32_e32 v177, v177
	s_nop 0
	v_fma_f32 v166, v164, s15, v188
	v_fma_f32 v169, v167, s15, v188
	v_fma_f32 v172, v170, s15, v188
	v_fma_f32 v175, v173, s15, v188
	v_fma_f32 v178, v176, s15, v188
	v_fma_f32 v166, v166, v164, v189
	v_fma_f32 v169, v169, v167, v189
	v_fma_f32 v172, v172, v170, v189
	v_fma_f32 v175, v175, v173, v189
	v_fma_f32 v178, v178, v176, v189
	v_fma_f32 v166, v166, v164, v190
	v_fma_f32 v169, v169, v167, v190
	v_fma_f32 v172, v172, v170, v190
	v_fma_f32 v175, v175, v173, v190
	v_fma_f32 v178, v178, v176, v190
	v_fma_f32 v166, v166, v164, v191
	v_fma_f32 v169, v169, v167, v191
	v_fma_f32 v172, v172, v170, v191
	v_fma_f32 v175, v175, v173, v191
	v_fma_f32 v178, v178, v176, v191
	v_mul_f32_e32 v166, v166, v164
	v_mul_f32_e32 v169, v169, v167
	v_mul_f32_e32 v172, v172, v170
	v_mul_f32_e32 v175, v175, v173
	v_mul_f32_e32 v178, v178, v176
	v_mul_f32_e32 v166, v166, v165
	v_mul_f32_e32 v169, v169, v168
	v_mul_f32_e32 v172, v172, v171
	v_mul_f32_e32 v175, v175, v174
	v_mul_f32_e32 v178, v178, v177
	v_mul_f32_e32 v166, v140, v166
	v_mul_f32_e32 v169, v141, v169
	v_mul_f32_e32 v172, v144, v172
	v_mul_f32_e32 v175, v145, v175
	v_mul_f32_e32 v178, v146, v178
	v_sub_f32_e32 v165, v140, v166
	v_sub_f32_e32 v168, v141, v169
	v_sub_f32_e32 v171, v144, v172
	v_sub_f32_e32 v174, v145, v175
	v_sub_f32_e32 v177, v146, v178
	v_cmp_gt_f32_e64 s[100:101], 0, v140
	s_nop 1
	v_cndmask_b32_e64 v140, v165, v166, s[100:101]
	v_cmp_gt_f32_e64 s[100:101], 0, v141
	s_nop 1
	v_cndmask_b32_e64 v141, v168, v169, s[100:101]
	v_cmp_gt_f32_e64 s[100:101], 0, v144
	s_nop 1
	v_cndmask_b32_e64 v144, v171, v172, s[100:101]
	v_cmp_gt_f32_e64 s[100:101], 0, v145
	s_nop 1
	v_cndmask_b32_e64 v145, v174, v175, s[100:101]
	v_cmp_gt_f32_e64 s[100:101], 0, v146
	s_nop 1
	v_cndmask_b32_e64 v146, v177, v178, s[100:101]
	s_mov_b32 s0, 0x40000
	v_cndmask_b32_e32 v128, v128, v129, vcc
	v_and_b32_e32 v164, 0x7fffffff, v147
	v_and_b32_e32 v167, 0x7fffffff, v138
	v_and_b32_e32 v170, 0x7fffffff, v139
	v_mul_f32_e32 v165, v147, v147
	v_mul_f32_e32 v168, v138, v138
	v_mul_f32_e32 v171, v139, v139
	v_fma_f32 v164, v164, s14, 1.0
	v_fma_f32 v167, v167, s14, 1.0
	v_fma_f32 v170, v170, s14, 1.0
	v_mul_f32_e32 v165, s20, v165
	v_mul_f32_e32 v168, s20, v168
	v_mul_f32_e32 v171, s20, v171
	v_rcp_f32_e32 v164, v164
	v_rcp_f32_e32 v167, v167
	v_rcp_f32_e32 v170, v170
	s_nop 0
	v_exp_f32_e32 v165, v165
	v_exp_f32_e32 v168, v168
	v_exp_f32_e32 v171, v171
	s_nop 0
	v_fma_f32 v166, v164, s15, v188
	v_fma_f32 v169, v167, s15, v188
	v_fma_f32 v172, v170, s15, v188
	v_fma_f32 v166, v166, v164, v189
	v_fma_f32 v169, v169, v167, v189
	v_fma_f32 v172, v172, v170, v189
	v_fma_f32 v166, v166, v164, v190
	v_fma_f32 v169, v169, v167, v190
	v_fma_f32 v172, v172, v170, v190
	v_fma_f32 v166, v166, v164, v191
	v_fma_f32 v169, v169, v167, v191
	v_fma_f32 v172, v172, v170, v191
	v_mul_f32_e32 v166, v166, v164
	v_mul_f32_e32 v169, v169, v167
	v_mul_f32_e32 v172, v172, v170
	v_mul_f32_e32 v166, v166, v165
	v_mul_f32_e32 v169, v169, v168
	v_mul_f32_e32 v172, v172, v171
	v_mul_f32_e32 v166, v147, v166
	v_mul_f32_e32 v169, v138, v169
	v_mul_f32_e32 v172, v139, v172
	v_sub_f32_e32 v165, v147, v166
	v_sub_f32_e32 v168, v138, v169
	v_sub_f32_e32 v171, v139, v172
	v_cmp_gt_f32_e64 s[100:101], 0, v147
	s_nop 1
	v_cndmask_b32_e64 v147, v165, v166, s[100:101]
	v_cmp_gt_f32_e64 s[100:101], 0, v138
	s_nop 1
	v_cndmask_b32_e64 v138, v168, v169, s[100:101]
	v_cmp_gt_f32_e64 s[100:101], 0, v139
	s_nop 1
	v_cndmask_b32_e64 v139, v171, v172, s[100:101]
	v_mov_b32_e32 v148, v138
	v_mov_b32_e32 v149, v139
	v_cvt_pk_bf16_f32 v138, v140, v141
	v_cvt_pk_bf16_f32 v141, v144, v145
	v_add_co_u32_e32 v144, vcc, s0, v136
	v_cvt_pk_bf16_f32 v139, v148, v149
	v_cvt_pk_bf16_f32 v140, v146, v147
	v_addc_co_u32_e32 v145, vcc, 0, v137, vcc
	global_store_dwordx4 v[144:145], v[138:141], off
	v_pk_mul_f32 v[144:145], v[58:59], v[134:135] op_sel_hi:[1,0]
	s_mov_b64 s[0:1], 0x48000
	v_pk_mul_f32 v[138:139], v[62:63], v[134:135] op_sel_hi:[1,0]
	v_pk_mul_f32 v[140:141], v[60:61], v[134:135] op_sel_hi:[1,0]
	v_pk_mul_f32 v[134:135], v[56:57], v[134:135] op_sel_hi:[1,0]
	v_and_b32_e32 v164, 0x7fffffff, v140
	v_and_b32_e32 v167, 0x7fffffff, v134
	v_and_b32_e32 v170, 0x7fffffff, v141
	v_and_b32_e32 v173, 0x7fffffff, v135
	v_and_b32_e32 v176, 0x7fffffff, v138
	v_and_b32_e32 v179, 0x7fffffff, v144
	v_and_b32_e32 v182, 0x7fffffff, v139
	v_and_b32_e32 v185, 0x7fffffff, v145
	v_mul_f32_e32 v165, v140, v140
	v_mul_f32_e32 v168, v134, v134
	v_mul_f32_e32 v171, v141, v141
; __device__ __forceinline__ unsigned cvt_pk_bf16(float lo, float hi) { const f32x2 v = {lo, hi}; const bf16v2_t b = __builtin_convertvector(v, bf16v2_t); return __builtin_bit_cast(unsigned, b); }
; __device__ __forceinline__ float sigmoidf_(float x) { return __builtin_amdgcn_rcpf(1.0f + __builtin_amdgcn_exp2f(x * -1.44269504089f)); }
; __device__ __forceinline__ float siluf_(float x) { return x * __builtin_amdgcn_rcpf(1.0f + __builtin_amdgcn_exp2f(x * -1.44269504089f)); }
; __device__ __forceinline__ f32x2 gelu_pk(f32x2 v) {
;     const f32x2 av = __builtin_elementwise_abs(v), d = av * 0.2316418882f + 1.0f;
;     f32x2 t; t.x = __builtin_amdgcn_rcpf(d.x); t.y = __builtin_amdgcn_rcpf(d.y);
;     f32x2 q = t * 0.5307027145f + (-0.7265760135f); q = q * t + 0.7107068705f; q = q * t + (-0.142248368f); q = q * t + 0.127414796f; q = q * t;
;     const f32x2 s = (v * v) * (-0.72134752044f);
;     f32x2 e; e.x = __builtin_amdgcn_exp2f(s.x); e.y = __builtin_amdgcn_exp2f(s.y);
;     const f32x2 m = v * (q * e), r = v - m;
;     f32x2 o; o.x = v.x < 0.f ? m.x : r.x; o.y = v.y < 0.f ? m.y : r.y; return o;
; }
;     __device__ __forceinline__ void epi_proj(const f32x4 (&acc)[2][2][4][2], const pg8::Unit& u, int wr, int wc, int fr, int fq) const {
;     ...
;                         for (int bj = 0; bj < 2; ++bj) {
;                             f32x4 v0 = acc[ai][bj][m][0] * rstd, v1 = acc[ai][bj][m][1] * rstd;
;                             if (slot < 2) {
;                                 f32x2 a = gelu_pk((f32x2){v0[0], v0[1]}), b = gelu_pk((f32x2){v0[2], v0[3]}), c = gelu_pk((f32x2){v1[0], v1[1]}), d = gelu_pk((f32x2){v1[2], v1[3]});
;                                 v0 = (f32x4){a.x, a.y, b.x, b.y}; v1 = (f32x4){c.x, c.y, d.x, d.y};
;                             } else if (slot == 5) {
; #pragma unroll
;                                 for (int j = 0; j < 4; ++j) { v0[j] = siluf_(v0[j]); v1[j] = siluf_(v1[j]); }
;                             } else if (slot >= 6) {
; #pragma unroll
;                                 for (int j = 0; j < 4; ++j) { v0[j] = sigmoidf_(v0[j]); v1[j] = sigmoidf_(v1[j]); }
;                             }
;                             u32x4 w; w.x = cvt_pk_bf16(v0[0], v0[1]); w.y = cvt_pk_bf16(v0[2], v0[3]); w.z = cvt_pk_bf16(v1[0], v1[1]); w.w = cvt_pk_bf16(v1[2], v1[3]);
;                             *(u32x4*)(rowp + bj * 128) = w;
	v_mul_f32_e32 v174, v135, v135
	v_mul_f32_e32 v177, v138, v138
	v_mul_f32_e32 v180, v144, v144
	v_mul_f32_e32 v183, v139, v139
	v_mul_f32_e32 v186, v145, v145
	v_fma_f32 v164, v164, s14, 1.0
	v_fma_f32 v167, v167, s14, 1.0
	v_fma_f32 v170, v170, s14, 1.0
	v_fma_f32 v173, v173, s14, 1.0
	v_fma_f32 v176, v176, s14, 1.0
	v_fma_f32 v179, v179, s14, 1.0
	v_fma_f32 v182, v182, s14, 1.0
	v_fma_f32 v185, v185, s14, 1.0
	v_mul_f32_e32 v165, s20, v165
	v_mul_f32_e32 v168, s20, v168
	v_mul_f32_e32 v171, s20, v171
	v_mul_f32_e32 v174, s20, v174
	v_mul_f32_e32 v177, s20, v177
	v_mul_f32_e32 v180, s20, v180
	v_mul_f32_e32 v183, s20, v183
	v_mul_f32_e32 v186, s20, v186
	v_rcp_f32_e32 v164, v164
	v_rcp_f32_e32 v167, v167
	v_rcp_f32_e32 v170, v170
	v_rcp_f32_e32 v173, v173
	v_rcp_f32_e32 v176, v176
	v_rcp_f32_e32 v179, v179
	v_rcp_f32_e32 v182, v182
	v_rcp_f32_e32 v185, v185
	s_nop 0
	v_exp_f32_e32 v165, v165
	v_exp_f32_e32 v168, v168
	v_exp_f32_e32 v171, v171
	v_exp_f32_e32 v174, v174
	v_exp_f32_e32 v177, v177
	v_exp_f32_e32 v180, v180
	v_exp_f32_e32 v183, v183
	v_exp_f32_e32 v186, v186
	s_nop 0
	v_fma_f32 v166, v164, s15, v188
	v_fma_f32 v169, v167, s15, v188
	v_fma_f32 v172, v170, s15, v188
	v_fma_f32 v175, v173, s15, v188
	v_fma_f32 v178, v176, s15, v188
	v_fma_f32 v181, v179, s15, v188
	v_fma_f32 v184, v182, s15, v188
	v_fma_f32 v187, v185, s15, v188
	v_fma_f32 v166, v166, v164, v189
	v_fma_f32 v169, v169, v167, v189
	v_fma_f32 v172, v172, v170, v189
	v_fma_f32 v175, v175, v173, v189
	v_fma_f32 v178, v178, v176, v189
	v_fma_f32 v181, v181, v179, v189
	v_fma_f32 v184, v184, v182, v189
	v_fma_f32 v187, v187, v185, v189
	v_fma_f32 v166, v166, v164, v190
	v_fma_f32 v169, v169, v167, v190
	v_fma_f32 v172, v172, v170, v190
	v_fma_f32 v175, v175, v173, v190
	v_fma_f32 v178, v178, v176, v190
	v_fma_f32 v181, v181, v179, v190
	v_fma_f32 v184, v184, v182, v190
	v_fma_f32 v187, v187, v185, v190
	v_fma_f32 v166, v166, v164, v191
	v_fma_f32 v169, v169, v167, v191
	v_fma_f32 v172, v172, v170, v191
	v_fma_f32 v175, v175, v173, v191
	v_fma_f32 v178, v178, v176, v191
	v_fma_f32 v181, v181, v179, v191
	v_fma_f32 v184, v184, v182, v191
	v_fma_f32 v187, v187, v185, v191
	v_mul_f32_e32 v166, v166, v164
	v_mul_f32_e32 v169, v169, v167
	v_mul_f32_e32 v172, v172, v170
	v_mul_f32_e32 v175, v175, v173
	v_mul_f32_e32 v178, v178, v176
	v_mul_f32_e32 v181, v181, v179
	v_mul_f32_e32 v184, v184, v182
	v_mul_f32_e32 v187, v187, v185
	v_mul_f32_e32 v166, v166, v165
	v_mul_f32_e32 v169, v169, v168
	v_mul_f32_e32 v172, v172, v171
	v_mul_f32_e32 v175, v175, v174
	v_mul_f32_e32 v178, v178, v177
	v_mul_f32_e32 v181, v181, v180
	v_mul_f32_e32 v184, v184, v183
	v_mul_f32_e32 v187, v187, v186
	v_mul_f32_e32 v166, v140, v166
	v_mul_f32_e32 v169, v134, v169
	v_mul_f32_e32 v172, v141, v172
	v_mul_f32_e32 v175, v135, v175
	v_mul_f32_e32 v178, v138, v178
	v_mul_f32_e32 v181, v144, v181
	v_mul_f32_e32 v184, v139, v184
	v_mul_f32_e32 v187, v145, v187
	v_sub_f32_e32 v165, v140, v166
	v_sub_f32_e32 v168, v134, v169
	v_sub_f32_e32 v171, v141, v172
	v_sub_f32_e32 v174, v135, v175
	v_sub_f32_e32 v177, v138, v178
	v_sub_f32_e32 v180, v144, v181
	v_sub_f32_e32 v183, v139, v184
	v_sub_f32_e32 v186, v145, v187
	v_cmp_gt_f32_e64 s[100:101], 0, v140
	s_nop 1
	v_cndmask_b32_e64 v140, v165, v166, s[100:101]
	v_cmp_gt_f32_e64 s[100:101], 0, v134
	s_nop 1
	v_cndmask_b32_e64 v134, v168, v169, s[100:101]
	v_cmp_gt_f32_e64 s[100:101], 0, v141
	s_nop 1
	v_cndmask_b32_e64 v141, v171, v172, s[100:101]
	v_cmp_gt_f32_e64 s[100:101], 0, v135
	s_nop 1
	v_cndmask_b32_e64 v135, v174, v175, s[100:101]
	v_cmp_gt_f32_e64 s[100:101], 0, v138
	s_nop 1
	v_cndmask_b32_e64 v138, v177, v178, s[100:101]
	v_cmp_gt_f32_e64 s[100:101], 0, v144
	s_nop 1
	v_cndmask_b32_e64 v144, v180, v181, s[100:101]
	v_cmp_gt_f32_e64 s[100:101], 0, v139
	s_nop 1
	v_cndmask_b32_e64 v139, v183, v184, s[100:101]
	v_cmp_gt_f32_e64 s[100:101], 0, v145
	s_nop 1
	v_cndmask_b32_e64 v145, v186, v187, s[100:101]
	v_mov_b32_e32 v146, v138
	v_mov_b32_e32 v147, v139
	v_cvt_pk_bf16_f32 v138, v140, v141
	v_cvt_pk_bf16_f32 v139, v146, v147
	v_cvt_pk_bf16_f32 v140, v134, v135
	v_cvt_pk_bf16_f32 v141, v144, v145
	global_store_dwordx4 v[142:143], v[138:141], off offset:256
	v_pk_mul_f32 v[134:135], v[38:39], v[132:133] op_sel_hi:[1,0]
	v_pk_mul_f32 v[144:145], v[32:33], v[132:133] op_sel_hi:[1,0]
	v_pk_mul_f32 v[138:139], v[36:37], v[132:133] op_sel_hi:[1,0]
	v_pk_mul_f32 v[140:141], v[34:35], v[132:133] op_sel_hi:[1,0]
	v_lshl_add_u64 v[142:143], v[136:137], 0, s[0:1]
	v_and_b32_e32 v164, 0x7fffffff, v138
	v_and_b32_e32 v167, 0x7fffffff, v139
	v_and_b32_e32 v170, 0x7fffffff, v134
	v_and_b32_e32 v173, 0x7fffffff, v135
	v_and_b32_e32 v176, 0x7fffffff, v144
	v_mul_f32_e32 v165, v138, v138
	v_mul_f32_e32 v168, v139, v139
	v_mul_f32_e32 v171, v134, v134
	v_mul_f32_e32 v174, v135, v135
	v_mul_f32_e32 v177, v144, v144
	v_fma_f32 v164, v164, s14, 1.0
	v_fma_f32 v167, v167, s14, 1.0
	v_fma_f32 v170, v170, s14, 1.0
	v_fma_f32 v173, v173, s14, 1.0
	v_fma_f32 v176, v176, s14, 1.0
	v_mul_f32_e32 v165, s20, v165
	v_mul_f32_e32 v168, s20, v168
	v_mul_f32_e32 v171, s20, v171
	v_mul_f32_e32 v174, s20, v174
	v_mul_f32_e32 v177, s20, v177
	v_rcp_f32_e32 v164, v164
	v_rcp_f32_e32 v167, v167
	v_rcp_f32_e32 v170, v170
	v_rcp_f32_e32 v173, v173
	v_rcp_f32_e32 v176, v176
	s_nop 0
	v_exp_f32_e32 v165, v165
	v_exp_f32_e32 v168, v168
	v_exp_f32_e32 v171, v171
	v_exp_f32_e32 v174, v174
	v_exp_f32_e32 v177, v177
	s_nop 0
	v_fma_f32 v166, v164, s15, v188
	v_fma_f32 v169, v167, s15, v188
	v_fma_f32 v172, v170, s15, v188
	v_fma_f32 v175, v173, s15, v188
	v_fma_f32 v178, v176, s15, v188
; __device__ __forceinline__ unsigned cvt_pk_bf16(float lo, float hi) { const f32x2 v = {lo, hi}; const bf16v2_t b = __builtin_convertvector(v, bf16v2_t); return __builtin_bit_cast(unsigned, b); }
; __device__ __forceinline__ float sigmoidf_(float x) { return __builtin_amdgcn_rcpf(1.0f + __builtin_amdgcn_exp2f(x * -1.44269504089f)); }
; __device__ __forceinline__ float siluf_(float x) { return x * __builtin_amdgcn_rcpf(1.0f + __builtin_amdgcn_exp2f(x * -1.44269504089f)); }
; __device__ __forceinline__ f32x2 gelu_pk(f32x2 v) {
;     const f32x2 av = __builtin_elementwise_abs(v), d = av * 0.2316418882f + 1.0f;
;     f32x2 t; t.x = __builtin_amdgcn_rcpf(d.x); t.y = __builtin_amdgcn_rcpf(d.y);
;     f32x2 q = t * 0.5307027145f + (-0.7265760135f); q = q * t + 0.7107068705f; q = q * t + (-0.142248368f); q = q * t + 0.127414796f; q = q * t;
;     const f32x2 s = (v * v) * (-0.72134752044f);
;     f32x2 e; e.x = __builtin_amdgcn_exp2f(s.x); e.y = __builtin_amdgcn_exp2f(s.y);
;     const f32x2 m = v * (q * e), r = v - m;
;     f32x2 o; o.x = v.x < 0.f ? m.x : r.x; o.y = v.y < 0.f ? m.y : r.y; return o;
; }
;     __device__ __forceinline__ void epi_proj(const f32x4 (&acc)[2][2][4][2], const pg8::Unit& u, int wr, int wc, int fr, int fq) const {
;     ...
;                         for (int bj = 0; bj < 2; ++bj) {
;                             f32x4 v0 = acc[ai][bj][m][0] * rstd, v1 = acc[ai][bj][m][1] * rstd;
;                             if (slot < 2) {
;                                 f32x2 a = gelu_pk((f32x2){v0[0], v0[1]}), b = gelu_pk((f32x2){v0[2], v0[3]}), c = gelu_pk((f32x2){v1[0], v1[1]}), d = gelu_pk((f32x2){v1[2], v1[3]});
;                                 v0 = (f32x4){a.x, a.y, b.x, b.y}; v1 = (f32x4){c.x, c.y, d.x, d.y};
;                             } else if (slot == 5) {
; #pragma unroll
;                                 for (int j = 0; j < 4; ++j) { v0[j] = siluf_(v0[j]); v1[j] = siluf_(v1[j]); }
;                             } else if (slot >= 6) {
; #pragma unroll
;                                 for (int j = 0; j < 4; ++j) { v0[j] = sigmoidf_(v0[j]); v1[j] = sigmoidf_(v1[j]); }
;                             }
;                             u32x4 w; w.x = cvt_pk_bf16(v0[0], v0[1]); w.y = cvt_pk_bf16(v0[2], v0[3]); w.z = cvt_pk_bf16(v1[0], v1[1]); w.w = cvt_pk_bf16(v1[2], v1[3]);
;                             *(u32x4*)(rowp + bj * 128) = w;
	v_fma_f32 v166, v166, v164, v189
	v_fma_f32 v169, v169, v167, v189
	v_fma_f32 v172, v172, v170, v189
	v_fma_f32 v175, v175, v173, v189
	v_fma_f32 v178, v178, v176, v189
	v_fma_f32 v166, v166, v164, v190
	v_fma_f32 v169, v169, v167, v190
	v_fma_f32 v172, v172, v170, v190
	v_fma_f32 v175, v175, v173, v190
	v_fma_f32 v178, v178, v176, v190
	v_fma_f32 v166, v166, v164, v191
	v_fma_f32 v169, v169, v167, v191
	v_fma_f32 v172, v172, v170, v191
	v_fma_f32 v175, v175, v173, v191
	v_fma_f32 v178, v178, v176, v191
	v_mul_f32_e32 v166, v166, v164
	v_mul_f32_e32 v169, v169, v167
	v_mul_f32_e32 v172, v172, v170
	v_mul_f32_e32 v175, v175, v173
	v_mul_f32_e32 v178, v178, v176
	v_mul_f32_e32 v166, v166, v165
	v_mul_f32_e32 v169, v169, v168
	v_mul_f32_e32 v172, v172, v171
	v_mul_f32_e32 v175, v175, v174
	v_mul_f32_e32 v178, v178, v177
	v_mul_f32_e32 v166, v138, v166
	v_mul_f32_e32 v169, v139, v169
	v_mul_f32_e32 v172, v134, v172
	v_mul_f32_e32 v175, v135, v175
	v_mul_f32_e32 v178, v144, v178
	v_sub_f32_e32 v165, v138, v166
	v_sub_f32_e32 v168, v139, v169
	v_sub_f32_e32 v171, v134, v172
	v_sub_f32_e32 v174, v135, v175
	v_sub_f32_e32 v177, v144, v178
	v_cmp_gt_f32_e64 s[100:101], 0, v138
	s_nop 1
	v_cndmask_b32_e64 v138, v165, v166, s[100:101]
	v_cmp_gt_f32_e64 s[100:101], 0, v139
	s_nop 1
	v_cndmask_b32_e64 v139, v168, v169, s[100:101]
	v_cmp_gt_f32_e64 s[100:101], 0, v134
	s_nop 1
	v_cndmask_b32_e64 v134, v171, v172, s[100:101]
	v_cmp_gt_f32_e64 s[100:101], 0, v135
	s_nop 1
	v_cndmask_b32_e64 v135, v174, v175, s[100:101]
	v_cmp_gt_f32_e64 s[100:101], 0, v144
	s_nop 1
	v_cndmask_b32_e64 v144, v177, v178, s[100:101]
	s_mov_b32 s0, 0x48000
	v_and_b32_e32 v164, 0x7fffffff, v145
	v_and_b32_e32 v167, 0x7fffffff, v140
	v_and_b32_e32 v170, 0x7fffffff, v141
	v_mul_f32_e32 v165, v145, v145
	v_mul_f32_e32 v168, v140, v140
	v_mul_f32_e32 v171, v141, v141
	v_fma_f32 v164, v164, s14, 1.0
	v_fma_f32 v167, v167, s14, 1.0
	v_fma_f32 v170, v170, s14, 1.0
	v_mul_f32_e32 v165, s20, v165
	v_mul_f32_e32 v168, s20, v168
	v_mul_f32_e32 v171, s20, v171
	v_rcp_f32_e32 v164, v164
	v_rcp_f32_e32 v167, v167
	v_rcp_f32_e32 v170, v170
	s_nop 0
	v_exp_f32_e32 v165, v165
	v_exp_f32_e32 v168, v168
	v_exp_f32_e32 v171, v171
	s_nop 0
	v_fma_f32 v166, v164, s15, v188
	v_fma_f32 v169, v167, s15, v188
	v_fma_f32 v172, v170, s15, v188
	v_fma_f32 v166, v166, v164, v189
	v_fma_f32 v169, v169, v167, v189
	v_fma_f32 v172, v172, v170, v189
	v_fma_f32 v166, v166, v164, v190
	v_fma_f32 v169, v169, v167, v190
	v_fma_f32 v172, v172, v170, v190
	v_fma_f32 v166, v166, v164, v191
	v_fma_f32 v169, v169, v167, v191
	v_fma_f32 v172, v172, v170, v191
	v_mul_f32_e32 v166, v166, v164
	v_mul_f32_e32 v169, v169, v167
	v_mul_f32_e32 v172, v172, v170
	v_mul_f32_e32 v166, v166, v165
	v_mul_f32_e32 v169, v169, v168
	v_mul_f32_e32 v172, v172, v171
	v_mul_f32_e32 v166, v145, v166
	v_mul_f32_e32 v169, v140, v169
	v_mul_f32_e32 v172, v141, v172
	v_sub_f32_e32 v165, v145, v166
	v_sub_f32_e32 v168, v140, v169
	v_sub_f32_e32 v171, v141, v172
	v_cmp_gt_f32_e64 s[100:101], 0, v145
	s_nop 1
	v_cndmask_b32_e64 v145, v165, v166, s[100:101]
	v_cmp_gt_f32_e64 s[100:101], 0, v140
	s_nop 1
	v_cndmask_b32_e64 v140, v168, v169, s[100:101]
	v_cmp_gt_f32_e64 s[100:101], 0, v141
	s_nop 1
	v_cndmask_b32_e64 v141, v171, v172, s[100:101]
	v_mov_b32_e32 v146, v140
	v_mov_b32_e32 v147, v141
	v_cvt_pk_bf16_f32 v138, v138, v139
	v_cvt_pk_bf16_f32 v139, v134, v135
	v_add_co_u32_e32 v134, vcc, s0, v136
	v_cvt_pk_bf16_f32 v140, v144, v145
	v_cvt_pk_bf16_f32 v141, v146, v147
	v_addc_co_u32_e32 v135, vcc, 0, v137, vcc
	global_store_dwordx4 v[134:135], v[138:141], off
	v_pk_mul_f32 v[134:135], v[46:47], v[132:133] op_sel_hi:[1,0]
	s_mov_b64 s[0:1], 0x50000
	v_pk_mul_f32 v[138:139], v[44:45], v[132:133] op_sel_hi:[1,0]
	v_pk_mul_f32 v[140:141], v[42:43], v[132:133] op_sel_hi:[1,0]
	v_pk_mul_f32 v[132:133], v[40:41], v[132:133] op_sel_hi:[1,0]
	v_and_b32_e32 v164, 0x7fffffff, v138
	v_and_b32_e32 v167, 0x7fffffff, v132
	v_and_b32_e32 v170, 0x7fffffff, v133
	v_and_b32_e32 v173, 0x7fffffff, v139
	v_mul_f32_e32 v165, v138, v138
	v_mul_f32_e32 v168, v132, v132
	v_mul_f32_e32 v171, v133, v133
	v_mul_f32_e32 v174, v139, v139
	v_fma_f32 v164, v164, s14, 1.0
	v_fma_f32 v167, v167, s14, 1.0
	v_fma_f32 v170, v170, s14, 1.0
	v_fma_f32 v173, v173, s14, 1.0
	v_mul_f32_e32 v165, s20, v165
	v_mul_f32_e32 v168, s20, v168
	v_mul_f32_e32 v171, s20, v171
	v_mul_f32_e32 v174, s20, v174
	v_rcp_f32_e32 v164, v164
	v_rcp_f32_e32 v167, v167
	v_rcp_f32_e32 v170, v170
	v_rcp_f32_e32 v173, v173
	s_nop 0
	v_exp_f32_e32 v165, v165
	v_exp_f32_e32 v168, v168
	v_exp_f32_e32 v171, v171
	v_exp_f32_e32 v174, v174
	s_nop 0
	v_fma_f32 v166, v164, s15, v188
	v_fma_f32 v169, v167, s15, v188
	v_fma_f32 v172, v170, s15, v188
	v_fma_f32 v175, v173, s15, v188
	v_fma_f32 v166, v166, v164, v189
	v_fma_f32 v169, v169, v167, v189
	v_fma_f32 v172, v172, v170, v189
	v_fma_f32 v175, v175, v173, v189
	v_fma_f32 v166, v166, v164, v190
	v_fma_f32 v169, v169, v167, v190
	v_fma_f32 v172, v172, v170, v190
	v_fma_f32 v175, v175, v173, v190
	v_fma_f32 v166, v166, v164, v191
	v_fma_f32 v169, v169, v167, v191
	v_fma_f32 v172, v172, v170, v191
	v_fma_f32 v175, v175, v173, v191
	v_mul_f32_e32 v166, v166, v164
	v_mul_f32_e32 v169, v169, v167
	v_mul_f32_e32 v172, v172, v170
	v_mul_f32_e32 v175, v175, v173
	v_mul_f32_e32 v166, v166, v165
	v_mul_f32_e32 v169, v169, v168
	v_mul_f32_e32 v172, v172, v171
	v_mul_f32_e32 v175, v175, v174
	v_mul_f32_e32 v166, v138, v166
	v_mul_f32_e32 v169, v132, v169
	v_mul_f32_e32 v172, v133, v172
	v_mul_f32_e32 v175, v139, v175
	v_sub_f32_e32 v165, v138, v166
	v_sub_f32_e32 v168, v132, v169
; __device__ __forceinline__ unsigned cvt_pk_bf16(float lo, float hi) { const f32x2 v = {lo, hi}; const bf16v2_t b = __builtin_convertvector(v, bf16v2_t); return __builtin_bit_cast(unsigned, b); }
; __device__ __forceinline__ float sigmoidf_(float x) { return __builtin_amdgcn_rcpf(1.0f + __builtin_amdgcn_exp2f(x * -1.44269504089f)); }
; __device__ __forceinline__ float siluf_(float x) { return x * __builtin_amdgcn_rcpf(1.0f + __builtin_amdgcn_exp2f(x * -1.44269504089f)); }
; __device__ __forceinline__ f32x2 gelu_pk(f32x2 v) {
;     const f32x2 av = __builtin_elementwise_abs(v), d = av * 0.2316418882f + 1.0f;
;     f32x2 t; t.x = __builtin_amdgcn_rcpf(d.x); t.y = __builtin_amdgcn_rcpf(d.y);
;     f32x2 q = t * 0.5307027145f + (-0.7265760135f); q = q * t + 0.7107068705f; q = q * t + (-0.142248368f); q = q * t + 0.127414796f; q = q * t;
;     const f32x2 s = (v * v) * (-0.72134752044f);
;     f32x2 e; e.x = __builtin_amdgcn_exp2f(s.x); e.y = __builtin_amdgcn_exp2f(s.y);
;     const f32x2 m = v * (q * e), r = v - m;
;     f32x2 o; o.x = v.x < 0.f ? m.x : r.x; o.y = v.y < 0.f ? m.y : r.y; return o;
; }
;     __device__ __forceinline__ void epi_proj(const f32x4 (&acc)[2][2][4][2], const pg8::Unit& u, int wr, int wc, int fr, int fq) const {
;     ...
;                         for (int bj = 0; bj < 2; ++bj) {
;                             f32x4 v0 = acc[ai][bj][m][0] * rstd, v1 = acc[ai][bj][m][1] * rstd;
;                             if (slot < 2) {
;                                 f32x2 a = gelu_pk((f32x2){v0[0], v0[1]}), b = gelu_pk((f32x2){v0[2], v0[3]}), c = gelu_pk((f32x2){v1[0], v1[1]}), d = gelu_pk((f32x2){v1[2], v1[3]});
;                                 v0 = (f32x4){a.x, a.y, b.x, b.y}; v1 = (f32x4){c.x, c.y, d.x, d.y};
;                             } else if (slot == 5) {
; #pragma unroll
;                                 for (int j = 0; j < 4; ++j) { v0[j] = siluf_(v0[j]); v1[j] = siluf_(v1[j]); }
;                             } else if (slot >= 6) {
; #pragma unroll
;                                 for (int j = 0; j < 4; ++j) { v0[j] = sigmoidf_(v0[j]); v1[j] = sigmoidf_(v1[j]); }
;                             }
;                             u32x4 w; w.x = cvt_pk_bf16(v0[0], v0[1]); w.y = cvt_pk_bf16(v0[2], v0[3]); w.z = cvt_pk_bf16(v1[0], v1[1]); w.w = cvt_pk_bf16(v1[2], v1[3]);
;                             *(u32x4*)(rowp + bj * 128) = w;
	v_sub_f32_e32 v171, v133, v172
	v_sub_f32_e32 v174, v139, v175
	v_cmp_gt_f32_e64 s[100:101], 0, v138
	s_nop 1
	v_cndmask_b32_e64 v138, v165, v166, s[100:101]
	v_cmp_gt_f32_e64 s[100:101], 0, v132
	s_nop 1
	v_cndmask_b32_e64 v132, v168, v169, s[100:101]
	v_cmp_gt_f32_e64 s[100:101], 0, v133
	s_nop 1
	v_cndmask_b32_e64 v133, v171, v172, s[100:101]
	v_cmp_gt_f32_e64 s[100:101], 0, v139
	s_nop 1
	v_cndmask_b32_e64 v139, v174, v175, s[100:101]
	v_mov_b32_e32 v144, v132
	v_mov_b32_e32 v145, v133
	v_and_b32_e32 v164, 0x7fffffff, v134
	v_mul_f32_e32 v165, v134, v134
	v_fma_f32 v164, v164, s14, 1.0
	v_mul_f32_e32 v165, s20, v165
	v_rcp_f32_e32 v164, v164
	s_nop 0
	v_exp_f32_e32 v165, v165
	s_nop 0
	v_fma_f32 v166, v164, s15, v188
	v_fma_f32 v166, v166, v164, v189
	v_fma_f32 v166, v166, v164, v190
	v_fma_f32 v166, v166, v164, v191
	v_mul_f32_e32 v166, v166, v164
	v_mul_f32_e32 v166, v166, v165
	v_mul_f32_e32 v166, v134, v166
	v_sub_f32_e32 v165, v134, v166
	v_cmp_gt_f32_e64 s[100:101], 0, v134
	s_nop 1
	v_cndmask_b32_e64 v132, v165, v166, s[100:101]
	v_and_b32_e32 v164, 0x7fffffff, v140
	v_and_b32_e32 v167, 0x7fffffff, v135
	v_mul_f32_e32 v165, v140, v140
	v_mul_f32_e32 v168, v135, v135
	v_fma_f32 v164, v164, s14, 1.0
	v_fma_f32 v167, v167, s14, 1.0
	v_mul_f32_e32 v165, s20, v165
	v_mul_f32_e32 v168, s20, v168
	v_rcp_f32_e32 v164, v164
	v_rcp_f32_e32 v167, v167
	s_nop 0
	v_exp_f32_e32 v165, v165
	v_exp_f32_e32 v168, v168
	s_nop 0
	v_fma_f32 v166, v164, s15, v188
	v_fma_f32 v169, v167, s15, v188
	v_fma_f32 v166, v166, v164, v189
	v_fma_f32 v169, v169, v167, v189
	v_fma_f32 v166, v166, v164, v190
	v_fma_f32 v169, v169, v167, v190
	v_fma_f32 v166, v166, v164, v191
	v_fma_f32 v169, v169, v167, v191
	v_mul_f32_e32 v166, v166, v164
	v_mul_f32_e32 v169, v169, v167
	v_mul_f32_e32 v166, v166, v165
	v_mul_f32_e32 v169, v169, v168
	v_mul_f32_e32 v166, v140, v166
	v_mul_f32_e32 v169, v135, v169
	v_sub_f32_e32 v165, v140, v166
	v_sub_f32_e32 v168, v135, v169
	v_cmp_gt_f32_e64 s[100:101], 0, v140
	s_nop 1
	v_cndmask_b32_e64 v134, v165, v166, s[100:101]
	v_cmp_gt_f32_e64 s[100:101], 0, v135
	s_nop 1
	v_cndmask_b32_e64 v133, v168, v169, s[100:101]
	v_mov_b32_e32 v146, v132
	v_mov_b32_e32 v147, v133
	v_and_b32_e32 v164, 0x7fffffff, v141
	v_mul_f32_e32 v165, v141, v141
	v_fma_f32 v164, v164, s14, 1.0
	v_mul_f32_e32 v165, s20, v165
	v_rcp_f32_e32 v164, v164
	s_nop 0
	v_exp_f32_e32 v165, v165
	s_nop 0
	v_fma_f32 v166, v164, s15, v188
	v_fma_f32 v166, v166, v164, v189
	v_fma_f32 v166, v166, v164, v190
	v_fma_f32 v166, v166, v164, v191
	v_mul_f32_e32 v166, v166, v164
	v_mul_f32_e32 v166, v166, v165
	v_mul_f32_e32 v166, v141, v166
	v_sub_f32_e32 v165, v141, v166
	v_cmp_gt_f32_e64 s[100:101], 0, v141
	s_nop 1
	v_cndmask_b32_e64 v135, v165, v166, s[100:101]
	v_mov_b32_e32 v140, v134
	v_mov_b32_e32 v141, v135
	v_cvt_pk_bf16_f32 v132, v138, v139
	v_cvt_pk_bf16_f32 v133, v146, v147
	v_cvt_pk_bf16_f32 v134, v144, v145
	v_cvt_pk_bf16_f32 v135, v140, v141
	global_store_dwordx4 v[142:143], v[132:135], off offset:256
	v_pk_mul_f32 v[140:141], v[18:19], v[130:131] op_sel_hi:[1,0]
	v_pk_mul_f32 v[142:143], v[16:17], v[130:131] op_sel_hi:[1,0]
	v_pk_mul_f32 v[134:135], v[20:21], v[130:131] op_sel_hi:[1,0]
	v_pk_mul_f32 v[132:133], v[22:23], v[130:131] op_sel_hi:[1,0]
	v_lshl_add_u64 v[138:139], v[136:137], 0, s[0:1]
	v_and_b32_e32 v164, 0x7fffffff, v134
	v_and_b32_e32 v167, 0x7fffffff, v135
	v_and_b32_e32 v170, 0x7fffffff, v140
	v_and_b32_e32 v173, 0x7fffffff, v141
	v_and_b32_e32 v176, 0x7fffffff, v142
	v_mul_f32_e32 v165, v134, v134
	v_mul_f32_e32 v168, v135, v135
	v_mul_f32_e32 v171, v140, v140
	v_mul_f32_e32 v174, v141, v141
	v_mul_f32_e32 v177, v142, v142
	v_fma_f32 v164, v164, s14, 1.0
	v_fma_f32 v167, v167, s14, 1.0
	v_fma_f32 v170, v170, s14, 1.0
	v_fma_f32 v173, v173, s14, 1.0
	v_fma_f32 v176, v176, s14, 1.0
	v_mul_f32_e32 v165, s20, v165
	v_mul_f32_e32 v168, s20, v168
	v_mul_f32_e32 v171, s20, v171
	v_mul_f32_e32 v174, s20, v174
	v_mul_f32_e32 v177, s20, v177
	v_rcp_f32_e32 v164, v164
	v_rcp_f32_e32 v167, v167
	v_rcp_f32_e32 v170, v170
	v_rcp_f32_e32 v173, v173
	v_rcp_f32_e32 v176, v176
	s_nop 0
	v_exp_f32_e32 v165, v165
	v_exp_f32_e32 v168, v168
	v_exp_f32_e32 v171, v171
	v_exp_f32_e32 v174, v174
	v_exp_f32_e32 v177, v177
	s_nop 0
	v_fma_f32 v166, v164, s15, v188
	v_fma_f32 v169, v167, s15, v188
	v_fma_f32 v172, v170, s15, v188
	v_fma_f32 v175, v173, s15, v188
	v_fma_f32 v178, v176, s15, v188
	v_fma_f32 v166, v166, v164, v189
	v_fma_f32 v169, v169, v167, v189
	v_fma_f32 v172, v172, v170, v189
	v_fma_f32 v175, v175, v173, v189
	v_fma_f32 v178, v178, v176, v189
	v_fma_f32 v166, v166, v164, v190
	v_fma_f32 v169, v169, v167, v190
	v_fma_f32 v172, v172, v170, v190
	v_fma_f32 v175, v175, v173, v190
	v_fma_f32 v178, v178, v176, v190
	v_fma_f32 v166, v166, v164, v191
	v_fma_f32 v169, v169, v167, v191
	v_fma_f32 v172, v172, v170, v191
	v_fma_f32 v175, v175, v173, v191
	v_fma_f32 v178, v178, v176, v191
	v_mul_f32_e32 v166, v166, v164
	v_mul_f32_e32 v169, v169, v167
	v_mul_f32_e32 v172, v172, v170
	v_mul_f32_e32 v175, v175, v173
	v_mul_f32_e32 v178, v178, v176
	v_mul_f32_e32 v166, v166, v165
	v_mul_f32_e32 v169, v169, v168
	v_mul_f32_e32 v172, v172, v171
	v_mul_f32_e32 v175, v175, v174
	v_mul_f32_e32 v178, v178, v177
	v_mul_f32_e32 v166, v134, v166
	v_mul_f32_e32 v169, v135, v169
	v_mul_f32_e32 v172, v140, v172
	v_mul_f32_e32 v175, v141, v175
	v_mul_f32_e32 v178, v142, v178
	v_sub_f32_e32 v165, v134, v166
	v_sub_f32_e32 v168, v135, v169
	v_sub_f32_e32 v171, v140, v172
	v_sub_f32_e32 v174, v141, v175
	v_sub_f32_e32 v177, v142, v178
	v_cmp_gt_f32_e64 s[100:101], 0, v134
	s_nop 1
; __device__ __forceinline__ unsigned cvt_pk_bf16(float lo, float hi) { const f32x2 v = {lo, hi}; const bf16v2_t b = __builtin_convertvector(v, bf16v2_t); return __builtin_bit_cast(unsigned, b); }
; __device__ __forceinline__ float sigmoidf_(float x) { return __builtin_amdgcn_rcpf(1.0f + __builtin_amdgcn_exp2f(x * -1.44269504089f)); }
; __device__ __forceinline__ float siluf_(float x) { return x * __builtin_amdgcn_rcpf(1.0f + __builtin_amdgcn_exp2f(x * -1.44269504089f)); }
; __device__ __forceinline__ f32x2 gelu_pk(f32x2 v) {
;     const f32x2 av = __builtin_elementwise_abs(v), d = av * 0.2316418882f + 1.0f;
;     f32x2 t; t.x = __builtin_amdgcn_rcpf(d.x); t.y = __builtin_amdgcn_rcpf(d.y);
;     f32x2 q = t * 0.5307027145f + (-0.7265760135f); q = q * t + 0.7107068705f; q = q * t + (-0.142248368f); q = q * t + 0.127414796f; q = q * t;
;     const f32x2 s = (v * v) * (-0.72134752044f);
;     f32x2 e; e.x = __builtin_amdgcn_exp2f(s.x); e.y = __builtin_amdgcn_exp2f(s.y);
;     const f32x2 m = v * (q * e), r = v - m;
;     f32x2 o; o.x = v.x < 0.f ? m.x : r.x; o.y = v.y < 0.f ? m.y : r.y; return o;
; }
;     __device__ __forceinline__ void epi_proj(const f32x4 (&acc)[2][2][4][2], const pg8::Unit& u, int wr, int wc, int fr, int fq) const {
;     ...
;                         for (int bj = 0; bj < 2; ++bj) {
;                             f32x4 v0 = acc[ai][bj][m][0] * rstd, v1 = acc[ai][bj][m][1] * rstd;
;                             if (slot < 2) {
;                                 f32x2 a = gelu_pk((f32x2){v0[0], v0[1]}), b = gelu_pk((f32x2){v0[2], v0[3]}), c = gelu_pk((f32x2){v1[0], v1[1]}), d = gelu_pk((f32x2){v1[2], v1[3]});
;                                 v0 = (f32x4){a.x, a.y, b.x, b.y}; v1 = (f32x4){c.x, c.y, d.x, d.y};
;                             } else if (slot == 5) {
; #pragma unroll
;                                 for (int j = 0; j < 4; ++j) { v0[j] = siluf_(v0[j]); v1[j] = siluf_(v1[j]); }
;                             } else if (slot >= 6) {
; #pragma unroll
;                                 for (int j = 0; j < 4; ++j) { v0[j] = sigmoidf_(v0[j]); v1[j] = sigmoidf_(v1[j]); }
;                             }
;                             u32x4 w; w.x = cvt_pk_bf16(v0[0], v0[1]); w.y = cvt_pk_bf16(v0[2], v0[3]); w.z = cvt_pk_bf16(v1[0], v1[1]); w.w = cvt_pk_bf16(v1[2], v1[3]);
;                             *(u32x4*)(rowp + bj * 128) = w;
	v_cndmask_b32_e64 v134, v165, v166, s[100:101]
	v_cmp_gt_f32_e64 s[100:101], 0, v135
	s_nop 1
	v_cndmask_b32_e64 v135, v168, v169, s[100:101]
	v_cmp_gt_f32_e64 s[100:101], 0, v140
	s_nop 1
	v_cndmask_b32_e64 v140, v171, v172, s[100:101]
	v_cmp_gt_f32_e64 s[100:101], 0, v141
	s_nop 1
	v_cndmask_b32_e64 v141, v174, v175, s[100:101]
	v_cmp_gt_f32_e64 s[100:101], 0, v142
	s_nop 1
	v_cndmask_b32_e64 v142, v177, v178, s[100:101]
	s_mov_b32 s0, 0x50000
	v_and_b32_e32 v164, 0x7fffffff, v143
	v_and_b32_e32 v167, 0x7fffffff, v132
	v_and_b32_e32 v170, 0x7fffffff, v133
	v_mul_f32_e32 v165, v143, v143
	v_mul_f32_e32 v168, v132, v132
	v_mul_f32_e32 v171, v133, v133
	v_fma_f32 v164, v164, s14, 1.0
	v_fma_f32 v167, v167, s14, 1.0
	v_fma_f32 v170, v170, s14, 1.0
	v_mul_f32_e32 v165, s20, v165
	v_mul_f32_e32 v168, s20, v168
	v_mul_f32_e32 v171, s20, v171
	v_rcp_f32_e32 v164, v164
	v_rcp_f32_e32 v167, v167
	v_rcp_f32_e32 v170, v170
	s_nop 0
	v_exp_f32_e32 v165, v165
	v_exp_f32_e32 v168, v168
	v_exp_f32_e32 v171, v171
	s_nop 0
	v_fma_f32 v166, v164, s15, v188
	v_fma_f32 v169, v167, s15, v188
	v_fma_f32 v172, v170, s15, v188
	v_fma_f32 v166, v166, v164, v189
	v_fma_f32 v169, v169, v167, v189
	v_fma_f32 v172, v172, v170, v189
	v_fma_f32 v166, v166, v164, v190
	v_fma_f32 v169, v169, v167, v190
	v_fma_f32 v172, v172, v170, v190
	v_fma_f32 v166, v166, v164, v191
	v_fma_f32 v169, v169, v167, v191
	v_fma_f32 v172, v172, v170, v191
	v_mul_f32_e32 v166, v166, v164
	v_mul_f32_e32 v169, v169, v167
	v_mul_f32_e32 v172, v172, v170
	v_mul_f32_e32 v166, v166, v165
	v_mul_f32_e32 v169, v169, v168
	v_mul_f32_e32 v172, v172, v171
	v_mul_f32_e32 v166, v143, v166
	v_mul_f32_e32 v169, v132, v169
	v_mul_f32_e32 v172, v133, v172
	v_sub_f32_e32 v165, v143, v166
	v_sub_f32_e32 v168, v132, v169
	v_sub_f32_e32 v171, v133, v172
	v_cmp_gt_f32_e64 s[100:101], 0, v143
	s_nop 1
	v_cndmask_b32_e64 v143, v165, v166, s[100:101]
	v_cmp_gt_f32_e64 s[100:101], 0, v132
	s_nop 1
	v_cndmask_b32_e64 v132, v168, v169, s[100:101]
	v_cmp_gt_f32_e64 s[100:101], 0, v133
	s_nop 1
	v_cndmask_b32_e64 v133, v171, v172, s[100:101]
	v_mov_b32_e32 v144, v132
	v_mov_b32_e32 v145, v133
	v_cvt_pk_bf16_f32 v132, v134, v135
	v_cvt_pk_bf16_f32 v135, v140, v141
	v_add_co_u32_e32 v140, vcc, s0, v136
	v_cvt_pk_bf16_f32 v133, v144, v145
	v_cvt_pk_bf16_f32 v134, v142, v143
	v_addc_co_u32_e32 v141, vcc, 0, v137, vcc
	global_store_dwordx4 v[140:141], v[132:135], off
	v_pk_mul_f32 v[140:141], v[26:27], v[130:131] op_sel_hi:[1,0]
	s_mov_b64 s[0:1], 0x58000
	v_pk_mul_f32 v[132:133], v[30:31], v[130:131] op_sel_hi:[1,0]
	v_pk_mul_f32 v[134:135], v[28:29], v[130:131] op_sel_hi:[1,0]
	v_pk_mul_f32 v[130:131], v[24:25], v[130:131] op_sel_hi:[1,0]
	v_and_b32_e32 v164, 0x7fffffff, v134
	v_and_b32_e32 v167, 0x7fffffff, v130
	v_and_b32_e32 v170, 0x7fffffff, v131
	v_and_b32_e32 v173, 0x7fffffff, v135
	v_mul_f32_e32 v165, v134, v134
	v_mul_f32_e32 v168, v130, v130
	v_mul_f32_e32 v171, v131, v131
	v_mul_f32_e32 v174, v135, v135
	v_fma_f32 v164, v164, s14, 1.0
	v_fma_f32 v167, v167, s14, 1.0
	v_fma_f32 v170, v170, s14, 1.0
	v_fma_f32 v173, v173, s14, 1.0
	v_mul_f32_e32 v165, s20, v165
	v_mul_f32_e32 v168, s20, v168
	v_mul_f32_e32 v171, s20, v171
	v_mul_f32_e32 v174, s20, v174
	v_rcp_f32_e32 v164, v164
	v_rcp_f32_e32 v167, v167
	v_rcp_f32_e32 v170, v170
	v_rcp_f32_e32 v173, v173
	s_nop 0
	v_exp_f32_e32 v165, v165
	v_exp_f32_e32 v168, v168
	v_exp_f32_e32 v171, v171
	v_exp_f32_e32 v174, v174
	s_nop 0
	v_fma_f32 v166, v164, s15, v188
	v_fma_f32 v169, v167, s15, v188
	v_fma_f32 v172, v170, s15, v188
	v_fma_f32 v175, v173, s15, v188
	v_fma_f32 v166, v166, v164, v189
	v_fma_f32 v169, v169, v167, v189
	v_fma_f32 v172, v172, v170, v189
	v_fma_f32 v175, v175, v173, v189
	v_fma_f32 v166, v166, v164, v190
	v_fma_f32 v169, v169, v167, v190
	v_fma_f32 v172, v172, v170, v190
	v_fma_f32 v175, v175, v173, v190
	v_fma_f32 v166, v166, v164, v191
	v_fma_f32 v169, v169, v167, v191
	v_fma_f32 v172, v172, v170, v191
	v_fma_f32 v175, v175, v173, v191
	v_mul_f32_e32 v166, v166, v164
	v_mul_f32_e32 v169, v169, v167
	v_mul_f32_e32 v172, v172, v170
	v_mul_f32_e32 v175, v175, v173
	v_mul_f32_e32 v166, v166, v165
	v_mul_f32_e32 v169, v169, v168
	v_mul_f32_e32 v172, v172, v171
	v_mul_f32_e32 v175, v175, v174
	v_mul_f32_e32 v166, v134, v166
	v_mul_f32_e32 v169, v130, v169
	v_mul_f32_e32 v172, v131, v172
	v_mul_f32_e32 v175, v135, v175
	v_sub_f32_e32 v165, v134, v166
	v_sub_f32_e32 v168, v130, v169
	v_sub_f32_e32 v171, v131, v172
	v_sub_f32_e32 v174, v135, v175
	v_cmp_gt_f32_e64 s[100:101], 0, v134
	s_nop 1
	v_cndmask_b32_e64 v134, v165, v166, s[100:101]
	v_cmp_gt_f32_e64 s[100:101], 0, v130
	s_nop 1
	v_cndmask_b32_e64 v130, v168, v169, s[100:101]
	v_cmp_gt_f32_e64 s[100:101], 0, v131
	s_nop 1
	v_cndmask_b32_e64 v131, v171, v172, s[100:101]
	v_cmp_gt_f32_e64 s[100:101], 0, v135
	s_nop 1
	v_cndmask_b32_e64 v135, v174, v175, s[100:101]
	v_mov_b32_e32 v142, v130
	v_mov_b32_e32 v143, v131
	v_and_b32_e32 v164, 0x7fffffff, v132
	v_mul_f32_e32 v165, v132, v132
	v_fma_f32 v164, v164, s14, 1.0
	v_mul_f32_e32 v165, s20, v165
	v_rcp_f32_e32 v164, v164
	s_nop 0
	v_exp_f32_e32 v165, v165
	s_nop 0
	v_fma_f32 v166, v164, s15, v188
	v_fma_f32 v166, v166, v164, v189
	v_fma_f32 v166, v166, v164, v190
	v_fma_f32 v166, v166, v164, v191
	v_mul_f32_e32 v166, v166, v164
	v_mul_f32_e32 v166, v166, v165
	v_mul_f32_e32 v166, v132, v166
	v_sub_f32_e32 v165, v132, v166
	v_cmp_gt_f32_e64 s[100:101], 0, v132
	s_nop 1
	v_cndmask_b32_e64 v130, v165, v166, s[100:101]
	v_and_b32_e32 v164, 0x7fffffff, v140
	v_and_b32_e32 v167, 0x7fffffff, v133
	v_mul_f32_e32 v165, v140, v140
	v_mul_f32_e32 v168, v133, v133
; __device__ __forceinline__ unsigned cvt_pk_bf16(float lo, float hi) { const f32x2 v = {lo, hi}; const bf16v2_t b = __builtin_convertvector(v, bf16v2_t); return __builtin_bit_cast(unsigned, b); }
; __device__ __forceinline__ float sigmoidf_(float x) { return __builtin_amdgcn_rcpf(1.0f + __builtin_amdgcn_exp2f(x * -1.44269504089f)); }
; __device__ __forceinline__ float siluf_(float x) { return x * __builtin_amdgcn_rcpf(1.0f + __builtin_amdgcn_exp2f(x * -1.44269504089f)); }
; __device__ __forceinline__ f32x2 gelu_pk(f32x2 v) {
;     const f32x2 av = __builtin_elementwise_abs(v), d = av * 0.2316418882f + 1.0f;
;     f32x2 t; t.x = __builtin_amdgcn_rcpf(d.x); t.y = __builtin_amdgcn_rcpf(d.y);
;     f32x2 q = t * 0.5307027145f + (-0.7265760135f); q = q * t + 0.7107068705f; q = q * t + (-0.142248368f); q = q * t + 0.127414796f; q = q * t;
;     const f32x2 s = (v * v) * (-0.72134752044f);
;     f32x2 e; e.x = __builtin_amdgcn_exp2f(s.x); e.y = __builtin_amdgcn_exp2f(s.y);
;     const f32x2 m = v * (q * e), r = v - m;
;     f32x2 o; o.x = v.x < 0.f ? m.x : r.x; o.y = v.y < 0.f ? m.y : r.y; return o;
; }
;     __device__ __forceinline__ void epi_proj(const f32x4 (&acc)[2][2][4][2], const pg8::Unit& u, int wr, int wc, int fr, int fq) const {
;     ...
;                         for (int bj = 0; bj < 2; ++bj) {
;                             f32x4 v0 = acc[ai][bj][m][0] * rstd, v1 = acc[ai][bj][m][1] * rstd;
;                             if (slot < 2) {
;                                 f32x2 a = gelu_pk((f32x2){v0[0], v0[1]}), b = gelu_pk((f32x2){v0[2], v0[3]}), c = gelu_pk((f32x2){v1[0], v1[1]}), d = gelu_pk((f32x2){v1[2], v1[3]});
;                                 v0 = (f32x4){a.x, a.y, b.x, b.y}; v1 = (f32x4){c.x, c.y, d.x, d.y};
;                             } else if (slot == 5) {
; #pragma unroll
;                                 for (int j = 0; j < 4; ++j) { v0[j] = siluf_(v0[j]); v1[j] = siluf_(v1[j]); }
;                             } else if (slot >= 6) {
; #pragma unroll
;                                 for (int j = 0; j < 4; ++j) { v0[j] = sigmoidf_(v0[j]); v1[j] = sigmoidf_(v1[j]); }
;                             }
;                             u32x4 w; w.x = cvt_pk_bf16(v0[0], v0[1]); w.y = cvt_pk_bf16(v0[2], v0[3]); w.z = cvt_pk_bf16(v1[0], v1[1]); w.w = cvt_pk_bf16(v1[2], v1[3]);
;                             *(u32x4*)(rowp + bj * 128) = w;
	v_fma_f32 v164, v164, s14, 1.0
	v_fma_f32 v167, v167, s14, 1.0
	v_mul_f32_e32 v165, s20, v165
	v_mul_f32_e32 v168, s20, v168
	v_rcp_f32_e32 v164, v164
	v_rcp_f32_e32 v167, v167
	s_nop 0
	v_exp_f32_e32 v165, v165
	v_exp_f32_e32 v168, v168
	s_nop 0
	v_fma_f32 v166, v164, s15, v188
	v_fma_f32 v169, v167, s15, v188
	v_fma_f32 v166, v166, v164, v189
	v_fma_f32 v169, v169, v167, v189
	v_fma_f32 v166, v166, v164, v190
	v_fma_f32 v169, v169, v167, v190
	v_fma_f32 v166, v166, v164, v191
	v_fma_f32 v169, v169, v167, v191
	v_mul_f32_e32 v166, v166, v164
	v_mul_f32_e32 v169, v169, v167
	v_mul_f32_e32 v166, v166, v165
	v_mul_f32_e32 v169, v169, v168
	v_mul_f32_e32 v166, v140, v166
	v_mul_f32_e32 v169, v133, v169
	v_sub_f32_e32 v165, v140, v166
	v_sub_f32_e32 v168, v133, v169
	v_cmp_gt_f32_e64 s[100:101], 0, v140
	s_nop 1
	v_cndmask_b32_e64 v132, v165, v166, s[100:101]
	v_cmp_gt_f32_e64 s[100:101], 0, v133
	s_nop 1
	v_cndmask_b32_e64 v131, v168, v169, s[100:101]
	v_mov_b32_e32 v144, v130
	v_mov_b32_e32 v145, v131
	v_and_b32_e32 v164, 0x7fffffff, v141
	v_mul_f32_e32 v165, v141, v141
	v_fma_f32 v164, v164, s14, 1.0
	v_mul_f32_e32 v165, s20, v165
	v_rcp_f32_e32 v164, v164
	s_nop 0
	v_exp_f32_e32 v165, v165
	s_nop 0
	v_fma_f32 v166, v164, s15, v188
	v_fma_f32 v166, v166, v164, v189
	v_fma_f32 v166, v166, v164, v190
	v_fma_f32 v166, v166, v164, v191
	v_mul_f32_e32 v166, v166, v164
	v_mul_f32_e32 v166, v166, v165
	v_mul_f32_e32 v166, v141, v166
	v_sub_f32_e32 v165, v141, v166
	v_cmp_gt_f32_e64 s[100:101], 0, v141
	s_nop 1
	v_cndmask_b32_e64 v133, v165, v166, s[100:101]
	v_mov_b32_e32 v140, v132
	v_mov_b32_e32 v141, v133
	v_cvt_pk_bf16_f32 v130, v134, v135
	v_cvt_pk_bf16_f32 v131, v144, v145
	v_cvt_pk_bf16_f32 v132, v142, v143
	v_cvt_pk_bf16_f32 v133, v140, v141
	global_store_dwordx4 v[138:139], v[130:133], off offset:256
	v_pk_mul_f32 v[138:139], v[2:3], v[128:129] op_sel_hi:[1,0]
	v_pk_mul_f32 v[140:141], v[0:1], v[128:129] op_sel_hi:[1,0]
	v_pk_mul_f32 v[130:131], v[6:7], v[128:129] op_sel_hi:[1,0]
	v_pk_mul_f32 v[132:133], v[4:5], v[128:129] op_sel_hi:[1,0]
	v_lshl_add_u64 v[134:135], v[136:137], 0, s[0:1]
	s_mov_b32 s0, 0x58000
	v_and_b32_e32 v164, 0x7fffffff, v132
	v_and_b32_e32 v167, 0x7fffffff, v140
	v_and_b32_e32 v170, 0x7fffffff, v133
	v_and_b32_e32 v173, 0x7fffffff, v141
	v_and_b32_e32 v176, 0x7fffffff, v130
	v_and_b32_e32 v179, 0x7fffffff, v138
	v_and_b32_e32 v182, 0x7fffffff, v131
	v_and_b32_e32 v185, 0x7fffffff, v139
	v_mul_f32_e32 v165, v132, v132
	v_mul_f32_e32 v168, v140, v140
	v_mul_f32_e32 v171, v133, v133
	v_mul_f32_e32 v174, v141, v141
	v_mul_f32_e32 v177, v130, v130
	v_mul_f32_e32 v180, v138, v138
	v_mul_f32_e32 v183, v131, v131
	v_mul_f32_e32 v186, v139, v139
	v_fma_f32 v164, v164, s14, 1.0
	v_fma_f32 v167, v167, s14, 1.0
	v_fma_f32 v170, v170, s14, 1.0
	v_fma_f32 v173, v173, s14, 1.0
	v_fma_f32 v176, v176, s14, 1.0
	v_fma_f32 v179, v179, s14, 1.0
	v_fma_f32 v182, v182, s14, 1.0
	v_fma_f32 v185, v185, s14, 1.0
	v_mul_f32_e32 v165, s20, v165
	v_mul_f32_e32 v168, s20, v168
	v_mul_f32_e32 v171, s20, v171
	v_mul_f32_e32 v174, s20, v174
	v_mul_f32_e32 v177, s20, v177
	v_mul_f32_e32 v180, s20, v180
	v_mul_f32_e32 v183, s20, v183
	v_mul_f32_e32 v186, s20, v186
	v_rcp_f32_e32 v164, v164
	v_rcp_f32_e32 v167, v167
	v_rcp_f32_e32 v170, v170
	v_rcp_f32_e32 v173, v173
	v_rcp_f32_e32 v176, v176
	v_rcp_f32_e32 v179, v179
	v_rcp_f32_e32 v182, v182
	v_rcp_f32_e32 v185, v185
	s_nop 0
	v_exp_f32_e32 v165, v165
	v_exp_f32_e32 v168, v168
	v_exp_f32_e32 v171, v171
	v_exp_f32_e32 v174, v174
	v_exp_f32_e32 v177, v177
	v_exp_f32_e32 v180, v180
	v_exp_f32_e32 v183, v183
	v_exp_f32_e32 v186, v186
	s_nop 0
	v_fma_f32 v166, v164, s15, v188
	v_fma_f32 v169, v167, s15, v188
	v_fma_f32 v172, v170, s15, v188
	v_fma_f32 v175, v173, s15, v188
	v_fma_f32 v178, v176, s15, v188
	v_fma_f32 v181, v179, s15, v188
	v_fma_f32 v184, v182, s15, v188
	v_fma_f32 v187, v185, s15, v188
	v_fma_f32 v166, v166, v164, v189
	v_fma_f32 v169, v169, v167, v189
	v_fma_f32 v172, v172, v170, v189
	v_fma_f32 v175, v175, v173, v189
	v_fma_f32 v178, v178, v176, v189
	v_fma_f32 v181, v181, v179, v189
	v_fma_f32 v184, v184, v182, v189
	v_fma_f32 v187, v187, v185, v189
	v_fma_f32 v166, v166, v164, v190
	v_fma_f32 v169, v169, v167, v190
	v_fma_f32 v172, v172, v170, v190
	v_fma_f32 v175, v175, v173, v190
	v_fma_f32 v178, v178, v176, v190
	v_fma_f32 v181, v181, v179, v190
	v_fma_f32 v184, v184, v182, v190
	v_fma_f32 v187, v187, v185, v190
	v_fma_f32 v166, v166, v164, v191
	v_fma_f32 v169, v169, v167, v191
	v_fma_f32 v172, v172, v170, v191
	v_fma_f32 v175, v175, v173, v191
	v_fma_f32 v178, v178, v176, v191
	v_fma_f32 v181, v181, v179, v191
	v_fma_f32 v184, v184, v182, v191
	v_fma_f32 v187, v187, v185, v191
	v_mul_f32_e32 v166, v166, v164
	v_mul_f32_e32 v169, v169, v167
	v_mul_f32_e32 v172, v172, v170
	v_mul_f32_e32 v175, v175, v173
	v_mul_f32_e32 v178, v178, v176
	v_mul_f32_e32 v181, v181, v179
	v_mul_f32_e32 v184, v184, v182
	v_mul_f32_e32 v187, v187, v185
	v_mul_f32_e32 v166, v166, v165
	v_mul_f32_e32 v169, v169, v168
	v_mul_f32_e32 v172, v172, v171
	v_mul_f32_e32 v175, v175, v174
	v_mul_f32_e32 v178, v178, v177
	v_mul_f32_e32 v181, v181, v180
	v_mul_f32_e32 v184, v184, v183
	v_mul_f32_e32 v187, v187, v186
	v_mul_f32_e32 v166, v132, v166
	v_mul_f32_e32 v169, v140, v169
	v_mul_f32_e32 v172, v133, v172
	v_mul_f32_e32 v175, v141, v175
	v_mul_f32_e32 v178, v130, v178
	v_mul_f32_e32 v181, v138, v181
	v_mul_f32_e32 v184, v131, v184
	v_mul_f32_e32 v187, v139, v187
	v_sub_f32_e32 v165, v132, v166
	v_sub_f32_e32 v168, v140, v169
	v_sub_f32_e32 v171, v133, v172
	v_sub_f32_e32 v174, v141, v175
; __device__ __forceinline__ unsigned cvt_pk_bf16(float lo, float hi) { const f32x2 v = {lo, hi}; const bf16v2_t b = __builtin_convertvector(v, bf16v2_t); return __builtin_bit_cast(unsigned, b); }
; __device__ __forceinline__ float sigmoidf_(float x) { return __builtin_amdgcn_rcpf(1.0f + __builtin_amdgcn_exp2f(x * -1.44269504089f)); }
; __device__ __forceinline__ float siluf_(float x) { return x * __builtin_amdgcn_rcpf(1.0f + __builtin_amdgcn_exp2f(x * -1.44269504089f)); }
; __device__ __forceinline__ f32x2 gelu_pk(f32x2 v) {
;     const f32x2 av = __builtin_elementwise_abs(v), d = av * 0.2316418882f + 1.0f;
;     f32x2 t; t.x = __builtin_amdgcn_rcpf(d.x); t.y = __builtin_amdgcn_rcpf(d.y);
;     f32x2 q = t * 0.5307027145f + (-0.7265760135f); q = q * t + 0.7107068705f; q = q * t + (-0.142248368f); q = q * t + 0.127414796f; q = q * t;
;     const f32x2 s = (v * v) * (-0.72134752044f);
;     f32x2 e; e.x = __builtin_amdgcn_exp2f(s.x); e.y = __builtin_amdgcn_exp2f(s.y);
;     const f32x2 m = v * (q * e), r = v - m;
;     f32x2 o; o.x = v.x < 0.f ? m.x : r.x; o.y = v.y < 0.f ? m.y : r.y; return o;
; }
;     __device__ __forceinline__ void epi_proj(const f32x4 (&acc)[2][2][4][2], const pg8::Unit& u, int wr, int wc, int fr, int fq) const {
;     ...
;                         for (int bj = 0; bj < 2; ++bj) {
;                             f32x4 v0 = acc[ai][bj][m][0] * rstd, v1 = acc[ai][bj][m][1] * rstd;
;                             if (slot < 2) {
;                                 f32x2 a = gelu_pk((f32x2){v0[0], v0[1]}), b = gelu_pk((f32x2){v0[2], v0[3]}), c = gelu_pk((f32x2){v1[0], v1[1]}), d = gelu_pk((f32x2){v1[2], v1[3]});
;                                 v0 = (f32x4){a.x, a.y, b.x, b.y}; v1 = (f32x4){c.x, c.y, d.x, d.y};
;                             } else if (slot == 5) {
; #pragma unroll
;                                 for (int j = 0; j < 4; ++j) { v0[j] = siluf_(v0[j]); v1[j] = siluf_(v1[j]); }
;                             } else if (slot >= 6) {
; #pragma unroll
;                                 for (int j = 0; j < 4; ++j) { v0[j] = sigmoidf_(v0[j]); v1[j] = sigmoidf_(v1[j]); }
;                             }
;                             u32x4 w; w.x = cvt_pk_bf16(v0[0], v0[1]); w.y = cvt_pk_bf16(v0[2], v0[3]); w.z = cvt_pk_bf16(v1[0], v1[1]); w.w = cvt_pk_bf16(v1[2], v1[3]);
;                             *(u32x4*)(rowp + bj * 128) = w;
	v_sub_f32_e32 v177, v130, v178
	v_sub_f32_e32 v180, v138, v181
	v_sub_f32_e32 v183, v131, v184
	v_sub_f32_e32 v186, v139, v187
	v_cmp_gt_f32_e64 s[100:101], 0, v132
	s_nop 1
	v_cndmask_b32_e64 v132, v165, v166, s[100:101]
	v_cmp_gt_f32_e64 s[100:101], 0, v140
	s_nop 1
	v_cndmask_b32_e64 v140, v168, v169, s[100:101]
	v_cmp_gt_f32_e64 s[100:101], 0, v133
	s_nop 1
	v_cndmask_b32_e64 v133, v171, v172, s[100:101]
	v_cmp_gt_f32_e64 s[100:101], 0, v141
	s_nop 1
	v_cndmask_b32_e64 v141, v174, v175, s[100:101]
	v_cmp_gt_f32_e64 s[100:101], 0, v130
	s_nop 1
	v_cndmask_b32_e64 v130, v177, v178, s[100:101]
	v_cmp_gt_f32_e64 s[100:101], 0, v138
	s_nop 1
	v_cndmask_b32_e64 v138, v180, v181, s[100:101]
	v_cmp_gt_f32_e64 s[100:101], 0, v131
	s_nop 1
	v_cndmask_b32_e64 v131, v183, v184, s[100:101]
	v_cmp_gt_f32_e64 s[100:101], 0, v139
	s_nop 1
	v_cndmask_b32_e64 v139, v186, v187, s[100:101]
	v_mov_b32_e32 v142, v130
	v_mov_b32_e32 v143, v131
	v_add_co_u32_e32 v136, vcc, s0, v136
	v_cvt_pk_bf16_f32 v130, v132, v133
	v_cvt_pk_bf16_f32 v131, v142, v143
	v_cvt_pk_bf16_f32 v132, v140, v141
	v_cvt_pk_bf16_f32 v133, v138, v139
	v_addc_co_u32_e32 v137, vcc, 0, v137, vcc
	global_store_dwordx4 v[136:137], v[130:133], off
	v_pk_mul_f32 v[136:137], v[10:11], v[128:129] op_sel_hi:[1,0]
	s_nop 0
	v_pk_mul_f32 v[130:131], v[14:15], v[128:129] op_sel_hi:[1,0]
	v_pk_mul_f32 v[132:133], v[12:13], v[128:129] op_sel_hi:[1,0]
	v_pk_mul_f32 v[128:129], v[8:9], v[128:129] op_sel_hi:[1,0]
	v_and_b32_e32 v164, 0x7fffffff, v132
	v_and_b32_e32 v167, 0x7fffffff, v128
	v_and_b32_e32 v170, 0x7fffffff, v129
	v_and_b32_e32 v173, 0x7fffffff, v133
	v_mul_f32_e32 v165, v132, v132
	v_mul_f32_e32 v168, v128, v128
	v_mul_f32_e32 v171, v129, v129
	v_mul_f32_e32 v174, v133, v133
	v_fma_f32 v164, v164, s14, 1.0
	v_fma_f32 v167, v167, s14, 1.0
	v_fma_f32 v170, v170, s14, 1.0
	v_fma_f32 v173, v173, s14, 1.0
	v_mul_f32_e32 v165, s20, v165
	v_mul_f32_e32 v168, s20, v168
	v_mul_f32_e32 v171, s20, v171
	v_mul_f32_e32 v174, s20, v174
	v_rcp_f32_e32 v164, v164
	v_rcp_f32_e32 v167, v167
	v_rcp_f32_e32 v170, v170
	v_rcp_f32_e32 v173, v173
	s_nop 0
	v_exp_f32_e32 v165, v165
	v_exp_f32_e32 v168, v168
	v_exp_f32_e32 v171, v171
	v_exp_f32_e32 v174, v174
	s_nop 0
	v_fma_f32 v166, v164, s15, v188
	v_fma_f32 v169, v167, s15, v188
	v_fma_f32 v172, v170, s15, v188
	v_fma_f32 v175, v173, s15, v188
	v_fma_f32 v166, v166, v164, v189
	v_fma_f32 v169, v169, v167, v189
	v_fma_f32 v172, v172, v170, v189
	v_fma_f32 v175, v175, v173, v189
	v_fma_f32 v166, v166, v164, v190
	v_fma_f32 v169, v169, v167, v190
	v_fma_f32 v172, v172, v170, v190
	v_fma_f32 v175, v175, v173, v190
	v_fma_f32 v166, v166, v164, v191
	v_fma_f32 v169, v169, v167, v191
	v_fma_f32 v172, v172, v170, v191
	v_fma_f32 v175, v175, v173, v191
	v_mul_f32_e32 v166, v166, v164
	v_mul_f32_e32 v169, v169, v167
	v_mul_f32_e32 v172, v172, v170
	v_mul_f32_e32 v175, v175, v173
	v_mul_f32_e32 v166, v166, v165
	v_mul_f32_e32 v169, v169, v168
	v_mul_f32_e32 v172, v172, v171
	v_mul_f32_e32 v175, v175, v174
	v_mul_f32_e32 v166, v132, v166
	v_mul_f32_e32 v169, v128, v169
	v_mul_f32_e32 v172, v129, v172
	v_mul_f32_e32 v175, v133, v175
	v_sub_f32_e32 v165, v132, v166
	v_sub_f32_e32 v168, v128, v169
	v_sub_f32_e32 v171, v129, v172
	v_sub_f32_e32 v174, v133, v175
	v_cmp_gt_f32_e64 s[100:101], 0, v132
	s_nop 1
	v_cndmask_b32_e64 v132, v165, v166, s[100:101]
	v_cmp_gt_f32_e64 s[100:101], 0, v128
	s_nop 1
	v_cndmask_b32_e64 v128, v168, v169, s[100:101]
	v_cmp_gt_f32_e64 s[100:101], 0, v129
	s_nop 1
	v_cndmask_b32_e64 v129, v171, v172, s[100:101]
	v_cmp_gt_f32_e64 s[100:101], 0, v133
	s_nop 1
	v_cndmask_b32_e64 v133, v174, v175, s[100:101]
	v_mov_b32_e32 v138, v128
	v_mov_b32_e32 v139, v129
	v_and_b32_e32 v164, 0x7fffffff, v130
	v_mul_f32_e32 v165, v130, v130
	v_fma_f32 v164, v164, s14, 1.0
	v_mul_f32_e32 v165, s20, v165
	v_rcp_f32_e32 v164, v164
	s_nop 0
	v_exp_f32_e32 v165, v165
	s_nop 0
	v_fma_f32 v166, v164, s15, v188
	v_fma_f32 v166, v166, v164, v189
	v_fma_f32 v166, v166, v164, v190
	v_fma_f32 v166, v166, v164, v191
	v_mul_f32_e32 v166, v166, v164
	v_mul_f32_e32 v166, v166, v165
	v_mul_f32_e32 v166, v130, v166
	v_sub_f32_e32 v165, v130, v166
	v_cmp_gt_f32_e64 s[100:101], 0, v130
	s_nop 1
	v_cndmask_b32_e64 v128, v165, v166, s[100:101]
	v_and_b32_e32 v164, 0x7fffffff, v136
	v_and_b32_e32 v167, 0x7fffffff, v131
	v_mul_f32_e32 v165, v136, v136
	v_mul_f32_e32 v168, v131, v131
	v_fma_f32 v164, v164, s14, 1.0
	v_fma_f32 v167, v167, s14, 1.0
	v_mul_f32_e32 v165, s20, v165
	v_mul_f32_e32 v168, s20, v168
	v_rcp_f32_e32 v164, v164
	v_rcp_f32_e32 v167, v167
	s_nop 0
	v_exp_f32_e32 v165, v165
	v_exp_f32_e32 v168, v168
	s_nop 0
	v_fma_f32 v166, v164, s15, v188
	v_fma_f32 v169, v167, s15, v188
	v_fma_f32 v166, v166, v164, v189
	v_fma_f32 v169, v169, v167, v189
	v_fma_f32 v166, v166, v164, v190
	v_fma_f32 v169, v169, v167, v190
	v_fma_f32 v166, v166, v164, v191
	v_fma_f32 v169, v169, v167, v191
	v_mul_f32_e32 v166, v166, v164
	v_mul_f32_e32 v169, v169, v167
	v_mul_f32_e32 v166, v166, v165
	v_mul_f32_e32 v169, v169, v168
	v_mul_f32_e32 v166, v136, v166
	v_mul_f32_e32 v169, v131, v169
	v_sub_f32_e32 v165, v136, v166
	v_sub_f32_e32 v168, v131, v169
	v_cmp_gt_f32_e64 s[100:101], 0, v136
	s_nop 1
	v_cndmask_b32_e64 v130, v165, v166, s[100:101]
	v_cmp_gt_f32_e64 s[100:101], 0, v131
	s_nop 1
	v_cndmask_b32_e64 v129, v168, v169, s[100:101]
	v_mov_b32_e32 v140, v128
	v_mov_b32_e32 v141, v129
	v_and_b32_e32 v164, 0x7fffffff, v137
	v_mul_f32_e32 v165, v137, v137
	v_fma_f32 v164, v164, s14, 1.0
	v_mul_f32_e32 v165, s20, v165
	v_rcp_f32_e32 v164, v164
	s_nop 0
	v_exp_f32_e32 v165, v165
	s_nop 0
	v_fma_f32 v166, v164, s15, v188
	v_fma_f32 v166, v166, v164, v189
	v_fma_f32 v166, v166, v164, v190
	v_fma_f32 v166, v166, v164, v191
	v_mul_f32_e32 v166, v166, v164
	v_mul_f32_e32 v166, v166, v165
	v_mul_f32_e32 v166, v137, v166
	v_sub_f32_e32 v165, v137, v166
	v_cmp_gt_f32_e64 s[100:101], 0, v137
	s_nop 1
	v_cndmask_b32_e64 v131, v165, v166, s[100:101]
	v_mov_b32_e32 v136, v130
	v_mov_b32_e32 v137, v131
	v_cvt_pk_bf16_f32 v128, v132, v133
	v_cvt_pk_bf16_f32 v129, v140, v141
	v_cvt_pk_bf16_f32 v130, v138, v139
	v_cvt_pk_bf16_f32 v131, v136, v137
	global_store_dwordx4 v[134:135], v[128:131], off offset:256
	s_branch .LBB0_701
